# team-local barriers at 10 of 13 seams (teams of 4 WGs own fixed row panels), hand-written team-local ew phases with 16B accesses and DPP reductions
# speedup vs baseline: 1.0370x; 1.0316x over previous
; __device__ __forceinline__ unsigned xb_ld(unsigned* p)              { return __hip_atomic_load(p, __ATOMIC_RELAXED, __HIP_MEMORY_SCOPE_AGENT); }
; __device__ __forceinline__ unsigned xb_add(unsigned* p, unsigned v) { return __hip_atomic_fetch_add(p, v, __ATOMIC_RELAXED, __HIP_MEMORY_SCOPE_AGENT); }
; #define XB_SPIN(cond, bar) do { unsigned _sp = 0; while (cond) { __builtin_amdgcn_s_sleep(1); \
;     if ((++_sp & 255u) == 0u) { if (xb_ld(&(bar)[XB_TMO])) break; if (_sp > XB_SPIN_CAP) { atomicAdd(&(bar)[XB_TMO], 1u); break; } } } } while (0)
; __device__ __forceinline__ void xcd_barrier(const XcdBarrier& b) {
;     asm volatile("s_waitcnt vmcnt(0)" ::: "memory");
;     __syncthreads();
;     if (threadIdx.x == 0) {
;         unsigned* bar = b.bar;
;         __builtin_amdgcn_s_waitcnt(0);
;         unsigned nloc = b.st[0], nx = b.st[1];
;         if (nloc == 0u) { xcd_barrier_complete(bar, b.x, nloc, nx); b.st[0] = nloc; b.st[1] = nx; }
;         const unsigned old = xb_add(&bar[XB_XSUB(b.x)], 1u);
;         const unsigned gen = old / nloc;
;         if (old + 1u == (gen + 1u) * nloc) {
;             __builtin_amdgcn_fence(__ATOMIC_RELEASE, "agent");
;             asm volatile("s_waitcnt vmcnt(0)" ::: "memory");
;             const unsigned og = xb_add(&bar[XB_TOP], 1u);
;             const unsigned tg = og / nx;
;             if (og + 1u == (tg + 1u) * nx) xb_add(&bar[XB_TOPGEN], 1u);
;             else XB_SPIN(xb_ld(&bar[XB_TOPGEN]) == tg, bar);
;             __builtin_amdgcn_fence(__ATOMIC_ACQUIRE, "agent");
;             xb_add(&bar[XB_XGEN(b.x)], 1u);
;             asm volatile("s_waitcnt vmcnt(0)" ::: "memory");
;         } else {
;             XB_SPIN(xb_ld(&bar[XB_XGEN(b.x)]) == gen, bar);
;             __builtin_amdgcn_fence(__ATOMIC_ACQUIRE, "agent");
;             asm volatile("s_waitcnt vmcnt(0)" ::: "memory");
;         }
;     }
;     __syncthreads();
; }
.LBB0_336:
	s_cmp_gt_i32 s31, 3
	s_cselect_b64 s[0:1], -1, 0
	s_and_b64 s[4:5], s[12:13], s[0:1]
	s_andn2_b64 vcc, exec, s[4:5]
	s_cbranch_vccnz .LBB0_386
	s_waitcnt vmcnt(0)
	s_barrier
	v_cmp_eq_u32_e32 vcc, 0, v195
	s_and_saveexec_b64 s[4:5], vcc
	s_cbranch_execz .Ltb386_done
	s_cmp_eq_u32 s99, 1
	s_cbranch_scc1 .Ltb386_fast
	buffer_wbl2 sc1
	s_waitcnt vmcnt(0)

; template <bool SRC_F32, int R> __device__ __forceinline__ void ew_load(EwSet<SRC_F32, R>& S, int rb, const float* hsrc32, const bf16* hsrcb, const bf16* f, const float* part, int lane) {
; #pragma unroll
;     for (int i = 0; i < R; ++i) S.p[i] = (lane < 16) ? part[(size_t)(rb + i) * 16 + lane] : 0.f;
; #pragma unroll
;     for (int i = 0; i < R; ++i)
; #pragma unroll
;         for (int j = 0; j < 4; ++j) {
;             S.fw[i][j] = ((const v2u*)(f + (size_t)(rb + i) * D) + lane)[64 * j];
;             if constexpr (SRC_F32) S.h32[i][j] = __builtin_nontemporal_load((const f32x4*)(hsrc32 + (size_t)(rb + i) * D) + lane + 64 * j);
;             else S.hb[i][j] = ((const v2u*)(hsrcb + (size_t)(rb + i) * D) + lane)[64 * j];
;         }
; }
; template <bool SRC_F32, bool FINAL, int R> __device__ __forceinline__ void ew_compute(const EwSet<SRC_F32, R>& S, int rb, const f32x4 (&g)[4], bf16* hb_out, float* out32, float scale, float* rs_out, int lane) {
; #pragma unroll
;     for (int i = 0; i < R; ++i) {
;         float q = S.p[i];
;         q += __shfl_xor(q, 1); q += __shfl_xor(q, 2); q += __shfl_xor(q, 4); q += __shfl_xor(q, 8);
;         const float ss = __shfl(q, 0);
;         const float rs = scale / sqrtf(ss * (1.f / D) + EPS);
; template <bool SRC_F32, bool FINAL> __device__ __forceinline__ void ew_phase(const float* hsrc32, const bf16* hsrcb, bf16* hb_out, float* out32, const bf16* f, const float* part, const float* gpost, float scale, float* rs_out, int gw, int NGW, int lane) {
;     constexpr int R = SRC_F32 ? 2 : 4;
;     f32x4 g[4];
; #pragma unroll
;     for (int j = 0; j < 4; ++j) g[j] = ((const f32x4*)gpost + lane)[64 * j];
;     const int step = NGW * R;
;     EwSet<SRC_F32, R> A, B;
;     int rb = gw * R;
;     if (rb < M) ew_load<SRC_F32, R>(A, rb, hsrc32, hsrcb, f, part, lane);
.LBB0_386:
	s_cmp_lt_i32 s30, 4
	s_cselect_b64 s[4:5], -1, 0
	s_and_b64 s[12:13], s[4:5], s[0:1]
	s_andn2_b64 vcc, exec, s[12:13]
	s_cbranch_vccnz .LBB0_432
	s_waitcnt vmcnt(0) lgkmcnt(0)
	s_add_u32 s22, s84, 0xffffff10
	s_addc_u32 s23, s85, -1
	s_load_dwordx2 s[26:27], s[22:23], 0x30
	s_add_u32 s0, s28, 0x5000000
	s_addc_u32 s1, s29, 0
	s_add_u32 s4, s28, 0x15000000
	s_addc_u32 s5, s29, 0
	s_add_u32 s6, s28, 0x3700000
	s_addc_u32 s7, s29, 0
	s_add_u32 s14, s28, 0x3910000
	s_addc_u32 s15, s29, 0
	v_and_b32_e32 v0, 63, v195
	v_lshlrev_b32_e32 v1, 5, v0
	s_waitcnt lgkmcnt(0)
	global_load_dwordx4 v[2:5], v1, s[26:27]
	global_load_dwordx4 v[6:9], v1, s[26:27] offset:16
	global_load_dwordx4 v[10:13], v1, s[26:27] offset:2048
	global_load_dwordx4 v[14:17], v1, s[26:27] offset:2064
	s_and_b32 s26, s2, 7
	s_lshl_b32 s26, s26, 4
	s_bfe_u32 s27, s2, 0x30003
	s_add_u32 s26, s26, s27
	s_lshl_b32 s26, s26, 8
	s_lshr_b32 s27, s2, 6
	s_lshl_b32 s27, s27, 6
	s_add_u32 s26, s26, s27
	v_readfirstlane_b32 s27, v195
	s_lshr_b32 s27, s27, 6
	s_lshl_b32 s27, s27, 3
	s_add_u32 s26, s26, s27
	s_add_u32 s27, s26, 0
	s_lshl_b32 s22, s27, 11
	v_lshl_add_u32 v18, v0, 4, s22
	v_add_u32_e32 v19, 0x1000, v18
	s_lshl_b32 s22, s27, 6
	v_lshl_add_u32 v20, v0, 2, s22
	s_lshl_b32 s22, s27, 2
	v_lshl_add_u32 v21, v0, 2, s22
	global_load_dwordx4 v[32:35], v18, s[0:1]
	global_load_dwordx4 v[36:39], v18, s[0:1] offset:1024
	global_load_dwordx4 v[64:67], v18, s[4:5]
	global_load_dwordx4 v[68:71], v18, s[4:5] offset:1024
	global_load_dwordx4 v[40:43], v18, s[0:1] offset:2048
	global_load_dwordx4 v[44:47], v18, s[0:1] offset:3072
	global_load_dwordx4 v[72:75], v18, s[4:5] offset:2048
	global_load_dwordx4 v[76:79], v18, s[4:5] offset:3072
	global_load_dwordx4 v[48:51], v19, s[0:1]
	global_load_dwordx4 v[52:55], v19, s[0:1] offset:1024
	global_load_dwordx4 v[80:83], v19, s[4:5]
	global_load_dwordx4 v[84:87], v19, s[4:5] offset:1024
	global_load_dwordx4 v[56:59], v19, s[0:1] offset:2048
	global_load_dwordx4 v[60:63], v19, s[0:1] offset:3072
	global_load_dwordx4 v[88:91], v19, s[4:5] offset:2048
	global_load_dwordx4 v[92:95], v19, s[4:5] offset:3072
	global_load_dword v96, v20, s[6:7]
	s_add_u32 s27, s26, 4
	s_lshl_b32 s22, s27, 11
	v_lshl_add_u32 v23, v0, 4, s22
	v_add_u32_e32 v24, 0x1000, v23
	s_lshl_b32 s22, s27, 6
	v_lshl_add_u32 v25, v0, 2, s22
	s_lshl_b32 s22, s27, 2
	v_lshl_add_u32 v26, v0, 2, s22
	global_load_dwordx4 v[100:103], v23, s[0:1]
	global_load_dwordx4 v[104:107], v23, s[0:1] offset:1024
	global_load_dwordx4 v[132:135], v23, s[4:5]
	global_load_dwordx4 v[136:139], v23, s[4:5] offset:1024
	global_load_dwordx4 v[108:111], v23, s[0:1] offset:2048
	global_load_dwordx4 v[112:115], v23, s[0:1] offset:3072
	global_load_dwordx4 v[140:143], v23, s[4:5] offset:2048
	global_load_dwordx4 v[144:147], v23, s[4:5] offset:3072
	global_load_dwordx4 v[116:119], v24, s[0:1]
	global_load_dwordx4 v[120:123], v24, s[0:1] offset:1024
	global_load_dwordx4 v[148:151], v24, s[4:5]
	global_load_dwordx4 v[152:155], v24, s[4:5] offset:1024
	global_load_dwordx4 v[124:127], v24, s[0:1] offset:2048
	global_load_dwordx4 v[128:131], v24, s[0:1] offset:3072
	global_load_dwordx4 v[156:159], v24, s[4:5] offset:2048
	global_load_dwordx4 v[160:163], v24, s[4:5] offset:3072
	global_load_dword v164, v25, s[6:7]
	s_waitcnt vmcnt(17)
	v_add_f32_dpp v96, v96, v96 quad_perm:[1,0,3,2] row_mask:0xf bank_mask:0xf
	s_nop 1
	v_add_f32_dpp v96, v96, v96 quad_perm:[2,3,0,1] row_mask:0xf bank_mask:0xf
	s_nop 1
	v_add_f32_dpp v96, v96, v96 row_half_mirror row_mask:0xf bank_mask:0xf
	s_nop 1
	v_add_f32_dpp v96, v96, v96 row_mirror row_mask:0xf bank_mask:0xf
	s_nop 1
	v_mul_f32_e32 v96, 0x3a800000, v96
	v_add_f32_e32 v96, 0x358637bd, v96
	v_rsq_f32_e32 v96, v96
	s_nop 0
	v_mul_f32_e32 v96, 0x3f000000, v96
	s_nop 0
	v_readlane_b32 s3, v96, 0
	v_readlane_b32 s24, v96, 16
	v_readlane_b32 s98, v96, 32
	v_readlane_b32 s101, v96, 48
	s_nop 1
	v_mov_b32_e32 v184, 0
	v_mov_b32_e32 v185, 0
	v_mov_b32_e32 v186, 0
	v_mov_b32_e32 v187, 0
	v_lshlrev_b32_e32 v168, 16, v32
	v_and_b32_e32 v169, 0xffff0000, v32
	v_lshlrev_b32_e32 v170, 16, v64
	v_and_b32_e32 v171, 0xffff0000, v64
	v_mul_f32_e32 v170, s3, v170
	v_mul_f32_e32 v171, s3, v171
	v_fma_f32 v168, v170, v2, v168
	v_fma_f32 v169, v171, v3, v169
	v_fma_f32 v184, v168, v168, v184
	v_fma_f32 v184, v169, v169, v184
	v_cvt_pk_bf16_f32 v32, v168, v169
	v_lshlrev_b32_e32 v168, 16, v33
	v_and_b32_e32 v169, 0xffff0000, v33
	v_lshlrev_b32_e32 v170, 16, v65
	v_and_b32_e32 v171, 0xffff0000, v65
	v_mul_f32_e32 v170, s3, v170
	v_mul_f32_e32 v171, s3, v171
	v_fma_f32 v168, v170, v4, v168
	v_fma_f32 v169, v171, v5, v169
	v_fma_f32 v184, v168, v168, v184
	v_fma_f32 v184, v169, v169, v184
	v_cvt_pk_bf16_f32 v33, v168, v169
	v_lshlrev_b32_e32 v168, 16, v34
	v_and_b32_e32 v169, 0xffff0000, v34
	v_lshlrev_b32_e32 v170, 16, v66
	v_and_b32_e32 v171, 0xffff0000, v66
	v_mul_f32_e32 v170, s3, v170
	v_mul_f32_e32 v171, s3, v171
	v_fma_f32 v168, v170, v6, v168
	v_fma_f32 v169, v171, v7, v169
	v_fma_f32 v184, v168, v168, v184
	v_fma_f32 v184, v169, v169, v184
	v_cvt_pk_bf16_f32 v34, v168, v169
	v_lshlrev_b32_e32 v168, 16, v35
	v_and_b32_e32 v169, 0xffff0000, v35
	v_lshlrev_b32_e32 v170, 16, v67
	v_and_b32_e32 v171, 0xffff0000, v67
	v_mul_f32_e32 v170, s3, v170
	v_mul_f32_e32 v171, s3, v171
	v_fma_f32 v168, v170, v8, v168
	v_fma_f32 v169, v171, v9, v169
	v_fma_f32 v184, v168, v168, v184
	v_fma_f32 v184, v169, v169, v184
	v_cvt_pk_bf16_f32 v35, v168, v169
	v_lshlrev_b32_e32 v168, 16, v36
	v_and_b32_e32 v169, 0xffff0000, v36
	v_lshlrev_b32_e32 v170, 16, v68
	v_and_b32_e32 v171, 0xffff0000, v68
	v_mul_f32_e32 v170, s3, v170
; __device__ __forceinline__ float bf_lo(unsigned w) { return __uint_as_float(w << 16); }
; __device__ __forceinline__ float bf_hi(unsigned w) { return __uint_as_float(w & 0xffff0000u); }
; __device__ __forceinline__ unsigned pk2(float lo, float hi) { bf16x2_t r = __builtin_convertvector((f32x2_t){lo, hi}, bf16x2_t); return __builtin_bit_cast(unsigned, r); }
; template <bool SRC_F32, bool FINAL, int R> __device__ __forceinline__ void ew_compute(const EwSet<SRC_F32, R>& S, int rb, const f32x4 (&g)[4], bf16* hb_out, float* out32, float scale, float* rs_out, int lane) {
;     ...
; #pragma unroll
;         for (int j = 0; j < 4; ++j) {
;             f32x4 h;
;             if constexpr (SRC_F32) h = S.h32[i][j];
;             else { const v2u hw = S.hb[i][j]; h.x = bf_lo(hw.x); h.y = bf_hi(hw.x); h.z = bf_lo(hw.y); h.w = bf_hi(hw.y); }
;             const v2u fw = S.fw[i][j];
;             f32x4 v; v.x = h.x + bf_lo(fw.x) * rs * g[j].x; v.y = h.y + bf_hi(fw.x) * rs * g[j].y; v.z = h.z + bf_lo(fw.y) * rs * g[j].z; v.w = h.w + bf_hi(fw.y) * rs * g[j].w;
;             if (FINAL) __builtin_nontemporal_store(v, (f32x4*)(out32 + (size_t)(rb + i) * D) + lane + 64 * j);
;             else { v2u o; o.x = pk2(v.x, v.y); o.y = pk2(v.z, v.w); ((v2u*)(hb_out + (size_t)(rb + i) * D) + lane)[64 * j] = o; s2 += (v.x * v.x + v.y * v.y) + (v.z * v.z + v.w * v.w); }
	v_mul_f32_e32 v171, s3, v171
	v_fma_f32 v168, v170, v10, v168
	v_fma_f32 v169, v171, v11, v169
	v_fma_f32 v184, v168, v168, v184
	v_fma_f32 v184, v169, v169, v184
	v_cvt_pk_bf16_f32 v36, v168, v169
	v_lshlrev_b32_e32 v168, 16, v37
	v_and_b32_e32 v169, 0xffff0000, v37
	v_lshlrev_b32_e32 v170, 16, v69
	v_and_b32_e32 v171, 0xffff0000, v69
	v_mul_f32_e32 v170, s3, v170
	v_mul_f32_e32 v171, s3, v171
	v_fma_f32 v168, v170, v12, v168
	v_fma_f32 v169, v171, v13, v169
	v_fma_f32 v184, v168, v168, v184
	v_fma_f32 v184, v169, v169, v184
	v_cvt_pk_bf16_f32 v37, v168, v169
	v_lshlrev_b32_e32 v168, 16, v38
	v_and_b32_e32 v169, 0xffff0000, v38
	v_lshlrev_b32_e32 v170, 16, v70
	v_and_b32_e32 v171, 0xffff0000, v70
	v_mul_f32_e32 v170, s3, v170
	v_mul_f32_e32 v171, s3, v171
	v_fma_f32 v168, v170, v14, v168
	v_fma_f32 v169, v171, v15, v169
	v_fma_f32 v184, v168, v168, v184
	v_fma_f32 v184, v169, v169, v184
	v_cvt_pk_bf16_f32 v38, v168, v169
	v_lshlrev_b32_e32 v168, 16, v39
	v_and_b32_e32 v169, 0xffff0000, v39
	v_lshlrev_b32_e32 v170, 16, v71
	v_and_b32_e32 v171, 0xffff0000, v71
	v_mul_f32_e32 v170, s3, v170
	v_mul_f32_e32 v171, s3, v171
	v_fma_f32 v168, v170, v16, v168
	v_fma_f32 v169, v171, v17, v169
	v_fma_f32 v184, v168, v168, v184
	v_fma_f32 v184, v169, v169, v184
	v_cvt_pk_bf16_f32 v39, v168, v169
	global_store_dwordx4 v18, v[32:35], s[0:1]
	global_store_dwordx4 v18, v[36:39], s[0:1] offset:1024
	v_lshlrev_b32_e32 v168, 16, v40
	v_and_b32_e32 v169, 0xffff0000, v40
	v_lshlrev_b32_e32 v170, 16, v72
	v_and_b32_e32 v171, 0xffff0000, v72
	v_mul_f32_e32 v170, s24, v170
	v_mul_f32_e32 v171, s24, v171
	v_fma_f32 v168, v170, v2, v168
	v_fma_f32 v169, v171, v3, v169
	v_fma_f32 v185, v168, v168, v185
	v_fma_f32 v185, v169, v169, v185
	v_cvt_pk_bf16_f32 v40, v168, v169
	v_lshlrev_b32_e32 v168, 16, v41
	v_and_b32_e32 v169, 0xffff0000, v41
	v_lshlrev_b32_e32 v170, 16, v73
	v_and_b32_e32 v171, 0xffff0000, v73
	v_mul_f32_e32 v170, s24, v170
	v_mul_f32_e32 v171, s24, v171
	v_fma_f32 v168, v170, v4, v168
	v_fma_f32 v169, v171, v5, v169
	v_fma_f32 v185, v168, v168, v185
	v_fma_f32 v185, v169, v169, v185
	v_cvt_pk_bf16_f32 v41, v168, v169
	v_lshlrev_b32_e32 v168, 16, v42
	v_and_b32_e32 v169, 0xffff0000, v42
	v_lshlrev_b32_e32 v170, 16, v74
	v_and_b32_e32 v171, 0xffff0000, v74
	v_mul_f32_e32 v170, s24, v170
	v_mul_f32_e32 v171, s24, v171
	v_fma_f32 v168, v170, v6, v168
	v_fma_f32 v169, v171, v7, v169
	v_fma_f32 v185, v168, v168, v185
	v_fma_f32 v185, v169, v169, v185
	v_cvt_pk_bf16_f32 v42, v168, v169
	v_lshlrev_b32_e32 v168, 16, v43
	v_and_b32_e32 v169, 0xffff0000, v43
	v_lshlrev_b32_e32 v170, 16, v75
	v_and_b32_e32 v171, 0xffff0000, v75
	v_mul_f32_e32 v170, s24, v170
	v_mul_f32_e32 v171, s24, v171
	v_fma_f32 v168, v170, v8, v168
	v_fma_f32 v169, v171, v9, v169
	v_fma_f32 v185, v168, v168, v185
	v_fma_f32 v185, v169, v169, v185
	v_cvt_pk_bf16_f32 v43, v168, v169
	v_lshlrev_b32_e32 v168, 16, v44
	v_and_b32_e32 v169, 0xffff0000, v44
	v_lshlrev_b32_e32 v170, 16, v76
	v_and_b32_e32 v171, 0xffff0000, v76
	v_mul_f32_e32 v170, s24, v170
	v_mul_f32_e32 v171, s24, v171
	v_fma_f32 v168, v170, v10, v168
	v_fma_f32 v169, v171, v11, v169
	v_fma_f32 v185, v168, v168, v185
	v_fma_f32 v185, v169, v169, v185
	v_cvt_pk_bf16_f32 v44, v168, v169
	v_lshlrev_b32_e32 v168, 16, v45
	v_and_b32_e32 v169, 0xffff0000, v45
	v_lshlrev_b32_e32 v170, 16, v77
	v_and_b32_e32 v171, 0xffff0000, v77
	v_mul_f32_e32 v170, s24, v170
	v_mul_f32_e32 v171, s24, v171
	v_fma_f32 v168, v170, v12, v168
	v_fma_f32 v169, v171, v13, v169
	v_fma_f32 v185, v168, v168, v185
	v_fma_f32 v185, v169, v169, v185
	v_cvt_pk_bf16_f32 v45, v168, v169
	v_lshlrev_b32_e32 v168, 16, v46
	v_and_b32_e32 v169, 0xffff0000, v46
	v_lshlrev_b32_e32 v170, 16, v78
	v_and_b32_e32 v171, 0xffff0000, v78
	v_mul_f32_e32 v170, s24, v170
	v_mul_f32_e32 v171, s24, v171
	v_fma_f32 v168, v170, v14, v168
	v_fma_f32 v169, v171, v15, v169
	v_fma_f32 v185, v168, v168, v185
	v_fma_f32 v185, v169, v169, v185
	v_cvt_pk_bf16_f32 v46, v168, v169
	v_lshlrev_b32_e32 v168, 16, v47
	v_and_b32_e32 v169, 0xffff0000, v47
	v_lshlrev_b32_e32 v170, 16, v79
	v_and_b32_e32 v171, 0xffff0000, v79
	v_mul_f32_e32 v170, s24, v170
	v_mul_f32_e32 v171, s24, v171
	v_fma_f32 v168, v170, v16, v168
	v_fma_f32 v169, v171, v17, v169
	v_fma_f32 v185, v168, v168, v185
	v_fma_f32 v185, v169, v169, v185
	v_cvt_pk_bf16_f32 v47, v168, v169
	global_store_dwordx4 v18, v[40:43], s[0:1] offset:2048
	global_store_dwordx4 v18, v[44:47], s[0:1] offset:3072
	v_lshlrev_b32_e32 v168, 16, v48
	v_and_b32_e32 v169, 0xffff0000, v48
	v_lshlrev_b32_e32 v170, 16, v80
	v_and_b32_e32 v171, 0xffff0000, v80
	v_mul_f32_e32 v170, s98, v170
	v_mul_f32_e32 v171, s98, v171
	v_fma_f32 v168, v170, v2, v168
	v_fma_f32 v169, v171, v3, v169
	v_fma_f32 v186, v168, v168, v186
	v_fma_f32 v186, v169, v169, v186
	v_cvt_pk_bf16_f32 v48, v168, v169
	v_lshlrev_b32_e32 v168, 16, v49
	v_and_b32_e32 v169, 0xffff0000, v49
	v_lshlrev_b32_e32 v170, 16, v81
	v_and_b32_e32 v171, 0xffff0000, v81
	v_mul_f32_e32 v170, s98, v170
	v_mul_f32_e32 v171, s98, v171
	v_fma_f32 v168, v170, v4, v168
	v_fma_f32 v169, v171, v5, v169
	v_fma_f32 v186, v168, v168, v186
	v_fma_f32 v186, v169, v169, v186
	v_cvt_pk_bf16_f32 v49, v168, v169
	v_lshlrev_b32_e32 v168, 16, v50
	v_and_b32_e32 v169, 0xffff0000, v50
	v_lshlrev_b32_e32 v170, 16, v82
	v_and_b32_e32 v171, 0xffff0000, v82
	v_mul_f32_e32 v170, s98, v170
	v_mul_f32_e32 v171, s98, v171
	v_fma_f32 v168, v170, v6, v168
	v_fma_f32 v169, v171, v7, v169
	v_fma_f32 v186, v168, v168, v186
	v_fma_f32 v186, v169, v169, v186
	v_cvt_pk_bf16_f32 v50, v168, v169
	v_lshlrev_b32_e32 v168, 16, v51
	v_and_b32_e32 v169, 0xffff0000, v51
; __device__ __forceinline__ float bf_lo(unsigned w) { return __uint_as_float(w << 16); }
; __device__ __forceinline__ float bf_hi(unsigned w) { return __uint_as_float(w & 0xffff0000u); }
; __device__ __forceinline__ unsigned pk2(float lo, float hi) { bf16x2_t r = __builtin_convertvector((f32x2_t){lo, hi}, bf16x2_t); return __builtin_bit_cast(unsigned, r); }
; template <bool SRC_F32, bool FINAL, int R> __device__ __forceinline__ void ew_compute(const EwSet<SRC_F32, R>& S, int rb, const f32x4 (&g)[4], bf16* hb_out, float* out32, float scale, float* rs_out, int lane) {
;     ...
; #pragma unroll
;         for (int j = 0; j < 4; ++j) {
;             f32x4 h;
;             if constexpr (SRC_F32) h = S.h32[i][j];
;             else { const v2u hw = S.hb[i][j]; h.x = bf_lo(hw.x); h.y = bf_hi(hw.x); h.z = bf_lo(hw.y); h.w = bf_hi(hw.y); }
;             const v2u fw = S.fw[i][j];
;             f32x4 v; v.x = h.x + bf_lo(fw.x) * rs * g[j].x; v.y = h.y + bf_hi(fw.x) * rs * g[j].y; v.z = h.z + bf_lo(fw.y) * rs * g[j].z; v.w = h.w + bf_hi(fw.y) * rs * g[j].w;
;             if (FINAL) __builtin_nontemporal_store(v, (f32x4*)(out32 + (size_t)(rb + i) * D) + lane + 64 * j);
;             else { v2u o; o.x = pk2(v.x, v.y); o.y = pk2(v.z, v.w); ((v2u*)(hb_out + (size_t)(rb + i) * D) + lane)[64 * j] = o; s2 += (v.x * v.x + v.y * v.y) + (v.z * v.z + v.w * v.w); }
;         }
;         if (!FINAL) { const float tot = wave_sum(s2); if (lane == 0) rs_out[rb + i] = 1.0f / sqrtf(tot * (1.f / D) + EPS); }
	v_lshlrev_b32_e32 v170, 16, v83
	v_and_b32_e32 v171, 0xffff0000, v83
	v_mul_f32_e32 v170, s98, v170
	v_mul_f32_e32 v171, s98, v171
	v_fma_f32 v168, v170, v8, v168
	v_fma_f32 v169, v171, v9, v169
	v_fma_f32 v186, v168, v168, v186
	v_fma_f32 v186, v169, v169, v186
	v_cvt_pk_bf16_f32 v51, v168, v169
	v_lshlrev_b32_e32 v168, 16, v52
	v_and_b32_e32 v169, 0xffff0000, v52
	v_lshlrev_b32_e32 v170, 16, v84
	v_and_b32_e32 v171, 0xffff0000, v84
	v_mul_f32_e32 v170, s98, v170
	v_mul_f32_e32 v171, s98, v171
	v_fma_f32 v168, v170, v10, v168
	v_fma_f32 v169, v171, v11, v169
	v_fma_f32 v186, v168, v168, v186
	v_fma_f32 v186, v169, v169, v186
	v_cvt_pk_bf16_f32 v52, v168, v169
	v_lshlrev_b32_e32 v168, 16, v53
	v_and_b32_e32 v169, 0xffff0000, v53
	v_lshlrev_b32_e32 v170, 16, v85
	v_and_b32_e32 v171, 0xffff0000, v85
	v_mul_f32_e32 v170, s98, v170
	v_mul_f32_e32 v171, s98, v171
	v_fma_f32 v168, v170, v12, v168
	v_fma_f32 v169, v171, v13, v169
	v_fma_f32 v186, v168, v168, v186
	v_fma_f32 v186, v169, v169, v186
	v_cvt_pk_bf16_f32 v53, v168, v169
	v_lshlrev_b32_e32 v168, 16, v54
	v_and_b32_e32 v169, 0xffff0000, v54
	v_lshlrev_b32_e32 v170, 16, v86
	v_and_b32_e32 v171, 0xffff0000, v86
	v_mul_f32_e32 v170, s98, v170
	v_mul_f32_e32 v171, s98, v171
	v_fma_f32 v168, v170, v14, v168
	v_fma_f32 v169, v171, v15, v169
	v_fma_f32 v186, v168, v168, v186
	v_fma_f32 v186, v169, v169, v186
	v_cvt_pk_bf16_f32 v54, v168, v169
	v_lshlrev_b32_e32 v168, 16, v55
	v_and_b32_e32 v169, 0xffff0000, v55
	v_lshlrev_b32_e32 v170, 16, v87
	v_and_b32_e32 v171, 0xffff0000, v87
	v_mul_f32_e32 v170, s98, v170
	v_mul_f32_e32 v171, s98, v171
	v_fma_f32 v168, v170, v16, v168
	v_fma_f32 v169, v171, v17, v169
	v_fma_f32 v186, v168, v168, v186
	v_fma_f32 v186, v169, v169, v186
	v_cvt_pk_bf16_f32 v55, v168, v169
	global_store_dwordx4 v19, v[48:51], s[0:1]
	global_store_dwordx4 v19, v[52:55], s[0:1] offset:1024
	v_lshlrev_b32_e32 v168, 16, v56
	v_and_b32_e32 v169, 0xffff0000, v56
	v_lshlrev_b32_e32 v170, 16, v88
	v_and_b32_e32 v171, 0xffff0000, v88
	v_mul_f32_e32 v170, s101, v170
	v_mul_f32_e32 v171, s101, v171
	v_fma_f32 v168, v170, v2, v168
	v_fma_f32 v169, v171, v3, v169
	v_fma_f32 v187, v168, v168, v187
	v_fma_f32 v187, v169, v169, v187
	v_cvt_pk_bf16_f32 v56, v168, v169
	v_lshlrev_b32_e32 v168, 16, v57
	v_and_b32_e32 v169, 0xffff0000, v57
	v_lshlrev_b32_e32 v170, 16, v89
	v_and_b32_e32 v171, 0xffff0000, v89
	v_mul_f32_e32 v170, s101, v170
	v_mul_f32_e32 v171, s101, v171
	v_fma_f32 v168, v170, v4, v168
	v_fma_f32 v169, v171, v5, v169
	v_fma_f32 v187, v168, v168, v187
	v_fma_f32 v187, v169, v169, v187
	v_cvt_pk_bf16_f32 v57, v168, v169
	v_lshlrev_b32_e32 v168, 16, v58
	v_and_b32_e32 v169, 0xffff0000, v58
	v_lshlrev_b32_e32 v170, 16, v90
	v_and_b32_e32 v171, 0xffff0000, v90
	v_mul_f32_e32 v170, s101, v170
	v_mul_f32_e32 v171, s101, v171
	v_fma_f32 v168, v170, v6, v168
	v_fma_f32 v169, v171, v7, v169
	v_fma_f32 v187, v168, v168, v187
	v_fma_f32 v187, v169, v169, v187
	v_cvt_pk_bf16_f32 v58, v168, v169
	v_lshlrev_b32_e32 v168, 16, v59
	v_and_b32_e32 v169, 0xffff0000, v59
	v_lshlrev_b32_e32 v170, 16, v91
	v_and_b32_e32 v171, 0xffff0000, v91
	v_mul_f32_e32 v170, s101, v170
	v_mul_f32_e32 v171, s101, v171
	v_fma_f32 v168, v170, v8, v168
	v_fma_f32 v169, v171, v9, v169
	v_fma_f32 v187, v168, v168, v187
	v_fma_f32 v187, v169, v169, v187
	v_cvt_pk_bf16_f32 v59, v168, v169
	v_lshlrev_b32_e32 v168, 16, v60
	v_and_b32_e32 v169, 0xffff0000, v60
	v_lshlrev_b32_e32 v170, 16, v92
	v_and_b32_e32 v171, 0xffff0000, v92
	v_mul_f32_e32 v170, s101, v170
	v_mul_f32_e32 v171, s101, v171
	v_fma_f32 v168, v170, v10, v168
	v_fma_f32 v169, v171, v11, v169
	v_fma_f32 v187, v168, v168, v187
	v_fma_f32 v187, v169, v169, v187
	v_cvt_pk_bf16_f32 v60, v168, v169
	v_lshlrev_b32_e32 v168, 16, v61
	v_and_b32_e32 v169, 0xffff0000, v61
	v_lshlrev_b32_e32 v170, 16, v93
	v_and_b32_e32 v171, 0xffff0000, v93
	v_mul_f32_e32 v170, s101, v170
	v_mul_f32_e32 v171, s101, v171
	v_fma_f32 v168, v170, v12, v168
	v_fma_f32 v169, v171, v13, v169
	v_fma_f32 v187, v168, v168, v187
	v_fma_f32 v187, v169, v169, v187
	v_cvt_pk_bf16_f32 v61, v168, v169
	v_lshlrev_b32_e32 v168, 16, v62
	v_and_b32_e32 v169, 0xffff0000, v62
	v_lshlrev_b32_e32 v170, 16, v94
	v_and_b32_e32 v171, 0xffff0000, v94
	v_mul_f32_e32 v170, s101, v170
	v_mul_f32_e32 v171, s101, v171
	v_fma_f32 v168, v170, v14, v168
	v_fma_f32 v169, v171, v15, v169
	v_fma_f32 v187, v168, v168, v187
	v_fma_f32 v187, v169, v169, v187
	v_cvt_pk_bf16_f32 v62, v168, v169
	v_lshlrev_b32_e32 v168, 16, v63
	v_and_b32_e32 v169, 0xffff0000, v63
	v_lshlrev_b32_e32 v170, 16, v95
	v_and_b32_e32 v171, 0xffff0000, v95
	v_mul_f32_e32 v170, s101, v170
	v_mul_f32_e32 v171, s101, v171
	v_fma_f32 v168, v170, v16, v168
	v_fma_f32 v169, v171, v17, v169
	v_fma_f32 v187, v168, v168, v187
	v_fma_f32 v187, v169, v169, v187
	v_cvt_pk_bf16_f32 v63, v168, v169
	global_store_dwordx4 v19, v[56:59], s[0:1] offset:2048
	global_store_dwordx4 v19, v[60:63], s[0:1] offset:3072
	s_nop 1
	v_add_f32_dpp v184, v184, v184 quad_perm:[1,0,3,2] row_mask:0xf bank_mask:0xf
	v_add_f32_dpp v185, v185, v185 quad_perm:[1,0,3,2] row_mask:0xf bank_mask:0xf
	v_add_f32_dpp v186, v186, v186 quad_perm:[1,0,3,2] row_mask:0xf bank_mask:0xf
	v_add_f32_dpp v187, v187, v187 quad_perm:[1,0,3,2] row_mask:0xf bank_mask:0xf
	v_add_f32_dpp v184, v184, v184 quad_perm:[2,3,0,1] row_mask:0xf bank_mask:0xf
	v_add_f32_dpp v185, v185, v185 quad_perm:[2,3,0,1] row_mask:0xf bank_mask:0xf
	v_add_f32_dpp v186, v186, v186 quad_perm:[2,3,0,1] row_mask:0xf bank_mask:0xf
	v_add_f32_dpp v187, v187, v187 quad_perm:[2,3,0,1] row_mask:0xf bank_mask:0xf
; __device__ __forceinline__ float bf_lo(unsigned w) { return __uint_as_float(w << 16); }
; __device__ __forceinline__ float bf_hi(unsigned w) { return __uint_as_float(w & 0xffff0000u); }
; template <bool SRC_F32, bool FINAL, int R> __device__ __forceinline__ void ew_compute(const EwSet<SRC_F32, R>& S, int rb, const f32x4 (&g)[4], bf16* hb_out, float* out32, float scale, float* rs_out, int lane) {
; #pragma unroll
;     for (int i = 0; i < R; ++i) {
;         float q = S.p[i];
;         q += __shfl_xor(q, 1); q += __shfl_xor(q, 2); q += __shfl_xor(q, 4); q += __shfl_xor(q, 8);
;         const float ss = __shfl(q, 0);
;         const float rs = scale / sqrtf(ss * (1.f / D) + EPS);
;         float s2 = 0.f;
; #pragma unroll
;         for (int j = 0; j < 4; ++j) {
;             f32x4 h;
;             if constexpr (SRC_F32) h = S.h32[i][j];
;             else { const v2u hw = S.hb[i][j]; h.x = bf_lo(hw.x); h.y = bf_hi(hw.x); h.z = bf_lo(hw.y); h.w = bf_hi(hw.y); }
;             const v2u fw = S.fw[i][j];
;             f32x4 v; v.x = h.x + bf_lo(fw.x) * rs * g[j].x; v.y = h.y + bf_hi(fw.x) * rs * g[j].y; v.z = h.z + bf_lo(fw.y) * rs * g[j].z; v.w = h.w + bf_hi(fw.y) * rs * g[j].w;
;             if (FINAL) __builtin_nontemporal_store(v, (f32x4*)(out32 + (size_t)(rb + i) * D) + lane + 64 * j);
;             else { v2u o; o.x = pk2(v.x, v.y); o.y = pk2(v.z, v.w); ((v2u*)(hb_out + (size_t)(rb + i) * D) + lane)[64 * j] = o; s2 += (v.x * v.x + v.y * v.y) + (v.z * v.z + v.w * v.w); }
;         }
;         if (!FINAL) { const float tot = wave_sum(s2); if (lane == 0) rs_out[rb + i] = 1.0f / sqrtf(tot * (1.f / D) + EPS); }
; template <bool SRC_F32, bool FINAL> __device__ __forceinline__ void ew_phase(const float* hsrc32, const bf16* hsrcb, bf16* hb_out, float* out32, const bf16* f, const float* part, const float* gpost, float scale, float* rs_out, int gw, int NGW, int lane) {
;     ...
; #pragma unroll 1
;     for (; rb < M; rb += 2 * step) {
;         const int nb = rb + step, nb2 = nb + step;
;         if (nb < M) ew_load<SRC_F32, R>(B, nb, hsrc32, hsrcb, f, part, lane);
;         ew_compute<SRC_F32, FINAL, R>(A, rb, g, hb_out, out32, scale, rs_out, lane);
;         if (nb2 < M) ew_load<SRC_F32, R>(A, nb2, hsrc32, hsrcb, f, part, lane);
;         if (nb < M) ew_compute<SRC_F32, FINAL, R>(B, nb, g, hb_out, out32, scale, rs_out, lane);
	v_add_f32_dpp v184, v184, v184 row_half_mirror row_mask:0xf bank_mask:0xf
	v_add_f32_dpp v185, v185, v185 row_half_mirror row_mask:0xf bank_mask:0xf
	v_add_f32_dpp v186, v186, v186 row_half_mirror row_mask:0xf bank_mask:0xf
	v_add_f32_dpp v187, v187, v187 row_half_mirror row_mask:0xf bank_mask:0xf
	v_add_f32_dpp v184, v184, v184 row_mirror row_mask:0xf bank_mask:0xf
	v_add_f32_dpp v185, v185, v185 row_mirror row_mask:0xf bank_mask:0xf
	v_add_f32_dpp v186, v186, v186 row_mirror row_mask:0xf bank_mask:0xf
	v_add_f32_dpp v187, v187, v187 row_mirror row_mask:0xf bank_mask:0xf
	v_add_f32_dpp v184, v184, v184 row_bcast:15 row_mask:0xa bank_mask:0xf
	v_add_f32_dpp v185, v185, v185 row_bcast:15 row_mask:0xa bank_mask:0xf
	v_add_f32_dpp v186, v186, v186 row_bcast:15 row_mask:0xa bank_mask:0xf
	v_add_f32_dpp v187, v187, v187 row_bcast:15 row_mask:0xa bank_mask:0xf
	v_add_f32_dpp v184, v184, v184 row_bcast:31 row_mask:0xc bank_mask:0xf
	v_add_f32_dpp v185, v185, v185 row_bcast:31 row_mask:0xc bank_mask:0xf
	v_add_f32_dpp v186, v186, v186 row_bcast:31 row_mask:0xc bank_mask:0xf
	v_add_f32_dpp v187, v187, v187 row_bcast:31 row_mask:0xc bank_mask:0xf
	s_nop 1
	v_readlane_b32 s3, v184, 63
	v_readlane_b32 s24, v185, 63
	v_readlane_b32 s98, v186, 63
	v_readlane_b32 s101, v187, 63
	s_nop 3
	v_writelane_b32 v188, s3, 0
	v_writelane_b32 v188, s24, 1
	v_writelane_b32 v188, s98, 2
	v_writelane_b32 v188, s101, 3
	s_nop 1
	v_mul_f32_e32 v188, 0x3a800000, v188
	v_add_f32_e32 v188, 0x358637bd, v188
	v_rsq_f32_e32 v188, v188
	s_mov_b64 exec, 15
	global_store_dword v21, v188, s[14:15]
	s_mov_b64 exec, -1
	s_add_u32 s27, s26, 2048
	s_lshl_b32 s22, s27, 11
	v_lshl_add_u32 v18, v0, 4, s22
	v_add_u32_e32 v19, 0x1000, v18
	s_lshl_b32 s22, s27, 6
	v_lshl_add_u32 v20, v0, 2, s22
	s_lshl_b32 s22, s27, 2
	v_lshl_add_u32 v21, v0, 2, s22
	global_load_dwordx4 v[32:35], v18, s[0:1]
	global_load_dwordx4 v[36:39], v18, s[0:1] offset:1024
	global_load_dwordx4 v[64:67], v18, s[4:5]
	global_load_dwordx4 v[68:71], v18, s[4:5] offset:1024
	global_load_dwordx4 v[40:43], v18, s[0:1] offset:2048
	global_load_dwordx4 v[44:47], v18, s[0:1] offset:3072
	global_load_dwordx4 v[72:75], v18, s[4:5] offset:2048
	global_load_dwordx4 v[76:79], v18, s[4:5] offset:3072
	global_load_dwordx4 v[48:51], v19, s[0:1]
	global_load_dwordx4 v[52:55], v19, s[0:1] offset:1024
	global_load_dwordx4 v[80:83], v19, s[4:5]
	global_load_dwordx4 v[84:87], v19, s[4:5] offset:1024
	global_load_dwordx4 v[56:59], v19, s[0:1] offset:2048
	global_load_dwordx4 v[60:63], v19, s[0:1] offset:3072
	global_load_dwordx4 v[88:91], v19, s[4:5] offset:2048
	global_load_dwordx4 v[92:95], v19, s[4:5] offset:3072
	global_load_dword v96, v20, s[6:7]
	s_waitcnt vmcnt(26)
	v_add_f32_dpp v164, v164, v164 quad_perm:[1,0,3,2] row_mask:0xf bank_mask:0xf
	s_nop 1
	v_add_f32_dpp v164, v164, v164 quad_perm:[2,3,0,1] row_mask:0xf bank_mask:0xf
	s_nop 1
	v_add_f32_dpp v164, v164, v164 row_half_mirror row_mask:0xf bank_mask:0xf
	s_nop 1
	v_add_f32_dpp v164, v164, v164 row_mirror row_mask:0xf bank_mask:0xf
	s_nop 1
	v_mul_f32_e32 v164, 0x3a800000, v164
	v_add_f32_e32 v164, 0x358637bd, v164
	v_rsq_f32_e32 v164, v164
	s_nop 0
	v_mul_f32_e32 v164, 0x3f000000, v164
	s_nop 0
	v_readlane_b32 s3, v164, 0
	v_readlane_b32 s24, v164, 16
	v_readlane_b32 s98, v164, 32
	v_readlane_b32 s101, v164, 48
	s_nop 1
	v_mov_b32_e32 v184, 0
	v_mov_b32_e32 v185, 0
	v_mov_b32_e32 v186, 0
	v_mov_b32_e32 v187, 0
	v_lshlrev_b32_e32 v168, 16, v100
	v_and_b32_e32 v169, 0xffff0000, v100
	v_lshlrev_b32_e32 v170, 16, v132
	v_and_b32_e32 v171, 0xffff0000, v132
	v_mul_f32_e32 v170, s3, v170
	v_mul_f32_e32 v171, s3, v171
	v_fma_f32 v168, v170, v2, v168
	v_fma_f32 v169, v171, v3, v169
	v_fma_f32 v184, v168, v168, v184
	v_fma_f32 v184, v169, v169, v184
	v_cvt_pk_bf16_f32 v100, v168, v169
	v_lshlrev_b32_e32 v168, 16, v101
	v_and_b32_e32 v169, 0xffff0000, v101
	v_lshlrev_b32_e32 v170, 16, v133
	v_and_b32_e32 v171, 0xffff0000, v133
	v_mul_f32_e32 v170, s3, v170
	v_mul_f32_e32 v171, s3, v171
	v_fma_f32 v168, v170, v4, v168
	v_fma_f32 v169, v171, v5, v169
	v_fma_f32 v184, v168, v168, v184
	v_fma_f32 v184, v169, v169, v184
	v_cvt_pk_bf16_f32 v101, v168, v169
	v_lshlrev_b32_e32 v168, 16, v102
	v_and_b32_e32 v169, 0xffff0000, v102
	v_lshlrev_b32_e32 v170, 16, v134
	v_and_b32_e32 v171, 0xffff0000, v134
	v_mul_f32_e32 v170, s3, v170
	v_mul_f32_e32 v171, s3, v171
	v_fma_f32 v168, v170, v6, v168
	v_fma_f32 v169, v171, v7, v169
	v_fma_f32 v184, v168, v168, v184
	v_fma_f32 v184, v169, v169, v184
	v_cvt_pk_bf16_f32 v102, v168, v169
	v_lshlrev_b32_e32 v168, 16, v103
	v_and_b32_e32 v169, 0xffff0000, v103
	v_lshlrev_b32_e32 v170, 16, v135
	v_and_b32_e32 v171, 0xffff0000, v135
	v_mul_f32_e32 v170, s3, v170
	v_mul_f32_e32 v171, s3, v171
	v_fma_f32 v168, v170, v8, v168
	v_fma_f32 v169, v171, v9, v169
	v_fma_f32 v184, v168, v168, v184
	v_fma_f32 v184, v169, v169, v184
	v_cvt_pk_bf16_f32 v103, v168, v169
	v_lshlrev_b32_e32 v168, 16, v104
	v_and_b32_e32 v169, 0xffff0000, v104
	v_lshlrev_b32_e32 v170, 16, v136
	v_and_b32_e32 v171, 0xffff0000, v136
	v_mul_f32_e32 v170, s3, v170
	v_mul_f32_e32 v171, s3, v171
	v_fma_f32 v168, v170, v10, v168
	v_fma_f32 v169, v171, v11, v169
	v_fma_f32 v184, v168, v168, v184
	v_fma_f32 v184, v169, v169, v184
	v_cvt_pk_bf16_f32 v104, v168, v169
	v_lshlrev_b32_e32 v168, 16, v105
	v_and_b32_e32 v169, 0xffff0000, v105
	v_lshlrev_b32_e32 v170, 16, v137
	v_and_b32_e32 v171, 0xffff0000, v137
	v_mul_f32_e32 v170, s3, v170
	v_mul_f32_e32 v171, s3, v171
	v_fma_f32 v168, v170, v12, v168
	v_fma_f32 v169, v171, v13, v169
	v_fma_f32 v184, v168, v168, v184
	v_fma_f32 v184, v169, v169, v184
; __device__ __forceinline__ float bf_lo(unsigned w) { return __uint_as_float(w << 16); }
; __device__ __forceinline__ float bf_hi(unsigned w) { return __uint_as_float(w & 0xffff0000u); }
; __device__ __forceinline__ unsigned pk2(float lo, float hi) { bf16x2_t r = __builtin_convertvector((f32x2_t){lo, hi}, bf16x2_t); return __builtin_bit_cast(unsigned, r); }
; template <bool SRC_F32, bool FINAL, int R> __device__ __forceinline__ void ew_compute(const EwSet<SRC_F32, R>& S, int rb, const f32x4 (&g)[4], bf16* hb_out, float* out32, float scale, float* rs_out, int lane) {
;     ...
; #pragma unroll
;         for (int j = 0; j < 4; ++j) {
;             f32x4 h;
;             if constexpr (SRC_F32) h = S.h32[i][j];
;             else { const v2u hw = S.hb[i][j]; h.x = bf_lo(hw.x); h.y = bf_hi(hw.x); h.z = bf_lo(hw.y); h.w = bf_hi(hw.y); }
;             const v2u fw = S.fw[i][j];
;             f32x4 v; v.x = h.x + bf_lo(fw.x) * rs * g[j].x; v.y = h.y + bf_hi(fw.x) * rs * g[j].y; v.z = h.z + bf_lo(fw.y) * rs * g[j].z; v.w = h.w + bf_hi(fw.y) * rs * g[j].w;
;             if (FINAL) __builtin_nontemporal_store(v, (f32x4*)(out32 + (size_t)(rb + i) * D) + lane + 64 * j);
;             else { v2u o; o.x = pk2(v.x, v.y); o.y = pk2(v.z, v.w); ((v2u*)(hb_out + (size_t)(rb + i) * D) + lane)[64 * j] = o; s2 += (v.x * v.x + v.y * v.y) + (v.z * v.z + v.w * v.w); }
	v_cvt_pk_bf16_f32 v105, v168, v169
	v_lshlrev_b32_e32 v168, 16, v106
	v_and_b32_e32 v169, 0xffff0000, v106
	v_lshlrev_b32_e32 v170, 16, v138
	v_and_b32_e32 v171, 0xffff0000, v138
	v_mul_f32_e32 v170, s3, v170
	v_mul_f32_e32 v171, s3, v171
	v_fma_f32 v168, v170, v14, v168
	v_fma_f32 v169, v171, v15, v169
	v_fma_f32 v184, v168, v168, v184
	v_fma_f32 v184, v169, v169, v184
	v_cvt_pk_bf16_f32 v106, v168, v169
	v_lshlrev_b32_e32 v168, 16, v107
	v_and_b32_e32 v169, 0xffff0000, v107
	v_lshlrev_b32_e32 v170, 16, v139
	v_and_b32_e32 v171, 0xffff0000, v139
	v_mul_f32_e32 v170, s3, v170
	v_mul_f32_e32 v171, s3, v171
	v_fma_f32 v168, v170, v16, v168
	v_fma_f32 v169, v171, v17, v169
	v_fma_f32 v184, v168, v168, v184
	v_fma_f32 v184, v169, v169, v184
	v_cvt_pk_bf16_f32 v107, v168, v169
	global_store_dwordx4 v23, v[100:103], s[0:1]
	global_store_dwordx4 v23, v[104:107], s[0:1] offset:1024
	v_lshlrev_b32_e32 v168, 16, v108
	v_and_b32_e32 v169, 0xffff0000, v108
	v_lshlrev_b32_e32 v170, 16, v140
	v_and_b32_e32 v171, 0xffff0000, v140
	v_mul_f32_e32 v170, s24, v170
	v_mul_f32_e32 v171, s24, v171
	v_fma_f32 v168, v170, v2, v168
	v_fma_f32 v169, v171, v3, v169
	v_fma_f32 v185, v168, v168, v185
	v_fma_f32 v185, v169, v169, v185
	v_cvt_pk_bf16_f32 v108, v168, v169
	v_lshlrev_b32_e32 v168, 16, v109
	v_and_b32_e32 v169, 0xffff0000, v109
	v_lshlrev_b32_e32 v170, 16, v141
	v_and_b32_e32 v171, 0xffff0000, v141
	v_mul_f32_e32 v170, s24, v170
	v_mul_f32_e32 v171, s24, v171
	v_fma_f32 v168, v170, v4, v168
	v_fma_f32 v169, v171, v5, v169
	v_fma_f32 v185, v168, v168, v185
	v_fma_f32 v185, v169, v169, v185
	v_cvt_pk_bf16_f32 v109, v168, v169
	v_lshlrev_b32_e32 v168, 16, v110
	v_and_b32_e32 v169, 0xffff0000, v110
	v_lshlrev_b32_e32 v170, 16, v142
	v_and_b32_e32 v171, 0xffff0000, v142
	v_mul_f32_e32 v170, s24, v170
	v_mul_f32_e32 v171, s24, v171
	v_fma_f32 v168, v170, v6, v168
	v_fma_f32 v169, v171, v7, v169
	v_fma_f32 v185, v168, v168, v185
	v_fma_f32 v185, v169, v169, v185
	v_cvt_pk_bf16_f32 v110, v168, v169
	v_lshlrev_b32_e32 v168, 16, v111
	v_and_b32_e32 v169, 0xffff0000, v111
	v_lshlrev_b32_e32 v170, 16, v143
	v_and_b32_e32 v171, 0xffff0000, v143
	v_mul_f32_e32 v170, s24, v170
	v_mul_f32_e32 v171, s24, v171
	v_fma_f32 v168, v170, v8, v168
	v_fma_f32 v169, v171, v9, v169
	v_fma_f32 v185, v168, v168, v185
	v_fma_f32 v185, v169, v169, v185
	v_cvt_pk_bf16_f32 v111, v168, v169
	v_lshlrev_b32_e32 v168, 16, v112
	v_and_b32_e32 v169, 0xffff0000, v112
	v_lshlrev_b32_e32 v170, 16, v144
	v_and_b32_e32 v171, 0xffff0000, v144
	v_mul_f32_e32 v170, s24, v170
	v_mul_f32_e32 v171, s24, v171
	v_fma_f32 v168, v170, v10, v168
	v_fma_f32 v169, v171, v11, v169
	v_fma_f32 v185, v168, v168, v185
	v_fma_f32 v185, v169, v169, v185
	v_cvt_pk_bf16_f32 v112, v168, v169
	v_lshlrev_b32_e32 v168, 16, v113
	v_and_b32_e32 v169, 0xffff0000, v113
	v_lshlrev_b32_e32 v170, 16, v145
	v_and_b32_e32 v171, 0xffff0000, v145
	v_mul_f32_e32 v170, s24, v170
	v_mul_f32_e32 v171, s24, v171
	v_fma_f32 v168, v170, v12, v168
	v_fma_f32 v169, v171, v13, v169
	v_fma_f32 v185, v168, v168, v185
	v_fma_f32 v185, v169, v169, v185
	v_cvt_pk_bf16_f32 v113, v168, v169
	v_lshlrev_b32_e32 v168, 16, v114
	v_and_b32_e32 v169, 0xffff0000, v114
	v_lshlrev_b32_e32 v170, 16, v146
	v_and_b32_e32 v171, 0xffff0000, v146
	v_mul_f32_e32 v170, s24, v170
	v_mul_f32_e32 v171, s24, v171
	v_fma_f32 v168, v170, v14, v168
	v_fma_f32 v169, v171, v15, v169
	v_fma_f32 v185, v168, v168, v185
	v_fma_f32 v185, v169, v169, v185
	v_cvt_pk_bf16_f32 v114, v168, v169
	v_lshlrev_b32_e32 v168, 16, v115
	v_and_b32_e32 v169, 0xffff0000, v115
	v_lshlrev_b32_e32 v170, 16, v147
	v_and_b32_e32 v171, 0xffff0000, v147
	v_mul_f32_e32 v170, s24, v170
	v_mul_f32_e32 v171, s24, v171
	v_fma_f32 v168, v170, v16, v168
	v_fma_f32 v169, v171, v17, v169
	v_fma_f32 v185, v168, v168, v185
	v_fma_f32 v185, v169, v169, v185
	v_cvt_pk_bf16_f32 v115, v168, v169
	global_store_dwordx4 v23, v[108:111], s[0:1] offset:2048
	global_store_dwordx4 v23, v[112:115], s[0:1] offset:3072
	v_lshlrev_b32_e32 v168, 16, v116
	v_and_b32_e32 v169, 0xffff0000, v116
	v_lshlrev_b32_e32 v170, 16, v148
	v_and_b32_e32 v171, 0xffff0000, v148
	v_mul_f32_e32 v170, s98, v170
	v_mul_f32_e32 v171, s98, v171
	v_fma_f32 v168, v170, v2, v168
	v_fma_f32 v169, v171, v3, v169
	v_fma_f32 v186, v168, v168, v186
	v_fma_f32 v186, v169, v169, v186
	v_cvt_pk_bf16_f32 v116, v168, v169
	v_lshlrev_b32_e32 v168, 16, v117
	v_and_b32_e32 v169, 0xffff0000, v117
	v_lshlrev_b32_e32 v170, 16, v149
	v_and_b32_e32 v171, 0xffff0000, v149
	v_mul_f32_e32 v170, s98, v170
	v_mul_f32_e32 v171, s98, v171
	v_fma_f32 v168, v170, v4, v168
	v_fma_f32 v169, v171, v5, v169
	v_fma_f32 v186, v168, v168, v186
	v_fma_f32 v186, v169, v169, v186
	v_cvt_pk_bf16_f32 v117, v168, v169
	v_lshlrev_b32_e32 v168, 16, v118
	v_and_b32_e32 v169, 0xffff0000, v118
	v_lshlrev_b32_e32 v170, 16, v150
	v_and_b32_e32 v171, 0xffff0000, v150
	v_mul_f32_e32 v170, s98, v170
	v_mul_f32_e32 v171, s98, v171
	v_fma_f32 v168, v170, v6, v168
	v_fma_f32 v169, v171, v7, v169
	v_fma_f32 v186, v168, v168, v186
	v_fma_f32 v186, v169, v169, v186
	v_cvt_pk_bf16_f32 v118, v168, v169
	v_lshlrev_b32_e32 v168, 16, v119
	v_and_b32_e32 v169, 0xffff0000, v119
	v_lshlrev_b32_e32 v170, 16, v151
	v_and_b32_e32 v171, 0xffff0000, v151
	v_mul_f32_e32 v170, s98, v170
	v_mul_f32_e32 v171, s98, v171
	v_fma_f32 v168, v170, v8, v168
	v_fma_f32 v169, v171, v9, v169
	v_fma_f32 v186, v168, v168, v186
	v_fma_f32 v186, v169, v169, v186
	v_cvt_pk_bf16_f32 v119, v168, v169
	v_lshlrev_b32_e32 v168, 16, v120
	v_and_b32_e32 v169, 0xffff0000, v120
	v_lshlrev_b32_e32 v170, 16, v152
	v_and_b32_e32 v171, 0xffff0000, v152
; __device__ __forceinline__ float bf_lo(unsigned w) { return __uint_as_float(w << 16); }
; __device__ __forceinline__ float bf_hi(unsigned w) { return __uint_as_float(w & 0xffff0000u); }
; __device__ __forceinline__ unsigned pk2(float lo, float hi) { bf16x2_t r = __builtin_convertvector((f32x2_t){lo, hi}, bf16x2_t); return __builtin_bit_cast(unsigned, r); }
; template <bool SRC_F32, bool FINAL, int R> __device__ __forceinline__ void ew_compute(const EwSet<SRC_F32, R>& S, int rb, const f32x4 (&g)[4], bf16* hb_out, float* out32, float scale, float* rs_out, int lane) {
;     ...
; #pragma unroll
;         for (int j = 0; j < 4; ++j) {
;             f32x4 h;
;             if constexpr (SRC_F32) h = S.h32[i][j];
;             else { const v2u hw = S.hb[i][j]; h.x = bf_lo(hw.x); h.y = bf_hi(hw.x); h.z = bf_lo(hw.y); h.w = bf_hi(hw.y); }
;             const v2u fw = S.fw[i][j];
;             f32x4 v; v.x = h.x + bf_lo(fw.x) * rs * g[j].x; v.y = h.y + bf_hi(fw.x) * rs * g[j].y; v.z = h.z + bf_lo(fw.y) * rs * g[j].z; v.w = h.w + bf_hi(fw.y) * rs * g[j].w;
;             if (FINAL) __builtin_nontemporal_store(v, (f32x4*)(out32 + (size_t)(rb + i) * D) + lane + 64 * j);
;             else { v2u o; o.x = pk2(v.x, v.y); o.y = pk2(v.z, v.w); ((v2u*)(hb_out + (size_t)(rb + i) * D) + lane)[64 * j] = o; s2 += (v.x * v.x + v.y * v.y) + (v.z * v.z + v.w * v.w); }
;         }
;         if (!FINAL) { const float tot = wave_sum(s2); if (lane == 0) rs_out[rb + i] = 1.0f / sqrtf(tot * (1.f / D) + EPS); }
	v_mul_f32_e32 v170, s98, v170
	v_mul_f32_e32 v171, s98, v171
	v_fma_f32 v168, v170, v10, v168
	v_fma_f32 v169, v171, v11, v169
	v_fma_f32 v186, v168, v168, v186
	v_fma_f32 v186, v169, v169, v186
	v_cvt_pk_bf16_f32 v120, v168, v169
	v_lshlrev_b32_e32 v168, 16, v121
	v_and_b32_e32 v169, 0xffff0000, v121
	v_lshlrev_b32_e32 v170, 16, v153
	v_and_b32_e32 v171, 0xffff0000, v153
	v_mul_f32_e32 v170, s98, v170
	v_mul_f32_e32 v171, s98, v171
	v_fma_f32 v168, v170, v12, v168
	v_fma_f32 v169, v171, v13, v169
	v_fma_f32 v186, v168, v168, v186
	v_fma_f32 v186, v169, v169, v186
	v_cvt_pk_bf16_f32 v121, v168, v169
	v_lshlrev_b32_e32 v168, 16, v122
	v_and_b32_e32 v169, 0xffff0000, v122
	v_lshlrev_b32_e32 v170, 16, v154
	v_and_b32_e32 v171, 0xffff0000, v154
	v_mul_f32_e32 v170, s98, v170
	v_mul_f32_e32 v171, s98, v171
	v_fma_f32 v168, v170, v14, v168
	v_fma_f32 v169, v171, v15, v169
	v_fma_f32 v186, v168, v168, v186
	v_fma_f32 v186, v169, v169, v186
	v_cvt_pk_bf16_f32 v122, v168, v169
	v_lshlrev_b32_e32 v168, 16, v123
	v_and_b32_e32 v169, 0xffff0000, v123
	v_lshlrev_b32_e32 v170, 16, v155
	v_and_b32_e32 v171, 0xffff0000, v155
	v_mul_f32_e32 v170, s98, v170
	v_mul_f32_e32 v171, s98, v171
	v_fma_f32 v168, v170, v16, v168
	v_fma_f32 v169, v171, v17, v169
	v_fma_f32 v186, v168, v168, v186
	v_fma_f32 v186, v169, v169, v186
	v_cvt_pk_bf16_f32 v123, v168, v169
	global_store_dwordx4 v24, v[116:119], s[0:1]
	global_store_dwordx4 v24, v[120:123], s[0:1] offset:1024
	v_lshlrev_b32_e32 v168, 16, v124
	v_and_b32_e32 v169, 0xffff0000, v124
	v_lshlrev_b32_e32 v170, 16, v156
	v_and_b32_e32 v171, 0xffff0000, v156
	v_mul_f32_e32 v170, s101, v170
	v_mul_f32_e32 v171, s101, v171
	v_fma_f32 v168, v170, v2, v168
	v_fma_f32 v169, v171, v3, v169
	v_fma_f32 v187, v168, v168, v187
	v_fma_f32 v187, v169, v169, v187
	v_cvt_pk_bf16_f32 v124, v168, v169
	v_lshlrev_b32_e32 v168, 16, v125
	v_and_b32_e32 v169, 0xffff0000, v125
	v_lshlrev_b32_e32 v170, 16, v157
	v_and_b32_e32 v171, 0xffff0000, v157
	v_mul_f32_e32 v170, s101, v170
	v_mul_f32_e32 v171, s101, v171
	v_fma_f32 v168, v170, v4, v168
	v_fma_f32 v169, v171, v5, v169
	v_fma_f32 v187, v168, v168, v187
	v_fma_f32 v187, v169, v169, v187
	v_cvt_pk_bf16_f32 v125, v168, v169
	v_lshlrev_b32_e32 v168, 16, v126
	v_and_b32_e32 v169, 0xffff0000, v126
	v_lshlrev_b32_e32 v170, 16, v158
	v_and_b32_e32 v171, 0xffff0000, v158
	v_mul_f32_e32 v170, s101, v170
	v_mul_f32_e32 v171, s101, v171
	v_fma_f32 v168, v170, v6, v168
	v_fma_f32 v169, v171, v7, v169
	v_fma_f32 v187, v168, v168, v187
	v_fma_f32 v187, v169, v169, v187
	v_cvt_pk_bf16_f32 v126, v168, v169
	v_lshlrev_b32_e32 v168, 16, v127
	v_and_b32_e32 v169, 0xffff0000, v127
	v_lshlrev_b32_e32 v170, 16, v159
	v_and_b32_e32 v171, 0xffff0000, v159
	v_mul_f32_e32 v170, s101, v170
	v_mul_f32_e32 v171, s101, v171
	v_fma_f32 v168, v170, v8, v168
	v_fma_f32 v169, v171, v9, v169
	v_fma_f32 v187, v168, v168, v187
	v_fma_f32 v187, v169, v169, v187
	v_cvt_pk_bf16_f32 v127, v168, v169
	v_lshlrev_b32_e32 v168, 16, v128
	v_and_b32_e32 v169, 0xffff0000, v128
	v_lshlrev_b32_e32 v170, 16, v160
	v_and_b32_e32 v171, 0xffff0000, v160
	v_mul_f32_e32 v170, s101, v170
	v_mul_f32_e32 v171, s101, v171
	v_fma_f32 v168, v170, v10, v168
	v_fma_f32 v169, v171, v11, v169
	v_fma_f32 v187, v168, v168, v187
	v_fma_f32 v187, v169, v169, v187
	v_cvt_pk_bf16_f32 v128, v168, v169
	v_lshlrev_b32_e32 v168, 16, v129
	v_and_b32_e32 v169, 0xffff0000, v129
	v_lshlrev_b32_e32 v170, 16, v161
	v_and_b32_e32 v171, 0xffff0000, v161
	v_mul_f32_e32 v170, s101, v170
	v_mul_f32_e32 v171, s101, v171
	v_fma_f32 v168, v170, v12, v168
	v_fma_f32 v169, v171, v13, v169
	v_fma_f32 v187, v168, v168, v187
	v_fma_f32 v187, v169, v169, v187
	v_cvt_pk_bf16_f32 v129, v168, v169
	v_lshlrev_b32_e32 v168, 16, v130
	v_and_b32_e32 v169, 0xffff0000, v130
	v_lshlrev_b32_e32 v170, 16, v162
	v_and_b32_e32 v171, 0xffff0000, v162
	v_mul_f32_e32 v170, s101, v170
	v_mul_f32_e32 v171, s101, v171
	v_fma_f32 v168, v170, v14, v168
	v_fma_f32 v169, v171, v15, v169
	v_fma_f32 v187, v168, v168, v187
	v_fma_f32 v187, v169, v169, v187
	v_cvt_pk_bf16_f32 v130, v168, v169
	v_lshlrev_b32_e32 v168, 16, v131
	v_and_b32_e32 v169, 0xffff0000, v131
	v_lshlrev_b32_e32 v170, 16, v163
	v_and_b32_e32 v171, 0xffff0000, v163
	v_mul_f32_e32 v170, s101, v170
	v_mul_f32_e32 v171, s101, v171
	v_fma_f32 v168, v170, v16, v168
	v_fma_f32 v169, v171, v17, v169
	v_fma_f32 v187, v168, v168, v187
	v_fma_f32 v187, v169, v169, v187
	v_cvt_pk_bf16_f32 v131, v168, v169
	global_store_dwordx4 v24, v[124:127], s[0:1] offset:2048
	global_store_dwordx4 v24, v[128:131], s[0:1] offset:3072
	s_nop 1
	v_add_f32_dpp v184, v184, v184 quad_perm:[1,0,3,2] row_mask:0xf bank_mask:0xf
	v_add_f32_dpp v185, v185, v185 quad_perm:[1,0,3,2] row_mask:0xf bank_mask:0xf
	v_add_f32_dpp v186, v186, v186 quad_perm:[1,0,3,2] row_mask:0xf bank_mask:0xf
	v_add_f32_dpp v187, v187, v187 quad_perm:[1,0,3,2] row_mask:0xf bank_mask:0xf
	v_add_f32_dpp v184, v184, v184 quad_perm:[2,3,0,1] row_mask:0xf bank_mask:0xf
	v_add_f32_dpp v185, v185, v185 quad_perm:[2,3,0,1] row_mask:0xf bank_mask:0xf
	v_add_f32_dpp v186, v186, v186 quad_perm:[2,3,0,1] row_mask:0xf bank_mask:0xf
	v_add_f32_dpp v187, v187, v187 quad_perm:[2,3,0,1] row_mask:0xf bank_mask:0xf
	v_add_f32_dpp v184, v184, v184 row_half_mirror row_mask:0xf bank_mask:0xf
	v_add_f32_dpp v185, v185, v185 row_half_mirror row_mask:0xf bank_mask:0xf
	v_add_f32_dpp v186, v186, v186 row_half_mirror row_mask:0xf bank_mask:0xf
	v_add_f32_dpp v187, v187, v187 row_half_mirror row_mask:0xf bank_mask:0xf
	v_add_f32_dpp v184, v184, v184 row_mirror row_mask:0xf bank_mask:0xf
; __device__ __forceinline__ float bf_lo(unsigned w) { return __uint_as_float(w << 16); }
; __device__ __forceinline__ float bf_hi(unsigned w) { return __uint_as_float(w & 0xffff0000u); }
; template <bool SRC_F32, bool FINAL, int R> __device__ __forceinline__ void ew_compute(const EwSet<SRC_F32, R>& S, int rb, const f32x4 (&g)[4], bf16* hb_out, float* out32, float scale, float* rs_out, int lane) {
; #pragma unroll
;     for (int i = 0; i < R; ++i) {
;         float q = S.p[i];
;         q += __shfl_xor(q, 1); q += __shfl_xor(q, 2); q += __shfl_xor(q, 4); q += __shfl_xor(q, 8);
;         const float ss = __shfl(q, 0);
;         const float rs = scale / sqrtf(ss * (1.f / D) + EPS);
;         float s2 = 0.f;
; #pragma unroll
;         for (int j = 0; j < 4; ++j) {
;             f32x4 h;
;             if constexpr (SRC_F32) h = S.h32[i][j];
;             else { const v2u hw = S.hb[i][j]; h.x = bf_lo(hw.x); h.y = bf_hi(hw.x); h.z = bf_lo(hw.y); h.w = bf_hi(hw.y); }
;             const v2u fw = S.fw[i][j];
;             f32x4 v; v.x = h.x + bf_lo(fw.x) * rs * g[j].x; v.y = h.y + bf_hi(fw.x) * rs * g[j].y; v.z = h.z + bf_lo(fw.y) * rs * g[j].z; v.w = h.w + bf_hi(fw.y) * rs * g[j].w;
;             if (FINAL) __builtin_nontemporal_store(v, (f32x4*)(out32 + (size_t)(rb + i) * D) + lane + 64 * j);
;             else { v2u o; o.x = pk2(v.x, v.y); o.y = pk2(v.z, v.w); ((v2u*)(hb_out + (size_t)(rb + i) * D) + lane)[64 * j] = o; s2 += (v.x * v.x + v.y * v.y) + (v.z * v.z + v.w * v.w); }
;         }
;         if (!FINAL) { const float tot = wave_sum(s2); if (lane == 0) rs_out[rb + i] = 1.0f / sqrtf(tot * (1.f / D) + EPS); }
; template <bool SRC_F32, bool FINAL> __device__ __forceinline__ void ew_phase(const float* hsrc32, const bf16* hsrcb, bf16* hb_out, float* out32, const bf16* f, const float* part, const float* gpost, float scale, float* rs_out, int gw, int NGW, int lane) {
;     ...
; #pragma unroll 1
;     for (; rb < M; rb += 2 * step) {
;         const int nb = rb + step, nb2 = nb + step;
;         if (nb < M) ew_load<SRC_F32, R>(B, nb, hsrc32, hsrcb, f, part, lane);
;         ew_compute<SRC_F32, FINAL, R>(A, rb, g, hb_out, out32, scale, rs_out, lane);
;         if (nb2 < M) ew_load<SRC_F32, R>(A, nb2, hsrc32, hsrcb, f, part, lane);
;         if (nb < M) ew_compute<SRC_F32, FINAL, R>(B, nb, g, hb_out, out32, scale, rs_out, lane);
	v_add_f32_dpp v185, v185, v185 row_mirror row_mask:0xf bank_mask:0xf
	v_add_f32_dpp v186, v186, v186 row_mirror row_mask:0xf bank_mask:0xf
	v_add_f32_dpp v187, v187, v187 row_mirror row_mask:0xf bank_mask:0xf
	v_add_f32_dpp v184, v184, v184 row_bcast:15 row_mask:0xa bank_mask:0xf
	v_add_f32_dpp v185, v185, v185 row_bcast:15 row_mask:0xa bank_mask:0xf
	v_add_f32_dpp v186, v186, v186 row_bcast:15 row_mask:0xa bank_mask:0xf
	v_add_f32_dpp v187, v187, v187 row_bcast:15 row_mask:0xa bank_mask:0xf
	v_add_f32_dpp v184, v184, v184 row_bcast:31 row_mask:0xc bank_mask:0xf
	v_add_f32_dpp v185, v185, v185 row_bcast:31 row_mask:0xc bank_mask:0xf
	v_add_f32_dpp v186, v186, v186 row_bcast:31 row_mask:0xc bank_mask:0xf
	v_add_f32_dpp v187, v187, v187 row_bcast:31 row_mask:0xc bank_mask:0xf
	s_nop 1
	v_readlane_b32 s3, v184, 63
	v_readlane_b32 s24, v185, 63
	v_readlane_b32 s98, v186, 63
	v_readlane_b32 s101, v187, 63
	s_nop 3
	v_writelane_b32 v188, s3, 0
	v_writelane_b32 v188, s24, 1
	v_writelane_b32 v188, s98, 2
	v_writelane_b32 v188, s101, 3
	s_nop 1
	v_mul_f32_e32 v188, 0x3a800000, v188
	v_add_f32_e32 v188, 0x358637bd, v188
	v_rsq_f32_e32 v188, v188
	s_mov_b64 exec, 15
	global_store_dword v26, v188, s[14:15]
	s_mov_b64 exec, -1
	s_add_u32 s27, s26, 2052
	s_lshl_b32 s22, s27, 11
	v_lshl_add_u32 v23, v0, 4, s22
	v_add_u32_e32 v24, 0x1000, v23
	s_lshl_b32 s22, s27, 6
	v_lshl_add_u32 v25, v0, 2, s22
	s_lshl_b32 s22, s27, 2
	v_lshl_add_u32 v26, v0, 2, s22
	global_load_dwordx4 v[100:103], v23, s[0:1]
	global_load_dwordx4 v[104:107], v23, s[0:1] offset:1024
	global_load_dwordx4 v[132:135], v23, s[4:5]
	global_load_dwordx4 v[136:139], v23, s[4:5] offset:1024
	global_load_dwordx4 v[108:111], v23, s[0:1] offset:2048
	global_load_dwordx4 v[112:115], v23, s[0:1] offset:3072
	global_load_dwordx4 v[140:143], v23, s[4:5] offset:2048
	global_load_dwordx4 v[144:147], v23, s[4:5] offset:3072
	global_load_dwordx4 v[116:119], v24, s[0:1]
	global_load_dwordx4 v[120:123], v24, s[0:1] offset:1024
	global_load_dwordx4 v[148:151], v24, s[4:5]
	global_load_dwordx4 v[152:155], v24, s[4:5] offset:1024
	global_load_dwordx4 v[124:127], v24, s[0:1] offset:2048
	global_load_dwordx4 v[128:131], v24, s[0:1] offset:3072
	global_load_dwordx4 v[156:159], v24, s[4:5] offset:2048
	global_load_dwordx4 v[160:163], v24, s[4:5] offset:3072
	global_load_dword v164, v25, s[6:7]
	s_waitcnt vmcnt(26)
	v_add_f32_dpp v96, v96, v96 quad_perm:[1,0,3,2] row_mask:0xf bank_mask:0xf
	s_nop 1
	v_add_f32_dpp v96, v96, v96 quad_perm:[2,3,0,1] row_mask:0xf bank_mask:0xf
	s_nop 1
	v_add_f32_dpp v96, v96, v96 row_half_mirror row_mask:0xf bank_mask:0xf
	s_nop 1
	v_add_f32_dpp v96, v96, v96 row_mirror row_mask:0xf bank_mask:0xf
	s_nop 1
	v_mul_f32_e32 v96, 0x3a800000, v96
	v_add_f32_e32 v96, 0x358637bd, v96
	v_rsq_f32_e32 v96, v96
	s_nop 0
	v_mul_f32_e32 v96, 0x3f000000, v96
	s_nop 0
	v_readlane_b32 s3, v96, 0
	v_readlane_b32 s24, v96, 16
	v_readlane_b32 s98, v96, 32
	v_readlane_b32 s101, v96, 48
	s_nop 1
	v_mov_b32_e32 v184, 0
	v_mov_b32_e32 v185, 0
	v_mov_b32_e32 v186, 0
	v_mov_b32_e32 v187, 0
	v_lshlrev_b32_e32 v168, 16, v32
	v_and_b32_e32 v169, 0xffff0000, v32
	v_lshlrev_b32_e32 v170, 16, v64
	v_and_b32_e32 v171, 0xffff0000, v64
	v_mul_f32_e32 v170, s3, v170
	v_mul_f32_e32 v171, s3, v171
	v_fma_f32 v168, v170, v2, v168
	v_fma_f32 v169, v171, v3, v169
	v_fma_f32 v184, v168, v168, v184
	v_fma_f32 v184, v169, v169, v184
	v_cvt_pk_bf16_f32 v32, v168, v169
	v_lshlrev_b32_e32 v168, 16, v33
	v_and_b32_e32 v169, 0xffff0000, v33
	v_lshlrev_b32_e32 v170, 16, v65
	v_and_b32_e32 v171, 0xffff0000, v65
	v_mul_f32_e32 v170, s3, v170
	v_mul_f32_e32 v171, s3, v171
	v_fma_f32 v168, v170, v4, v168
	v_fma_f32 v169, v171, v5, v169
	v_fma_f32 v184, v168, v168, v184
	v_fma_f32 v184, v169, v169, v184
	v_cvt_pk_bf16_f32 v33, v168, v169
	v_lshlrev_b32_e32 v168, 16, v34
	v_and_b32_e32 v169, 0xffff0000, v34
	v_lshlrev_b32_e32 v170, 16, v66
	v_and_b32_e32 v171, 0xffff0000, v66
	v_mul_f32_e32 v170, s3, v170
	v_mul_f32_e32 v171, s3, v171
	v_fma_f32 v168, v170, v6, v168
	v_fma_f32 v169, v171, v7, v169
	v_fma_f32 v184, v168, v168, v184
	v_fma_f32 v184, v169, v169, v184
	v_cvt_pk_bf16_f32 v34, v168, v169
	v_lshlrev_b32_e32 v168, 16, v35
	v_and_b32_e32 v169, 0xffff0000, v35
	v_lshlrev_b32_e32 v170, 16, v67
	v_and_b32_e32 v171, 0xffff0000, v67
	v_mul_f32_e32 v170, s3, v170
	v_mul_f32_e32 v171, s3, v171
	v_fma_f32 v168, v170, v8, v168
	v_fma_f32 v169, v171, v9, v169
	v_fma_f32 v184, v168, v168, v184
	v_fma_f32 v184, v169, v169, v184
	v_cvt_pk_bf16_f32 v35, v168, v169
	v_lshlrev_b32_e32 v168, 16, v36
	v_and_b32_e32 v169, 0xffff0000, v36
	v_lshlrev_b32_e32 v170, 16, v68
	v_and_b32_e32 v171, 0xffff0000, v68
	v_mul_f32_e32 v170, s3, v170
	v_mul_f32_e32 v171, s3, v171
	v_fma_f32 v168, v170, v10, v168
	v_fma_f32 v169, v171, v11, v169
	v_fma_f32 v184, v168, v168, v184
	v_fma_f32 v184, v169, v169, v184
	v_cvt_pk_bf16_f32 v36, v168, v169
	v_lshlrev_b32_e32 v168, 16, v37
	v_and_b32_e32 v169, 0xffff0000, v37
	v_lshlrev_b32_e32 v170, 16, v69
	v_and_b32_e32 v171, 0xffff0000, v69
	v_mul_f32_e32 v170, s3, v170
	v_mul_f32_e32 v171, s3, v171
	v_fma_f32 v168, v170, v12, v168
	v_fma_f32 v169, v171, v13, v169
	v_fma_f32 v184, v168, v168, v184
	v_fma_f32 v184, v169, v169, v184
	v_cvt_pk_bf16_f32 v37, v168, v169
	v_lshlrev_b32_e32 v168, 16, v38
	v_and_b32_e32 v169, 0xffff0000, v38
	v_lshlrev_b32_e32 v170, 16, v70
	v_and_b32_e32 v171, 0xffff0000, v70
	v_mul_f32_e32 v170, s3, v170
	v_mul_f32_e32 v171, s3, v171
	v_fma_f32 v168, v170, v14, v168
	v_fma_f32 v169, v171, v15, v169
	v_fma_f32 v184, v168, v168, v184
	v_fma_f32 v184, v169, v169, v184
	v_cvt_pk_bf16_f32 v38, v168, v169
; __device__ __forceinline__ float bf_lo(unsigned w) { return __uint_as_float(w << 16); }
; __device__ __forceinline__ float bf_hi(unsigned w) { return __uint_as_float(w & 0xffff0000u); }
; __device__ __forceinline__ unsigned pk2(float lo, float hi) { bf16x2_t r = __builtin_convertvector((f32x2_t){lo, hi}, bf16x2_t); return __builtin_bit_cast(unsigned, r); }
; template <bool SRC_F32, bool FINAL, int R> __device__ __forceinline__ void ew_compute(const EwSet<SRC_F32, R>& S, int rb, const f32x4 (&g)[4], bf16* hb_out, float* out32, float scale, float* rs_out, int lane) {
;     ...
; #pragma unroll
;         for (int j = 0; j < 4; ++j) {
;             f32x4 h;
;             if constexpr (SRC_F32) h = S.h32[i][j];
;             else { const v2u hw = S.hb[i][j]; h.x = bf_lo(hw.x); h.y = bf_hi(hw.x); h.z = bf_lo(hw.y); h.w = bf_hi(hw.y); }
;             const v2u fw = S.fw[i][j];
;             f32x4 v; v.x = h.x + bf_lo(fw.x) * rs * g[j].x; v.y = h.y + bf_hi(fw.x) * rs * g[j].y; v.z = h.z + bf_lo(fw.y) * rs * g[j].z; v.w = h.w + bf_hi(fw.y) * rs * g[j].w;
;             if (FINAL) __builtin_nontemporal_store(v, (f32x4*)(out32 + (size_t)(rb + i) * D) + lane + 64 * j);
;             else { v2u o; o.x = pk2(v.x, v.y); o.y = pk2(v.z, v.w); ((v2u*)(hb_out + (size_t)(rb + i) * D) + lane)[64 * j] = o; s2 += (v.x * v.x + v.y * v.y) + (v.z * v.z + v.w * v.w); }
	v_lshlrev_b32_e32 v168, 16, v39
	v_and_b32_e32 v169, 0xffff0000, v39
	v_lshlrev_b32_e32 v170, 16, v71
	v_and_b32_e32 v171, 0xffff0000, v71
	v_mul_f32_e32 v170, s3, v170
	v_mul_f32_e32 v171, s3, v171
	v_fma_f32 v168, v170, v16, v168
	v_fma_f32 v169, v171, v17, v169
	v_fma_f32 v184, v168, v168, v184
	v_fma_f32 v184, v169, v169, v184
	v_cvt_pk_bf16_f32 v39, v168, v169
	global_store_dwordx4 v18, v[32:35], s[0:1]
	global_store_dwordx4 v18, v[36:39], s[0:1] offset:1024
	v_lshlrev_b32_e32 v168, 16, v40
	v_and_b32_e32 v169, 0xffff0000, v40
	v_lshlrev_b32_e32 v170, 16, v72
	v_and_b32_e32 v171, 0xffff0000, v72
	v_mul_f32_e32 v170, s24, v170
	v_mul_f32_e32 v171, s24, v171
	v_fma_f32 v168, v170, v2, v168
	v_fma_f32 v169, v171, v3, v169
	v_fma_f32 v185, v168, v168, v185
	v_fma_f32 v185, v169, v169, v185
	v_cvt_pk_bf16_f32 v40, v168, v169
	v_lshlrev_b32_e32 v168, 16, v41
	v_and_b32_e32 v169, 0xffff0000, v41
	v_lshlrev_b32_e32 v170, 16, v73
	v_and_b32_e32 v171, 0xffff0000, v73
	v_mul_f32_e32 v170, s24, v170
	v_mul_f32_e32 v171, s24, v171
	v_fma_f32 v168, v170, v4, v168
	v_fma_f32 v169, v171, v5, v169
	v_fma_f32 v185, v168, v168, v185
	v_fma_f32 v185, v169, v169, v185
	v_cvt_pk_bf16_f32 v41, v168, v169
	v_lshlrev_b32_e32 v168, 16, v42
	v_and_b32_e32 v169, 0xffff0000, v42
	v_lshlrev_b32_e32 v170, 16, v74
	v_and_b32_e32 v171, 0xffff0000, v74
	v_mul_f32_e32 v170, s24, v170
	v_mul_f32_e32 v171, s24, v171
	v_fma_f32 v168, v170, v6, v168
	v_fma_f32 v169, v171, v7, v169
	v_fma_f32 v185, v168, v168, v185
	v_fma_f32 v185, v169, v169, v185
	v_cvt_pk_bf16_f32 v42, v168, v169
	v_lshlrev_b32_e32 v168, 16, v43
	v_and_b32_e32 v169, 0xffff0000, v43
	v_lshlrev_b32_e32 v170, 16, v75
	v_and_b32_e32 v171, 0xffff0000, v75
	v_mul_f32_e32 v170, s24, v170
	v_mul_f32_e32 v171, s24, v171
	v_fma_f32 v168, v170, v8, v168
	v_fma_f32 v169, v171, v9, v169
	v_fma_f32 v185, v168, v168, v185
	v_fma_f32 v185, v169, v169, v185
	v_cvt_pk_bf16_f32 v43, v168, v169
	v_lshlrev_b32_e32 v168, 16, v44
	v_and_b32_e32 v169, 0xffff0000, v44
	v_lshlrev_b32_e32 v170, 16, v76
	v_and_b32_e32 v171, 0xffff0000, v76
	v_mul_f32_e32 v170, s24, v170
	v_mul_f32_e32 v171, s24, v171
	v_fma_f32 v168, v170, v10, v168
	v_fma_f32 v169, v171, v11, v169
	v_fma_f32 v185, v168, v168, v185
	v_fma_f32 v185, v169, v169, v185
	v_cvt_pk_bf16_f32 v44, v168, v169
	v_lshlrev_b32_e32 v168, 16, v45
	v_and_b32_e32 v169, 0xffff0000, v45
	v_lshlrev_b32_e32 v170, 16, v77
	v_and_b32_e32 v171, 0xffff0000, v77
	v_mul_f32_e32 v170, s24, v170
	v_mul_f32_e32 v171, s24, v171
	v_fma_f32 v168, v170, v12, v168
	v_fma_f32 v169, v171, v13, v169
	v_fma_f32 v185, v168, v168, v185
	v_fma_f32 v185, v169, v169, v185
	v_cvt_pk_bf16_f32 v45, v168, v169
	v_lshlrev_b32_e32 v168, 16, v46
	v_and_b32_e32 v169, 0xffff0000, v46
	v_lshlrev_b32_e32 v170, 16, v78
	v_and_b32_e32 v171, 0xffff0000, v78
	v_mul_f32_e32 v170, s24, v170
	v_mul_f32_e32 v171, s24, v171
	v_fma_f32 v168, v170, v14, v168
	v_fma_f32 v169, v171, v15, v169
	v_fma_f32 v185, v168, v168, v185
	v_fma_f32 v185, v169, v169, v185
	v_cvt_pk_bf16_f32 v46, v168, v169
	v_lshlrev_b32_e32 v168, 16, v47
	v_and_b32_e32 v169, 0xffff0000, v47
	v_lshlrev_b32_e32 v170, 16, v79
	v_and_b32_e32 v171, 0xffff0000, v79
	v_mul_f32_e32 v170, s24, v170
	v_mul_f32_e32 v171, s24, v171
	v_fma_f32 v168, v170, v16, v168
	v_fma_f32 v169, v171, v17, v169
	v_fma_f32 v185, v168, v168, v185
	v_fma_f32 v185, v169, v169, v185
	v_cvt_pk_bf16_f32 v47, v168, v169
	global_store_dwordx4 v18, v[40:43], s[0:1] offset:2048
	global_store_dwordx4 v18, v[44:47], s[0:1] offset:3072
	v_lshlrev_b32_e32 v168, 16, v48
	v_and_b32_e32 v169, 0xffff0000, v48
	v_lshlrev_b32_e32 v170, 16, v80
	v_and_b32_e32 v171, 0xffff0000, v80
	v_mul_f32_e32 v170, s98, v170
	v_mul_f32_e32 v171, s98, v171
	v_fma_f32 v168, v170, v2, v168
	v_fma_f32 v169, v171, v3, v169
	v_fma_f32 v186, v168, v168, v186
	v_fma_f32 v186, v169, v169, v186
	v_cvt_pk_bf16_f32 v48, v168, v169
	v_lshlrev_b32_e32 v168, 16, v49
	v_and_b32_e32 v169, 0xffff0000, v49
	v_lshlrev_b32_e32 v170, 16, v81
	v_and_b32_e32 v171, 0xffff0000, v81
	v_mul_f32_e32 v170, s98, v170
	v_mul_f32_e32 v171, s98, v171
	v_fma_f32 v168, v170, v4, v168
	v_fma_f32 v169, v171, v5, v169
	v_fma_f32 v186, v168, v168, v186
	v_fma_f32 v186, v169, v169, v186
	v_cvt_pk_bf16_f32 v49, v168, v169
	v_lshlrev_b32_e32 v168, 16, v50
	v_and_b32_e32 v169, 0xffff0000, v50
	v_lshlrev_b32_e32 v170, 16, v82
	v_and_b32_e32 v171, 0xffff0000, v82
	v_mul_f32_e32 v170, s98, v170
	v_mul_f32_e32 v171, s98, v171
	v_fma_f32 v168, v170, v6, v168
	v_fma_f32 v169, v171, v7, v169
	v_fma_f32 v186, v168, v168, v186
	v_fma_f32 v186, v169, v169, v186
	v_cvt_pk_bf16_f32 v50, v168, v169
	v_lshlrev_b32_e32 v168, 16, v51
	v_and_b32_e32 v169, 0xffff0000, v51
	v_lshlrev_b32_e32 v170, 16, v83
	v_and_b32_e32 v171, 0xffff0000, v83
	v_mul_f32_e32 v170, s98, v170
	v_mul_f32_e32 v171, s98, v171
	v_fma_f32 v168, v170, v8, v168
	v_fma_f32 v169, v171, v9, v169
	v_fma_f32 v186, v168, v168, v186
	v_fma_f32 v186, v169, v169, v186
	v_cvt_pk_bf16_f32 v51, v168, v169
	v_lshlrev_b32_e32 v168, 16, v52
	v_and_b32_e32 v169, 0xffff0000, v52
	v_lshlrev_b32_e32 v170, 16, v84
	v_and_b32_e32 v171, 0xffff0000, v84
	v_mul_f32_e32 v170, s98, v170
	v_mul_f32_e32 v171, s98, v171
	v_fma_f32 v168, v170, v10, v168
	v_fma_f32 v169, v171, v11, v169
	v_fma_f32 v186, v168, v168, v186
	v_fma_f32 v186, v169, v169, v186
	v_cvt_pk_bf16_f32 v52, v168, v169
	v_lshlrev_b32_e32 v168, 16, v53
	v_and_b32_e32 v169, 0xffff0000, v53
	v_lshlrev_b32_e32 v170, 16, v85
	v_and_b32_e32 v171, 0xffff0000, v85
	v_mul_f32_e32 v170, s98, v170
	v_mul_f32_e32 v171, s98, v171
	v_fma_f32 v168, v170, v12, v168
	v_fma_f32 v169, v171, v13, v169
; __device__ __forceinline__ float bf_lo(unsigned w) { return __uint_as_float(w << 16); }
; __device__ __forceinline__ float bf_hi(unsigned w) { return __uint_as_float(w & 0xffff0000u); }
; __device__ __forceinline__ unsigned pk2(float lo, float hi) { bf16x2_t r = __builtin_convertvector((f32x2_t){lo, hi}, bf16x2_t); return __builtin_bit_cast(unsigned, r); }
; template <bool SRC_F32, bool FINAL, int R> __device__ __forceinline__ void ew_compute(const EwSet<SRC_F32, R>& S, int rb, const f32x4 (&g)[4], bf16* hb_out, float* out32, float scale, float* rs_out, int lane) {
;     ...
; #pragma unroll
;         for (int j = 0; j < 4; ++j) {
;             f32x4 h;
;             if constexpr (SRC_F32) h = S.h32[i][j];
;             else { const v2u hw = S.hb[i][j]; h.x = bf_lo(hw.x); h.y = bf_hi(hw.x); h.z = bf_lo(hw.y); h.w = bf_hi(hw.y); }
;             const v2u fw = S.fw[i][j];
;             f32x4 v; v.x = h.x + bf_lo(fw.x) * rs * g[j].x; v.y = h.y + bf_hi(fw.x) * rs * g[j].y; v.z = h.z + bf_lo(fw.y) * rs * g[j].z; v.w = h.w + bf_hi(fw.y) * rs * g[j].w;
;             if (FINAL) __builtin_nontemporal_store(v, (f32x4*)(out32 + (size_t)(rb + i) * D) + lane + 64 * j);
;             else { v2u o; o.x = pk2(v.x, v.y); o.y = pk2(v.z, v.w); ((v2u*)(hb_out + (size_t)(rb + i) * D) + lane)[64 * j] = o; s2 += (v.x * v.x + v.y * v.y) + (v.z * v.z + v.w * v.w); }
;         }
;         if (!FINAL) { const float tot = wave_sum(s2); if (lane == 0) rs_out[rb + i] = 1.0f / sqrtf(tot * (1.f / D) + EPS); }
;     }
	v_fma_f32 v186, v168, v168, v186
	v_fma_f32 v186, v169, v169, v186
	v_cvt_pk_bf16_f32 v53, v168, v169
	v_lshlrev_b32_e32 v168, 16, v54
	v_and_b32_e32 v169, 0xffff0000, v54
	v_lshlrev_b32_e32 v170, 16, v86
	v_and_b32_e32 v171, 0xffff0000, v86
	v_mul_f32_e32 v170, s98, v170
	v_mul_f32_e32 v171, s98, v171
	v_fma_f32 v168, v170, v14, v168
	v_fma_f32 v169, v171, v15, v169
	v_fma_f32 v186, v168, v168, v186
	v_fma_f32 v186, v169, v169, v186
	v_cvt_pk_bf16_f32 v54, v168, v169
	v_lshlrev_b32_e32 v168, 16, v55
	v_and_b32_e32 v169, 0xffff0000, v55
	v_lshlrev_b32_e32 v170, 16, v87
	v_and_b32_e32 v171, 0xffff0000, v87
	v_mul_f32_e32 v170, s98, v170
	v_mul_f32_e32 v171, s98, v171
	v_fma_f32 v168, v170, v16, v168
	v_fma_f32 v169, v171, v17, v169
	v_fma_f32 v186, v168, v168, v186
	v_fma_f32 v186, v169, v169, v186
	v_cvt_pk_bf16_f32 v55, v168, v169
	global_store_dwordx4 v19, v[48:51], s[0:1]
	global_store_dwordx4 v19, v[52:55], s[0:1] offset:1024
	v_lshlrev_b32_e32 v168, 16, v56
	v_and_b32_e32 v169, 0xffff0000, v56
	v_lshlrev_b32_e32 v170, 16, v88
	v_and_b32_e32 v171, 0xffff0000, v88
	v_mul_f32_e32 v170, s101, v170
	v_mul_f32_e32 v171, s101, v171
	v_fma_f32 v168, v170, v2, v168
	v_fma_f32 v169, v171, v3, v169
	v_fma_f32 v187, v168, v168, v187
	v_fma_f32 v187, v169, v169, v187
	v_cvt_pk_bf16_f32 v56, v168, v169
	v_lshlrev_b32_e32 v168, 16, v57
	v_and_b32_e32 v169, 0xffff0000, v57
	v_lshlrev_b32_e32 v170, 16, v89
	v_and_b32_e32 v171, 0xffff0000, v89
	v_mul_f32_e32 v170, s101, v170
	v_mul_f32_e32 v171, s101, v171
	v_fma_f32 v168, v170, v4, v168
	v_fma_f32 v169, v171, v5, v169
	v_fma_f32 v187, v168, v168, v187
	v_fma_f32 v187, v169, v169, v187
	v_cvt_pk_bf16_f32 v57, v168, v169
	v_lshlrev_b32_e32 v168, 16, v58
	v_and_b32_e32 v169, 0xffff0000, v58
	v_lshlrev_b32_e32 v170, 16, v90
	v_and_b32_e32 v171, 0xffff0000, v90
	v_mul_f32_e32 v170, s101, v170
	v_mul_f32_e32 v171, s101, v171
	v_fma_f32 v168, v170, v6, v168
	v_fma_f32 v169, v171, v7, v169
	v_fma_f32 v187, v168, v168, v187
	v_fma_f32 v187, v169, v169, v187
	v_cvt_pk_bf16_f32 v58, v168, v169
	v_lshlrev_b32_e32 v168, 16, v59
	v_and_b32_e32 v169, 0xffff0000, v59
	v_lshlrev_b32_e32 v170, 16, v91
	v_and_b32_e32 v171, 0xffff0000, v91
	v_mul_f32_e32 v170, s101, v170
	v_mul_f32_e32 v171, s101, v171
	v_fma_f32 v168, v170, v8, v168
	v_fma_f32 v169, v171, v9, v169
	v_fma_f32 v187, v168, v168, v187
	v_fma_f32 v187, v169, v169, v187
	v_cvt_pk_bf16_f32 v59, v168, v169
	v_lshlrev_b32_e32 v168, 16, v60
	v_and_b32_e32 v169, 0xffff0000, v60
	v_lshlrev_b32_e32 v170, 16, v92
	v_and_b32_e32 v171, 0xffff0000, v92
	v_mul_f32_e32 v170, s101, v170
	v_mul_f32_e32 v171, s101, v171
	v_fma_f32 v168, v170, v10, v168
	v_fma_f32 v169, v171, v11, v169
	v_fma_f32 v187, v168, v168, v187
	v_fma_f32 v187, v169, v169, v187
	v_cvt_pk_bf16_f32 v60, v168, v169
	v_lshlrev_b32_e32 v168, 16, v61
	v_and_b32_e32 v169, 0xffff0000, v61
	v_lshlrev_b32_e32 v170, 16, v93
	v_and_b32_e32 v171, 0xffff0000, v93
	v_mul_f32_e32 v170, s101, v170
	v_mul_f32_e32 v171, s101, v171
	v_fma_f32 v168, v170, v12, v168
	v_fma_f32 v169, v171, v13, v169
	v_fma_f32 v187, v168, v168, v187
	v_fma_f32 v187, v169, v169, v187
	v_cvt_pk_bf16_f32 v61, v168, v169
	v_lshlrev_b32_e32 v168, 16, v62
	v_and_b32_e32 v169, 0xffff0000, v62
	v_lshlrev_b32_e32 v170, 16, v94
	v_and_b32_e32 v171, 0xffff0000, v94
	v_mul_f32_e32 v170, s101, v170
	v_mul_f32_e32 v171, s101, v171
	v_fma_f32 v168, v170, v14, v168
	v_fma_f32 v169, v171, v15, v169
	v_fma_f32 v187, v168, v168, v187
	v_fma_f32 v187, v169, v169, v187
	v_cvt_pk_bf16_f32 v62, v168, v169
	v_lshlrev_b32_e32 v168, 16, v63
	v_and_b32_e32 v169, 0xffff0000, v63
	v_lshlrev_b32_e32 v170, 16, v95
	v_and_b32_e32 v171, 0xffff0000, v95
	v_mul_f32_e32 v170, s101, v170
	v_mul_f32_e32 v171, s101, v171
	v_fma_f32 v168, v170, v16, v168
	v_fma_f32 v169, v171, v17, v169
	v_fma_f32 v187, v168, v168, v187
	v_fma_f32 v187, v169, v169, v187
	v_cvt_pk_bf16_f32 v63, v168, v169
	global_store_dwordx4 v19, v[56:59], s[0:1] offset:2048
	global_store_dwordx4 v19, v[60:63], s[0:1] offset:3072
	s_nop 1
	v_add_f32_dpp v184, v184, v184 quad_perm:[1,0,3,2] row_mask:0xf bank_mask:0xf
	v_add_f32_dpp v185, v185, v185 quad_perm:[1,0,3,2] row_mask:0xf bank_mask:0xf
	v_add_f32_dpp v186, v186, v186 quad_perm:[1,0,3,2] row_mask:0xf bank_mask:0xf
	v_add_f32_dpp v187, v187, v187 quad_perm:[1,0,3,2] row_mask:0xf bank_mask:0xf
	v_add_f32_dpp v184, v184, v184 quad_perm:[2,3,0,1] row_mask:0xf bank_mask:0xf
	v_add_f32_dpp v185, v185, v185 quad_perm:[2,3,0,1] row_mask:0xf bank_mask:0xf
	v_add_f32_dpp v186, v186, v186 quad_perm:[2,3,0,1] row_mask:0xf bank_mask:0xf
	v_add_f32_dpp v187, v187, v187 quad_perm:[2,3,0,1] row_mask:0xf bank_mask:0xf
	v_add_f32_dpp v184, v184, v184 row_half_mirror row_mask:0xf bank_mask:0xf
	v_add_f32_dpp v185, v185, v185 row_half_mirror row_mask:0xf bank_mask:0xf
	v_add_f32_dpp v186, v186, v186 row_half_mirror row_mask:0xf bank_mask:0xf
	v_add_f32_dpp v187, v187, v187 row_half_mirror row_mask:0xf bank_mask:0xf
	v_add_f32_dpp v184, v184, v184 row_mirror row_mask:0xf bank_mask:0xf
	v_add_f32_dpp v185, v185, v185 row_mirror row_mask:0xf bank_mask:0xf
	v_add_f32_dpp v186, v186, v186 row_mirror row_mask:0xf bank_mask:0xf
	v_add_f32_dpp v187, v187, v187 row_mirror row_mask:0xf bank_mask:0xf
	v_add_f32_dpp v184, v184, v184 row_bcast:15 row_mask:0xa bank_mask:0xf
	v_add_f32_dpp v185, v185, v185 row_bcast:15 row_mask:0xa bank_mask:0xf
	v_add_f32_dpp v186, v186, v186 row_bcast:15 row_mask:0xa bank_mask:0xf
	v_add_f32_dpp v187, v187, v187 row_bcast:15 row_mask:0xa bank_mask:0xf
	v_add_f32_dpp v184, v184, v184 row_bcast:31 row_mask:0xc bank_mask:0xf
	v_add_f32_dpp v185, v185, v185 row_bcast:31 row_mask:0xc bank_mask:0xf
	v_add_f32_dpp v186, v186, v186 row_bcast:31 row_mask:0xc bank_mask:0xf
	v_add_f32_dpp v187, v187, v187 row_bcast:31 row_mask:0xc bank_mask:0xf
	s_nop 1
	v_readlane_b32 s3, v184, 63
	v_readlane_b32 s24, v185, 63
	v_readlane_b32 s98, v186, 63
	v_readlane_b32 s101, v187, 63
	s_nop 3
	v_writelane_b32 v188, s3, 0
	v_writelane_b32 v188, s24, 1
	v_writelane_b32 v188, s98, 2
	v_writelane_b32 v188, s101, 3
	s_nop 1
	v_mul_f32_e32 v188, 0x3a800000, v188
	v_add_f32_e32 v188, 0x358637bd, v188
	v_rsq_f32_e32 v188, v188
	s_mov_b64 exec, 15
	global_store_dword v21, v188, s[14:15]
	s_mov_b64 exec, -1
	s_waitcnt vmcnt(9)
; __device__ __forceinline__ float bf_lo(unsigned w) { return __uint_as_float(w << 16); }
; __device__ __forceinline__ float bf_hi(unsigned w) { return __uint_as_float(w & 0xffff0000u); }
; __device__ __forceinline__ unsigned pk2(float lo, float hi) { bf16x2_t r = __builtin_convertvector((f32x2_t){lo, hi}, bf16x2_t); return __builtin_bit_cast(unsigned, r); }
; template <bool SRC_F32, bool FINAL, int R> __device__ __forceinline__ void ew_compute(const EwSet<SRC_F32, R>& S, int rb, const f32x4 (&g)[4], bf16* hb_out, float* out32, float scale, float* rs_out, int lane) {
; #pragma unroll
;     for (int i = 0; i < R; ++i) {
;         float q = S.p[i];
;         q += __shfl_xor(q, 1); q += __shfl_xor(q, 2); q += __shfl_xor(q, 4); q += __shfl_xor(q, 8);
;         const float ss = __shfl(q, 0);
;         const float rs = scale / sqrtf(ss * (1.f / D) + EPS);
;         float s2 = 0.f;
; #pragma unroll
;         for (int j = 0; j < 4; ++j) {
;             f32x4 h;
;             if constexpr (SRC_F32) h = S.h32[i][j];
;             else { const v2u hw = S.hb[i][j]; h.x = bf_lo(hw.x); h.y = bf_hi(hw.x); h.z = bf_lo(hw.y); h.w = bf_hi(hw.y); }
;             const v2u fw = S.fw[i][j];
;             f32x4 v; v.x = h.x + bf_lo(fw.x) * rs * g[j].x; v.y = h.y + bf_hi(fw.x) * rs * g[j].y; v.z = h.z + bf_lo(fw.y) * rs * g[j].z; v.w = h.w + bf_hi(fw.y) * rs * g[j].w;
;             if (FINAL) __builtin_nontemporal_store(v, (f32x4*)(out32 + (size_t)(rb + i) * D) + lane + 64 * j);
;             else { v2u o; o.x = pk2(v.x, v.y); o.y = pk2(v.z, v.w); ((v2u*)(hb_out + (size_t)(rb + i) * D) + lane)[64 * j] = o; s2 += (v.x * v.x + v.y * v.y) + (v.z * v.z + v.w * v.w); }
	v_add_f32_dpp v164, v164, v164 quad_perm:[1,0,3,2] row_mask:0xf bank_mask:0xf
	s_nop 1
	v_add_f32_dpp v164, v164, v164 quad_perm:[2,3,0,1] row_mask:0xf bank_mask:0xf
	s_nop 1
	v_add_f32_dpp v164, v164, v164 row_half_mirror row_mask:0xf bank_mask:0xf
	s_nop 1
	v_add_f32_dpp v164, v164, v164 row_mirror row_mask:0xf bank_mask:0xf
	s_nop 1
	v_mul_f32_e32 v164, 0x3a800000, v164
	v_add_f32_e32 v164, 0x358637bd, v164
	v_rsq_f32_e32 v164, v164
	s_nop 0
	v_mul_f32_e32 v164, 0x3f000000, v164
	s_nop 0
	v_readlane_b32 s3, v164, 0
	v_readlane_b32 s24, v164, 16
	v_readlane_b32 s98, v164, 32
	v_readlane_b32 s101, v164, 48
	s_nop 1
	v_mov_b32_e32 v184, 0
	v_mov_b32_e32 v185, 0
	v_mov_b32_e32 v186, 0
	v_mov_b32_e32 v187, 0
	v_lshlrev_b32_e32 v168, 16, v100
	v_and_b32_e32 v169, 0xffff0000, v100
	v_lshlrev_b32_e32 v170, 16, v132
	v_and_b32_e32 v171, 0xffff0000, v132
	v_mul_f32_e32 v170, s3, v170
	v_mul_f32_e32 v171, s3, v171
	v_fma_f32 v168, v170, v2, v168
	v_fma_f32 v169, v171, v3, v169
	v_fma_f32 v184, v168, v168, v184
	v_fma_f32 v184, v169, v169, v184
	v_cvt_pk_bf16_f32 v100, v168, v169
	v_lshlrev_b32_e32 v168, 16, v101
	v_and_b32_e32 v169, 0xffff0000, v101
	v_lshlrev_b32_e32 v170, 16, v133
	v_and_b32_e32 v171, 0xffff0000, v133
	v_mul_f32_e32 v170, s3, v170
	v_mul_f32_e32 v171, s3, v171
	v_fma_f32 v168, v170, v4, v168
	v_fma_f32 v169, v171, v5, v169
	v_fma_f32 v184, v168, v168, v184
	v_fma_f32 v184, v169, v169, v184
	v_cvt_pk_bf16_f32 v101, v168, v169
	v_lshlrev_b32_e32 v168, 16, v102
	v_and_b32_e32 v169, 0xffff0000, v102
	v_lshlrev_b32_e32 v170, 16, v134
	v_and_b32_e32 v171, 0xffff0000, v134
	v_mul_f32_e32 v170, s3, v170
	v_mul_f32_e32 v171, s3, v171
	v_fma_f32 v168, v170, v6, v168
	v_fma_f32 v169, v171, v7, v169
	v_fma_f32 v184, v168, v168, v184
	v_fma_f32 v184, v169, v169, v184
	v_cvt_pk_bf16_f32 v102, v168, v169
	v_lshlrev_b32_e32 v168, 16, v103
	v_and_b32_e32 v169, 0xffff0000, v103
	v_lshlrev_b32_e32 v170, 16, v135
	v_and_b32_e32 v171, 0xffff0000, v135
	v_mul_f32_e32 v170, s3, v170
	v_mul_f32_e32 v171, s3, v171
	v_fma_f32 v168, v170, v8, v168
	v_fma_f32 v169, v171, v9, v169
	v_fma_f32 v184, v168, v168, v184
	v_fma_f32 v184, v169, v169, v184
	v_cvt_pk_bf16_f32 v103, v168, v169
	v_lshlrev_b32_e32 v168, 16, v104
	v_and_b32_e32 v169, 0xffff0000, v104
	v_lshlrev_b32_e32 v170, 16, v136
	v_and_b32_e32 v171, 0xffff0000, v136
	v_mul_f32_e32 v170, s3, v170
	v_mul_f32_e32 v171, s3, v171
	v_fma_f32 v168, v170, v10, v168
	v_fma_f32 v169, v171, v11, v169
	v_fma_f32 v184, v168, v168, v184
	v_fma_f32 v184, v169, v169, v184
	v_cvt_pk_bf16_f32 v104, v168, v169
	v_lshlrev_b32_e32 v168, 16, v105
	v_and_b32_e32 v169, 0xffff0000, v105
	v_lshlrev_b32_e32 v170, 16, v137
	v_and_b32_e32 v171, 0xffff0000, v137
	v_mul_f32_e32 v170, s3, v170
	v_mul_f32_e32 v171, s3, v171
	v_fma_f32 v168, v170, v12, v168
	v_fma_f32 v169, v171, v13, v169
	v_fma_f32 v184, v168, v168, v184
	v_fma_f32 v184, v169, v169, v184
	v_cvt_pk_bf16_f32 v105, v168, v169
	v_lshlrev_b32_e32 v168, 16, v106
	v_and_b32_e32 v169, 0xffff0000, v106
	v_lshlrev_b32_e32 v170, 16, v138
	v_and_b32_e32 v171, 0xffff0000, v138
	v_mul_f32_e32 v170, s3, v170
	v_mul_f32_e32 v171, s3, v171
	v_fma_f32 v168, v170, v14, v168
	v_fma_f32 v169, v171, v15, v169
	v_fma_f32 v184, v168, v168, v184
	v_fma_f32 v184, v169, v169, v184
	v_cvt_pk_bf16_f32 v106, v168, v169
	v_lshlrev_b32_e32 v168, 16, v107
	v_and_b32_e32 v169, 0xffff0000, v107
	v_lshlrev_b32_e32 v170, 16, v139
	v_and_b32_e32 v171, 0xffff0000, v139
	v_mul_f32_e32 v170, s3, v170
	v_mul_f32_e32 v171, s3, v171
	v_fma_f32 v168, v170, v16, v168
	v_fma_f32 v169, v171, v17, v169
	v_fma_f32 v184, v168, v168, v184
	v_fma_f32 v184, v169, v169, v184
	v_cvt_pk_bf16_f32 v107, v168, v169
	global_store_dwordx4 v23, v[100:103], s[0:1]
	global_store_dwordx4 v23, v[104:107], s[0:1] offset:1024
	v_lshlrev_b32_e32 v168, 16, v108
	v_and_b32_e32 v169, 0xffff0000, v108
	v_lshlrev_b32_e32 v170, 16, v140
	v_and_b32_e32 v171, 0xffff0000, v140
	v_mul_f32_e32 v170, s24, v170
	v_mul_f32_e32 v171, s24, v171
	v_fma_f32 v168, v170, v2, v168
	v_fma_f32 v169, v171, v3, v169
	v_fma_f32 v185, v168, v168, v185
	v_fma_f32 v185, v169, v169, v185
	v_cvt_pk_bf16_f32 v108, v168, v169
	v_lshlrev_b32_e32 v168, 16, v109
	v_and_b32_e32 v169, 0xffff0000, v109
	v_lshlrev_b32_e32 v170, 16, v141
	v_and_b32_e32 v171, 0xffff0000, v141
	v_mul_f32_e32 v170, s24, v170
	v_mul_f32_e32 v171, s24, v171
	v_fma_f32 v168, v170, v4, v168
	v_fma_f32 v169, v171, v5, v169
	v_fma_f32 v185, v168, v168, v185
	v_fma_f32 v185, v169, v169, v185
	v_cvt_pk_bf16_f32 v109, v168, v169
	v_lshlrev_b32_e32 v168, 16, v110
	v_and_b32_e32 v169, 0xffff0000, v110
	v_lshlrev_b32_e32 v170, 16, v142
	v_and_b32_e32 v171, 0xffff0000, v142
	v_mul_f32_e32 v170, s24, v170
	v_mul_f32_e32 v171, s24, v171
	v_fma_f32 v168, v170, v6, v168
	v_fma_f32 v169, v171, v7, v169
	v_fma_f32 v185, v168, v168, v185
	v_fma_f32 v185, v169, v169, v185
	v_cvt_pk_bf16_f32 v110, v168, v169
	v_lshlrev_b32_e32 v168, 16, v111
	v_and_b32_e32 v169, 0xffff0000, v111
	v_lshlrev_b32_e32 v170, 16, v143
	v_and_b32_e32 v171, 0xffff0000, v143
	v_mul_f32_e32 v170, s24, v170
	v_mul_f32_e32 v171, s24, v171
	v_fma_f32 v168, v170, v8, v168
	v_fma_f32 v169, v171, v9, v169
	v_fma_f32 v185, v168, v168, v185
	v_fma_f32 v185, v169, v169, v185
	v_cvt_pk_bf16_f32 v111, v168, v169
	v_lshlrev_b32_e32 v168, 16, v112
	v_and_b32_e32 v169, 0xffff0000, v112
	v_lshlrev_b32_e32 v170, 16, v144
	v_and_b32_e32 v171, 0xffff0000, v144
	v_mul_f32_e32 v170, s24, v170
	v_mul_f32_e32 v171, s24, v171
	v_fma_f32 v168, v170, v10, v168
	v_fma_f32 v169, v171, v11, v169
	v_fma_f32 v185, v168, v168, v185
	v_fma_f32 v185, v169, v169, v185
; __device__ __forceinline__ float bf_lo(unsigned w) { return __uint_as_float(w << 16); }
; __device__ __forceinline__ float bf_hi(unsigned w) { return __uint_as_float(w & 0xffff0000u); }
; __device__ __forceinline__ unsigned pk2(float lo, float hi) { bf16x2_t r = __builtin_convertvector((f32x2_t){lo, hi}, bf16x2_t); return __builtin_bit_cast(unsigned, r); }
; template <bool SRC_F32, bool FINAL, int R> __device__ __forceinline__ void ew_compute(const EwSet<SRC_F32, R>& S, int rb, const f32x4 (&g)[4], bf16* hb_out, float* out32, float scale, float* rs_out, int lane) {
;     ...
; #pragma unroll
;         for (int j = 0; j < 4; ++j) {
;             f32x4 h;
;             if constexpr (SRC_F32) h = S.h32[i][j];
;             else { const v2u hw = S.hb[i][j]; h.x = bf_lo(hw.x); h.y = bf_hi(hw.x); h.z = bf_lo(hw.y); h.w = bf_hi(hw.y); }
;             const v2u fw = S.fw[i][j];
;             f32x4 v; v.x = h.x + bf_lo(fw.x) * rs * g[j].x; v.y = h.y + bf_hi(fw.x) * rs * g[j].y; v.z = h.z + bf_lo(fw.y) * rs * g[j].z; v.w = h.w + bf_hi(fw.y) * rs * g[j].w;
;             if (FINAL) __builtin_nontemporal_store(v, (f32x4*)(out32 + (size_t)(rb + i) * D) + lane + 64 * j);
;             else { v2u o; o.x = pk2(v.x, v.y); o.y = pk2(v.z, v.w); ((v2u*)(hb_out + (size_t)(rb + i) * D) + lane)[64 * j] = o; s2 += (v.x * v.x + v.y * v.y) + (v.z * v.z + v.w * v.w); }
	v_cvt_pk_bf16_f32 v112, v168, v169
	v_lshlrev_b32_e32 v168, 16, v113
	v_and_b32_e32 v169, 0xffff0000, v113
	v_lshlrev_b32_e32 v170, 16, v145
	v_and_b32_e32 v171, 0xffff0000, v145
	v_mul_f32_e32 v170, s24, v170
	v_mul_f32_e32 v171, s24, v171
	v_fma_f32 v168, v170, v12, v168
	v_fma_f32 v169, v171, v13, v169
	v_fma_f32 v185, v168, v168, v185
	v_fma_f32 v185, v169, v169, v185
	v_cvt_pk_bf16_f32 v113, v168, v169
	v_lshlrev_b32_e32 v168, 16, v114
	v_and_b32_e32 v169, 0xffff0000, v114
	v_lshlrev_b32_e32 v170, 16, v146
	v_and_b32_e32 v171, 0xffff0000, v146
	v_mul_f32_e32 v170, s24, v170
	v_mul_f32_e32 v171, s24, v171
	v_fma_f32 v168, v170, v14, v168
	v_fma_f32 v169, v171, v15, v169
	v_fma_f32 v185, v168, v168, v185
	v_fma_f32 v185, v169, v169, v185
	v_cvt_pk_bf16_f32 v114, v168, v169
	v_lshlrev_b32_e32 v168, 16, v115
	v_and_b32_e32 v169, 0xffff0000, v115
	v_lshlrev_b32_e32 v170, 16, v147
	v_and_b32_e32 v171, 0xffff0000, v147
	v_mul_f32_e32 v170, s24, v170
	v_mul_f32_e32 v171, s24, v171
	v_fma_f32 v168, v170, v16, v168
	v_fma_f32 v169, v171, v17, v169
	v_fma_f32 v185, v168, v168, v185
	v_fma_f32 v185, v169, v169, v185
	v_cvt_pk_bf16_f32 v115, v168, v169
	global_store_dwordx4 v23, v[108:111], s[0:1] offset:2048
	global_store_dwordx4 v23, v[112:115], s[0:1] offset:3072
	v_lshlrev_b32_e32 v168, 16, v116
	v_and_b32_e32 v169, 0xffff0000, v116
	v_lshlrev_b32_e32 v170, 16, v148
	v_and_b32_e32 v171, 0xffff0000, v148
	v_mul_f32_e32 v170, s98, v170
	v_mul_f32_e32 v171, s98, v171
	v_fma_f32 v168, v170, v2, v168
	v_fma_f32 v169, v171, v3, v169
	v_fma_f32 v186, v168, v168, v186
	v_fma_f32 v186, v169, v169, v186
	v_cvt_pk_bf16_f32 v116, v168, v169
	v_lshlrev_b32_e32 v168, 16, v117
	v_and_b32_e32 v169, 0xffff0000, v117
	v_lshlrev_b32_e32 v170, 16, v149
	v_and_b32_e32 v171, 0xffff0000, v149
	v_mul_f32_e32 v170, s98, v170
	v_mul_f32_e32 v171, s98, v171
	v_fma_f32 v168, v170, v4, v168
	v_fma_f32 v169, v171, v5, v169
	v_fma_f32 v186, v168, v168, v186
	v_fma_f32 v186, v169, v169, v186
	v_cvt_pk_bf16_f32 v117, v168, v169
	v_lshlrev_b32_e32 v168, 16, v118
	v_and_b32_e32 v169, 0xffff0000, v118
	v_lshlrev_b32_e32 v170, 16, v150
	v_and_b32_e32 v171, 0xffff0000, v150
	v_mul_f32_e32 v170, s98, v170
	v_mul_f32_e32 v171, s98, v171
	v_fma_f32 v168, v170, v6, v168
	v_fma_f32 v169, v171, v7, v169
	v_fma_f32 v186, v168, v168, v186
	v_fma_f32 v186, v169, v169, v186
	v_cvt_pk_bf16_f32 v118, v168, v169
	v_lshlrev_b32_e32 v168, 16, v119
	v_and_b32_e32 v169, 0xffff0000, v119
	v_lshlrev_b32_e32 v170, 16, v151
	v_and_b32_e32 v171, 0xffff0000, v151
	v_mul_f32_e32 v170, s98, v170
	v_mul_f32_e32 v171, s98, v171
	v_fma_f32 v168, v170, v8, v168
	v_fma_f32 v169, v171, v9, v169
	v_fma_f32 v186, v168, v168, v186
	v_fma_f32 v186, v169, v169, v186
	v_cvt_pk_bf16_f32 v119, v168, v169
	v_lshlrev_b32_e32 v168, 16, v120
	v_and_b32_e32 v169, 0xffff0000, v120
	v_lshlrev_b32_e32 v170, 16, v152
	v_and_b32_e32 v171, 0xffff0000, v152
	v_mul_f32_e32 v170, s98, v170
	v_mul_f32_e32 v171, s98, v171
	v_fma_f32 v168, v170, v10, v168
	v_fma_f32 v169, v171, v11, v169
	v_fma_f32 v186, v168, v168, v186
	v_fma_f32 v186, v169, v169, v186
	v_cvt_pk_bf16_f32 v120, v168, v169
	v_lshlrev_b32_e32 v168, 16, v121
	v_and_b32_e32 v169, 0xffff0000, v121
	v_lshlrev_b32_e32 v170, 16, v153
	v_and_b32_e32 v171, 0xffff0000, v153
	v_mul_f32_e32 v170, s98, v170
	v_mul_f32_e32 v171, s98, v171
	v_fma_f32 v168, v170, v12, v168
	v_fma_f32 v169, v171, v13, v169
	v_fma_f32 v186, v168, v168, v186
	v_fma_f32 v186, v169, v169, v186
	v_cvt_pk_bf16_f32 v121, v168, v169
	v_lshlrev_b32_e32 v168, 16, v122
	v_and_b32_e32 v169, 0xffff0000, v122
	v_lshlrev_b32_e32 v170, 16, v154
	v_and_b32_e32 v171, 0xffff0000, v154
	v_mul_f32_e32 v170, s98, v170
	v_mul_f32_e32 v171, s98, v171
	v_fma_f32 v168, v170, v14, v168
	v_fma_f32 v169, v171, v15, v169
	v_fma_f32 v186, v168, v168, v186
	v_fma_f32 v186, v169, v169, v186
	v_cvt_pk_bf16_f32 v122, v168, v169
	v_lshlrev_b32_e32 v168, 16, v123
	v_and_b32_e32 v169, 0xffff0000, v123
	v_lshlrev_b32_e32 v170, 16, v155
	v_and_b32_e32 v171, 0xffff0000, v155
	v_mul_f32_e32 v170, s98, v170
	v_mul_f32_e32 v171, s98, v171
	v_fma_f32 v168, v170, v16, v168
	v_fma_f32 v169, v171, v17, v169
	v_fma_f32 v186, v168, v168, v186
	v_fma_f32 v186, v169, v169, v186
	v_cvt_pk_bf16_f32 v123, v168, v169
	global_store_dwordx4 v24, v[116:119], s[0:1]
	global_store_dwordx4 v24, v[120:123], s[0:1] offset:1024
	v_lshlrev_b32_e32 v168, 16, v124
	v_and_b32_e32 v169, 0xffff0000, v124
	v_lshlrev_b32_e32 v170, 16, v156
	v_and_b32_e32 v171, 0xffff0000, v156
	v_mul_f32_e32 v170, s101, v170
	v_mul_f32_e32 v171, s101, v171
	v_fma_f32 v168, v170, v2, v168
	v_fma_f32 v169, v171, v3, v169
	v_fma_f32 v187, v168, v168, v187
	v_fma_f32 v187, v169, v169, v187
	v_cvt_pk_bf16_f32 v124, v168, v169
	v_lshlrev_b32_e32 v168, 16, v125
	v_and_b32_e32 v169, 0xffff0000, v125
	v_lshlrev_b32_e32 v170, 16, v157
	v_and_b32_e32 v171, 0xffff0000, v157
	v_mul_f32_e32 v170, s101, v170
	v_mul_f32_e32 v171, s101, v171
	v_fma_f32 v168, v170, v4, v168
	v_fma_f32 v169, v171, v5, v169
	v_fma_f32 v187, v168, v168, v187
; template <bool SRC_F32, bool FINAL, int R> __device__ __forceinline__ void ew_compute(const EwSet<SRC_F32, R>& S, int rb, const f32x4 (&g)[4], bf16* hb_out, float* out32, float scale, float* rs_out, int lane) {
;     ...
; #pragma unroll
;         for (int j = 0; j < 4; ++j) {
;             f32x4 h;
;             if constexpr (SRC_F32) h = S.h32[i][j];
;             else { const v2u hw = S.hb[i][j]; h.x = bf_lo(hw.x); h.y = bf_hi(hw.x); h.z = bf_lo(hw.y); h.w = bf_hi(hw.y); }
;             const v2u fw = S.fw[i][j];
;             f32x4 v; v.x = h.x + bf_lo(fw.x) * rs * g[j].x; v.y = h.y + bf_hi(fw.x) * rs * g[j].y; v.z = h.z + bf_lo(fw.y) * rs * g[j].z; v.w = h.w + bf_hi(fw.y) * rs * g[j].w;
;             if (FINAL) __builtin_nontemporal_store(v, (f32x4*)(out32 + (size_t)(rb + i) * D) + lane + 64 * j);
;             else { v2u o; o.x = pk2(v.x, v.y); o.y = pk2(v.z, v.w); ((v2u*)(hb_out + (size_t)(rb + i) * D) + lane)[64 * j] = o; s2 += (v.x * v.x + v.y * v.y) + (v.z * v.z + v.w * v.w); }
;         }
;         if (!FINAL) { const float tot = wave_sum(s2); if (lane == 0) rs_out[rb + i] = 1.0f / sqrtf(tot * (1.f / D) + EPS); }
;     }
; __device__ __forceinline__ void xcd_barrier(const XcdBarrier& b) {
;     asm volatile("s_waitcnt vmcnt(0)" ::: "memory");
;     __syncthreads();
;     if (threadIdx.x == 0) {
;         unsigned* bar = b.bar;
;         __builtin_amdgcn_s_waitcnt(0);
;         unsigned nloc = b.st[0], nx = b.st[1];
;         if (nloc == 0u) { xcd_barrier_complete(bar, b.x, nloc, nx); b.st[0] = nloc; b.st[1] = nx; }
;         const unsigned old = xb_add(&bar[XB_XSUB(b.x)], 1u);
;         const unsigned gen = old / nloc;
;         if (old + 1u == (gen + 1u) * nloc) {
;             __builtin_amdgcn_fence(__ATOMIC_RELEASE, "agent");
;             asm volatile("s_waitcnt vmcnt(0)" ::: "memory");
;             const unsigned og = xb_add(&bar[XB_TOP], 1u);
;             const unsigned tg = og / nx;
;             if (og + 1u == (tg + 1u) * nx) xb_add(&bar[XB_TOPGEN], 1u);
;             else XB_SPIN(xb_ld(&bar[XB_TOPGEN]) == tg, bar);
;             __builtin_amdgcn_fence(__ATOMIC_ACQUIRE, "agent");
;             xb_add(&bar[XB_XGEN(b.x)], 1u);
;             asm volatile("s_waitcnt vmcnt(0)" ::: "memory");
;         } else {
;             XB_SPIN(xb_ld(&bar[XB_XGEN(b.x)]) == gen, bar);
;             __builtin_amdgcn_fence(__ATOMIC_ACQUIRE, "agent");
	v_fma_f32 v187, v169, v169, v187
	v_cvt_pk_bf16_f32 v125, v168, v169
	v_lshlrev_b32_e32 v168, 16, v126
	v_and_b32_e32 v169, 0xffff0000, v126
	v_lshlrev_b32_e32 v170, 16, v158
	v_and_b32_e32 v171, 0xffff0000, v158
	v_mul_f32_e32 v170, s101, v170
	v_mul_f32_e32 v171, s101, v171
	v_fma_f32 v168, v170, v6, v168
	v_fma_f32 v169, v171, v7, v169
	v_fma_f32 v187, v168, v168, v187
	v_fma_f32 v187, v169, v169, v187
	v_cvt_pk_bf16_f32 v126, v168, v169
	v_lshlrev_b32_e32 v168, 16, v127
	v_and_b32_e32 v169, 0xffff0000, v127
	v_lshlrev_b32_e32 v170, 16, v159
	v_and_b32_e32 v171, 0xffff0000, v159
	v_mul_f32_e32 v170, s101, v170
	v_mul_f32_e32 v171, s101, v171
	v_fma_f32 v168, v170, v8, v168
	v_fma_f32 v169, v171, v9, v169
	v_fma_f32 v187, v168, v168, v187
	v_fma_f32 v187, v169, v169, v187
	v_cvt_pk_bf16_f32 v127, v168, v169
	v_lshlrev_b32_e32 v168, 16, v128
	v_and_b32_e32 v169, 0xffff0000, v128
	v_lshlrev_b32_e32 v170, 16, v160
	v_and_b32_e32 v171, 0xffff0000, v160
	v_mul_f32_e32 v170, s101, v170
	v_mul_f32_e32 v171, s101, v171
	v_fma_f32 v168, v170, v10, v168
	v_fma_f32 v169, v171, v11, v169
	v_fma_f32 v187, v168, v168, v187
	v_fma_f32 v187, v169, v169, v187
	v_cvt_pk_bf16_f32 v128, v168, v169
	v_lshlrev_b32_e32 v168, 16, v129
	v_and_b32_e32 v169, 0xffff0000, v129
	v_lshlrev_b32_e32 v170, 16, v161
	v_and_b32_e32 v171, 0xffff0000, v161
	v_mul_f32_e32 v170, s101, v170
	v_mul_f32_e32 v171, s101, v171
	v_fma_f32 v168, v170, v12, v168
	v_fma_f32 v169, v171, v13, v169
	v_fma_f32 v187, v168, v168, v187
	v_fma_f32 v187, v169, v169, v187
	v_cvt_pk_bf16_f32 v129, v168, v169
	v_lshlrev_b32_e32 v168, 16, v130
	v_and_b32_e32 v169, 0xffff0000, v130
	v_lshlrev_b32_e32 v170, 16, v162
	v_and_b32_e32 v171, 0xffff0000, v162
	v_mul_f32_e32 v170, s101, v170
	v_mul_f32_e32 v171, s101, v171
	v_fma_f32 v168, v170, v14, v168
	v_fma_f32 v169, v171, v15, v169
	v_fma_f32 v187, v168, v168, v187
	v_fma_f32 v187, v169, v169, v187
	v_cvt_pk_bf16_f32 v130, v168, v169
	v_lshlrev_b32_e32 v168, 16, v131
	v_and_b32_e32 v169, 0xffff0000, v131
	v_lshlrev_b32_e32 v170, 16, v163
	v_and_b32_e32 v171, 0xffff0000, v163
	v_mul_f32_e32 v170, s101, v170
	v_mul_f32_e32 v171, s101, v171
	v_fma_f32 v168, v170, v16, v168
	v_fma_f32 v169, v171, v17, v169
	v_fma_f32 v187, v168, v168, v187
	v_fma_f32 v187, v169, v169, v187
	v_cvt_pk_bf16_f32 v131, v168, v169
	global_store_dwordx4 v24, v[124:127], s[0:1] offset:2048
	global_store_dwordx4 v24, v[128:131], s[0:1] offset:3072
	s_nop 1
	v_add_f32_dpp v184, v184, v184 quad_perm:[1,0,3,2] row_mask:0xf bank_mask:0xf
	v_add_f32_dpp v185, v185, v185 quad_perm:[1,0,3,2] row_mask:0xf bank_mask:0xf
	v_add_f32_dpp v186, v186, v186 quad_perm:[1,0,3,2] row_mask:0xf bank_mask:0xf
	v_add_f32_dpp v187, v187, v187 quad_perm:[1,0,3,2] row_mask:0xf bank_mask:0xf
	v_add_f32_dpp v184, v184, v184 quad_perm:[2,3,0,1] row_mask:0xf bank_mask:0xf
	v_add_f32_dpp v185, v185, v185 quad_perm:[2,3,0,1] row_mask:0xf bank_mask:0xf
	v_add_f32_dpp v186, v186, v186 quad_perm:[2,3,0,1] row_mask:0xf bank_mask:0xf
	v_add_f32_dpp v187, v187, v187 quad_perm:[2,3,0,1] row_mask:0xf bank_mask:0xf
	v_add_f32_dpp v184, v184, v184 row_half_mirror row_mask:0xf bank_mask:0xf
	v_add_f32_dpp v185, v185, v185 row_half_mirror row_mask:0xf bank_mask:0xf
	v_add_f32_dpp v186, v186, v186 row_half_mirror row_mask:0xf bank_mask:0xf
	v_add_f32_dpp v187, v187, v187 row_half_mirror row_mask:0xf bank_mask:0xf
	v_add_f32_dpp v184, v184, v184 row_mirror row_mask:0xf bank_mask:0xf
	v_add_f32_dpp v185, v185, v185 row_mirror row_mask:0xf bank_mask:0xf
	v_add_f32_dpp v186, v186, v186 row_mirror row_mask:0xf bank_mask:0xf
	v_add_f32_dpp v187, v187, v187 row_mirror row_mask:0xf bank_mask:0xf
	v_add_f32_dpp v184, v184, v184 row_bcast:15 row_mask:0xa bank_mask:0xf
	v_add_f32_dpp v185, v185, v185 row_bcast:15 row_mask:0xa bank_mask:0xf
	v_add_f32_dpp v186, v186, v186 row_bcast:15 row_mask:0xa bank_mask:0xf
	v_add_f32_dpp v187, v187, v187 row_bcast:15 row_mask:0xa bank_mask:0xf
	v_add_f32_dpp v184, v184, v184 row_bcast:31 row_mask:0xc bank_mask:0xf
	v_add_f32_dpp v185, v185, v185 row_bcast:31 row_mask:0xc bank_mask:0xf
	v_add_f32_dpp v186, v186, v186 row_bcast:31 row_mask:0xc bank_mask:0xf
	v_add_f32_dpp v187, v187, v187 row_bcast:31 row_mask:0xc bank_mask:0xf
	s_nop 1
	v_readlane_b32 s3, v184, 63
	v_readlane_b32 s24, v185, 63
	v_readlane_b32 s98, v186, 63
	v_readlane_b32 s101, v187, 63
	s_nop 3
	v_writelane_b32 v188, s3, 0
	v_writelane_b32 v188, s24, 1
	v_writelane_b32 v188, s98, 2
	v_writelane_b32 v188, s101, 3
	s_nop 1
	v_mul_f32_e32 v188, 0x3a800000, v188
	v_add_f32_e32 v188, 0x358637bd, v188
	v_rsq_f32_e32 v188, v188
	s_mov_b64 exec, 15
	global_store_dword v26, v188, s[14:15]
	s_mov_b64 exec, -1
.LBB0_432:
	s_cmp_gt_i32 s31, 4
	s_cselect_b64 s[0:1], -1, 0
	s_and_b64 s[4:5], s[12:13], s[0:1]
	s_andn2_b64 vcc, exec, s[4:5]
	s_cbranch_vccnz .LBB0_482
	s_waitcnt vmcnt(0)
	s_barrier
	v_cmp_eq_u32_e32 vcc, 0, v195
	s_and_saveexec_b64 s[4:5], vcc
	s_cbranch_execz .Ltb482_done
	s_cmp_eq_u32 s99, 1
	s_cbranch_scc1 .Ltb482_fast
	buffer_wbl2 sc1
	s_waitcnt vmcnt(0)

; __global__ void __launch_bounds__(NWAVES * 64, 2) mk_fwd(Args a) {
;     ...
;     if (IN(4)) { pg8::Gemm g{XN, WIN, M, DIN, D}; pg8::StaticOrder S; S.init(M, DIN, G, bid); EpiIn E{S1, RS, lds}; rs_table_fill(lds, S, RS);
;         pg8::gemm_phase<EpiIn, pg8::StaticOrder, true, true, NT_WIDE, ZZ, PEELK>(lds, g, S, E); }
.Ltb482_done:
	s_or_b64 exec, exec, s[4:5]
	s_barrier
.LBB0_482:
	s_cmp_lt_i32 s30, 5
	s_cselect_b64 s[4:5], -1, 0
	s_and_b64 s[12:13], s[4:5], s[0:1]
	s_andn2_b64 vcc, exec, s[12:13]
	s_cbranch_vccnz .LBB0_625
	s_mov_b32 s6, -1
	s_ashr_i32 s3, s2, 31
	s_mov_b32 s7, s6
	s_ashr_i32 s54, s33, 31
	s_waitcnt vmcnt(0)
	v_mov_b64_e32 v[0:1], 0xa00
	v_mov_b64_e32 v[2:3], 0x9ff
	s_movk_i32 s9, 0x141
	s_mov_b64 s[22:23], s[2:3]
	s_mov_b32 s8, s6
	s_mov_b64 s[14:15], s[6:7]
	s_branch .LBB0_486

; __device__ __forceinline__ unsigned xb_ld(unsigned* p)              { return __hip_atomic_load(p, __ATOMIC_RELAXED, __HIP_MEMORY_SCOPE_AGENT); }
; __device__ __forceinline__ unsigned xb_add(unsigned* p, unsigned v) { return __hip_atomic_fetch_add(p, v, __ATOMIC_RELAXED, __HIP_MEMORY_SCOPE_AGENT); }
; #define XB_SPIN(cond, bar) do { unsigned _sp = 0; while (cond) { __builtin_amdgcn_s_sleep(1); \
;     if ((++_sp & 255u) == 0u) { if (xb_ld(&(bar)[XB_TMO])) break; if (_sp > XB_SPIN_CAP) { atomicAdd(&(bar)[XB_TMO], 1u); break; } } } } while (0)
; __device__ __forceinline__ void xcd_barrier(const XcdBarrier& b) {
;     asm volatile("s_waitcnt vmcnt(0)" ::: "memory");
;     __syncthreads();
;     if (threadIdx.x == 0) {
;         unsigned* bar = b.bar;
;         __builtin_amdgcn_s_waitcnt(0);
;         unsigned nloc = b.st[0], nx = b.st[1];
;         if (nloc == 0u) { xcd_barrier_complete(bar, b.x, nloc, nx); b.st[0] = nloc; b.st[1] = nx; }
;         const unsigned old = xb_add(&bar[XB_XSUB(b.x)], 1u);
;         const unsigned gen = old / nloc;
;         if (old + 1u == (gen + 1u) * nloc) {
;             __builtin_amdgcn_fence(__ATOMIC_RELEASE, "agent");
;             asm volatile("s_waitcnt vmcnt(0)" ::: "memory");
;             const unsigned og = xb_add(&bar[XB_TOP], 1u);
;             const unsigned tg = og / nx;
;             if (og + 1u == (tg + 1u) * nx) xb_add(&bar[XB_TOPGEN], 1u);
;             else XB_SPIN(xb_ld(&bar[XB_TOPGEN]) == tg, bar);
;             __builtin_amdgcn_fence(__ATOMIC_ACQUIRE, "agent");
;             xb_add(&bar[XB_XGEN(b.x)], 1u);
;             asm volatile("s_waitcnt vmcnt(0)" ::: "memory");
;         } else {
;             XB_SPIN(xb_ld(&bar[XB_XGEN(b.x)]) == gen, bar);
;             __builtin_amdgcn_fence(__ATOMIC_ACQUIRE, "agent");
;             asm volatile("s_waitcnt vmcnt(0)" ::: "memory");
;         }
;     }
;     __syncthreads();
; }
.LBB0_893:
	s_cmp_gt_i32 s31, 8
	s_cselect_b64 s[0:1], -1, 0
	s_and_b64 s[4:5], s[4:5], s[0:1]
	s_andn2_b64 vcc, exec, s[4:5]
	s_cbranch_vccnz .LBB0_943
	s_waitcnt vmcnt(0)
	s_barrier
	v_cmp_eq_u32_e32 vcc, 0, v195
	s_and_saveexec_b64 s[4:5], vcc
	s_cbranch_execz .Ltb943_done
	s_cmp_eq_u32 s99, 1
	s_cbranch_scc1 .Ltb943_fast
	buffer_wbl2 sc1
	s_waitcnt vmcnt(0)

; template <bool SRC_F32, int R> __device__ __forceinline__ void ew_load(EwSet<SRC_F32, R>& S, int rb, const float* hsrc32, const bf16* hsrcb, const bf16* f, const float* part, int lane) {
; #pragma unroll
;     for (int i = 0; i < R; ++i) S.p[i] = (lane < 16) ? part[(size_t)(rb + i) * 16 + lane] : 0.f;
; #pragma unroll
;     for (int i = 0; i < R; ++i)
; #pragma unroll
;         for (int j = 0; j < 4; ++j) {
;             S.fw[i][j] = ((const v2u*)(f + (size_t)(rb + i) * D) + lane)[64 * j];
;             if constexpr (SRC_F32) S.h32[i][j] = __builtin_nontemporal_load((const f32x4*)(hsrc32 + (size_t)(rb + i) * D) + lane + 64 * j);
;             else S.hb[i][j] = ((const v2u*)(hsrcb + (size_t)(rb + i) * D) + lane)[64 * j];
;         }
; }
; template <bool SRC_F32, bool FINAL, int R> __device__ __forceinline__ void ew_compute(const EwSet<SRC_F32, R>& S, int rb, const f32x4 (&g)[4], bf16* hb_out, float* out32, float scale, float* rs_out, int lane) {
; #pragma unroll
;     for (int i = 0; i < R; ++i) {
;         float q = S.p[i];
;         q += __shfl_xor(q, 1); q += __shfl_xor(q, 2); q += __shfl_xor(q, 4); q += __shfl_xor(q, 8);
;         const float ss = __shfl(q, 0);
;         const float rs = scale / sqrtf(ss * (1.f / D) + EPS);
; template <bool SRC_F32, bool FINAL> __device__ __forceinline__ void ew_phase(const float* hsrc32, const bf16* hsrcb, bf16* hb_out, float* out32, const bf16* f, const float* part, const float* gpost, float scale, float* rs_out, int gw, int NGW, int lane) {
;     constexpr int R = SRC_F32 ? 2 : 4;
;     f32x4 g[4];
; #pragma unroll
;     for (int j = 0; j < 4; ++j) g[j] = ((const f32x4*)gpost + lane)[64 * j];
;     const int step = NGW * R;
;     EwSet<SRC_F32, R> A, B;
;     int rb = gw * R;
;     if (rb < M) ew_load<SRC_F32, R>(A, rb, hsrc32, hsrcb, f, part, lane);
.LBB0_943:
	s_cmp_lt_i32 s30, 9
	s_cselect_b64 s[4:5], -1, 0
	s_and_b64 s[8:9], s[4:5], s[0:1]
	s_andn2_b64 vcc, exec, s[8:9]
	s_cbranch_vccnz .LBB0_989
	s_waitcnt vmcnt(0) lgkmcnt(0)
	s_add_u32 s22, s84, 0xffffff10
	s_addc_u32 s23, s85, -1
	s_load_dwordx2 s[26:27], s[22:23], 0x88
	s_add_u32 s0, s28, 0x5000000
	s_addc_u32 s1, s29, 0
	s_add_u32 s4, s28, 0x11000000
	s_addc_u32 s5, s29, 0
	s_add_u32 s6, s28, 0x3700000
	s_addc_u32 s7, s29, 0
	s_add_u32 s14, s28, 0x3910000
	s_addc_u32 s15, s29, 0
	v_and_b32_e32 v0, 63, v195
	v_lshlrev_b32_e32 v1, 5, v0
	s_waitcnt lgkmcnt(0)
	global_load_dwordx4 v[2:5], v1, s[26:27]
	global_load_dwordx4 v[6:9], v1, s[26:27] offset:16
	global_load_dwordx4 v[10:13], v1, s[26:27] offset:2048
	global_load_dwordx4 v[14:17], v1, s[26:27] offset:2064
	s_and_b32 s26, s2, 7
	s_lshl_b32 s26, s26, 4
	s_bfe_u32 s27, s2, 0x30003
	s_add_u32 s26, s26, s27
	s_lshl_b32 s26, s26, 8
	s_lshr_b32 s27, s2, 6
	s_lshl_b32 s27, s27, 6
	s_add_u32 s26, s26, s27
	v_readfirstlane_b32 s27, v195
	s_lshr_b32 s27, s27, 6
	s_lshl_b32 s27, s27, 3
	s_add_u32 s26, s26, s27
	s_add_u32 s27, s26, 0
	s_lshl_b32 s22, s27, 11
	v_lshl_add_u32 v18, v0, 4, s22
	v_add_u32_e32 v19, 0x1000, v18
	s_lshl_b32 s22, s27, 6
	v_lshl_add_u32 v20, v0, 2, s22
	s_lshl_b32 s22, s27, 2
	v_lshl_add_u32 v21, v0, 2, s22
	global_load_dwordx4 v[32:35], v18, s[0:1]
	global_load_dwordx4 v[36:39], v18, s[0:1] offset:1024
	global_load_dwordx4 v[64:67], v18, s[4:5]
	global_load_dwordx4 v[68:71], v18, s[4:5] offset:1024
	global_load_dwordx4 v[40:43], v18, s[0:1] offset:2048
	global_load_dwordx4 v[44:47], v18, s[0:1] offset:3072
	global_load_dwordx4 v[72:75], v18, s[4:5] offset:2048
	global_load_dwordx4 v[76:79], v18, s[4:5] offset:3072
	global_load_dwordx4 v[48:51], v19, s[0:1]
	global_load_dwordx4 v[52:55], v19, s[0:1] offset:1024
	global_load_dwordx4 v[80:83], v19, s[4:5]
	global_load_dwordx4 v[84:87], v19, s[4:5] offset:1024
	global_load_dwordx4 v[56:59], v19, s[0:1] offset:2048
	global_load_dwordx4 v[60:63], v19, s[0:1] offset:3072
	global_load_dwordx4 v[88:91], v19, s[4:5] offset:2048
	global_load_dwordx4 v[92:95], v19, s[4:5] offset:3072
	global_load_dword v96, v20, s[6:7]
	s_add_u32 s27, s26, 4
	s_lshl_b32 s22, s27, 11
	v_lshl_add_u32 v23, v0, 4, s22
	v_add_u32_e32 v24, 0x1000, v23
	s_lshl_b32 s22, s27, 6
	v_lshl_add_u32 v25, v0, 2, s22
	s_lshl_b32 s22, s27, 2
	v_lshl_add_u32 v26, v0, 2, s22
	global_load_dwordx4 v[100:103], v23, s[0:1]
	global_load_dwordx4 v[104:107], v23, s[0:1] offset:1024
	global_load_dwordx4 v[132:135], v23, s[4:5]
	global_load_dwordx4 v[136:139], v23, s[4:5] offset:1024
	global_load_dwordx4 v[108:111], v23, s[0:1] offset:2048
	global_load_dwordx4 v[112:115], v23, s[0:1] offset:3072
	global_load_dwordx4 v[140:143], v23, s[4:5] offset:2048
	global_load_dwordx4 v[144:147], v23, s[4:5] offset:3072
	global_load_dwordx4 v[116:119], v24, s[0:1]
	global_load_dwordx4 v[120:123], v24, s[0:1] offset:1024
	global_load_dwordx4 v[148:151], v24, s[4:5]
	global_load_dwordx4 v[152:155], v24, s[4:5] offset:1024
	global_load_dwordx4 v[124:127], v24, s[0:1] offset:2048
	global_load_dwordx4 v[128:131], v24, s[0:1] offset:3072
	global_load_dwordx4 v[156:159], v24, s[4:5] offset:2048
	global_load_dwordx4 v[160:163], v24, s[4:5] offset:3072
	global_load_dword v164, v25, s[6:7]
	s_waitcnt vmcnt(17)
	v_add_f32_dpp v96, v96, v96 quad_perm:[1,0,3,2] row_mask:0xf bank_mask:0xf
	s_nop 1
	v_add_f32_dpp v96, v96, v96 quad_perm:[2,3,0,1] row_mask:0xf bank_mask:0xf
	s_nop 1
	v_add_f32_dpp v96, v96, v96 row_half_mirror row_mask:0xf bank_mask:0xf
	s_nop 1
	v_add_f32_dpp v96, v96, v96 row_mirror row_mask:0xf bank_mask:0xf
	s_nop 1
	v_mul_f32_e32 v96, 0x3a800000, v96
	v_add_f32_e32 v96, 0x358637bd, v96
	v_rsq_f32_e32 v96, v96
	s_nop 0
	v_readlane_b32 s3, v96, 0
	v_readlane_b32 s24, v96, 16
	v_readlane_b32 s98, v96, 32
	v_readlane_b32 s101, v96, 48
	s_nop 1
	v_mov_b32_e32 v184, 0
	v_mov_b32_e32 v185, 0
	v_mov_b32_e32 v186, 0
	v_mov_b32_e32 v187, 0
	v_lshlrev_b32_e32 v168, 16, v32
	v_and_b32_e32 v169, 0xffff0000, v32
	v_lshlrev_b32_e32 v170, 16, v64
	v_and_b32_e32 v171, 0xffff0000, v64
	v_mul_f32_e32 v170, s3, v170
	v_mul_f32_e32 v171, s3, v171
	v_fma_f32 v168, v170, v2, v168
	v_fma_f32 v169, v171, v3, v169
	v_fma_f32 v184, v168, v168, v184
	v_fma_f32 v184, v169, v169, v184
	v_cvt_pk_bf16_f32 v32, v168, v169
	v_lshlrev_b32_e32 v168, 16, v33
	v_and_b32_e32 v169, 0xffff0000, v33
	v_lshlrev_b32_e32 v170, 16, v65
	v_and_b32_e32 v171, 0xffff0000, v65
	v_mul_f32_e32 v170, s3, v170
	v_mul_f32_e32 v171, s3, v171
	v_fma_f32 v168, v170, v4, v168
	v_fma_f32 v169, v171, v5, v169
	v_fma_f32 v184, v168, v168, v184
	v_fma_f32 v184, v169, v169, v184
	v_cvt_pk_bf16_f32 v33, v168, v169
	v_lshlrev_b32_e32 v168, 16, v34
	v_and_b32_e32 v169, 0xffff0000, v34
	v_lshlrev_b32_e32 v170, 16, v66
	v_and_b32_e32 v171, 0xffff0000, v66
	v_mul_f32_e32 v170, s3, v170
	v_mul_f32_e32 v171, s3, v171
	v_fma_f32 v168, v170, v6, v168
	v_fma_f32 v169, v171, v7, v169
	v_fma_f32 v184, v168, v168, v184
	v_fma_f32 v184, v169, v169, v184
	v_cvt_pk_bf16_f32 v34, v168, v169
	v_lshlrev_b32_e32 v168, 16, v35
	v_and_b32_e32 v169, 0xffff0000, v35
	v_lshlrev_b32_e32 v170, 16, v67
	v_and_b32_e32 v171, 0xffff0000, v67
	v_mul_f32_e32 v170, s3, v170
	v_mul_f32_e32 v171, s3, v171
	v_fma_f32 v168, v170, v8, v168
	v_fma_f32 v169, v171, v9, v169
	v_fma_f32 v184, v168, v168, v184
	v_fma_f32 v184, v169, v169, v184
	v_cvt_pk_bf16_f32 v35, v168, v169
	v_lshlrev_b32_e32 v168, 16, v36
	v_and_b32_e32 v169, 0xffff0000, v36
	v_lshlrev_b32_e32 v170, 16, v68
	v_and_b32_e32 v171, 0xffff0000, v68
	v_mul_f32_e32 v170, s3, v170
	v_mul_f32_e32 v171, s3, v171
; __device__ __forceinline__ float bf_lo(unsigned w) { return __uint_as_float(w << 16); }
; __device__ __forceinline__ float bf_hi(unsigned w) { return __uint_as_float(w & 0xffff0000u); }
; __device__ __forceinline__ unsigned pk2(float lo, float hi) { bf16x2_t r = __builtin_convertvector((f32x2_t){lo, hi}, bf16x2_t); return __builtin_bit_cast(unsigned, r); }
; template <bool SRC_F32, bool FINAL, int R> __device__ __forceinline__ void ew_compute(const EwSet<SRC_F32, R>& S, int rb, const f32x4 (&g)[4], bf16* hb_out, float* out32, float scale, float* rs_out, int lane) {
;     ...
; #pragma unroll
;         for (int j = 0; j < 4; ++j) {
;             f32x4 h;
;             if constexpr (SRC_F32) h = S.h32[i][j];
;             else { const v2u hw = S.hb[i][j]; h.x = bf_lo(hw.x); h.y = bf_hi(hw.x); h.z = bf_lo(hw.y); h.w = bf_hi(hw.y); }
;             const v2u fw = S.fw[i][j];
;             f32x4 v; v.x = h.x + bf_lo(fw.x) * rs * g[j].x; v.y = h.y + bf_hi(fw.x) * rs * g[j].y; v.z = h.z + bf_lo(fw.y) * rs * g[j].z; v.w = h.w + bf_hi(fw.y) * rs * g[j].w;
;             if (FINAL) __builtin_nontemporal_store(v, (f32x4*)(out32 + (size_t)(rb + i) * D) + lane + 64 * j);
;             else { v2u o; o.x = pk2(v.x, v.y); o.y = pk2(v.z, v.w); ((v2u*)(hb_out + (size_t)(rb + i) * D) + lane)[64 * j] = o; s2 += (v.x * v.x + v.y * v.y) + (v.z * v.z + v.w * v.w); }
	v_fma_f32 v168, v170, v10, v168
	v_fma_f32 v169, v171, v11, v169
	v_fma_f32 v184, v168, v168, v184
	v_fma_f32 v184, v169, v169, v184
	v_cvt_pk_bf16_f32 v36, v168, v169
	v_lshlrev_b32_e32 v168, 16, v37
	v_and_b32_e32 v169, 0xffff0000, v37
	v_lshlrev_b32_e32 v170, 16, v69
	v_and_b32_e32 v171, 0xffff0000, v69
	v_mul_f32_e32 v170, s3, v170
	v_mul_f32_e32 v171, s3, v171
	v_fma_f32 v168, v170, v12, v168
	v_fma_f32 v169, v171, v13, v169
	v_fma_f32 v184, v168, v168, v184
	v_fma_f32 v184, v169, v169, v184
	v_cvt_pk_bf16_f32 v37, v168, v169
	v_lshlrev_b32_e32 v168, 16, v38
	v_and_b32_e32 v169, 0xffff0000, v38
	v_lshlrev_b32_e32 v170, 16, v70
	v_and_b32_e32 v171, 0xffff0000, v70
	v_mul_f32_e32 v170, s3, v170
	v_mul_f32_e32 v171, s3, v171
	v_fma_f32 v168, v170, v14, v168
	v_fma_f32 v169, v171, v15, v169
	v_fma_f32 v184, v168, v168, v184
	v_fma_f32 v184, v169, v169, v184
	v_cvt_pk_bf16_f32 v38, v168, v169
	v_lshlrev_b32_e32 v168, 16, v39
	v_and_b32_e32 v169, 0xffff0000, v39
	v_lshlrev_b32_e32 v170, 16, v71
	v_and_b32_e32 v171, 0xffff0000, v71
	v_mul_f32_e32 v170, s3, v170
	v_mul_f32_e32 v171, s3, v171
	v_fma_f32 v168, v170, v16, v168
	v_fma_f32 v169, v171, v17, v169
	v_fma_f32 v184, v168, v168, v184
	v_fma_f32 v184, v169, v169, v184
	v_cvt_pk_bf16_f32 v39, v168, v169
	global_store_dwordx4 v18, v[32:35], s[0:1]
	global_store_dwordx4 v18, v[36:39], s[0:1] offset:1024
	v_lshlrev_b32_e32 v168, 16, v40
	v_and_b32_e32 v169, 0xffff0000, v40
	v_lshlrev_b32_e32 v170, 16, v72
	v_and_b32_e32 v171, 0xffff0000, v72
	v_mul_f32_e32 v170, s24, v170
	v_mul_f32_e32 v171, s24, v171
	v_fma_f32 v168, v170, v2, v168
	v_fma_f32 v169, v171, v3, v169
	v_fma_f32 v185, v168, v168, v185
	v_fma_f32 v185, v169, v169, v185
	v_cvt_pk_bf16_f32 v40, v168, v169
	v_lshlrev_b32_e32 v168, 16, v41
	v_and_b32_e32 v169, 0xffff0000, v41
	v_lshlrev_b32_e32 v170, 16, v73
	v_and_b32_e32 v171, 0xffff0000, v73
	v_mul_f32_e32 v170, s24, v170
	v_mul_f32_e32 v171, s24, v171
	v_fma_f32 v168, v170, v4, v168
	v_fma_f32 v169, v171, v5, v169
	v_fma_f32 v185, v168, v168, v185
	v_fma_f32 v185, v169, v169, v185
	v_cvt_pk_bf16_f32 v41, v168, v169
	v_lshlrev_b32_e32 v168, 16, v42
	v_and_b32_e32 v169, 0xffff0000, v42
	v_lshlrev_b32_e32 v170, 16, v74
	v_and_b32_e32 v171, 0xffff0000, v74
	v_mul_f32_e32 v170, s24, v170
	v_mul_f32_e32 v171, s24, v171
	v_fma_f32 v168, v170, v6, v168
	v_fma_f32 v169, v171, v7, v169
	v_fma_f32 v185, v168, v168, v185
	v_fma_f32 v185, v169, v169, v185
	v_cvt_pk_bf16_f32 v42, v168, v169
	v_lshlrev_b32_e32 v168, 16, v43
	v_and_b32_e32 v169, 0xffff0000, v43
	v_lshlrev_b32_e32 v170, 16, v75
	v_and_b32_e32 v171, 0xffff0000, v75
	v_mul_f32_e32 v170, s24, v170
	v_mul_f32_e32 v171, s24, v171
	v_fma_f32 v168, v170, v8, v168
	v_fma_f32 v169, v171, v9, v169
	v_fma_f32 v185, v168, v168, v185
	v_fma_f32 v185, v169, v169, v185
	v_cvt_pk_bf16_f32 v43, v168, v169
	v_lshlrev_b32_e32 v168, 16, v44
	v_and_b32_e32 v169, 0xffff0000, v44
	v_lshlrev_b32_e32 v170, 16, v76
	v_and_b32_e32 v171, 0xffff0000, v76
	v_mul_f32_e32 v170, s24, v170
	v_mul_f32_e32 v171, s24, v171
	v_fma_f32 v168, v170, v10, v168
	v_fma_f32 v169, v171, v11, v169
	v_fma_f32 v185, v168, v168, v185
	v_fma_f32 v185, v169, v169, v185
	v_cvt_pk_bf16_f32 v44, v168, v169
	v_lshlrev_b32_e32 v168, 16, v45
	v_and_b32_e32 v169, 0xffff0000, v45
	v_lshlrev_b32_e32 v170, 16, v77
	v_and_b32_e32 v171, 0xffff0000, v77
	v_mul_f32_e32 v170, s24, v170
	v_mul_f32_e32 v171, s24, v171
	v_fma_f32 v168, v170, v12, v168
	v_fma_f32 v169, v171, v13, v169
	v_fma_f32 v185, v168, v168, v185
	v_fma_f32 v185, v169, v169, v185
	v_cvt_pk_bf16_f32 v45, v168, v169
	v_lshlrev_b32_e32 v168, 16, v46
	v_and_b32_e32 v169, 0xffff0000, v46
	v_lshlrev_b32_e32 v170, 16, v78
	v_and_b32_e32 v171, 0xffff0000, v78
	v_mul_f32_e32 v170, s24, v170
	v_mul_f32_e32 v171, s24, v171
	v_fma_f32 v168, v170, v14, v168
	v_fma_f32 v169, v171, v15, v169
	v_fma_f32 v185, v168, v168, v185
	v_fma_f32 v185, v169, v169, v185
	v_cvt_pk_bf16_f32 v46, v168, v169
	v_lshlrev_b32_e32 v168, 16, v47
	v_and_b32_e32 v169, 0xffff0000, v47
	v_lshlrev_b32_e32 v170, 16, v79
	v_and_b32_e32 v171, 0xffff0000, v79
	v_mul_f32_e32 v170, s24, v170
	v_mul_f32_e32 v171, s24, v171
	v_fma_f32 v168, v170, v16, v168
	v_fma_f32 v169, v171, v17, v169
	v_fma_f32 v185, v168, v168, v185
	v_fma_f32 v185, v169, v169, v185
	v_cvt_pk_bf16_f32 v47, v168, v169
	global_store_dwordx4 v18, v[40:43], s[0:1] offset:2048
	global_store_dwordx4 v18, v[44:47], s[0:1] offset:3072
	v_lshlrev_b32_e32 v168, 16, v48
	v_and_b32_e32 v169, 0xffff0000, v48
	v_lshlrev_b32_e32 v170, 16, v80
	v_and_b32_e32 v171, 0xffff0000, v80
	v_mul_f32_e32 v170, s98, v170
	v_mul_f32_e32 v171, s98, v171
	v_fma_f32 v168, v170, v2, v168
	v_fma_f32 v169, v171, v3, v169
	v_fma_f32 v186, v168, v168, v186
	v_fma_f32 v186, v169, v169, v186
	v_cvt_pk_bf16_f32 v48, v168, v169
	v_lshlrev_b32_e32 v168, 16, v49
	v_and_b32_e32 v169, 0xffff0000, v49
	v_lshlrev_b32_e32 v170, 16, v81
	v_and_b32_e32 v171, 0xffff0000, v81
	v_mul_f32_e32 v170, s98, v170
	v_mul_f32_e32 v171, s98, v171
	v_fma_f32 v168, v170, v4, v168
	v_fma_f32 v169, v171, v5, v169
	v_fma_f32 v186, v168, v168, v186
	v_fma_f32 v186, v169, v169, v186
	v_cvt_pk_bf16_f32 v49, v168, v169
	v_lshlrev_b32_e32 v168, 16, v50
	v_and_b32_e32 v169, 0xffff0000, v50
	v_lshlrev_b32_e32 v170, 16, v82
	v_and_b32_e32 v171, 0xffff0000, v82
	v_mul_f32_e32 v170, s98, v170
	v_mul_f32_e32 v171, s98, v171
	v_fma_f32 v168, v170, v6, v168
	v_fma_f32 v169, v171, v7, v169
	v_fma_f32 v186, v168, v168, v186
	v_fma_f32 v186, v169, v169, v186
	v_cvt_pk_bf16_f32 v50, v168, v169
	v_lshlrev_b32_e32 v168, 16, v51
	v_and_b32_e32 v169, 0xffff0000, v51
; __device__ __forceinline__ float bf_lo(unsigned w) { return __uint_as_float(w << 16); }
; __device__ __forceinline__ float bf_hi(unsigned w) { return __uint_as_float(w & 0xffff0000u); }
; __device__ __forceinline__ unsigned pk2(float lo, float hi) { bf16x2_t r = __builtin_convertvector((f32x2_t){lo, hi}, bf16x2_t); return __builtin_bit_cast(unsigned, r); }
; template <bool SRC_F32, bool FINAL, int R> __device__ __forceinline__ void ew_compute(const EwSet<SRC_F32, R>& S, int rb, const f32x4 (&g)[4], bf16* hb_out, float* out32, float scale, float* rs_out, int lane) {
;     ...
; #pragma unroll
;         for (int j = 0; j < 4; ++j) {
;             f32x4 h;
;             if constexpr (SRC_F32) h = S.h32[i][j];
;             else { const v2u hw = S.hb[i][j]; h.x = bf_lo(hw.x); h.y = bf_hi(hw.x); h.z = bf_lo(hw.y); h.w = bf_hi(hw.y); }
;             const v2u fw = S.fw[i][j];
;             f32x4 v; v.x = h.x + bf_lo(fw.x) * rs * g[j].x; v.y = h.y + bf_hi(fw.x) * rs * g[j].y; v.z = h.z + bf_lo(fw.y) * rs * g[j].z; v.w = h.w + bf_hi(fw.y) * rs * g[j].w;
;             if (FINAL) __builtin_nontemporal_store(v, (f32x4*)(out32 + (size_t)(rb + i) * D) + lane + 64 * j);
;             else { v2u o; o.x = pk2(v.x, v.y); o.y = pk2(v.z, v.w); ((v2u*)(hb_out + (size_t)(rb + i) * D) + lane)[64 * j] = o; s2 += (v.x * v.x + v.y * v.y) + (v.z * v.z + v.w * v.w); }
;         }
;         if (!FINAL) { const float tot = wave_sum(s2); if (lane == 0) rs_out[rb + i] = 1.0f / sqrtf(tot * (1.f / D) + EPS); }
	v_lshlrev_b32_e32 v170, 16, v83
	v_and_b32_e32 v171, 0xffff0000, v83
	v_mul_f32_e32 v170, s98, v170
	v_mul_f32_e32 v171, s98, v171
	v_fma_f32 v168, v170, v8, v168
	v_fma_f32 v169, v171, v9, v169
	v_fma_f32 v186, v168, v168, v186
	v_fma_f32 v186, v169, v169, v186
	v_cvt_pk_bf16_f32 v51, v168, v169
	v_lshlrev_b32_e32 v168, 16, v52
	v_and_b32_e32 v169, 0xffff0000, v52
	v_lshlrev_b32_e32 v170, 16, v84
	v_and_b32_e32 v171, 0xffff0000, v84
	v_mul_f32_e32 v170, s98, v170
	v_mul_f32_e32 v171, s98, v171
	v_fma_f32 v168, v170, v10, v168
	v_fma_f32 v169, v171, v11, v169
	v_fma_f32 v186, v168, v168, v186
	v_fma_f32 v186, v169, v169, v186
	v_cvt_pk_bf16_f32 v52, v168, v169
	v_lshlrev_b32_e32 v168, 16, v53
	v_and_b32_e32 v169, 0xffff0000, v53
	v_lshlrev_b32_e32 v170, 16, v85
	v_and_b32_e32 v171, 0xffff0000, v85
	v_mul_f32_e32 v170, s98, v170
	v_mul_f32_e32 v171, s98, v171
	v_fma_f32 v168, v170, v12, v168
	v_fma_f32 v169, v171, v13, v169
	v_fma_f32 v186, v168, v168, v186
	v_fma_f32 v186, v169, v169, v186
	v_cvt_pk_bf16_f32 v53, v168, v169
	v_lshlrev_b32_e32 v168, 16, v54
	v_and_b32_e32 v169, 0xffff0000, v54
	v_lshlrev_b32_e32 v170, 16, v86
	v_and_b32_e32 v171, 0xffff0000, v86
	v_mul_f32_e32 v170, s98, v170
	v_mul_f32_e32 v171, s98, v171
	v_fma_f32 v168, v170, v14, v168
	v_fma_f32 v169, v171, v15, v169
	v_fma_f32 v186, v168, v168, v186
	v_fma_f32 v186, v169, v169, v186
	v_cvt_pk_bf16_f32 v54, v168, v169
	v_lshlrev_b32_e32 v168, 16, v55
	v_and_b32_e32 v169, 0xffff0000, v55
	v_lshlrev_b32_e32 v170, 16, v87
	v_and_b32_e32 v171, 0xffff0000, v87
	v_mul_f32_e32 v170, s98, v170
	v_mul_f32_e32 v171, s98, v171
	v_fma_f32 v168, v170, v16, v168
	v_fma_f32 v169, v171, v17, v169
	v_fma_f32 v186, v168, v168, v186
	v_fma_f32 v186, v169, v169, v186
	v_cvt_pk_bf16_f32 v55, v168, v169
	global_store_dwordx4 v19, v[48:51], s[0:1]
	global_store_dwordx4 v19, v[52:55], s[0:1] offset:1024
	v_lshlrev_b32_e32 v168, 16, v56
	v_and_b32_e32 v169, 0xffff0000, v56
	v_lshlrev_b32_e32 v170, 16, v88
	v_and_b32_e32 v171, 0xffff0000, v88
	v_mul_f32_e32 v170, s101, v170
	v_mul_f32_e32 v171, s101, v171
	v_fma_f32 v168, v170, v2, v168
	v_fma_f32 v169, v171, v3, v169
	v_fma_f32 v187, v168, v168, v187
	v_fma_f32 v187, v169, v169, v187
	v_cvt_pk_bf16_f32 v56, v168, v169
	v_lshlrev_b32_e32 v168, 16, v57
	v_and_b32_e32 v169, 0xffff0000, v57
	v_lshlrev_b32_e32 v170, 16, v89
	v_and_b32_e32 v171, 0xffff0000, v89
	v_mul_f32_e32 v170, s101, v170
	v_mul_f32_e32 v171, s101, v171
	v_fma_f32 v168, v170, v4, v168
	v_fma_f32 v169, v171, v5, v169
	v_fma_f32 v187, v168, v168, v187
	v_fma_f32 v187, v169, v169, v187
	v_cvt_pk_bf16_f32 v57, v168, v169
	v_lshlrev_b32_e32 v168, 16, v58
	v_and_b32_e32 v169, 0xffff0000, v58
	v_lshlrev_b32_e32 v170, 16, v90
	v_and_b32_e32 v171, 0xffff0000, v90
	v_mul_f32_e32 v170, s101, v170
	v_mul_f32_e32 v171, s101, v171
	v_fma_f32 v168, v170, v6, v168
	v_fma_f32 v169, v171, v7, v169
	v_fma_f32 v187, v168, v168, v187
	v_fma_f32 v187, v169, v169, v187
	v_cvt_pk_bf16_f32 v58, v168, v169
	v_lshlrev_b32_e32 v168, 16, v59
	v_and_b32_e32 v169, 0xffff0000, v59
	v_lshlrev_b32_e32 v170, 16, v91
	v_and_b32_e32 v171, 0xffff0000, v91
	v_mul_f32_e32 v170, s101, v170
	v_mul_f32_e32 v171, s101, v171
	v_fma_f32 v168, v170, v8, v168
	v_fma_f32 v169, v171, v9, v169
	v_fma_f32 v187, v168, v168, v187
	v_fma_f32 v187, v169, v169, v187
	v_cvt_pk_bf16_f32 v59, v168, v169
	v_lshlrev_b32_e32 v168, 16, v60
	v_and_b32_e32 v169, 0xffff0000, v60
	v_lshlrev_b32_e32 v170, 16, v92
	v_and_b32_e32 v171, 0xffff0000, v92
	v_mul_f32_e32 v170, s101, v170
	v_mul_f32_e32 v171, s101, v171
	v_fma_f32 v168, v170, v10, v168
	v_fma_f32 v169, v171, v11, v169
	v_fma_f32 v187, v168, v168, v187
	v_fma_f32 v187, v169, v169, v187
	v_cvt_pk_bf16_f32 v60, v168, v169
	v_lshlrev_b32_e32 v168, 16, v61
	v_and_b32_e32 v169, 0xffff0000, v61
	v_lshlrev_b32_e32 v170, 16, v93
	v_and_b32_e32 v171, 0xffff0000, v93
	v_mul_f32_e32 v170, s101, v170
	v_mul_f32_e32 v171, s101, v171
	v_fma_f32 v168, v170, v12, v168
	v_fma_f32 v169, v171, v13, v169
	v_fma_f32 v187, v168, v168, v187
	v_fma_f32 v187, v169, v169, v187
	v_cvt_pk_bf16_f32 v61, v168, v169
	v_lshlrev_b32_e32 v168, 16, v62
	v_and_b32_e32 v169, 0xffff0000, v62
	v_lshlrev_b32_e32 v170, 16, v94
	v_and_b32_e32 v171, 0xffff0000, v94
	v_mul_f32_e32 v170, s101, v170
	v_mul_f32_e32 v171, s101, v171
	v_fma_f32 v168, v170, v14, v168
	v_fma_f32 v169, v171, v15, v169
	v_fma_f32 v187, v168, v168, v187
	v_fma_f32 v187, v169, v169, v187
	v_cvt_pk_bf16_f32 v62, v168, v169
	v_lshlrev_b32_e32 v168, 16, v63
	v_and_b32_e32 v169, 0xffff0000, v63
	v_lshlrev_b32_e32 v170, 16, v95
	v_and_b32_e32 v171, 0xffff0000, v95
	v_mul_f32_e32 v170, s101, v170
	v_mul_f32_e32 v171, s101, v171
	v_fma_f32 v168, v170, v16, v168
	v_fma_f32 v169, v171, v17, v169
	v_fma_f32 v187, v168, v168, v187
	v_fma_f32 v187, v169, v169, v187
	v_cvt_pk_bf16_f32 v63, v168, v169
	global_store_dwordx4 v19, v[56:59], s[0:1] offset:2048
	global_store_dwordx4 v19, v[60:63], s[0:1] offset:3072
	s_nop 1
	v_add_f32_dpp v184, v184, v184 quad_perm:[1,0,3,2] row_mask:0xf bank_mask:0xf
	v_add_f32_dpp v185, v185, v185 quad_perm:[1,0,3,2] row_mask:0xf bank_mask:0xf
	v_add_f32_dpp v186, v186, v186 quad_perm:[1,0,3,2] row_mask:0xf bank_mask:0xf
	v_add_f32_dpp v187, v187, v187 quad_perm:[1,0,3,2] row_mask:0xf bank_mask:0xf
	v_add_f32_dpp v184, v184, v184 quad_perm:[2,3,0,1] row_mask:0xf bank_mask:0xf
	v_add_f32_dpp v185, v185, v185 quad_perm:[2,3,0,1] row_mask:0xf bank_mask:0xf
	v_add_f32_dpp v186, v186, v186 quad_perm:[2,3,0,1] row_mask:0xf bank_mask:0xf
	v_add_f32_dpp v187, v187, v187 quad_perm:[2,3,0,1] row_mask:0xf bank_mask:0xf
; __device__ __forceinline__ float bf_lo(unsigned w) { return __uint_as_float(w << 16); }
; __device__ __forceinline__ float bf_hi(unsigned w) { return __uint_as_float(w & 0xffff0000u); }
; template <bool SRC_F32, bool FINAL, int R> __device__ __forceinline__ void ew_compute(const EwSet<SRC_F32, R>& S, int rb, const f32x4 (&g)[4], bf16* hb_out, float* out32, float scale, float* rs_out, int lane) {
; #pragma unroll
;     for (int i = 0; i < R; ++i) {
;         float q = S.p[i];
;         q += __shfl_xor(q, 1); q += __shfl_xor(q, 2); q += __shfl_xor(q, 4); q += __shfl_xor(q, 8);
;         const float ss = __shfl(q, 0);
;         const float rs = scale / sqrtf(ss * (1.f / D) + EPS);
;         float s2 = 0.f;
; #pragma unroll
;         for (int j = 0; j < 4; ++j) {
;             f32x4 h;
;             if constexpr (SRC_F32) h = S.h32[i][j];
;             else { const v2u hw = S.hb[i][j]; h.x = bf_lo(hw.x); h.y = bf_hi(hw.x); h.z = bf_lo(hw.y); h.w = bf_hi(hw.y); }
;             const v2u fw = S.fw[i][j];
;             f32x4 v; v.x = h.x + bf_lo(fw.x) * rs * g[j].x; v.y = h.y + bf_hi(fw.x) * rs * g[j].y; v.z = h.z + bf_lo(fw.y) * rs * g[j].z; v.w = h.w + bf_hi(fw.y) * rs * g[j].w;
;             if (FINAL) __builtin_nontemporal_store(v, (f32x4*)(out32 + (size_t)(rb + i) * D) + lane + 64 * j);
;             else { v2u o; o.x = pk2(v.x, v.y); o.y = pk2(v.z, v.w); ((v2u*)(hb_out + (size_t)(rb + i) * D) + lane)[64 * j] = o; s2 += (v.x * v.x + v.y * v.y) + (v.z * v.z + v.w * v.w); }
;         }
;         if (!FINAL) { const float tot = wave_sum(s2); if (lane == 0) rs_out[rb + i] = 1.0f / sqrtf(tot * (1.f / D) + EPS); }
; template <bool SRC_F32, bool FINAL> __device__ __forceinline__ void ew_phase(const float* hsrc32, const bf16* hsrcb, bf16* hb_out, float* out32, const bf16* f, const float* part, const float* gpost, float scale, float* rs_out, int gw, int NGW, int lane) {
;     ...
; #pragma unroll 1
;     for (; rb < M; rb += 2 * step) {
;         const int nb = rb + step, nb2 = nb + step;
;         if (nb < M) ew_load<SRC_F32, R>(B, nb, hsrc32, hsrcb, f, part, lane);
;         ew_compute<SRC_F32, FINAL, R>(A, rb, g, hb_out, out32, scale, rs_out, lane);
;         if (nb2 < M) ew_load<SRC_F32, R>(A, nb2, hsrc32, hsrcb, f, part, lane);
;         if (nb < M) ew_compute<SRC_F32, FINAL, R>(B, nb, g, hb_out, out32, scale, rs_out, lane);
	v_add_f32_dpp v184, v184, v184 row_half_mirror row_mask:0xf bank_mask:0xf
	v_add_f32_dpp v185, v185, v185 row_half_mirror row_mask:0xf bank_mask:0xf
	v_add_f32_dpp v186, v186, v186 row_half_mirror row_mask:0xf bank_mask:0xf
	v_add_f32_dpp v187, v187, v187 row_half_mirror row_mask:0xf bank_mask:0xf
	v_add_f32_dpp v184, v184, v184 row_mirror row_mask:0xf bank_mask:0xf
	v_add_f32_dpp v185, v185, v185 row_mirror row_mask:0xf bank_mask:0xf
	v_add_f32_dpp v186, v186, v186 row_mirror row_mask:0xf bank_mask:0xf
	v_add_f32_dpp v187, v187, v187 row_mirror row_mask:0xf bank_mask:0xf
	v_add_f32_dpp v184, v184, v184 row_bcast:15 row_mask:0xa bank_mask:0xf
	v_add_f32_dpp v185, v185, v185 row_bcast:15 row_mask:0xa bank_mask:0xf
	v_add_f32_dpp v186, v186, v186 row_bcast:15 row_mask:0xa bank_mask:0xf
	v_add_f32_dpp v187, v187, v187 row_bcast:15 row_mask:0xa bank_mask:0xf
	v_add_f32_dpp v184, v184, v184 row_bcast:31 row_mask:0xc bank_mask:0xf
	v_add_f32_dpp v185, v185, v185 row_bcast:31 row_mask:0xc bank_mask:0xf
	v_add_f32_dpp v186, v186, v186 row_bcast:31 row_mask:0xc bank_mask:0xf
	v_add_f32_dpp v187, v187, v187 row_bcast:31 row_mask:0xc bank_mask:0xf
	s_nop 1
	v_readlane_b32 s3, v184, 63
	v_readlane_b32 s24, v185, 63
	v_readlane_b32 s98, v186, 63
	v_readlane_b32 s101, v187, 63
	s_nop 3
	v_writelane_b32 v188, s3, 0
	v_writelane_b32 v188, s24, 1
	v_writelane_b32 v188, s98, 2
	v_writelane_b32 v188, s101, 3
	s_nop 1
	v_mul_f32_e32 v188, 0x3a800000, v188
	v_add_f32_e32 v188, 0x358637bd, v188
	v_rsq_f32_e32 v188, v188
	s_mov_b64 exec, 15
	global_store_dword v21, v188, s[14:15]
	s_mov_b64 exec, -1
	s_add_u32 s27, s26, 2048
	s_lshl_b32 s22, s27, 11
	v_lshl_add_u32 v18, v0, 4, s22
	v_add_u32_e32 v19, 0x1000, v18
	s_lshl_b32 s22, s27, 6
	v_lshl_add_u32 v20, v0, 2, s22
	s_lshl_b32 s22, s27, 2
	v_lshl_add_u32 v21, v0, 2, s22
	global_load_dwordx4 v[32:35], v18, s[0:1]
	global_load_dwordx4 v[36:39], v18, s[0:1] offset:1024
	global_load_dwordx4 v[64:67], v18, s[4:5]
	global_load_dwordx4 v[68:71], v18, s[4:5] offset:1024
	global_load_dwordx4 v[40:43], v18, s[0:1] offset:2048
	global_load_dwordx4 v[44:47], v18, s[0:1] offset:3072
	global_load_dwordx4 v[72:75], v18, s[4:5] offset:2048
	global_load_dwordx4 v[76:79], v18, s[4:5] offset:3072
	global_load_dwordx4 v[48:51], v19, s[0:1]
	global_load_dwordx4 v[52:55], v19, s[0:1] offset:1024
	global_load_dwordx4 v[80:83], v19, s[4:5]
	global_load_dwordx4 v[84:87], v19, s[4:5] offset:1024
	global_load_dwordx4 v[56:59], v19, s[0:1] offset:2048
	global_load_dwordx4 v[60:63], v19, s[0:1] offset:3072
	global_load_dwordx4 v[88:91], v19, s[4:5] offset:2048
	global_load_dwordx4 v[92:95], v19, s[4:5] offset:3072
	global_load_dword v96, v20, s[6:7]
	s_waitcnt vmcnt(26)
	v_add_f32_dpp v164, v164, v164 quad_perm:[1,0,3,2] row_mask:0xf bank_mask:0xf
	s_nop 1
	v_add_f32_dpp v164, v164, v164 quad_perm:[2,3,0,1] row_mask:0xf bank_mask:0xf
	s_nop 1
	v_add_f32_dpp v164, v164, v164 row_half_mirror row_mask:0xf bank_mask:0xf
	s_nop 1
	v_add_f32_dpp v164, v164, v164 row_mirror row_mask:0xf bank_mask:0xf
	s_nop 1
	v_mul_f32_e32 v164, 0x3a800000, v164
	v_add_f32_e32 v164, 0x358637bd, v164
	v_rsq_f32_e32 v164, v164
	s_nop 0
	v_readlane_b32 s3, v164, 0
	v_readlane_b32 s24, v164, 16
	v_readlane_b32 s98, v164, 32
	v_readlane_b32 s101, v164, 48
	s_nop 1
	v_mov_b32_e32 v184, 0
	v_mov_b32_e32 v185, 0
	v_mov_b32_e32 v186, 0
	v_mov_b32_e32 v187, 0
	v_lshlrev_b32_e32 v168, 16, v100
	v_and_b32_e32 v169, 0xffff0000, v100
	v_lshlrev_b32_e32 v170, 16, v132
	v_and_b32_e32 v171, 0xffff0000, v132
	v_mul_f32_e32 v170, s3, v170
	v_mul_f32_e32 v171, s3, v171
	v_fma_f32 v168, v170, v2, v168
	v_fma_f32 v169, v171, v3, v169
	v_fma_f32 v184, v168, v168, v184
	v_fma_f32 v184, v169, v169, v184
	v_cvt_pk_bf16_f32 v100, v168, v169
	v_lshlrev_b32_e32 v168, 16, v101
	v_and_b32_e32 v169, 0xffff0000, v101
	v_lshlrev_b32_e32 v170, 16, v133
	v_and_b32_e32 v171, 0xffff0000, v133
	v_mul_f32_e32 v170, s3, v170
	v_mul_f32_e32 v171, s3, v171
	v_fma_f32 v168, v170, v4, v168
	v_fma_f32 v169, v171, v5, v169
	v_fma_f32 v184, v168, v168, v184
	v_fma_f32 v184, v169, v169, v184
	v_cvt_pk_bf16_f32 v101, v168, v169
	v_lshlrev_b32_e32 v168, 16, v102
	v_and_b32_e32 v169, 0xffff0000, v102
	v_lshlrev_b32_e32 v170, 16, v134
	v_and_b32_e32 v171, 0xffff0000, v134
	v_mul_f32_e32 v170, s3, v170
	v_mul_f32_e32 v171, s3, v171
	v_fma_f32 v168, v170, v6, v168
	v_fma_f32 v169, v171, v7, v169
	v_fma_f32 v184, v168, v168, v184
	v_fma_f32 v184, v169, v169, v184
	v_cvt_pk_bf16_f32 v102, v168, v169
	v_lshlrev_b32_e32 v168, 16, v103
	v_and_b32_e32 v169, 0xffff0000, v103
	v_lshlrev_b32_e32 v170, 16, v135
	v_and_b32_e32 v171, 0xffff0000, v135
	v_mul_f32_e32 v170, s3, v170
	v_mul_f32_e32 v171, s3, v171
	v_fma_f32 v168, v170, v8, v168
	v_fma_f32 v169, v171, v9, v169
	v_fma_f32 v184, v168, v168, v184
	v_fma_f32 v184, v169, v169, v184
	v_cvt_pk_bf16_f32 v103, v168, v169
	v_lshlrev_b32_e32 v168, 16, v104
	v_and_b32_e32 v169, 0xffff0000, v104
	v_lshlrev_b32_e32 v170, 16, v136
	v_and_b32_e32 v171, 0xffff0000, v136
	v_mul_f32_e32 v170, s3, v170
	v_mul_f32_e32 v171, s3, v171
	v_fma_f32 v168, v170, v10, v168
	v_fma_f32 v169, v171, v11, v169
	v_fma_f32 v184, v168, v168, v184
	v_fma_f32 v184, v169, v169, v184
	v_cvt_pk_bf16_f32 v104, v168, v169
	v_lshlrev_b32_e32 v168, 16, v105
	v_and_b32_e32 v169, 0xffff0000, v105
	v_lshlrev_b32_e32 v170, 16, v137
	v_and_b32_e32 v171, 0xffff0000, v137
	v_mul_f32_e32 v170, s3, v170
	v_mul_f32_e32 v171, s3, v171
	v_fma_f32 v168, v170, v12, v168
	v_fma_f32 v169, v171, v13, v169
	v_fma_f32 v184, v168, v168, v184
	v_fma_f32 v184, v169, v169, v184
	v_cvt_pk_bf16_f32 v105, v168, v169
; __device__ __forceinline__ float bf_lo(unsigned w) { return __uint_as_float(w << 16); }
; __device__ __forceinline__ float bf_hi(unsigned w) { return __uint_as_float(w & 0xffff0000u); }
; __device__ __forceinline__ unsigned pk2(float lo, float hi) { bf16x2_t r = __builtin_convertvector((f32x2_t){lo, hi}, bf16x2_t); return __builtin_bit_cast(unsigned, r); }
; template <bool SRC_F32, bool FINAL, int R> __device__ __forceinline__ void ew_compute(const EwSet<SRC_F32, R>& S, int rb, const f32x4 (&g)[4], bf16* hb_out, float* out32, float scale, float* rs_out, int lane) {
; #pragma unroll
;     for (int i = 0; i < R; ++i) {
;         float q = S.p[i];
;         q += __shfl_xor(q, 1); q += __shfl_xor(q, 2); q += __shfl_xor(q, 4); q += __shfl_xor(q, 8);
;         const float ss = __shfl(q, 0);
;         const float rs = scale / sqrtf(ss * (1.f / D) + EPS);
;         float s2 = 0.f;
; #pragma unroll
;         for (int j = 0; j < 4; ++j) {
;             f32x4 h;
;             if constexpr (SRC_F32) h = S.h32[i][j];
;             else { const v2u hw = S.hb[i][j]; h.x = bf_lo(hw.x); h.y = bf_hi(hw.x); h.z = bf_lo(hw.y); h.w = bf_hi(hw.y); }
;             const v2u fw = S.fw[i][j];
;             f32x4 v; v.x = h.x + bf_lo(fw.x) * rs * g[j].x; v.y = h.y + bf_hi(fw.x) * rs * g[j].y; v.z = h.z + bf_lo(fw.y) * rs * g[j].z; v.w = h.w + bf_hi(fw.y) * rs * g[j].w;
;             if (FINAL) __builtin_nontemporal_store(v, (f32x4*)(out32 + (size_t)(rb + i) * D) + lane + 64 * j);
;             else { v2u o; o.x = pk2(v.x, v.y); o.y = pk2(v.z, v.w); ((v2u*)(hb_out + (size_t)(rb + i) * D) + lane)[64 * j] = o; s2 += (v.x * v.x + v.y * v.y) + (v.z * v.z + v.w * v.w); }
;         }
;         if (!FINAL) { const float tot = wave_sum(s2); if (lane == 0) rs_out[rb + i] = 1.0f / sqrtf(tot * (1.f / D) + EPS); }
;     }
	v_lshlrev_b32_e32 v168, 16, v106
	v_and_b32_e32 v169, 0xffff0000, v106
	v_lshlrev_b32_e32 v170, 16, v138
	v_and_b32_e32 v171, 0xffff0000, v138
	v_mul_f32_e32 v170, s3, v170
	v_mul_f32_e32 v171, s3, v171
	v_fma_f32 v168, v170, v14, v168
	v_fma_f32 v169, v171, v15, v169
	v_fma_f32 v184, v168, v168, v184
	v_fma_f32 v184, v169, v169, v184
	v_cvt_pk_bf16_f32 v106, v168, v169
	v_lshlrev_b32_e32 v168, 16, v107
	v_and_b32_e32 v169, 0xffff0000, v107
	v_lshlrev_b32_e32 v170, 16, v139
	v_and_b32_e32 v171, 0xffff0000, v139
	v_mul_f32_e32 v170, s3, v170
	v_mul_f32_e32 v171, s3, v171
	v_fma_f32 v168, v170, v16, v168
	v_fma_f32 v169, v171, v17, v169
	v_fma_f32 v184, v168, v168, v184
	v_fma_f32 v184, v169, v169, v184
	v_cvt_pk_bf16_f32 v107, v168, v169
	global_store_dwordx4 v23, v[100:103], s[0:1]
	global_store_dwordx4 v23, v[104:107], s[0:1] offset:1024
	v_lshlrev_b32_e32 v168, 16, v108
	v_and_b32_e32 v169, 0xffff0000, v108
	v_lshlrev_b32_e32 v170, 16, v140
	v_and_b32_e32 v171, 0xffff0000, v140
	v_mul_f32_e32 v170, s24, v170
	v_mul_f32_e32 v171, s24, v171
	v_fma_f32 v168, v170, v2, v168
	v_fma_f32 v169, v171, v3, v169
	v_fma_f32 v185, v168, v168, v185
	v_fma_f32 v185, v169, v169, v185
	v_cvt_pk_bf16_f32 v108, v168, v169
	v_lshlrev_b32_e32 v168, 16, v109
	v_and_b32_e32 v169, 0xffff0000, v109
	v_lshlrev_b32_e32 v170, 16, v141
	v_and_b32_e32 v171, 0xffff0000, v141
	v_mul_f32_e32 v170, s24, v170
	v_mul_f32_e32 v171, s24, v171
	v_fma_f32 v168, v170, v4, v168
	v_fma_f32 v169, v171, v5, v169
	v_fma_f32 v185, v168, v168, v185
	v_fma_f32 v185, v169, v169, v185
	v_cvt_pk_bf16_f32 v109, v168, v169
	v_lshlrev_b32_e32 v168, 16, v110
	v_and_b32_e32 v169, 0xffff0000, v110
	v_lshlrev_b32_e32 v170, 16, v142
	v_and_b32_e32 v171, 0xffff0000, v142
	v_mul_f32_e32 v170, s24, v170
	v_mul_f32_e32 v171, s24, v171
	v_fma_f32 v168, v170, v6, v168
	v_fma_f32 v169, v171, v7, v169
	v_fma_f32 v185, v168, v168, v185
	v_fma_f32 v185, v169, v169, v185
	v_cvt_pk_bf16_f32 v110, v168, v169
	v_lshlrev_b32_e32 v168, 16, v111
	v_and_b32_e32 v169, 0xffff0000, v111
	v_lshlrev_b32_e32 v170, 16, v143
	v_and_b32_e32 v171, 0xffff0000, v143
	v_mul_f32_e32 v170, s24, v170
	v_mul_f32_e32 v171, s24, v171
	v_fma_f32 v168, v170, v8, v168
	v_fma_f32 v169, v171, v9, v169
	v_fma_f32 v185, v168, v168, v185
	v_fma_f32 v185, v169, v169, v185
	v_cvt_pk_bf16_f32 v111, v168, v169
	v_lshlrev_b32_e32 v168, 16, v112
	v_and_b32_e32 v169, 0xffff0000, v112
	v_lshlrev_b32_e32 v170, 16, v144
	v_and_b32_e32 v171, 0xffff0000, v144
	v_mul_f32_e32 v170, s24, v170
	v_mul_f32_e32 v171, s24, v171
	v_fma_f32 v168, v170, v10, v168
	v_fma_f32 v169, v171, v11, v169
	v_fma_f32 v185, v168, v168, v185
	v_fma_f32 v185, v169, v169, v185
	v_cvt_pk_bf16_f32 v112, v168, v169
	v_lshlrev_b32_e32 v168, 16, v113
	v_and_b32_e32 v169, 0xffff0000, v113
	v_lshlrev_b32_e32 v170, 16, v145
	v_and_b32_e32 v171, 0xffff0000, v145
	v_mul_f32_e32 v170, s24, v170
	v_mul_f32_e32 v171, s24, v171
	v_fma_f32 v168, v170, v12, v168
	v_fma_f32 v169, v171, v13, v169
	v_fma_f32 v185, v168, v168, v185
	v_fma_f32 v185, v169, v169, v185
	v_cvt_pk_bf16_f32 v113, v168, v169
	v_lshlrev_b32_e32 v168, 16, v114
	v_and_b32_e32 v169, 0xffff0000, v114
	v_lshlrev_b32_e32 v170, 16, v146
	v_and_b32_e32 v171, 0xffff0000, v146
	v_mul_f32_e32 v170, s24, v170
	v_mul_f32_e32 v171, s24, v171
	v_fma_f32 v168, v170, v14, v168
	v_fma_f32 v169, v171, v15, v169
	v_fma_f32 v185, v168, v168, v185
	v_fma_f32 v185, v169, v169, v185
	v_cvt_pk_bf16_f32 v114, v168, v169
	v_lshlrev_b32_e32 v168, 16, v115
	v_and_b32_e32 v169, 0xffff0000, v115
	v_lshlrev_b32_e32 v170, 16, v147
	v_and_b32_e32 v171, 0xffff0000, v147
	v_mul_f32_e32 v170, s24, v170
	v_mul_f32_e32 v171, s24, v171
	v_fma_f32 v168, v170, v16, v168
	v_fma_f32 v169, v171, v17, v169
	v_fma_f32 v185, v168, v168, v185
	v_fma_f32 v185, v169, v169, v185
	v_cvt_pk_bf16_f32 v115, v168, v169
	global_store_dwordx4 v23, v[108:111], s[0:1] offset:2048
	global_store_dwordx4 v23, v[112:115], s[0:1] offset:3072
	v_lshlrev_b32_e32 v168, 16, v116
	v_and_b32_e32 v169, 0xffff0000, v116
	v_lshlrev_b32_e32 v170, 16, v148
	v_and_b32_e32 v171, 0xffff0000, v148
	v_mul_f32_e32 v170, s98, v170
	v_mul_f32_e32 v171, s98, v171
	v_fma_f32 v168, v170, v2, v168
	v_fma_f32 v169, v171, v3, v169
	v_fma_f32 v186, v168, v168, v186
	v_fma_f32 v186, v169, v169, v186
	v_cvt_pk_bf16_f32 v116, v168, v169
	v_lshlrev_b32_e32 v168, 16, v117
	v_and_b32_e32 v169, 0xffff0000, v117
	v_lshlrev_b32_e32 v170, 16, v149
	v_and_b32_e32 v171, 0xffff0000, v149
	v_mul_f32_e32 v170, s98, v170
	v_mul_f32_e32 v171, s98, v171
	v_fma_f32 v168, v170, v4, v168
	v_fma_f32 v169, v171, v5, v169
	v_fma_f32 v186, v168, v168, v186
	v_fma_f32 v186, v169, v169, v186
	v_cvt_pk_bf16_f32 v117, v168, v169
	v_lshlrev_b32_e32 v168, 16, v118
	v_and_b32_e32 v169, 0xffff0000, v118
	v_lshlrev_b32_e32 v170, 16, v150
	v_and_b32_e32 v171, 0xffff0000, v150
	v_mul_f32_e32 v170, s98, v170
	v_mul_f32_e32 v171, s98, v171
	v_fma_f32 v168, v170, v6, v168
	v_fma_f32 v169, v171, v7, v169
	v_fma_f32 v186, v168, v168, v186
	v_fma_f32 v186, v169, v169, v186
	v_cvt_pk_bf16_f32 v118, v168, v169
	v_lshlrev_b32_e32 v168, 16, v119
	v_and_b32_e32 v169, 0xffff0000, v119
	v_lshlrev_b32_e32 v170, 16, v151
	v_and_b32_e32 v171, 0xffff0000, v151
	v_mul_f32_e32 v170, s98, v170
	v_mul_f32_e32 v171, s98, v171
	v_fma_f32 v168, v170, v8, v168
	v_fma_f32 v169, v171, v9, v169
	v_fma_f32 v186, v168, v168, v186
	v_fma_f32 v186, v169, v169, v186
	v_cvt_pk_bf16_f32 v119, v168, v169
	v_lshlrev_b32_e32 v168, 16, v120
	v_and_b32_e32 v169, 0xffff0000, v120
	v_lshlrev_b32_e32 v170, 16, v152
	v_and_b32_e32 v171, 0xffff0000, v152
	v_mul_f32_e32 v170, s98, v170
; __device__ __forceinline__ float bf_lo(unsigned w) { return __uint_as_float(w << 16); }
; __device__ __forceinline__ float bf_hi(unsigned w) { return __uint_as_float(w & 0xffff0000u); }
; __device__ __forceinline__ unsigned pk2(float lo, float hi) { bf16x2_t r = __builtin_convertvector((f32x2_t){lo, hi}, bf16x2_t); return __builtin_bit_cast(unsigned, r); }
; template <bool SRC_F32, bool FINAL, int R> __device__ __forceinline__ void ew_compute(const EwSet<SRC_F32, R>& S, int rb, const f32x4 (&g)[4], bf16* hb_out, float* out32, float scale, float* rs_out, int lane) {
; #pragma unroll
;     for (int i = 0; i < R; ++i) {
;         float q = S.p[i];
;         q += __shfl_xor(q, 1); q += __shfl_xor(q, 2); q += __shfl_xor(q, 4); q += __shfl_xor(q, 8);
;         const float ss = __shfl(q, 0);
;         const float rs = scale / sqrtf(ss * (1.f / D) + EPS);
;         float s2 = 0.f;
; #pragma unroll
;         for (int j = 0; j < 4; ++j) {
;             f32x4 h;
;             if constexpr (SRC_F32) h = S.h32[i][j];
;             else { const v2u hw = S.hb[i][j]; h.x = bf_lo(hw.x); h.y = bf_hi(hw.x); h.z = bf_lo(hw.y); h.w = bf_hi(hw.y); }
;             const v2u fw = S.fw[i][j];
;             f32x4 v; v.x = h.x + bf_lo(fw.x) * rs * g[j].x; v.y = h.y + bf_hi(fw.x) * rs * g[j].y; v.z = h.z + bf_lo(fw.y) * rs * g[j].z; v.w = h.w + bf_hi(fw.y) * rs * g[j].w;
;             if (FINAL) __builtin_nontemporal_store(v, (f32x4*)(out32 + (size_t)(rb + i) * D) + lane + 64 * j);
;             else { v2u o; o.x = pk2(v.x, v.y); o.y = pk2(v.z, v.w); ((v2u*)(hb_out + (size_t)(rb + i) * D) + lane)[64 * j] = o; s2 += (v.x * v.x + v.y * v.y) + (v.z * v.z + v.w * v.w); }
;         }
;         if (!FINAL) { const float tot = wave_sum(s2); if (lane == 0) rs_out[rb + i] = 1.0f / sqrtf(tot * (1.f / D) + EPS); }
;     }
	v_mul_f32_e32 v171, s98, v171
	v_fma_f32 v168, v170, v10, v168
	v_fma_f32 v169, v171, v11, v169
	v_fma_f32 v186, v168, v168, v186
	v_fma_f32 v186, v169, v169, v186
	v_cvt_pk_bf16_f32 v120, v168, v169
	v_lshlrev_b32_e32 v168, 16, v121
	v_and_b32_e32 v169, 0xffff0000, v121
	v_lshlrev_b32_e32 v170, 16, v153
	v_and_b32_e32 v171, 0xffff0000, v153
	v_mul_f32_e32 v170, s98, v170
	v_mul_f32_e32 v171, s98, v171
	v_fma_f32 v168, v170, v12, v168
	v_fma_f32 v169, v171, v13, v169
	v_fma_f32 v186, v168, v168, v186
	v_fma_f32 v186, v169, v169, v186
	v_cvt_pk_bf16_f32 v121, v168, v169
	v_lshlrev_b32_e32 v168, 16, v122
	v_and_b32_e32 v169, 0xffff0000, v122
	v_lshlrev_b32_e32 v170, 16, v154
	v_and_b32_e32 v171, 0xffff0000, v154
	v_mul_f32_e32 v170, s98, v170
	v_mul_f32_e32 v171, s98, v171
	v_fma_f32 v168, v170, v14, v168
	v_fma_f32 v169, v171, v15, v169
	v_fma_f32 v186, v168, v168, v186
	v_fma_f32 v186, v169, v169, v186
	v_cvt_pk_bf16_f32 v122, v168, v169
	v_lshlrev_b32_e32 v168, 16, v123
	v_and_b32_e32 v169, 0xffff0000, v123
	v_lshlrev_b32_e32 v170, 16, v155
	v_and_b32_e32 v171, 0xffff0000, v155
	v_mul_f32_e32 v170, s98, v170
	v_mul_f32_e32 v171, s98, v171
	v_fma_f32 v168, v170, v16, v168
	v_fma_f32 v169, v171, v17, v169
	v_fma_f32 v186, v168, v168, v186
	v_fma_f32 v186, v169, v169, v186
	v_cvt_pk_bf16_f32 v123, v168, v169
	global_store_dwordx4 v24, v[116:119], s[0:1]
	global_store_dwordx4 v24, v[120:123], s[0:1] offset:1024
	v_lshlrev_b32_e32 v168, 16, v124
	v_and_b32_e32 v169, 0xffff0000, v124
	v_lshlrev_b32_e32 v170, 16, v156
	v_and_b32_e32 v171, 0xffff0000, v156
	v_mul_f32_e32 v170, s101, v170
	v_mul_f32_e32 v171, s101, v171
	v_fma_f32 v168, v170, v2, v168
	v_fma_f32 v169, v171, v3, v169
	v_fma_f32 v187, v168, v168, v187
	v_fma_f32 v187, v169, v169, v187
	v_cvt_pk_bf16_f32 v124, v168, v169
	v_lshlrev_b32_e32 v168, 16, v125
	v_and_b32_e32 v169, 0xffff0000, v125
	v_lshlrev_b32_e32 v170, 16, v157
	v_and_b32_e32 v171, 0xffff0000, v157
	v_mul_f32_e32 v170, s101, v170
	v_mul_f32_e32 v171, s101, v171
	v_fma_f32 v168, v170, v4, v168
	v_fma_f32 v169, v171, v5, v169
	v_fma_f32 v187, v168, v168, v187
	v_fma_f32 v187, v169, v169, v187
	v_cvt_pk_bf16_f32 v125, v168, v169
	v_lshlrev_b32_e32 v168, 16, v126
	v_and_b32_e32 v169, 0xffff0000, v126
	v_lshlrev_b32_e32 v170, 16, v158
	v_and_b32_e32 v171, 0xffff0000, v158
	v_mul_f32_e32 v170, s101, v170
	v_mul_f32_e32 v171, s101, v171
	v_fma_f32 v168, v170, v6, v168
	v_fma_f32 v169, v171, v7, v169
	v_fma_f32 v187, v168, v168, v187
	v_fma_f32 v187, v169, v169, v187
	v_cvt_pk_bf16_f32 v126, v168, v169
	v_lshlrev_b32_e32 v168, 16, v127
	v_and_b32_e32 v169, 0xffff0000, v127
	v_lshlrev_b32_e32 v170, 16, v159
	v_and_b32_e32 v171, 0xffff0000, v159
	v_mul_f32_e32 v170, s101, v170
	v_mul_f32_e32 v171, s101, v171
	v_fma_f32 v168, v170, v8, v168
	v_fma_f32 v169, v171, v9, v169
	v_fma_f32 v187, v168, v168, v187
	v_fma_f32 v187, v169, v169, v187
	v_cvt_pk_bf16_f32 v127, v168, v169
	v_lshlrev_b32_e32 v168, 16, v128
	v_and_b32_e32 v169, 0xffff0000, v128
	v_lshlrev_b32_e32 v170, 16, v160
	v_and_b32_e32 v171, 0xffff0000, v160
	v_mul_f32_e32 v170, s101, v170
	v_mul_f32_e32 v171, s101, v171
	v_fma_f32 v168, v170, v10, v168
	v_fma_f32 v169, v171, v11, v169
	v_fma_f32 v187, v168, v168, v187
	v_fma_f32 v187, v169, v169, v187
	v_cvt_pk_bf16_f32 v128, v168, v169
	v_lshlrev_b32_e32 v168, 16, v129
	v_and_b32_e32 v169, 0xffff0000, v129
	v_lshlrev_b32_e32 v170, 16, v161
	v_and_b32_e32 v171, 0xffff0000, v161
	v_mul_f32_e32 v170, s101, v170
	v_mul_f32_e32 v171, s101, v171
	v_fma_f32 v168, v170, v12, v168
	v_fma_f32 v169, v171, v13, v169
	v_fma_f32 v187, v168, v168, v187
	v_fma_f32 v187, v169, v169, v187
	v_cvt_pk_bf16_f32 v129, v168, v169
	v_lshlrev_b32_e32 v168, 16, v130
	v_and_b32_e32 v169, 0xffff0000, v130
	v_lshlrev_b32_e32 v170, 16, v162
	v_and_b32_e32 v171, 0xffff0000, v162
	v_mul_f32_e32 v170, s101, v170
	v_mul_f32_e32 v171, s101, v171
	v_fma_f32 v168, v170, v14, v168
	v_fma_f32 v169, v171, v15, v169
	v_fma_f32 v187, v168, v168, v187
	v_fma_f32 v187, v169, v169, v187
	v_cvt_pk_bf16_f32 v130, v168, v169
	v_lshlrev_b32_e32 v168, 16, v131
	v_and_b32_e32 v169, 0xffff0000, v131
	v_lshlrev_b32_e32 v170, 16, v163
	v_and_b32_e32 v171, 0xffff0000, v163
	v_mul_f32_e32 v170, s101, v170
	v_mul_f32_e32 v171, s101, v171
	v_fma_f32 v168, v170, v16, v168
	v_fma_f32 v169, v171, v17, v169
	v_fma_f32 v187, v168, v168, v187
	v_fma_f32 v187, v169, v169, v187
	v_cvt_pk_bf16_f32 v131, v168, v169
	global_store_dwordx4 v24, v[124:127], s[0:1] offset:2048
	global_store_dwordx4 v24, v[128:131], s[0:1] offset:3072
	s_nop 1
	v_add_f32_dpp v184, v184, v184 quad_perm:[1,0,3,2] row_mask:0xf bank_mask:0xf
	v_add_f32_dpp v185, v185, v185 quad_perm:[1,0,3,2] row_mask:0xf bank_mask:0xf
	v_add_f32_dpp v186, v186, v186 quad_perm:[1,0,3,2] row_mask:0xf bank_mask:0xf
	v_add_f32_dpp v187, v187, v187 quad_perm:[1,0,3,2] row_mask:0xf bank_mask:0xf
	v_add_f32_dpp v184, v184, v184 quad_perm:[2,3,0,1] row_mask:0xf bank_mask:0xf
	v_add_f32_dpp v185, v185, v185 quad_perm:[2,3,0,1] row_mask:0xf bank_mask:0xf
	v_add_f32_dpp v186, v186, v186 quad_perm:[2,3,0,1] row_mask:0xf bank_mask:0xf
	v_add_f32_dpp v187, v187, v187 quad_perm:[2,3,0,1] row_mask:0xf bank_mask:0xf
	v_add_f32_dpp v184, v184, v184 row_half_mirror row_mask:0xf bank_mask:0xf
	v_add_f32_dpp v185, v185, v185 row_half_mirror row_mask:0xf bank_mask:0xf
	v_add_f32_dpp v186, v186, v186 row_half_mirror row_mask:0xf bank_mask:0xf
	v_add_f32_dpp v187, v187, v187 row_half_mirror row_mask:0xf bank_mask:0xf
	v_add_f32_dpp v184, v184, v184 row_mirror row_mask:0xf bank_mask:0xf
	v_add_f32_dpp v185, v185, v185 row_mirror row_mask:0xf bank_mask:0xf
; __device__ __forceinline__ float bf_lo(unsigned w) { return __uint_as_float(w << 16); }
; __device__ __forceinline__ float bf_hi(unsigned w) { return __uint_as_float(w & 0xffff0000u); }
; template <bool SRC_F32, int R> __device__ __forceinline__ void ew_load(EwSet<SRC_F32, R>& S, int rb, const float* hsrc32, const bf16* hsrcb, const bf16* f, const float* part, int lane) {
; #pragma unroll
;     for (int i = 0; i < R; ++i) S.p[i] = (lane < 16) ? part[(size_t)(rb + i) * 16 + lane] : 0.f;
; #pragma unroll
;     for (int i = 0; i < R; ++i)
; #pragma unroll
;         for (int j = 0; j < 4; ++j) {
;             S.fw[i][j] = ((const v2u*)(f + (size_t)(rb + i) * D) + lane)[64 * j];
;             if constexpr (SRC_F32) S.h32[i][j] = __builtin_nontemporal_load((const f32x4*)(hsrc32 + (size_t)(rb + i) * D) + lane + 64 * j);
;             else S.hb[i][j] = ((const v2u*)(hsrcb + (size_t)(rb + i) * D) + lane)[64 * j];
;         }
; }
; template <bool SRC_F32, bool FINAL, int R> __device__ __forceinline__ void ew_compute(const EwSet<SRC_F32, R>& S, int rb, const f32x4 (&g)[4], bf16* hb_out, float* out32, float scale, float* rs_out, int lane) {
; #pragma unroll
;     for (int i = 0; i < R; ++i) {
;         float q = S.p[i];
;         q += __shfl_xor(q, 1); q += __shfl_xor(q, 2); q += __shfl_xor(q, 4); q += __shfl_xor(q, 8);
;         const float ss = __shfl(q, 0);
;         const float rs = scale / sqrtf(ss * (1.f / D) + EPS);
;         float s2 = 0.f;
; #pragma unroll
;         for (int j = 0; j < 4; ++j) {
;             f32x4 h;
;             if constexpr (SRC_F32) h = S.h32[i][j];
;             else { const v2u hw = S.hb[i][j]; h.x = bf_lo(hw.x); h.y = bf_hi(hw.x); h.z = bf_lo(hw.y); h.w = bf_hi(hw.y); }
;             const v2u fw = S.fw[i][j];
;             f32x4 v; v.x = h.x + bf_lo(fw.x) * rs * g[j].x; v.y = h.y + bf_hi(fw.x) * rs * g[j].y; v.z = h.z + bf_lo(fw.y) * rs * g[j].z; v.w = h.w + bf_hi(fw.y) * rs * g[j].w;
;             if (FINAL) __builtin_nontemporal_store(v, (f32x4*)(out32 + (size_t)(rb + i) * D) + lane + 64 * j);
;             else { v2u o; o.x = pk2(v.x, v.y); o.y = pk2(v.z, v.w); ((v2u*)(hb_out + (size_t)(rb + i) * D) + lane)[64 * j] = o; s2 += (v.x * v.x + v.y * v.y) + (v.z * v.z + v.w * v.w); }
;         }
;         if (!FINAL) { const float tot = wave_sum(s2); if (lane == 0) rs_out[rb + i] = 1.0f / sqrtf(tot * (1.f / D) + EPS); }
;     }
	v_add_f32_dpp v186, v186, v186 row_mirror row_mask:0xf bank_mask:0xf
	v_add_f32_dpp v187, v187, v187 row_mirror row_mask:0xf bank_mask:0xf
	v_add_f32_dpp v184, v184, v184 row_bcast:15 row_mask:0xa bank_mask:0xf
	v_add_f32_dpp v185, v185, v185 row_bcast:15 row_mask:0xa bank_mask:0xf
	v_add_f32_dpp v186, v186, v186 row_bcast:15 row_mask:0xa bank_mask:0xf
	v_add_f32_dpp v187, v187, v187 row_bcast:15 row_mask:0xa bank_mask:0xf
	v_add_f32_dpp v184, v184, v184 row_bcast:31 row_mask:0xc bank_mask:0xf
	v_add_f32_dpp v185, v185, v185 row_bcast:31 row_mask:0xc bank_mask:0xf
	v_add_f32_dpp v186, v186, v186 row_bcast:31 row_mask:0xc bank_mask:0xf
	v_add_f32_dpp v187, v187, v187 row_bcast:31 row_mask:0xc bank_mask:0xf
	s_nop 1
	v_readlane_b32 s3, v184, 63
	v_readlane_b32 s24, v185, 63
	v_readlane_b32 s98, v186, 63
	v_readlane_b32 s101, v187, 63
	s_nop 3
	v_writelane_b32 v188, s3, 0
	v_writelane_b32 v188, s24, 1
	v_writelane_b32 v188, s98, 2
	v_writelane_b32 v188, s101, 3
	s_nop 1
	v_mul_f32_e32 v188, 0x3a800000, v188
	v_add_f32_e32 v188, 0x358637bd, v188
	v_rsq_f32_e32 v188, v188
	s_mov_b64 exec, 15
	global_store_dword v26, v188, s[14:15]
	s_mov_b64 exec, -1
	s_add_u32 s27, s26, 2052
	s_lshl_b32 s22, s27, 11
	v_lshl_add_u32 v23, v0, 4, s22
	v_add_u32_e32 v24, 0x1000, v23
	s_lshl_b32 s22, s27, 6
	v_lshl_add_u32 v25, v0, 2, s22
	s_lshl_b32 s22, s27, 2
	v_lshl_add_u32 v26, v0, 2, s22
	global_load_dwordx4 v[100:103], v23, s[0:1]
	global_load_dwordx4 v[104:107], v23, s[0:1] offset:1024
	global_load_dwordx4 v[132:135], v23, s[4:5]
	global_load_dwordx4 v[136:139], v23, s[4:5] offset:1024
	global_load_dwordx4 v[108:111], v23, s[0:1] offset:2048
	global_load_dwordx4 v[112:115], v23, s[0:1] offset:3072
	global_load_dwordx4 v[140:143], v23, s[4:5] offset:2048
	global_load_dwordx4 v[144:147], v23, s[4:5] offset:3072
	global_load_dwordx4 v[116:119], v24, s[0:1]
	global_load_dwordx4 v[120:123], v24, s[0:1] offset:1024
	global_load_dwordx4 v[148:151], v24, s[4:5]
	global_load_dwordx4 v[152:155], v24, s[4:5] offset:1024
	global_load_dwordx4 v[124:127], v24, s[0:1] offset:2048
	global_load_dwordx4 v[128:131], v24, s[0:1] offset:3072
	global_load_dwordx4 v[156:159], v24, s[4:5] offset:2048
	global_load_dwordx4 v[160:163], v24, s[4:5] offset:3072
	global_load_dword v164, v25, s[6:7]
	s_waitcnt vmcnt(26)
	v_add_f32_dpp v96, v96, v96 quad_perm:[1,0,3,2] row_mask:0xf bank_mask:0xf
	s_nop 1
	v_add_f32_dpp v96, v96, v96 quad_perm:[2,3,0,1] row_mask:0xf bank_mask:0xf
	s_nop 1
	v_add_f32_dpp v96, v96, v96 row_half_mirror row_mask:0xf bank_mask:0xf
	s_nop 1
	v_add_f32_dpp v96, v96, v96 row_mirror row_mask:0xf bank_mask:0xf
	s_nop 1
	v_mul_f32_e32 v96, 0x3a800000, v96
	v_add_f32_e32 v96, 0x358637bd, v96
	v_rsq_f32_e32 v96, v96
	s_nop 0
	v_readlane_b32 s3, v96, 0
	v_readlane_b32 s24, v96, 16
	v_readlane_b32 s98, v96, 32
	v_readlane_b32 s101, v96, 48
	s_nop 1
	v_mov_b32_e32 v184, 0
	v_mov_b32_e32 v185, 0
	v_mov_b32_e32 v186, 0
	v_mov_b32_e32 v187, 0
	v_lshlrev_b32_e32 v168, 16, v32
	v_and_b32_e32 v169, 0xffff0000, v32
	v_lshlrev_b32_e32 v170, 16, v64
	v_and_b32_e32 v171, 0xffff0000, v64
	v_mul_f32_e32 v170, s3, v170
	v_mul_f32_e32 v171, s3, v171
	v_fma_f32 v168, v170, v2, v168
	v_fma_f32 v169, v171, v3, v169
	v_fma_f32 v184, v168, v168, v184
	v_fma_f32 v184, v169, v169, v184
	v_cvt_pk_bf16_f32 v32, v168, v169
	v_lshlrev_b32_e32 v168, 16, v33
	v_and_b32_e32 v169, 0xffff0000, v33
	v_lshlrev_b32_e32 v170, 16, v65
	v_and_b32_e32 v171, 0xffff0000, v65
	v_mul_f32_e32 v170, s3, v170
	v_mul_f32_e32 v171, s3, v171
	v_fma_f32 v168, v170, v4, v168
	v_fma_f32 v169, v171, v5, v169
	v_fma_f32 v184, v168, v168, v184
	v_fma_f32 v184, v169, v169, v184
	v_cvt_pk_bf16_f32 v33, v168, v169
	v_lshlrev_b32_e32 v168, 16, v34
	v_and_b32_e32 v169, 0xffff0000, v34
	v_lshlrev_b32_e32 v170, 16, v66
	v_and_b32_e32 v171, 0xffff0000, v66
	v_mul_f32_e32 v170, s3, v170
	v_mul_f32_e32 v171, s3, v171
	v_fma_f32 v168, v170, v6, v168
	v_fma_f32 v169, v171, v7, v169
	v_fma_f32 v184, v168, v168, v184
	v_fma_f32 v184, v169, v169, v184
	v_cvt_pk_bf16_f32 v34, v168, v169
	v_lshlrev_b32_e32 v168, 16, v35
	v_and_b32_e32 v169, 0xffff0000, v35
	v_lshlrev_b32_e32 v170, 16, v67
	v_and_b32_e32 v171, 0xffff0000, v67
	v_mul_f32_e32 v170, s3, v170
	v_mul_f32_e32 v171, s3, v171
	v_fma_f32 v168, v170, v8, v168
	v_fma_f32 v169, v171, v9, v169
	v_fma_f32 v184, v168, v168, v184
	v_fma_f32 v184, v169, v169, v184
	v_cvt_pk_bf16_f32 v35, v168, v169
	v_lshlrev_b32_e32 v168, 16, v36
	v_and_b32_e32 v169, 0xffff0000, v36
	v_lshlrev_b32_e32 v170, 16, v68
	v_and_b32_e32 v171, 0xffff0000, v68
	v_mul_f32_e32 v170, s3, v170
	v_mul_f32_e32 v171, s3, v171
	v_fma_f32 v168, v170, v10, v168
	v_fma_f32 v169, v171, v11, v169
	v_fma_f32 v184, v168, v168, v184
	v_fma_f32 v184, v169, v169, v184
	v_cvt_pk_bf16_f32 v36, v168, v169
	v_lshlrev_b32_e32 v168, 16, v37
	v_and_b32_e32 v169, 0xffff0000, v37
	v_lshlrev_b32_e32 v170, 16, v69
	v_and_b32_e32 v171, 0xffff0000, v69
	v_mul_f32_e32 v170, s3, v170
	v_mul_f32_e32 v171, s3, v171
	v_fma_f32 v168, v170, v12, v168
	v_fma_f32 v169, v171, v13, v169
	v_fma_f32 v184, v168, v168, v184
	v_fma_f32 v184, v169, v169, v184
	v_cvt_pk_bf16_f32 v37, v168, v169
	v_lshlrev_b32_e32 v168, 16, v38
	v_and_b32_e32 v169, 0xffff0000, v38
	v_lshlrev_b32_e32 v170, 16, v70
	v_and_b32_e32 v171, 0xffff0000, v70
	v_mul_f32_e32 v170, s3, v170
	v_mul_f32_e32 v171, s3, v171
	v_fma_f32 v168, v170, v14, v168
	v_fma_f32 v169, v171, v15, v169
	v_fma_f32 v184, v168, v168, v184
	v_fma_f32 v184, v169, v169, v184
	v_cvt_pk_bf16_f32 v38, v168, v169
	v_lshlrev_b32_e32 v168, 16, v39
	v_and_b32_e32 v169, 0xffff0000, v39
	v_lshlrev_b32_e32 v170, 16, v71
; __device__ __forceinline__ float bf_lo(unsigned w) { return __uint_as_float(w << 16); }
; __device__ __forceinline__ float bf_hi(unsigned w) { return __uint_as_float(w & 0xffff0000u); }
; __device__ __forceinline__ unsigned pk2(float lo, float hi) { bf16x2_t r = __builtin_convertvector((f32x2_t){lo, hi}, bf16x2_t); return __builtin_bit_cast(unsigned, r); }
; template <bool SRC_F32, bool FINAL, int R> __device__ __forceinline__ void ew_compute(const EwSet<SRC_F32, R>& S, int rb, const f32x4 (&g)[4], bf16* hb_out, float* out32, float scale, float* rs_out, int lane) {
; #pragma unroll
;     for (int i = 0; i < R; ++i) {
;         float q = S.p[i];
;         q += __shfl_xor(q, 1); q += __shfl_xor(q, 2); q += __shfl_xor(q, 4); q += __shfl_xor(q, 8);
;         const float ss = __shfl(q, 0);
;         const float rs = scale / sqrtf(ss * (1.f / D) + EPS);
;         float s2 = 0.f;
; #pragma unroll
;         for (int j = 0; j < 4; ++j) {
;             f32x4 h;
;             if constexpr (SRC_F32) h = S.h32[i][j];
;             else { const v2u hw = S.hb[i][j]; h.x = bf_lo(hw.x); h.y = bf_hi(hw.x); h.z = bf_lo(hw.y); h.w = bf_hi(hw.y); }
;             const v2u fw = S.fw[i][j];
;             f32x4 v; v.x = h.x + bf_lo(fw.x) * rs * g[j].x; v.y = h.y + bf_hi(fw.x) * rs * g[j].y; v.z = h.z + bf_lo(fw.y) * rs * g[j].z; v.w = h.w + bf_hi(fw.y) * rs * g[j].w;
;             if (FINAL) __builtin_nontemporal_store(v, (f32x4*)(out32 + (size_t)(rb + i) * D) + lane + 64 * j);
;             else { v2u o; o.x = pk2(v.x, v.y); o.y = pk2(v.z, v.w); ((v2u*)(hb_out + (size_t)(rb + i) * D) + lane)[64 * j] = o; s2 += (v.x * v.x + v.y * v.y) + (v.z * v.z + v.w * v.w); }
;         }
;         if (!FINAL) { const float tot = wave_sum(s2); if (lane == 0) rs_out[rb + i] = 1.0f / sqrtf(tot * (1.f / D) + EPS); }
;     }
	v_and_b32_e32 v171, 0xffff0000, v71
	v_mul_f32_e32 v170, s3, v170
	v_mul_f32_e32 v171, s3, v171
	v_fma_f32 v168, v170, v16, v168
	v_fma_f32 v169, v171, v17, v169
	v_fma_f32 v184, v168, v168, v184
	v_fma_f32 v184, v169, v169, v184
	v_cvt_pk_bf16_f32 v39, v168, v169
	global_store_dwordx4 v18, v[32:35], s[0:1]
	global_store_dwordx4 v18, v[36:39], s[0:1] offset:1024
	v_lshlrev_b32_e32 v168, 16, v40
	v_and_b32_e32 v169, 0xffff0000, v40
	v_lshlrev_b32_e32 v170, 16, v72
	v_and_b32_e32 v171, 0xffff0000, v72
	v_mul_f32_e32 v170, s24, v170
	v_mul_f32_e32 v171, s24, v171
	v_fma_f32 v168, v170, v2, v168
	v_fma_f32 v169, v171, v3, v169
	v_fma_f32 v185, v168, v168, v185
	v_fma_f32 v185, v169, v169, v185
	v_cvt_pk_bf16_f32 v40, v168, v169
	v_lshlrev_b32_e32 v168, 16, v41
	v_and_b32_e32 v169, 0xffff0000, v41
	v_lshlrev_b32_e32 v170, 16, v73
	v_and_b32_e32 v171, 0xffff0000, v73
	v_mul_f32_e32 v170, s24, v170
	v_mul_f32_e32 v171, s24, v171
	v_fma_f32 v168, v170, v4, v168
	v_fma_f32 v169, v171, v5, v169
	v_fma_f32 v185, v168, v168, v185
	v_fma_f32 v185, v169, v169, v185
	v_cvt_pk_bf16_f32 v41, v168, v169
	v_lshlrev_b32_e32 v168, 16, v42
	v_and_b32_e32 v169, 0xffff0000, v42
	v_lshlrev_b32_e32 v170, 16, v74
	v_and_b32_e32 v171, 0xffff0000, v74
	v_mul_f32_e32 v170, s24, v170
	v_mul_f32_e32 v171, s24, v171
	v_fma_f32 v168, v170, v6, v168
	v_fma_f32 v169, v171, v7, v169
	v_fma_f32 v185, v168, v168, v185
	v_fma_f32 v185, v169, v169, v185
	v_cvt_pk_bf16_f32 v42, v168, v169
	v_lshlrev_b32_e32 v168, 16, v43
	v_and_b32_e32 v169, 0xffff0000, v43
	v_lshlrev_b32_e32 v170, 16, v75
	v_and_b32_e32 v171, 0xffff0000, v75
	v_mul_f32_e32 v170, s24, v170
	v_mul_f32_e32 v171, s24, v171
	v_fma_f32 v168, v170, v8, v168
	v_fma_f32 v169, v171, v9, v169
	v_fma_f32 v185, v168, v168, v185
	v_fma_f32 v185, v169, v169, v185
	v_cvt_pk_bf16_f32 v43, v168, v169
	v_lshlrev_b32_e32 v168, 16, v44
	v_and_b32_e32 v169, 0xffff0000, v44
	v_lshlrev_b32_e32 v170, 16, v76
	v_and_b32_e32 v171, 0xffff0000, v76
	v_mul_f32_e32 v170, s24, v170
	v_mul_f32_e32 v171, s24, v171
	v_fma_f32 v168, v170, v10, v168
	v_fma_f32 v169, v171, v11, v169
	v_fma_f32 v185, v168, v168, v185
	v_fma_f32 v185, v169, v169, v185
	v_cvt_pk_bf16_f32 v44, v168, v169
	v_lshlrev_b32_e32 v168, 16, v45
	v_and_b32_e32 v169, 0xffff0000, v45
	v_lshlrev_b32_e32 v170, 16, v77
	v_and_b32_e32 v171, 0xffff0000, v77
	v_mul_f32_e32 v170, s24, v170
	v_mul_f32_e32 v171, s24, v171
	v_fma_f32 v168, v170, v12, v168
	v_fma_f32 v169, v171, v13, v169
	v_fma_f32 v185, v168, v168, v185
	v_fma_f32 v185, v169, v169, v185
	v_cvt_pk_bf16_f32 v45, v168, v169
	v_lshlrev_b32_e32 v168, 16, v46
	v_and_b32_e32 v169, 0xffff0000, v46
	v_lshlrev_b32_e32 v170, 16, v78
	v_and_b32_e32 v171, 0xffff0000, v78
	v_mul_f32_e32 v170, s24, v170
	v_mul_f32_e32 v171, s24, v171
	v_fma_f32 v168, v170, v14, v168
	v_fma_f32 v169, v171, v15, v169
	v_fma_f32 v185, v168, v168, v185
	v_fma_f32 v185, v169, v169, v185
	v_cvt_pk_bf16_f32 v46, v168, v169
	v_lshlrev_b32_e32 v168, 16, v47
	v_and_b32_e32 v169, 0xffff0000, v47
	v_lshlrev_b32_e32 v170, 16, v79
	v_and_b32_e32 v171, 0xffff0000, v79
	v_mul_f32_e32 v170, s24, v170
	v_mul_f32_e32 v171, s24, v171
	v_fma_f32 v168, v170, v16, v168
	v_fma_f32 v169, v171, v17, v169
	v_fma_f32 v185, v168, v168, v185
	v_fma_f32 v185, v169, v169, v185
	v_cvt_pk_bf16_f32 v47, v168, v169
	global_store_dwordx4 v18, v[40:43], s[0:1] offset:2048
	global_store_dwordx4 v18, v[44:47], s[0:1] offset:3072
	v_lshlrev_b32_e32 v168, 16, v48
	v_and_b32_e32 v169, 0xffff0000, v48
	v_lshlrev_b32_e32 v170, 16, v80
	v_and_b32_e32 v171, 0xffff0000, v80
	v_mul_f32_e32 v170, s98, v170
	v_mul_f32_e32 v171, s98, v171
	v_fma_f32 v168, v170, v2, v168
	v_fma_f32 v169, v171, v3, v169
	v_fma_f32 v186, v168, v168, v186
	v_fma_f32 v186, v169, v169, v186
	v_cvt_pk_bf16_f32 v48, v168, v169
	v_lshlrev_b32_e32 v168, 16, v49
	v_and_b32_e32 v169, 0xffff0000, v49
	v_lshlrev_b32_e32 v170, 16, v81
	v_and_b32_e32 v171, 0xffff0000, v81
	v_mul_f32_e32 v170, s98, v170
	v_mul_f32_e32 v171, s98, v171
	v_fma_f32 v168, v170, v4, v168
	v_fma_f32 v169, v171, v5, v169
	v_fma_f32 v186, v168, v168, v186
	v_fma_f32 v186, v169, v169, v186
	v_cvt_pk_bf16_f32 v49, v168, v169
	v_lshlrev_b32_e32 v168, 16, v50
	v_and_b32_e32 v169, 0xffff0000, v50
	v_lshlrev_b32_e32 v170, 16, v82
	v_and_b32_e32 v171, 0xffff0000, v82
	v_mul_f32_e32 v170, s98, v170
	v_mul_f32_e32 v171, s98, v171
	v_fma_f32 v168, v170, v6, v168
	v_fma_f32 v169, v171, v7, v169
	v_fma_f32 v186, v168, v168, v186
	v_fma_f32 v186, v169, v169, v186
	v_cvt_pk_bf16_f32 v50, v168, v169
	v_lshlrev_b32_e32 v168, 16, v51
	v_and_b32_e32 v169, 0xffff0000, v51
	v_lshlrev_b32_e32 v170, 16, v83
	v_and_b32_e32 v171, 0xffff0000, v83
	v_mul_f32_e32 v170, s98, v170
	v_mul_f32_e32 v171, s98, v171
	v_fma_f32 v168, v170, v8, v168
	v_fma_f32 v169, v171, v9, v169
	v_fma_f32 v186, v168, v168, v186
	v_fma_f32 v186, v169, v169, v186
	v_cvt_pk_bf16_f32 v51, v168, v169
	v_lshlrev_b32_e32 v168, 16, v52
	v_and_b32_e32 v169, 0xffff0000, v52
	v_lshlrev_b32_e32 v170, 16, v84
	v_and_b32_e32 v171, 0xffff0000, v84
	v_mul_f32_e32 v170, s98, v170
	v_mul_f32_e32 v171, s98, v171
	v_fma_f32 v168, v170, v10, v168
	v_fma_f32 v169, v171, v11, v169
	v_fma_f32 v186, v168, v168, v186
	v_fma_f32 v186, v169, v169, v186
	v_cvt_pk_bf16_f32 v52, v168, v169
	v_lshlrev_b32_e32 v168, 16, v53
	v_and_b32_e32 v169, 0xffff0000, v53
	v_lshlrev_b32_e32 v170, 16, v85
	v_and_b32_e32 v171, 0xffff0000, v85
	v_mul_f32_e32 v170, s98, v170
	v_mul_f32_e32 v171, s98, v171
	v_fma_f32 v168, v170, v12, v168
	v_fma_f32 v169, v171, v13, v169
	v_fma_f32 v186, v168, v168, v186
	v_fma_f32 v186, v169, v169, v186
	v_cvt_pk_bf16_f32 v53, v168, v169
; __device__ __forceinline__ float bf_lo(unsigned w) { return __uint_as_float(w << 16); }
; __device__ __forceinline__ float bf_hi(unsigned w) { return __uint_as_float(w & 0xffff0000u); }
; __device__ __forceinline__ unsigned pk2(float lo, float hi) { bf16x2_t r = __builtin_convertvector((f32x2_t){lo, hi}, bf16x2_t); return __builtin_bit_cast(unsigned, r); }
; template <bool SRC_F32, bool FINAL, int R> __device__ __forceinline__ void ew_compute(const EwSet<SRC_F32, R>& S, int rb, const f32x4 (&g)[4], bf16* hb_out, float* out32, float scale, float* rs_out, int lane) {
; #pragma unroll
;     for (int i = 0; i < R; ++i) {
;         float q = S.p[i];
;         q += __shfl_xor(q, 1); q += __shfl_xor(q, 2); q += __shfl_xor(q, 4); q += __shfl_xor(q, 8);
;         const float ss = __shfl(q, 0);
;         const float rs = scale / sqrtf(ss * (1.f / D) + EPS);
;         float s2 = 0.f;
; #pragma unroll
;         for (int j = 0; j < 4; ++j) {
;             f32x4 h;
;             if constexpr (SRC_F32) h = S.h32[i][j];
;             else { const v2u hw = S.hb[i][j]; h.x = bf_lo(hw.x); h.y = bf_hi(hw.x); h.z = bf_lo(hw.y); h.w = bf_hi(hw.y); }
;             const v2u fw = S.fw[i][j];
;             f32x4 v; v.x = h.x + bf_lo(fw.x) * rs * g[j].x; v.y = h.y + bf_hi(fw.x) * rs * g[j].y; v.z = h.z + bf_lo(fw.y) * rs * g[j].z; v.w = h.w + bf_hi(fw.y) * rs * g[j].w;
;             if (FINAL) __builtin_nontemporal_store(v, (f32x4*)(out32 + (size_t)(rb + i) * D) + lane + 64 * j);
;             else { v2u o; o.x = pk2(v.x, v.y); o.y = pk2(v.z, v.w); ((v2u*)(hb_out + (size_t)(rb + i) * D) + lane)[64 * j] = o; s2 += (v.x * v.x + v.y * v.y) + (v.z * v.z + v.w * v.w); }
;         }
;         if (!FINAL) { const float tot = wave_sum(s2); if (lane == 0) rs_out[rb + i] = 1.0f / sqrtf(tot * (1.f / D) + EPS); }
;     }
	v_lshlrev_b32_e32 v168, 16, v54
	v_and_b32_e32 v169, 0xffff0000, v54
	v_lshlrev_b32_e32 v170, 16, v86
	v_and_b32_e32 v171, 0xffff0000, v86
	v_mul_f32_e32 v170, s98, v170
	v_mul_f32_e32 v171, s98, v171
	v_fma_f32 v168, v170, v14, v168
	v_fma_f32 v169, v171, v15, v169
	v_fma_f32 v186, v168, v168, v186
	v_fma_f32 v186, v169, v169, v186
	v_cvt_pk_bf16_f32 v54, v168, v169
	v_lshlrev_b32_e32 v168, 16, v55
	v_and_b32_e32 v169, 0xffff0000, v55
	v_lshlrev_b32_e32 v170, 16, v87
	v_and_b32_e32 v171, 0xffff0000, v87
	v_mul_f32_e32 v170, s98, v170
	v_mul_f32_e32 v171, s98, v171
	v_fma_f32 v168, v170, v16, v168
	v_fma_f32 v169, v171, v17, v169
	v_fma_f32 v186, v168, v168, v186
	v_fma_f32 v186, v169, v169, v186
	v_cvt_pk_bf16_f32 v55, v168, v169
	global_store_dwordx4 v19, v[48:51], s[0:1]
	global_store_dwordx4 v19, v[52:55], s[0:1] offset:1024
	v_lshlrev_b32_e32 v168, 16, v56
	v_and_b32_e32 v169, 0xffff0000, v56
	v_lshlrev_b32_e32 v170, 16, v88
	v_and_b32_e32 v171, 0xffff0000, v88
	v_mul_f32_e32 v170, s101, v170
	v_mul_f32_e32 v171, s101, v171
	v_fma_f32 v168, v170, v2, v168
	v_fma_f32 v169, v171, v3, v169
	v_fma_f32 v187, v168, v168, v187
	v_fma_f32 v187, v169, v169, v187
	v_cvt_pk_bf16_f32 v56, v168, v169
	v_lshlrev_b32_e32 v168, 16, v57
	v_and_b32_e32 v169, 0xffff0000, v57
	v_lshlrev_b32_e32 v170, 16, v89
	v_and_b32_e32 v171, 0xffff0000, v89
	v_mul_f32_e32 v170, s101, v170
	v_mul_f32_e32 v171, s101, v171
	v_fma_f32 v168, v170, v4, v168
	v_fma_f32 v169, v171, v5, v169
	v_fma_f32 v187, v168, v168, v187
	v_fma_f32 v187, v169, v169, v187
	v_cvt_pk_bf16_f32 v57, v168, v169
	v_lshlrev_b32_e32 v168, 16, v58
	v_and_b32_e32 v169, 0xffff0000, v58
	v_lshlrev_b32_e32 v170, 16, v90
	v_and_b32_e32 v171, 0xffff0000, v90
	v_mul_f32_e32 v170, s101, v170
	v_mul_f32_e32 v171, s101, v171
	v_fma_f32 v168, v170, v6, v168
	v_fma_f32 v169, v171, v7, v169
	v_fma_f32 v187, v168, v168, v187
	v_fma_f32 v187, v169, v169, v187
	v_cvt_pk_bf16_f32 v58, v168, v169
	v_lshlrev_b32_e32 v168, 16, v59
	v_and_b32_e32 v169, 0xffff0000, v59
	v_lshlrev_b32_e32 v170, 16, v91
	v_and_b32_e32 v171, 0xffff0000, v91
	v_mul_f32_e32 v170, s101, v170
	v_mul_f32_e32 v171, s101, v171
	v_fma_f32 v168, v170, v8, v168
	v_fma_f32 v169, v171, v9, v169
	v_fma_f32 v187, v168, v168, v187
	v_fma_f32 v187, v169, v169, v187
	v_cvt_pk_bf16_f32 v59, v168, v169
	v_lshlrev_b32_e32 v168, 16, v60
	v_and_b32_e32 v169, 0xffff0000, v60
	v_lshlrev_b32_e32 v170, 16, v92
	v_and_b32_e32 v171, 0xffff0000, v92
	v_mul_f32_e32 v170, s101, v170
	v_mul_f32_e32 v171, s101, v171
	v_fma_f32 v168, v170, v10, v168
	v_fma_f32 v169, v171, v11, v169
	v_fma_f32 v187, v168, v168, v187
	v_fma_f32 v187, v169, v169, v187
	v_cvt_pk_bf16_f32 v60, v168, v169
	v_lshlrev_b32_e32 v168, 16, v61
	v_and_b32_e32 v169, 0xffff0000, v61
	v_lshlrev_b32_e32 v170, 16, v93
	v_and_b32_e32 v171, 0xffff0000, v93
	v_mul_f32_e32 v170, s101, v170
	v_mul_f32_e32 v171, s101, v171
	v_fma_f32 v168, v170, v12, v168
	v_fma_f32 v169, v171, v13, v169
	v_fma_f32 v187, v168, v168, v187
	v_fma_f32 v187, v169, v169, v187
	v_cvt_pk_bf16_f32 v61, v168, v169
	v_lshlrev_b32_e32 v168, 16, v62
	v_and_b32_e32 v169, 0xffff0000, v62
	v_lshlrev_b32_e32 v170, 16, v94
	v_and_b32_e32 v171, 0xffff0000, v94
	v_mul_f32_e32 v170, s101, v170
	v_mul_f32_e32 v171, s101, v171
	v_fma_f32 v168, v170, v14, v168
	v_fma_f32 v169, v171, v15, v169
	v_fma_f32 v187, v168, v168, v187
	v_fma_f32 v187, v169, v169, v187
	v_cvt_pk_bf16_f32 v62, v168, v169
	v_lshlrev_b32_e32 v168, 16, v63
	v_and_b32_e32 v169, 0xffff0000, v63
	v_lshlrev_b32_e32 v170, 16, v95
	v_and_b32_e32 v171, 0xffff0000, v95
	v_mul_f32_e32 v170, s101, v170
	v_mul_f32_e32 v171, s101, v171
	v_fma_f32 v168, v170, v16, v168
	v_fma_f32 v169, v171, v17, v169
	v_fma_f32 v187, v168, v168, v187
	v_fma_f32 v187, v169, v169, v187
	v_cvt_pk_bf16_f32 v63, v168, v169
	global_store_dwordx4 v19, v[56:59], s[0:1] offset:2048
	global_store_dwordx4 v19, v[60:63], s[0:1] offset:3072
	s_nop 1
	v_add_f32_dpp v184, v184, v184 quad_perm:[1,0,3,2] row_mask:0xf bank_mask:0xf
	v_add_f32_dpp v185, v185, v185 quad_perm:[1,0,3,2] row_mask:0xf bank_mask:0xf
	v_add_f32_dpp v186, v186, v186 quad_perm:[1,0,3,2] row_mask:0xf bank_mask:0xf
	v_add_f32_dpp v187, v187, v187 quad_perm:[1,0,3,2] row_mask:0xf bank_mask:0xf
	v_add_f32_dpp v184, v184, v184 quad_perm:[2,3,0,1] row_mask:0xf bank_mask:0xf
	v_add_f32_dpp v185, v185, v185 quad_perm:[2,3,0,1] row_mask:0xf bank_mask:0xf
	v_add_f32_dpp v186, v186, v186 quad_perm:[2,3,0,1] row_mask:0xf bank_mask:0xf
	v_add_f32_dpp v187, v187, v187 quad_perm:[2,3,0,1] row_mask:0xf bank_mask:0xf
	v_add_f32_dpp v184, v184, v184 row_half_mirror row_mask:0xf bank_mask:0xf
	v_add_f32_dpp v185, v185, v185 row_half_mirror row_mask:0xf bank_mask:0xf
	v_add_f32_dpp v186, v186, v186 row_half_mirror row_mask:0xf bank_mask:0xf
	v_add_f32_dpp v187, v187, v187 row_half_mirror row_mask:0xf bank_mask:0xf
	v_add_f32_dpp v184, v184, v184 row_mirror row_mask:0xf bank_mask:0xf
	v_add_f32_dpp v185, v185, v185 row_mirror row_mask:0xf bank_mask:0xf
	v_add_f32_dpp v186, v186, v186 row_mirror row_mask:0xf bank_mask:0xf
	v_add_f32_dpp v187, v187, v187 row_mirror row_mask:0xf bank_mask:0xf
	v_add_f32_dpp v184, v184, v184 row_bcast:15 row_mask:0xa bank_mask:0xf
	v_add_f32_dpp v185, v185, v185 row_bcast:15 row_mask:0xa bank_mask:0xf
	v_add_f32_dpp v186, v186, v186 row_bcast:15 row_mask:0xa bank_mask:0xf
	v_add_f32_dpp v187, v187, v187 row_bcast:15 row_mask:0xa bank_mask:0xf
	v_add_f32_dpp v184, v184, v184 row_bcast:31 row_mask:0xc bank_mask:0xf
	v_add_f32_dpp v185, v185, v185 row_bcast:31 row_mask:0xc bank_mask:0xf
	v_add_f32_dpp v186, v186, v186 row_bcast:31 row_mask:0xc bank_mask:0xf
	v_add_f32_dpp v187, v187, v187 row_bcast:31 row_mask:0xc bank_mask:0xf
	s_nop 1
	v_readlane_b32 s3, v184, 63
	v_readlane_b32 s24, v185, 63
	v_readlane_b32 s98, v186, 63
	v_readlane_b32 s101, v187, 63
	s_nop 3
	v_writelane_b32 v188, s3, 0
	v_writelane_b32 v188, s24, 1
	v_writelane_b32 v188, s98, 2
	v_writelane_b32 v188, s101, 3
	s_nop 1
	v_mul_f32_e32 v188, 0x3a800000, v188
	v_add_f32_e32 v188, 0x358637bd, v188
	v_rsq_f32_e32 v188, v188
	s_mov_b64 exec, 15
	global_store_dword v21, v188, s[14:15]
	s_mov_b64 exec, -1
	s_waitcnt vmcnt(9)
; __device__ __forceinline__ float bf_lo(unsigned w) { return __uint_as_float(w << 16); }
; __device__ __forceinline__ float bf_hi(unsigned w) { return __uint_as_float(w & 0xffff0000u); }
; __device__ __forceinline__ unsigned pk2(float lo, float hi) { bf16x2_t r = __builtin_convertvector((f32x2_t){lo, hi}, bf16x2_t); return __builtin_bit_cast(unsigned, r); }
; template <bool SRC_F32, bool FINAL, int R> __device__ __forceinline__ void ew_compute(const EwSet<SRC_F32, R>& S, int rb, const f32x4 (&g)[4], bf16* hb_out, float* out32, float scale, float* rs_out, int lane) {
;     ...
;         float q = S.p[i];
;         q += __shfl_xor(q, 1); q += __shfl_xor(q, 2); q += __shfl_xor(q, 4); q += __shfl_xor(q, 8);
;         const float ss = __shfl(q, 0);
;         const float rs = scale / sqrtf(ss * (1.f / D) + EPS);
;         float s2 = 0.f;
; #pragma unroll
;         for (int j = 0; j < 4; ++j) {
;             f32x4 h;
;             if constexpr (SRC_F32) h = S.h32[i][j];
;             else { const v2u hw = S.hb[i][j]; h.x = bf_lo(hw.x); h.y = bf_hi(hw.x); h.z = bf_lo(hw.y); h.w = bf_hi(hw.y); }
;             const v2u fw = S.fw[i][j];
;             f32x4 v; v.x = h.x + bf_lo(fw.x) * rs * g[j].x; v.y = h.y + bf_hi(fw.x) * rs * g[j].y; v.z = h.z + bf_lo(fw.y) * rs * g[j].z; v.w = h.w + bf_hi(fw.y) * rs * g[j].w;
;             if (FINAL) __builtin_nontemporal_store(v, (f32x4*)(out32 + (size_t)(rb + i) * D) + lane + 64 * j);
;             else { v2u o; o.x = pk2(v.x, v.y); o.y = pk2(v.z, v.w); ((v2u*)(hb_out + (size_t)(rb + i) * D) + lane)[64 * j] = o; s2 += (v.x * v.x + v.y * v.y) + (v.z * v.z + v.w * v.w); }
	v_add_f32_dpp v164, v164, v164 quad_perm:[1,0,3,2] row_mask:0xf bank_mask:0xf
	s_nop 1
	v_add_f32_dpp v164, v164, v164 quad_perm:[2,3,0,1] row_mask:0xf bank_mask:0xf
	s_nop 1
	v_add_f32_dpp v164, v164, v164 row_half_mirror row_mask:0xf bank_mask:0xf
	s_nop 1
	v_add_f32_dpp v164, v164, v164 row_mirror row_mask:0xf bank_mask:0xf
	s_nop 1
	v_mul_f32_e32 v164, 0x3a800000, v164
	v_add_f32_e32 v164, 0x358637bd, v164
	v_rsq_f32_e32 v164, v164
	s_nop 0
	v_readlane_b32 s3, v164, 0
	v_readlane_b32 s24, v164, 16
	v_readlane_b32 s98, v164, 32
	v_readlane_b32 s101, v164, 48
	s_nop 1
	v_mov_b32_e32 v184, 0
	v_mov_b32_e32 v185, 0
	v_mov_b32_e32 v186, 0
	v_mov_b32_e32 v187, 0
	v_lshlrev_b32_e32 v168, 16, v100
	v_and_b32_e32 v169, 0xffff0000, v100
	v_lshlrev_b32_e32 v170, 16, v132
	v_and_b32_e32 v171, 0xffff0000, v132
	v_mul_f32_e32 v170, s3, v170
	v_mul_f32_e32 v171, s3, v171
	v_fma_f32 v168, v170, v2, v168
	v_fma_f32 v169, v171, v3, v169
	v_fma_f32 v184, v168, v168, v184
	v_fma_f32 v184, v169, v169, v184
	v_cvt_pk_bf16_f32 v100, v168, v169
	v_lshlrev_b32_e32 v168, 16, v101
	v_and_b32_e32 v169, 0xffff0000, v101
	v_lshlrev_b32_e32 v170, 16, v133
	v_and_b32_e32 v171, 0xffff0000, v133
	v_mul_f32_e32 v170, s3, v170
	v_mul_f32_e32 v171, s3, v171
	v_fma_f32 v168, v170, v4, v168
	v_fma_f32 v169, v171, v5, v169
	v_fma_f32 v184, v168, v168, v184
	v_fma_f32 v184, v169, v169, v184
	v_cvt_pk_bf16_f32 v101, v168, v169
	v_lshlrev_b32_e32 v168, 16, v102
	v_and_b32_e32 v169, 0xffff0000, v102
	v_lshlrev_b32_e32 v170, 16, v134
	v_and_b32_e32 v171, 0xffff0000, v134
	v_mul_f32_e32 v170, s3, v170
	v_mul_f32_e32 v171, s3, v171
	v_fma_f32 v168, v170, v6, v168
	v_fma_f32 v169, v171, v7, v169
	v_fma_f32 v184, v168, v168, v184
	v_fma_f32 v184, v169, v169, v184
	v_cvt_pk_bf16_f32 v102, v168, v169
	v_lshlrev_b32_e32 v168, 16, v103
	v_and_b32_e32 v169, 0xffff0000, v103
	v_lshlrev_b32_e32 v170, 16, v135
	v_and_b32_e32 v171, 0xffff0000, v135
	v_mul_f32_e32 v170, s3, v170
	v_mul_f32_e32 v171, s3, v171
	v_fma_f32 v168, v170, v8, v168
	v_fma_f32 v169, v171, v9, v169
	v_fma_f32 v184, v168, v168, v184
	v_fma_f32 v184, v169, v169, v184
	v_cvt_pk_bf16_f32 v103, v168, v169
	v_lshlrev_b32_e32 v168, 16, v104
	v_and_b32_e32 v169, 0xffff0000, v104
	v_lshlrev_b32_e32 v170, 16, v136
	v_and_b32_e32 v171, 0xffff0000, v136
	v_mul_f32_e32 v170, s3, v170
	v_mul_f32_e32 v171, s3, v171
	v_fma_f32 v168, v170, v10, v168
	v_fma_f32 v169, v171, v11, v169
	v_fma_f32 v184, v168, v168, v184
	v_fma_f32 v184, v169, v169, v184
	v_cvt_pk_bf16_f32 v104, v168, v169
	v_lshlrev_b32_e32 v168, 16, v105
	v_and_b32_e32 v169, 0xffff0000, v105
	v_lshlrev_b32_e32 v170, 16, v137
	v_and_b32_e32 v171, 0xffff0000, v137
	v_mul_f32_e32 v170, s3, v170
	v_mul_f32_e32 v171, s3, v171
	v_fma_f32 v168, v170, v12, v168
	v_fma_f32 v169, v171, v13, v169
	v_fma_f32 v184, v168, v168, v184
	v_fma_f32 v184, v169, v169, v184
	v_cvt_pk_bf16_f32 v105, v168, v169
	v_lshlrev_b32_e32 v168, 16, v106
	v_and_b32_e32 v169, 0xffff0000, v106
	v_lshlrev_b32_e32 v170, 16, v138
	v_and_b32_e32 v171, 0xffff0000, v138
	v_mul_f32_e32 v170, s3, v170
	v_mul_f32_e32 v171, s3, v171
	v_fma_f32 v168, v170, v14, v168
	v_fma_f32 v169, v171, v15, v169
	v_fma_f32 v184, v168, v168, v184
	v_fma_f32 v184, v169, v169, v184
	v_cvt_pk_bf16_f32 v106, v168, v169
	v_lshlrev_b32_e32 v168, 16, v107
	v_and_b32_e32 v169, 0xffff0000, v107
	v_lshlrev_b32_e32 v170, 16, v139
	v_and_b32_e32 v171, 0xffff0000, v139
	v_mul_f32_e32 v170, s3, v170
	v_mul_f32_e32 v171, s3, v171
	v_fma_f32 v168, v170, v16, v168
	v_fma_f32 v169, v171, v17, v169
	v_fma_f32 v184, v168, v168, v184
	v_fma_f32 v184, v169, v169, v184
	v_cvt_pk_bf16_f32 v107, v168, v169
	global_store_dwordx4 v23, v[100:103], s[0:1]
	global_store_dwordx4 v23, v[104:107], s[0:1] offset:1024
	v_lshlrev_b32_e32 v168, 16, v108
	v_and_b32_e32 v169, 0xffff0000, v108
	v_lshlrev_b32_e32 v170, 16, v140
	v_and_b32_e32 v171, 0xffff0000, v140
	v_mul_f32_e32 v170, s24, v170
	v_mul_f32_e32 v171, s24, v171
	v_fma_f32 v168, v170, v2, v168
	v_fma_f32 v169, v171, v3, v169
	v_fma_f32 v185, v168, v168, v185
	v_fma_f32 v185, v169, v169, v185
	v_cvt_pk_bf16_f32 v108, v168, v169
	v_lshlrev_b32_e32 v168, 16, v109
	v_and_b32_e32 v169, 0xffff0000, v109
	v_lshlrev_b32_e32 v170, 16, v141
	v_and_b32_e32 v171, 0xffff0000, v141
	v_mul_f32_e32 v170, s24, v170
	v_mul_f32_e32 v171, s24, v171
	v_fma_f32 v168, v170, v4, v168
	v_fma_f32 v169, v171, v5, v169
	v_fma_f32 v185, v168, v168, v185
	v_fma_f32 v185, v169, v169, v185
	v_cvt_pk_bf16_f32 v109, v168, v169
	v_lshlrev_b32_e32 v168, 16, v110
	v_and_b32_e32 v169, 0xffff0000, v110
	v_lshlrev_b32_e32 v170, 16, v142
	v_and_b32_e32 v171, 0xffff0000, v142
	v_mul_f32_e32 v170, s24, v170
	v_mul_f32_e32 v171, s24, v171
	v_fma_f32 v168, v170, v6, v168
	v_fma_f32 v169, v171, v7, v169
	v_fma_f32 v185, v168, v168, v185
	v_fma_f32 v185, v169, v169, v185
	v_cvt_pk_bf16_f32 v110, v168, v169
	v_lshlrev_b32_e32 v168, 16, v111
	v_and_b32_e32 v169, 0xffff0000, v111
	v_lshlrev_b32_e32 v170, 16, v143
	v_and_b32_e32 v171, 0xffff0000, v143
	v_mul_f32_e32 v170, s24, v170
	v_mul_f32_e32 v171, s24, v171
	v_fma_f32 v168, v170, v8, v168
	v_fma_f32 v169, v171, v9, v169
	v_fma_f32 v185, v168, v168, v185
	v_fma_f32 v185, v169, v169, v185
	v_cvt_pk_bf16_f32 v111, v168, v169
	v_lshlrev_b32_e32 v168, 16, v112
	v_and_b32_e32 v169, 0xffff0000, v112
	v_lshlrev_b32_e32 v170, 16, v144
	v_and_b32_e32 v171, 0xffff0000, v144
	v_mul_f32_e32 v170, s24, v170
	v_mul_f32_e32 v171, s24, v171
	v_fma_f32 v168, v170, v10, v168
	v_fma_f32 v169, v171, v11, v169
	v_fma_f32 v185, v168, v168, v185
	v_fma_f32 v185, v169, v169, v185
	v_cvt_pk_bf16_f32 v112, v168, v169
; __device__ __forceinline__ float bf_lo(unsigned w) { return __uint_as_float(w << 16); }
; __device__ __forceinline__ float bf_hi(unsigned w) { return __uint_as_float(w & 0xffff0000u); }
; __device__ __forceinline__ unsigned pk2(float lo, float hi) { bf16x2_t r = __builtin_convertvector((f32x2_t){lo, hi}, bf16x2_t); return __builtin_bit_cast(unsigned, r); }
; template <bool SRC_F32, bool FINAL, int R> __device__ __forceinline__ void ew_compute(const EwSet<SRC_F32, R>& S, int rb, const f32x4 (&g)[4], bf16* hb_out, float* out32, float scale, float* rs_out, int lane) {
; #pragma unroll
;     for (int i = 0; i < R; ++i) {
;         float q = S.p[i];
;         q += __shfl_xor(q, 1); q += __shfl_xor(q, 2); q += __shfl_xor(q, 4); q += __shfl_xor(q, 8);
;         const float ss = __shfl(q, 0);
;         const float rs = scale / sqrtf(ss * (1.f / D) + EPS);
;         float s2 = 0.f;
; #pragma unroll
;         for (int j = 0; j < 4; ++j) {
;             f32x4 h;
;             if constexpr (SRC_F32) h = S.h32[i][j];
;             else { const v2u hw = S.hb[i][j]; h.x = bf_lo(hw.x); h.y = bf_hi(hw.x); h.z = bf_lo(hw.y); h.w = bf_hi(hw.y); }
;             const v2u fw = S.fw[i][j];
;             f32x4 v; v.x = h.x + bf_lo(fw.x) * rs * g[j].x; v.y = h.y + bf_hi(fw.x) * rs * g[j].y; v.z = h.z + bf_lo(fw.y) * rs * g[j].z; v.w = h.w + bf_hi(fw.y) * rs * g[j].w;
;             if (FINAL) __builtin_nontemporal_store(v, (f32x4*)(out32 + (size_t)(rb + i) * D) + lane + 64 * j);
;             else { v2u o; o.x = pk2(v.x, v.y); o.y = pk2(v.z, v.w); ((v2u*)(hb_out + (size_t)(rb + i) * D) + lane)[64 * j] = o; s2 += (v.x * v.x + v.y * v.y) + (v.z * v.z + v.w * v.w); }
;         }
;         if (!FINAL) { const float tot = wave_sum(s2); if (lane == 0) rs_out[rb + i] = 1.0f / sqrtf(tot * (1.f / D) + EPS); }
;     }
	v_lshlrev_b32_e32 v168, 16, v113
	v_and_b32_e32 v169, 0xffff0000, v113
	v_lshlrev_b32_e32 v170, 16, v145
	v_and_b32_e32 v171, 0xffff0000, v145
	v_mul_f32_e32 v170, s24, v170
	v_mul_f32_e32 v171, s24, v171
	v_fma_f32 v168, v170, v12, v168
	v_fma_f32 v169, v171, v13, v169
	v_fma_f32 v185, v168, v168, v185
	v_fma_f32 v185, v169, v169, v185
	v_cvt_pk_bf16_f32 v113, v168, v169
	v_lshlrev_b32_e32 v168, 16, v114
	v_and_b32_e32 v169, 0xffff0000, v114
	v_lshlrev_b32_e32 v170, 16, v146
	v_and_b32_e32 v171, 0xffff0000, v146
	v_mul_f32_e32 v170, s24, v170
	v_mul_f32_e32 v171, s24, v171
	v_fma_f32 v168, v170, v14, v168
	v_fma_f32 v169, v171, v15, v169
	v_fma_f32 v185, v168, v168, v185
	v_fma_f32 v185, v169, v169, v185
	v_cvt_pk_bf16_f32 v114, v168, v169
	v_lshlrev_b32_e32 v168, 16, v115
	v_and_b32_e32 v169, 0xffff0000, v115
	v_lshlrev_b32_e32 v170, 16, v147
	v_and_b32_e32 v171, 0xffff0000, v147
	v_mul_f32_e32 v170, s24, v170
	v_mul_f32_e32 v171, s24, v171
	v_fma_f32 v168, v170, v16, v168
	v_fma_f32 v169, v171, v17, v169
	v_fma_f32 v185, v168, v168, v185
	v_fma_f32 v185, v169, v169, v185
	v_cvt_pk_bf16_f32 v115, v168, v169
	global_store_dwordx4 v23, v[108:111], s[0:1] offset:2048
	global_store_dwordx4 v23, v[112:115], s[0:1] offset:3072
	v_lshlrev_b32_e32 v168, 16, v116
	v_and_b32_e32 v169, 0xffff0000, v116
	v_lshlrev_b32_e32 v170, 16, v148
	v_and_b32_e32 v171, 0xffff0000, v148
	v_mul_f32_e32 v170, s98, v170
	v_mul_f32_e32 v171, s98, v171
	v_fma_f32 v168, v170, v2, v168
	v_fma_f32 v169, v171, v3, v169
	v_fma_f32 v186, v168, v168, v186
	v_fma_f32 v186, v169, v169, v186
	v_cvt_pk_bf16_f32 v116, v168, v169
	v_lshlrev_b32_e32 v168, 16, v117
	v_and_b32_e32 v169, 0xffff0000, v117
	v_lshlrev_b32_e32 v170, 16, v149
	v_and_b32_e32 v171, 0xffff0000, v149
	v_mul_f32_e32 v170, s98, v170
	v_mul_f32_e32 v171, s98, v171
	v_fma_f32 v168, v170, v4, v168
	v_fma_f32 v169, v171, v5, v169
	v_fma_f32 v186, v168, v168, v186
	v_fma_f32 v186, v169, v169, v186
	v_cvt_pk_bf16_f32 v117, v168, v169
	v_lshlrev_b32_e32 v168, 16, v118
	v_and_b32_e32 v169, 0xffff0000, v118
	v_lshlrev_b32_e32 v170, 16, v150
	v_and_b32_e32 v171, 0xffff0000, v150
	v_mul_f32_e32 v170, s98, v170
	v_mul_f32_e32 v171, s98, v171
	v_fma_f32 v168, v170, v6, v168
	v_fma_f32 v169, v171, v7, v169
	v_fma_f32 v186, v168, v168, v186
	v_fma_f32 v186, v169, v169, v186
	v_cvt_pk_bf16_f32 v118, v168, v169
	v_lshlrev_b32_e32 v168, 16, v119
	v_and_b32_e32 v169, 0xffff0000, v119
	v_lshlrev_b32_e32 v170, 16, v151
	v_and_b32_e32 v171, 0xffff0000, v151
	v_mul_f32_e32 v170, s98, v170
	v_mul_f32_e32 v171, s98, v171
	v_fma_f32 v168, v170, v8, v168
	v_fma_f32 v169, v171, v9, v169
	v_fma_f32 v186, v168, v168, v186
	v_fma_f32 v186, v169, v169, v186
	v_cvt_pk_bf16_f32 v119, v168, v169
	v_lshlrev_b32_e32 v168, 16, v120
	v_and_b32_e32 v169, 0xffff0000, v120
	v_lshlrev_b32_e32 v170, 16, v152
	v_and_b32_e32 v171, 0xffff0000, v152
	v_mul_f32_e32 v170, s98, v170
	v_mul_f32_e32 v171, s98, v171
	v_fma_f32 v168, v170, v10, v168
	v_fma_f32 v169, v171, v11, v169
	v_fma_f32 v186, v168, v168, v186
	v_fma_f32 v186, v169, v169, v186
	v_cvt_pk_bf16_f32 v120, v168, v169
	v_lshlrev_b32_e32 v168, 16, v121
	v_and_b32_e32 v169, 0xffff0000, v121
	v_lshlrev_b32_e32 v170, 16, v153
	v_and_b32_e32 v171, 0xffff0000, v153
	v_mul_f32_e32 v170, s98, v170
	v_mul_f32_e32 v171, s98, v171
	v_fma_f32 v168, v170, v12, v168
	v_fma_f32 v169, v171, v13, v169
	v_fma_f32 v186, v168, v168, v186
	v_fma_f32 v186, v169, v169, v186
	v_cvt_pk_bf16_f32 v121, v168, v169
	v_lshlrev_b32_e32 v168, 16, v122
	v_and_b32_e32 v169, 0xffff0000, v122
	v_lshlrev_b32_e32 v170, 16, v154
	v_and_b32_e32 v171, 0xffff0000, v154
	v_mul_f32_e32 v170, s98, v170
	v_mul_f32_e32 v171, s98, v171
	v_fma_f32 v168, v170, v14, v168
	v_fma_f32 v169, v171, v15, v169
	v_fma_f32 v186, v168, v168, v186
	v_fma_f32 v186, v169, v169, v186
	v_cvt_pk_bf16_f32 v122, v168, v169
	v_lshlrev_b32_e32 v168, 16, v123
	v_and_b32_e32 v169, 0xffff0000, v123
	v_lshlrev_b32_e32 v170, 16, v155
	v_and_b32_e32 v171, 0xffff0000, v155
	v_mul_f32_e32 v170, s98, v170
	v_mul_f32_e32 v171, s98, v171
	v_fma_f32 v168, v170, v16, v168
	v_fma_f32 v169, v171, v17, v169
	v_fma_f32 v186, v168, v168, v186
	v_fma_f32 v186, v169, v169, v186
	v_cvt_pk_bf16_f32 v123, v168, v169
	global_store_dwordx4 v24, v[116:119], s[0:1]
	global_store_dwordx4 v24, v[120:123], s[0:1] offset:1024
	v_lshlrev_b32_e32 v168, 16, v124
	v_and_b32_e32 v169, 0xffff0000, v124
	v_lshlrev_b32_e32 v170, 16, v156
	v_and_b32_e32 v171, 0xffff0000, v156
	v_mul_f32_e32 v170, s101, v170
	v_mul_f32_e32 v171, s101, v171
	v_fma_f32 v168, v170, v2, v168
	v_fma_f32 v169, v171, v3, v169
	v_fma_f32 v187, v168, v168, v187
	v_fma_f32 v187, v169, v169, v187
	v_cvt_pk_bf16_f32 v124, v168, v169
	v_lshlrev_b32_e32 v168, 16, v125
	v_and_b32_e32 v169, 0xffff0000, v125
	v_lshlrev_b32_e32 v170, 16, v157
	v_and_b32_e32 v171, 0xffff0000, v157
	v_mul_f32_e32 v170, s101, v170
	v_mul_f32_e32 v171, s101, v171
	v_fma_f32 v168, v170, v4, v168
	v_fma_f32 v169, v171, v5, v169
	v_fma_f32 v187, v168, v168, v187
; __device__ __forceinline__ float bf_lo(unsigned w) { return __uint_as_float(w << 16); }
; __device__ __forceinline__ float bf_hi(unsigned w) { return __uint_as_float(w & 0xffff0000u); }
; __device__ __forceinline__ unsigned pk2(float lo, float hi) { bf16x2_t r = __builtin_convertvector((f32x2_t){lo, hi}, bf16x2_t); return __builtin_bit_cast(unsigned, r); }
; template <bool SRC_F32, bool FINAL, int R> __device__ __forceinline__ void ew_compute(const EwSet<SRC_F32, R>& S, int rb, const f32x4 (&g)[4], bf16* hb_out, float* out32, float scale, float* rs_out, int lane) {
; #pragma unroll
;     for (int i = 0; i < R; ++i) {
;         float q = S.p[i];
;         q += __shfl_xor(q, 1); q += __shfl_xor(q, 2); q += __shfl_xor(q, 4); q += __shfl_xor(q, 8);
;         const float ss = __shfl(q, 0);
;         const float rs = scale / sqrtf(ss * (1.f / D) + EPS);
;         float s2 = 0.f;
; #pragma unroll
;         for (int j = 0; j < 4; ++j) {
;             f32x4 h;
;             if constexpr (SRC_F32) h = S.h32[i][j];
;             else { const v2u hw = S.hb[i][j]; h.x = bf_lo(hw.x); h.y = bf_hi(hw.x); h.z = bf_lo(hw.y); h.w = bf_hi(hw.y); }
;             const v2u fw = S.fw[i][j];
;             f32x4 v; v.x = h.x + bf_lo(fw.x) * rs * g[j].x; v.y = h.y + bf_hi(fw.x) * rs * g[j].y; v.z = h.z + bf_lo(fw.y) * rs * g[j].z; v.w = h.w + bf_hi(fw.y) * rs * g[j].w;
;             if (FINAL) __builtin_nontemporal_store(v, (f32x4*)(out32 + (size_t)(rb + i) * D) + lane + 64 * j);
;             else { v2u o; o.x = pk2(v.x, v.y); o.y = pk2(v.z, v.w); ((v2u*)(hb_out + (size_t)(rb + i) * D) + lane)[64 * j] = o; s2 += (v.x * v.x + v.y * v.y) + (v.z * v.z + v.w * v.w); }
;         }
;         if (!FINAL) { const float tot = wave_sum(s2); if (lane == 0) rs_out[rb + i] = 1.0f / sqrtf(tot * (1.f / D) + EPS); }
;     }
; __device__ __forceinline__ void xcd_barrier(const XcdBarrier& b) {
;     asm volatile("s_waitcnt vmcnt(0)" ::: "memory");
;     __syncthreads();
;     if (threadIdx.x == 0) {
;         unsigned* bar = b.bar;
;         __builtin_amdgcn_s_waitcnt(0);
;         unsigned nloc = b.st[0], nx = b.st[1];
;         if (nloc == 0u) { xcd_barrier_complete(bar, b.x, nloc, nx); b.st[0] = nloc; b.st[1] = nx; }
;         const unsigned old = xb_add(&bar[XB_XSUB(b.x)], 1u);
;         const unsigned gen = old / nloc;
;         if (old + 1u == (gen + 1u) * nloc) {
	v_fma_f32 v187, v169, v169, v187
	v_cvt_pk_bf16_f32 v125, v168, v169
	v_lshlrev_b32_e32 v168, 16, v126
	v_and_b32_e32 v169, 0xffff0000, v126
	v_lshlrev_b32_e32 v170, 16, v158
	v_and_b32_e32 v171, 0xffff0000, v158
	v_mul_f32_e32 v170, s101, v170
	v_mul_f32_e32 v171, s101, v171
	v_fma_f32 v168, v170, v6, v168
	v_fma_f32 v169, v171, v7, v169
	v_fma_f32 v187, v168, v168, v187
	v_fma_f32 v187, v169, v169, v187
	v_cvt_pk_bf16_f32 v126, v168, v169
	v_lshlrev_b32_e32 v168, 16, v127
	v_and_b32_e32 v169, 0xffff0000, v127
	v_lshlrev_b32_e32 v170, 16, v159
	v_and_b32_e32 v171, 0xffff0000, v159
	v_mul_f32_e32 v170, s101, v170
	v_mul_f32_e32 v171, s101, v171
	v_fma_f32 v168, v170, v8, v168
	v_fma_f32 v169, v171, v9, v169
	v_fma_f32 v187, v168, v168, v187
	v_fma_f32 v187, v169, v169, v187
	v_cvt_pk_bf16_f32 v127, v168, v169
	v_lshlrev_b32_e32 v168, 16, v128
	v_and_b32_e32 v169, 0xffff0000, v128
	v_lshlrev_b32_e32 v170, 16, v160
	v_and_b32_e32 v171, 0xffff0000, v160
	v_mul_f32_e32 v170, s101, v170
	v_mul_f32_e32 v171, s101, v171
	v_fma_f32 v168, v170, v10, v168
	v_fma_f32 v169, v171, v11, v169
	v_fma_f32 v187, v168, v168, v187
	v_fma_f32 v187, v169, v169, v187
	v_cvt_pk_bf16_f32 v128, v168, v169
	v_lshlrev_b32_e32 v168, 16, v129
	v_and_b32_e32 v169, 0xffff0000, v129
	v_lshlrev_b32_e32 v170, 16, v161
	v_and_b32_e32 v171, 0xffff0000, v161
	v_mul_f32_e32 v170, s101, v170
	v_mul_f32_e32 v171, s101, v171
	v_fma_f32 v168, v170, v12, v168
	v_fma_f32 v169, v171, v13, v169
	v_fma_f32 v187, v168, v168, v187
	v_fma_f32 v187, v169, v169, v187
	v_cvt_pk_bf16_f32 v129, v168, v169
	v_lshlrev_b32_e32 v168, 16, v130
	v_and_b32_e32 v169, 0xffff0000, v130
	v_lshlrev_b32_e32 v170, 16, v162
	v_and_b32_e32 v171, 0xffff0000, v162
	v_mul_f32_e32 v170, s101, v170
	v_mul_f32_e32 v171, s101, v171
	v_fma_f32 v168, v170, v14, v168
	v_fma_f32 v169, v171, v15, v169
	v_fma_f32 v187, v168, v168, v187
	v_fma_f32 v187, v169, v169, v187
	v_cvt_pk_bf16_f32 v130, v168, v169
	v_lshlrev_b32_e32 v168, 16, v131
	v_and_b32_e32 v169, 0xffff0000, v131
	v_lshlrev_b32_e32 v170, 16, v163
	v_and_b32_e32 v171, 0xffff0000, v163
	v_mul_f32_e32 v170, s101, v170
	v_mul_f32_e32 v171, s101, v171
	v_fma_f32 v168, v170, v16, v168
	v_fma_f32 v169, v171, v17, v169
	v_fma_f32 v187, v168, v168, v187
	v_fma_f32 v187, v169, v169, v187
	v_cvt_pk_bf16_f32 v131, v168, v169
	global_store_dwordx4 v24, v[124:127], s[0:1] offset:2048
	global_store_dwordx4 v24, v[128:131], s[0:1] offset:3072
	s_nop 1
	v_add_f32_dpp v184, v184, v184 quad_perm:[1,0,3,2] row_mask:0xf bank_mask:0xf
	v_add_f32_dpp v185, v185, v185 quad_perm:[1,0,3,2] row_mask:0xf bank_mask:0xf
	v_add_f32_dpp v186, v186, v186 quad_perm:[1,0,3,2] row_mask:0xf bank_mask:0xf
	v_add_f32_dpp v187, v187, v187 quad_perm:[1,0,3,2] row_mask:0xf bank_mask:0xf
	v_add_f32_dpp v184, v184, v184 quad_perm:[2,3,0,1] row_mask:0xf bank_mask:0xf
	v_add_f32_dpp v185, v185, v185 quad_perm:[2,3,0,1] row_mask:0xf bank_mask:0xf
	v_add_f32_dpp v186, v186, v186 quad_perm:[2,3,0,1] row_mask:0xf bank_mask:0xf
	v_add_f32_dpp v187, v187, v187 quad_perm:[2,3,0,1] row_mask:0xf bank_mask:0xf
	v_add_f32_dpp v184, v184, v184 row_half_mirror row_mask:0xf bank_mask:0xf
	v_add_f32_dpp v185, v185, v185 row_half_mirror row_mask:0xf bank_mask:0xf
	v_add_f32_dpp v186, v186, v186 row_half_mirror row_mask:0xf bank_mask:0xf
	v_add_f32_dpp v187, v187, v187 row_half_mirror row_mask:0xf bank_mask:0xf
	v_add_f32_dpp v184, v184, v184 row_mirror row_mask:0xf bank_mask:0xf
	v_add_f32_dpp v185, v185, v185 row_mirror row_mask:0xf bank_mask:0xf
	v_add_f32_dpp v186, v186, v186 row_mirror row_mask:0xf bank_mask:0xf
	v_add_f32_dpp v187, v187, v187 row_mirror row_mask:0xf bank_mask:0xf
	v_add_f32_dpp v184, v184, v184 row_bcast:15 row_mask:0xa bank_mask:0xf
	v_add_f32_dpp v185, v185, v185 row_bcast:15 row_mask:0xa bank_mask:0xf
	v_add_f32_dpp v186, v186, v186 row_bcast:15 row_mask:0xa bank_mask:0xf
	v_add_f32_dpp v187, v187, v187 row_bcast:15 row_mask:0xa bank_mask:0xf
	v_add_f32_dpp v184, v184, v184 row_bcast:31 row_mask:0xc bank_mask:0xf
	v_add_f32_dpp v185, v185, v185 row_bcast:31 row_mask:0xc bank_mask:0xf
	v_add_f32_dpp v186, v186, v186 row_bcast:31 row_mask:0xc bank_mask:0xf
	v_add_f32_dpp v187, v187, v187 row_bcast:31 row_mask:0xc bank_mask:0xf
	s_nop 1
	v_readlane_b32 s3, v184, 63
	v_readlane_b32 s24, v185, 63
	v_readlane_b32 s98, v186, 63
	v_readlane_b32 s101, v187, 63
	s_nop 3
	v_writelane_b32 v188, s3, 0
	v_writelane_b32 v188, s24, 1
	v_writelane_b32 v188, s98, 2
	v_writelane_b32 v188, s101, 3
	s_nop 1
	v_mul_f32_e32 v188, 0x3a800000, v188
	v_add_f32_e32 v188, 0x358637bd, v188
	v_rsq_f32_e32 v188, v188
	s_mov_b64 exec, 15
	global_store_dword v26, v188, s[14:15]
	s_mov_b64 exec, -1
.LBB0_989:
	s_cmp_gt_i32 s31, 9
	s_cselect_b64 s[0:1], -1, 0
	s_and_b64 s[4:5], s[8:9], s[0:1]
	s_andn2_b64 vcc, exec, s[4:5]
	s_cbranch_vccnz .LBB0_1039
	s_waitcnt vmcnt(0)
	s_barrier
	v_cmp_eq_u32_e32 vcc, 0, v195
	s_and_saveexec_b64 s[4:5], vcc
	s_cbranch_execz .Ltb1039_done
	s_cmp_eq_u32 s99, 1
	s_cbranch_scc1 .Ltb1039_fast
	buffer_wbl2 sc1
	s_waitcnt vmcnt(0)

; __device__ __forceinline__ unsigned xb_ld(unsigned* p)              { return __hip_atomic_load(p, __ATOMIC_RELAXED, __HIP_MEMORY_SCOPE_AGENT); }
; __device__ __forceinline__ unsigned xb_add(unsigned* p, unsigned v) { return __hip_atomic_fetch_add(p, v, __ATOMIC_RELAXED, __HIP_MEMORY_SCOPE_AGENT); }
; #define XB_SPIN(cond, bar) do { unsigned _sp = 0; while (cond) { __builtin_amdgcn_s_sleep(1); \
;     if ((++_sp & 255u) == 0u) { if (xb_ld(&(bar)[XB_TMO])) break; if (_sp > XB_SPIN_CAP) { atomicAdd(&(bar)[XB_TMO], 1u); break; } } } } while (0)
; __device__ __forceinline__ void xcd_barrier(const XcdBarrier& b) {
;     asm volatile("s_waitcnt vmcnt(0)" ::: "memory");
;     __syncthreads();
;     if (threadIdx.x == 0) {
;         unsigned* bar = b.bar;
;         __builtin_amdgcn_s_waitcnt(0);
;         unsigned nloc = b.st[0], nx = b.st[1];
;         if (nloc == 0u) { xcd_barrier_complete(bar, b.x, nloc, nx); b.st[0] = nloc; b.st[1] = nx; }
;         const unsigned old = xb_add(&bar[XB_XSUB(b.x)], 1u);
;         const unsigned gen = old / nloc;
;         if (old + 1u == (gen + 1u) * nloc) {
;             __builtin_amdgcn_fence(__ATOMIC_RELEASE, "agent");
;             asm volatile("s_waitcnt vmcnt(0)" ::: "memory");
;             const unsigned og = xb_add(&bar[XB_TOP], 1u);
;             const unsigned tg = og / nx;
;             if (og + 1u == (tg + 1u) * nx) xb_add(&bar[XB_TOPGEN], 1u);
;             else XB_SPIN(xb_ld(&bar[XB_TOPGEN]) == tg, bar);
;             __builtin_amdgcn_fence(__ATOMIC_ACQUIRE, "agent");
;             xb_add(&bar[XB_XGEN(b.x)], 1u);
;             asm volatile("s_waitcnt vmcnt(0)" ::: "memory");
;         } else {
;             XB_SPIN(xb_ld(&bar[XB_XGEN(b.x)]) == gen, bar);
;             __builtin_amdgcn_fence(__ATOMIC_ACQUIRE, "agent");
;             asm volatile("s_waitcnt vmcnt(0)" ::: "memory");
;         }
;     }
;     __syncthreads();
; }
.Ltb1039_done:
	s_or_b64 exec, exec, s[4:5]
	s_barrier
.LBB0_1039:
	s_cmp_lt_i32 s30, 10
	s_cselect_b64 s[4:5], -1, 0
	s_and_b64 s[6:7], s[4:5], s[0:1]
	s_andn2_b64 vcc, exec, s[6:7]
	s_cbranch_vccnz .LBB0_1084
	s_mov_b32 s8, -1
	s_ashr_i32 s3, s2, 31
	s_mov_b32 s9, s8
	s_ashr_i32 s42, s33, 31
	s_waitcnt vmcnt(0)
	v_mov_b64_e32 v[0:1], 0xb00
	v_mov_b64_e32 v[2:3], 0xaff
	s_movk_i32 s23, 0x161
	s_mov_b64 s[12:13], s[2:3]
	s_mov_b32 s22, s8
	s_mov_b64 s[10:11], s[8:9]
	s_branch .LBB0_1043

; __device__ __forceinline__ unsigned xb_add(unsigned* p, unsigned v) { return __hip_atomic_fetch_add(p, v, __ATOMIC_RELAXED, __HIP_MEMORY_SCOPE_AGENT); }
; __device__ __forceinline__ void xcd_barrier(const XcdBarrier& b) {
;     asm volatile("s_waitcnt vmcnt(0)" ::: "memory");
;     __syncthreads();
;     if (threadIdx.x == 0) {
;         unsigned* bar = b.bar;
;         __builtin_amdgcn_s_waitcnt(0);
;         unsigned nloc = b.st[0], nx = b.st[1];
;         if (nloc == 0u) { xcd_barrier_complete(bar, b.x, nloc, nx); b.st[0] = nloc; b.st[1] = nx; }
;         const unsigned old = xb_add(&bar[XB_XSUB(b.x)], 1u);
;         const unsigned gen = old / nloc;
;         if (old + 1u == (gen + 1u) * nloc) {
.LBB0_1163:
	s_cmp_gt_i32 s31, 11
	s_cselect_b64 s[0:1], -1, 0
	s_and_b64 s[4:5], s[6:7], s[0:1]
	s_andn2_b64 vcc, exec, s[4:5]
	s_cbranch_vccnz .LBB0_1213
	s_waitcnt vmcnt(0)
	s_barrier
	v_cmp_eq_u32_e32 vcc, 0, v195
	s_and_saveexec_b64 s[4:5], vcc
	s_cbranch_execz .Ltb1213_done
	s_cmp_eq_u32 s99, 1
	s_cbranch_scc1 .Ltb1213_fast
	buffer_wbl2 sc1
	s_waitcnt vmcnt(0)

; template <bool SRC_F32, int R> __device__ __forceinline__ void ew_load(EwSet<SRC_F32, R>& S, int rb, const float* hsrc32, const bf16* hsrcb, const bf16* f, const float* part, int lane) {
; #pragma unroll
;     for (int i = 0; i < R; ++i) S.p[i] = (lane < 16) ? part[(size_t)(rb + i) * 16 + lane] : 0.f;
; #pragma unroll
;     for (int i = 0; i < R; ++i)
; #pragma unroll
;         for (int j = 0; j < 4; ++j) {
;             S.fw[i][j] = ((const v2u*)(f + (size_t)(rb + i) * D) + lane)[64 * j];
;             if constexpr (SRC_F32) S.h32[i][j] = __builtin_nontemporal_load((const f32x4*)(hsrc32 + (size_t)(rb + i) * D) + lane + 64 * j);
;             else S.hb[i][j] = ((const v2u*)(hsrcb + (size_t)(rb + i) * D) + lane)[64 * j];
;         }
; }
; template <bool SRC_F32, bool FINAL> __device__ __forceinline__ void ew_phase(const float* hsrc32, const bf16* hsrcb, bf16* hb_out, float* out32, const bf16* f, const float* part, const float* gpost, float scale, float* rs_out, int gw, int NGW, int lane) {
;     constexpr int R = SRC_F32 ? 2 : 4;
;     f32x4 g[4];
; #pragma unroll
;     for (int j = 0; j < 4; ++j) g[j] = ((const f32x4*)gpost + lane)[64 * j];
;     const int step = NGW * R;
;     EwSet<SRC_F32, R> A, B;
;     int rb = gw * R;
;     if (rb < M) ew_load<SRC_F32, R>(A, rb, hsrc32, hsrcb, f, part, lane);
; #pragma unroll 1
;     for (; rb < M; rb += 2 * step) {
;         const int nb = rb + step, nb2 = nb + step;
;         if (nb < M) ew_load<SRC_F32, R>(B, nb, hsrc32, hsrcb, f, part, lane);
;         ew_compute<SRC_F32, FINAL, R>(A, rb, g, hb_out, out32, scale, rs_out, lane);
;         if (nb2 < M) ew_load<SRC_F32, R>(A, nb2, hsrc32, hsrcb, f, part, lane);
;         if (nb < M) ew_compute<SRC_F32, FINAL, R>(B, nb, g, hb_out, out32, scale, rs_out, lane);
;     }
; }
.LBB0_1213:
	s_cmp_lt_i32 s30, 12
	s_cselect_b64 s[4:5], -1, 0
	s_and_b64 s[8:9], s[4:5], s[0:1]
	s_andn2_b64 vcc, exec, s[8:9]
	s_cbranch_vccnz .LBB0_1259
	s_waitcnt vmcnt(0) lgkmcnt(0)
	s_add_u32 s22, s84, 0xffffff10
	s_addc_u32 s23, s85, -1
	s_load_dwordx2 s[26:27], s[22:23], 0xb0
	s_add_u32 s0, s28, 0x5000000
	s_addc_u32 s1, s29, 0
	s_add_u32 s4, s28, 0x15000000
	s_addc_u32 s5, s29, 0
	s_add_u32 s6, s28, 0x3700000
	s_addc_u32 s7, s29, 0
	s_add_u32 s14, s28, 0x3910000
	s_addc_u32 s15, s29, 0
	v_and_b32_e32 v0, 63, v195
	v_lshlrev_b32_e32 v1, 5, v0
	s_waitcnt lgkmcnt(0)
	global_load_dwordx4 v[2:5], v1, s[26:27]
	global_load_dwordx4 v[6:9], v1, s[26:27] offset:16
	global_load_dwordx4 v[10:13], v1, s[26:27] offset:2048
	global_load_dwordx4 v[14:17], v1, s[26:27] offset:2064
	s_and_b32 s26, s2, 7
	s_lshl_b32 s26, s26, 4
	s_bfe_u32 s27, s2, 0x30003
	s_add_u32 s26, s26, s27
	s_lshl_b32 s26, s26, 8
	s_lshr_b32 s27, s2, 6
	s_lshl_b32 s27, s27, 6
	s_add_u32 s26, s26, s27
	v_readfirstlane_b32 s27, v195
	s_lshr_b32 s27, s27, 6
	s_lshl_b32 s27, s27, 3
	s_add_u32 s26, s26, s27
	s_add_u32 s27, s26, 0
	s_lshl_b32 s22, s27, 11
	v_lshl_add_u32 v18, v0, 4, s22
	v_add_u32_e32 v19, 0x1000, v18
	s_lshl_b32 s22, s27, 6
	v_lshl_add_u32 v20, v0, 2, s22
	s_lshl_b32 s22, s27, 2
	v_lshl_add_u32 v21, v0, 2, s22
	global_load_dwordx4 v[32:35], v18, s[0:1]
	global_load_dwordx4 v[36:39], v18, s[0:1] offset:1024
	global_load_dwordx4 v[64:67], v18, s[4:5]
	global_load_dwordx4 v[68:71], v18, s[4:5] offset:1024
	global_load_dwordx4 v[40:43], v18, s[0:1] offset:2048
	global_load_dwordx4 v[44:47], v18, s[0:1] offset:3072
	global_load_dwordx4 v[72:75], v18, s[4:5] offset:2048
	global_load_dwordx4 v[76:79], v18, s[4:5] offset:3072
	global_load_dwordx4 v[48:51], v19, s[0:1]
	global_load_dwordx4 v[52:55], v19, s[0:1] offset:1024
	global_load_dwordx4 v[80:83], v19, s[4:5]
	global_load_dwordx4 v[84:87], v19, s[4:5] offset:1024
	global_load_dwordx4 v[56:59], v19, s[0:1] offset:2048
	global_load_dwordx4 v[60:63], v19, s[0:1] offset:3072
	global_load_dwordx4 v[88:91], v19, s[4:5] offset:2048
	global_load_dwordx4 v[92:95], v19, s[4:5] offset:3072
	global_load_dword v96, v20, s[6:7]
	s_add_u32 s27, s26, 4
	s_lshl_b32 s22, s27, 11
	v_lshl_add_u32 v23, v0, 4, s22
	v_add_u32_e32 v24, 0x1000, v23
	s_lshl_b32 s22, s27, 6
	v_lshl_add_u32 v25, v0, 2, s22
	s_lshl_b32 s22, s27, 2
	v_lshl_add_u32 v26, v0, 2, s22
	global_load_dwordx4 v[100:103], v23, s[0:1]
	global_load_dwordx4 v[104:107], v23, s[0:1] offset:1024
	global_load_dwordx4 v[132:135], v23, s[4:5]
	global_load_dwordx4 v[136:139], v23, s[4:5] offset:1024
	global_load_dwordx4 v[108:111], v23, s[0:1] offset:2048
	global_load_dwordx4 v[112:115], v23, s[0:1] offset:3072
	global_load_dwordx4 v[140:143], v23, s[4:5] offset:2048
	global_load_dwordx4 v[144:147], v23, s[4:5] offset:3072
	global_load_dwordx4 v[116:119], v24, s[0:1]
	global_load_dwordx4 v[120:123], v24, s[0:1] offset:1024
	global_load_dwordx4 v[148:151], v24, s[4:5]
	global_load_dwordx4 v[152:155], v24, s[4:5] offset:1024
	global_load_dwordx4 v[124:127], v24, s[0:1] offset:2048
	global_load_dwordx4 v[128:131], v24, s[0:1] offset:3072
	global_load_dwordx4 v[156:159], v24, s[4:5] offset:2048
	global_load_dwordx4 v[160:163], v24, s[4:5] offset:3072
	global_load_dword v164, v25, s[6:7]
	s_waitcnt vmcnt(17)
	v_add_f32_dpp v96, v96, v96 quad_perm:[1,0,3,2] row_mask:0xf bank_mask:0xf
	s_nop 1
	v_add_f32_dpp v96, v96, v96 quad_perm:[2,3,0,1] row_mask:0xf bank_mask:0xf
	s_nop 1
	v_add_f32_dpp v96, v96, v96 row_half_mirror row_mask:0xf bank_mask:0xf
	s_nop 1
	v_add_f32_dpp v96, v96, v96 row_mirror row_mask:0xf bank_mask:0xf
	s_nop 1
	v_mul_f32_e32 v96, 0x3a800000, v96
	v_add_f32_e32 v96, 0x358637bd, v96
	v_rsq_f32_e32 v96, v96
	s_nop 0
	v_mul_f32_e32 v96, 0x3f000000, v96
	s_nop 0
	v_readlane_b32 s3, v96, 0
	v_readlane_b32 s24, v96, 16
	v_readlane_b32 s98, v96, 32
	v_readlane_b32 s101, v96, 48
	s_nop 1
	v_mov_b32_e32 v184, 0
	v_mov_b32_e32 v185, 0
	v_mov_b32_e32 v186, 0
	v_mov_b32_e32 v187, 0
	v_lshlrev_b32_e32 v168, 16, v32
	v_and_b32_e32 v169, 0xffff0000, v32
	v_lshlrev_b32_e32 v170, 16, v64
	v_and_b32_e32 v171, 0xffff0000, v64
	v_mul_f32_e32 v170, s3, v170
	v_mul_f32_e32 v171, s3, v171
	v_fma_f32 v168, v170, v2, v168
	v_fma_f32 v169, v171, v3, v169
	v_fma_f32 v184, v168, v168, v184
	v_fma_f32 v184, v169, v169, v184
	v_cvt_pk_bf16_f32 v32, v168, v169
	v_lshlrev_b32_e32 v168, 16, v33
	v_and_b32_e32 v169, 0xffff0000, v33
	v_lshlrev_b32_e32 v170, 16, v65
	v_and_b32_e32 v171, 0xffff0000, v65
	v_mul_f32_e32 v170, s3, v170
	v_mul_f32_e32 v171, s3, v171
	v_fma_f32 v168, v170, v4, v168
	v_fma_f32 v169, v171, v5, v169
	v_fma_f32 v184, v168, v168, v184
	v_fma_f32 v184, v169, v169, v184
	v_cvt_pk_bf16_f32 v33, v168, v169
	v_lshlrev_b32_e32 v168, 16, v34
	v_and_b32_e32 v169, 0xffff0000, v34
	v_lshlrev_b32_e32 v170, 16, v66
	v_and_b32_e32 v171, 0xffff0000, v66
	v_mul_f32_e32 v170, s3, v170
	v_mul_f32_e32 v171, s3, v171
	v_fma_f32 v168, v170, v6, v168
	v_fma_f32 v169, v171, v7, v169
	v_fma_f32 v184, v168, v168, v184
	v_fma_f32 v184, v169, v169, v184
	v_cvt_pk_bf16_f32 v34, v168, v169
	v_lshlrev_b32_e32 v168, 16, v35
	v_and_b32_e32 v169, 0xffff0000, v35
	v_lshlrev_b32_e32 v170, 16, v67
	v_and_b32_e32 v171, 0xffff0000, v67
	v_mul_f32_e32 v170, s3, v170
	v_mul_f32_e32 v171, s3, v171
	v_fma_f32 v168, v170, v8, v168
	v_fma_f32 v169, v171, v9, v169
	v_fma_f32 v184, v168, v168, v184
	v_fma_f32 v184, v169, v169, v184
	v_cvt_pk_bf16_f32 v35, v168, v169
	v_lshlrev_b32_e32 v168, 16, v36
	v_and_b32_e32 v169, 0xffff0000, v36
	v_lshlrev_b32_e32 v170, 16, v68
	v_and_b32_e32 v171, 0xffff0000, v68
	v_mul_f32_e32 v170, s3, v170
; __device__ __forceinline__ float bf_lo(unsigned w) { return __uint_as_float(w << 16); }
; __device__ __forceinline__ float bf_hi(unsigned w) { return __uint_as_float(w & 0xffff0000u); }
; __device__ __forceinline__ unsigned pk2(float lo, float hi) { bf16x2_t r = __builtin_convertvector((f32x2_t){lo, hi}, bf16x2_t); return __builtin_bit_cast(unsigned, r); }
; template <bool SRC_F32, bool FINAL, int R> __device__ __forceinline__ void ew_compute(const EwSet<SRC_F32, R>& S, int rb, const f32x4 (&g)[4], bf16* hb_out, float* out32, float scale, float* rs_out, int lane) {
; #pragma unroll
;     for (int i = 0; i < R; ++i) {
;         float q = S.p[i];
;         q += __shfl_xor(q, 1); q += __shfl_xor(q, 2); q += __shfl_xor(q, 4); q += __shfl_xor(q, 8);
;         const float ss = __shfl(q, 0);
;         const float rs = scale / sqrtf(ss * (1.f / D) + EPS);
;         float s2 = 0.f;
; #pragma unroll
;         for (int j = 0; j < 4; ++j) {
;             f32x4 h;
;             if constexpr (SRC_F32) h = S.h32[i][j];
;             else { const v2u hw = S.hb[i][j]; h.x = bf_lo(hw.x); h.y = bf_hi(hw.x); h.z = bf_lo(hw.y); h.w = bf_hi(hw.y); }
;             const v2u fw = S.fw[i][j];
;             f32x4 v; v.x = h.x + bf_lo(fw.x) * rs * g[j].x; v.y = h.y + bf_hi(fw.x) * rs * g[j].y; v.z = h.z + bf_lo(fw.y) * rs * g[j].z; v.w = h.w + bf_hi(fw.y) * rs * g[j].w;
;             if (FINAL) __builtin_nontemporal_store(v, (f32x4*)(out32 + (size_t)(rb + i) * D) + lane + 64 * j);
;             else { v2u o; o.x = pk2(v.x, v.y); o.y = pk2(v.z, v.w); ((v2u*)(hb_out + (size_t)(rb + i) * D) + lane)[64 * j] = o; s2 += (v.x * v.x + v.y * v.y) + (v.z * v.z + v.w * v.w); }
;         }
;         if (!FINAL) { const float tot = wave_sum(s2); if (lane == 0) rs_out[rb + i] = 1.0f / sqrtf(tot * (1.f / D) + EPS); }
;     }
	v_mul_f32_e32 v171, s3, v171
	v_fma_f32 v168, v170, v10, v168
	v_fma_f32 v169, v171, v11, v169
	v_fma_f32 v184, v168, v168, v184
	v_fma_f32 v184, v169, v169, v184
	v_cvt_pk_bf16_f32 v36, v168, v169
	v_lshlrev_b32_e32 v168, 16, v37
	v_and_b32_e32 v169, 0xffff0000, v37
	v_lshlrev_b32_e32 v170, 16, v69
	v_and_b32_e32 v171, 0xffff0000, v69
	v_mul_f32_e32 v170, s3, v170
	v_mul_f32_e32 v171, s3, v171
	v_fma_f32 v168, v170, v12, v168
	v_fma_f32 v169, v171, v13, v169
	v_fma_f32 v184, v168, v168, v184
	v_fma_f32 v184, v169, v169, v184
	v_cvt_pk_bf16_f32 v37, v168, v169
	v_lshlrev_b32_e32 v168, 16, v38
	v_and_b32_e32 v169, 0xffff0000, v38
	v_lshlrev_b32_e32 v170, 16, v70
	v_and_b32_e32 v171, 0xffff0000, v70
	v_mul_f32_e32 v170, s3, v170
	v_mul_f32_e32 v171, s3, v171
	v_fma_f32 v168, v170, v14, v168
	v_fma_f32 v169, v171, v15, v169
	v_fma_f32 v184, v168, v168, v184
	v_fma_f32 v184, v169, v169, v184
	v_cvt_pk_bf16_f32 v38, v168, v169
	v_lshlrev_b32_e32 v168, 16, v39
	v_and_b32_e32 v169, 0xffff0000, v39
	v_lshlrev_b32_e32 v170, 16, v71
	v_and_b32_e32 v171, 0xffff0000, v71
	v_mul_f32_e32 v170, s3, v170
	v_mul_f32_e32 v171, s3, v171
	v_fma_f32 v168, v170, v16, v168
	v_fma_f32 v169, v171, v17, v169
	v_fma_f32 v184, v168, v168, v184
	v_fma_f32 v184, v169, v169, v184
	v_cvt_pk_bf16_f32 v39, v168, v169
	global_store_dwordx4 v18, v[32:35], s[0:1]
	global_store_dwordx4 v18, v[36:39], s[0:1] offset:1024
	v_lshlrev_b32_e32 v168, 16, v40
	v_and_b32_e32 v169, 0xffff0000, v40
	v_lshlrev_b32_e32 v170, 16, v72
	v_and_b32_e32 v171, 0xffff0000, v72
	v_mul_f32_e32 v170, s24, v170
	v_mul_f32_e32 v171, s24, v171
	v_fma_f32 v168, v170, v2, v168
	v_fma_f32 v169, v171, v3, v169
	v_fma_f32 v185, v168, v168, v185
	v_fma_f32 v185, v169, v169, v185
	v_cvt_pk_bf16_f32 v40, v168, v169
	v_lshlrev_b32_e32 v168, 16, v41
	v_and_b32_e32 v169, 0xffff0000, v41
	v_lshlrev_b32_e32 v170, 16, v73
	v_and_b32_e32 v171, 0xffff0000, v73
	v_mul_f32_e32 v170, s24, v170
	v_mul_f32_e32 v171, s24, v171
	v_fma_f32 v168, v170, v4, v168
	v_fma_f32 v169, v171, v5, v169
	v_fma_f32 v185, v168, v168, v185
	v_fma_f32 v185, v169, v169, v185
	v_cvt_pk_bf16_f32 v41, v168, v169
	v_lshlrev_b32_e32 v168, 16, v42
	v_and_b32_e32 v169, 0xffff0000, v42
	v_lshlrev_b32_e32 v170, 16, v74
	v_and_b32_e32 v171, 0xffff0000, v74
	v_mul_f32_e32 v170, s24, v170
	v_mul_f32_e32 v171, s24, v171
	v_fma_f32 v168, v170, v6, v168
	v_fma_f32 v169, v171, v7, v169
	v_fma_f32 v185, v168, v168, v185
	v_fma_f32 v185, v169, v169, v185
	v_cvt_pk_bf16_f32 v42, v168, v169
	v_lshlrev_b32_e32 v168, 16, v43
	v_and_b32_e32 v169, 0xffff0000, v43
	v_lshlrev_b32_e32 v170, 16, v75
	v_and_b32_e32 v171, 0xffff0000, v75
	v_mul_f32_e32 v170, s24, v170
	v_mul_f32_e32 v171, s24, v171
	v_fma_f32 v168, v170, v8, v168
	v_fma_f32 v169, v171, v9, v169
	v_fma_f32 v185, v168, v168, v185
	v_fma_f32 v185, v169, v169, v185
	v_cvt_pk_bf16_f32 v43, v168, v169
	v_lshlrev_b32_e32 v168, 16, v44
	v_and_b32_e32 v169, 0xffff0000, v44
	v_lshlrev_b32_e32 v170, 16, v76
	v_and_b32_e32 v171, 0xffff0000, v76
	v_mul_f32_e32 v170, s24, v170
	v_mul_f32_e32 v171, s24, v171
	v_fma_f32 v168, v170, v10, v168
	v_fma_f32 v169, v171, v11, v169
	v_fma_f32 v185, v168, v168, v185
	v_fma_f32 v185, v169, v169, v185
	v_cvt_pk_bf16_f32 v44, v168, v169
	v_lshlrev_b32_e32 v168, 16, v45
	v_and_b32_e32 v169, 0xffff0000, v45
	v_lshlrev_b32_e32 v170, 16, v77
	v_and_b32_e32 v171, 0xffff0000, v77
	v_mul_f32_e32 v170, s24, v170
	v_mul_f32_e32 v171, s24, v171
	v_fma_f32 v168, v170, v12, v168
	v_fma_f32 v169, v171, v13, v169
	v_fma_f32 v185, v168, v168, v185
	v_fma_f32 v185, v169, v169, v185
	v_cvt_pk_bf16_f32 v45, v168, v169
	v_lshlrev_b32_e32 v168, 16, v46
	v_and_b32_e32 v169, 0xffff0000, v46
	v_lshlrev_b32_e32 v170, 16, v78
	v_and_b32_e32 v171, 0xffff0000, v78
	v_mul_f32_e32 v170, s24, v170
	v_mul_f32_e32 v171, s24, v171
	v_fma_f32 v168, v170, v14, v168
	v_fma_f32 v169, v171, v15, v169
	v_fma_f32 v185, v168, v168, v185
	v_fma_f32 v185, v169, v169, v185
	v_cvt_pk_bf16_f32 v46, v168, v169
	v_lshlrev_b32_e32 v168, 16, v47
	v_and_b32_e32 v169, 0xffff0000, v47
	v_lshlrev_b32_e32 v170, 16, v79
	v_and_b32_e32 v171, 0xffff0000, v79
	v_mul_f32_e32 v170, s24, v170
	v_mul_f32_e32 v171, s24, v171
	v_fma_f32 v168, v170, v16, v168
	v_fma_f32 v169, v171, v17, v169
	v_fma_f32 v185, v168, v168, v185
	v_fma_f32 v185, v169, v169, v185
	v_cvt_pk_bf16_f32 v47, v168, v169
	global_store_dwordx4 v18, v[40:43], s[0:1] offset:2048
	global_store_dwordx4 v18, v[44:47], s[0:1] offset:3072
	v_lshlrev_b32_e32 v168, 16, v48
	v_and_b32_e32 v169, 0xffff0000, v48
	v_lshlrev_b32_e32 v170, 16, v80
	v_and_b32_e32 v171, 0xffff0000, v80
	v_mul_f32_e32 v170, s98, v170
	v_mul_f32_e32 v171, s98, v171
	v_fma_f32 v168, v170, v2, v168
	v_fma_f32 v169, v171, v3, v169
	v_fma_f32 v186, v168, v168, v186
	v_fma_f32 v186, v169, v169, v186
	v_cvt_pk_bf16_f32 v48, v168, v169
	v_lshlrev_b32_e32 v168, 16, v49
	v_and_b32_e32 v169, 0xffff0000, v49
	v_lshlrev_b32_e32 v170, 16, v81
	v_and_b32_e32 v171, 0xffff0000, v81
	v_mul_f32_e32 v170, s98, v170
	v_mul_f32_e32 v171, s98, v171
	v_fma_f32 v168, v170, v4, v168
	v_fma_f32 v169, v171, v5, v169
	v_fma_f32 v186, v168, v168, v186
	v_fma_f32 v186, v169, v169, v186
	v_cvt_pk_bf16_f32 v49, v168, v169
	v_lshlrev_b32_e32 v168, 16, v50
	v_and_b32_e32 v169, 0xffff0000, v50
	v_lshlrev_b32_e32 v170, 16, v82
	v_and_b32_e32 v171, 0xffff0000, v82
	v_mul_f32_e32 v170, s98, v170
	v_mul_f32_e32 v171, s98, v171
	v_fma_f32 v168, v170, v6, v168
	v_fma_f32 v169, v171, v7, v169
	v_fma_f32 v186, v168, v168, v186
	v_fma_f32 v186, v169, v169, v186
	v_cvt_pk_bf16_f32 v50, v168, v169
	v_lshlrev_b32_e32 v168, 16, v51
	v_and_b32_e32 v169, 0xffff0000, v51
; __device__ __forceinline__ float bf_lo(unsigned w) { return __uint_as_float(w << 16); }
; __device__ __forceinline__ float bf_hi(unsigned w) { return __uint_as_float(w & 0xffff0000u); }
; __device__ __forceinline__ unsigned pk2(float lo, float hi) { bf16x2_t r = __builtin_convertvector((f32x2_t){lo, hi}, bf16x2_t); return __builtin_bit_cast(unsigned, r); }
; template <bool SRC_F32, bool FINAL, int R> __device__ __forceinline__ void ew_compute(const EwSet<SRC_F32, R>& S, int rb, const f32x4 (&g)[4], bf16* hb_out, float* out32, float scale, float* rs_out, int lane) {
; #pragma unroll
;     for (int i = 0; i < R; ++i) {
;         float q = S.p[i];
;         q += __shfl_xor(q, 1); q += __shfl_xor(q, 2); q += __shfl_xor(q, 4); q += __shfl_xor(q, 8);
;         const float ss = __shfl(q, 0);
;         const float rs = scale / sqrtf(ss * (1.f / D) + EPS);
;         float s2 = 0.f;
; #pragma unroll
;         for (int j = 0; j < 4; ++j) {
;             f32x4 h;
;             if constexpr (SRC_F32) h = S.h32[i][j];
;             else { const v2u hw = S.hb[i][j]; h.x = bf_lo(hw.x); h.y = bf_hi(hw.x); h.z = bf_lo(hw.y); h.w = bf_hi(hw.y); }
;             const v2u fw = S.fw[i][j];
;             f32x4 v; v.x = h.x + bf_lo(fw.x) * rs * g[j].x; v.y = h.y + bf_hi(fw.x) * rs * g[j].y; v.z = h.z + bf_lo(fw.y) * rs * g[j].z; v.w = h.w + bf_hi(fw.y) * rs * g[j].w;
;             if (FINAL) __builtin_nontemporal_store(v, (f32x4*)(out32 + (size_t)(rb + i) * D) + lane + 64 * j);
;             else { v2u o; o.x = pk2(v.x, v.y); o.y = pk2(v.z, v.w); ((v2u*)(hb_out + (size_t)(rb + i) * D) + lane)[64 * j] = o; s2 += (v.x * v.x + v.y * v.y) + (v.z * v.z + v.w * v.w); }
;         }
;         if (!FINAL) { const float tot = wave_sum(s2); if (lane == 0) rs_out[rb + i] = 1.0f / sqrtf(tot * (1.f / D) + EPS); }
;     }
	v_lshlrev_b32_e32 v170, 16, v83
	v_and_b32_e32 v171, 0xffff0000, v83
	v_mul_f32_e32 v170, s98, v170
	v_mul_f32_e32 v171, s98, v171
	v_fma_f32 v168, v170, v8, v168
	v_fma_f32 v169, v171, v9, v169
	v_fma_f32 v186, v168, v168, v186
	v_fma_f32 v186, v169, v169, v186
	v_cvt_pk_bf16_f32 v51, v168, v169
	v_lshlrev_b32_e32 v168, 16, v52
	v_and_b32_e32 v169, 0xffff0000, v52
	v_lshlrev_b32_e32 v170, 16, v84
	v_and_b32_e32 v171, 0xffff0000, v84
	v_mul_f32_e32 v170, s98, v170
	v_mul_f32_e32 v171, s98, v171
	v_fma_f32 v168, v170, v10, v168
	v_fma_f32 v169, v171, v11, v169
	v_fma_f32 v186, v168, v168, v186
	v_fma_f32 v186, v169, v169, v186
	v_cvt_pk_bf16_f32 v52, v168, v169
	v_lshlrev_b32_e32 v168, 16, v53
	v_and_b32_e32 v169, 0xffff0000, v53
	v_lshlrev_b32_e32 v170, 16, v85
	v_and_b32_e32 v171, 0xffff0000, v85
	v_mul_f32_e32 v170, s98, v170
	v_mul_f32_e32 v171, s98, v171
	v_fma_f32 v168, v170, v12, v168
	v_fma_f32 v169, v171, v13, v169
	v_fma_f32 v186, v168, v168, v186
	v_fma_f32 v186, v169, v169, v186
	v_cvt_pk_bf16_f32 v53, v168, v169
	v_lshlrev_b32_e32 v168, 16, v54
	v_and_b32_e32 v169, 0xffff0000, v54
	v_lshlrev_b32_e32 v170, 16, v86
	v_and_b32_e32 v171, 0xffff0000, v86
	v_mul_f32_e32 v170, s98, v170
	v_mul_f32_e32 v171, s98, v171
	v_fma_f32 v168, v170, v14, v168
	v_fma_f32 v169, v171, v15, v169
	v_fma_f32 v186, v168, v168, v186
	v_fma_f32 v186, v169, v169, v186
	v_cvt_pk_bf16_f32 v54, v168, v169
	v_lshlrev_b32_e32 v168, 16, v55
	v_and_b32_e32 v169, 0xffff0000, v55
	v_lshlrev_b32_e32 v170, 16, v87
	v_and_b32_e32 v171, 0xffff0000, v87
	v_mul_f32_e32 v170, s98, v170
	v_mul_f32_e32 v171, s98, v171
	v_fma_f32 v168, v170, v16, v168
	v_fma_f32 v169, v171, v17, v169
	v_fma_f32 v186, v168, v168, v186
	v_fma_f32 v186, v169, v169, v186
	v_cvt_pk_bf16_f32 v55, v168, v169
	global_store_dwordx4 v19, v[48:51], s[0:1]
	global_store_dwordx4 v19, v[52:55], s[0:1] offset:1024
	v_lshlrev_b32_e32 v168, 16, v56
	v_and_b32_e32 v169, 0xffff0000, v56
	v_lshlrev_b32_e32 v170, 16, v88
	v_and_b32_e32 v171, 0xffff0000, v88
	v_mul_f32_e32 v170, s101, v170
	v_mul_f32_e32 v171, s101, v171
	v_fma_f32 v168, v170, v2, v168
	v_fma_f32 v169, v171, v3, v169
	v_fma_f32 v187, v168, v168, v187
	v_fma_f32 v187, v169, v169, v187
	v_cvt_pk_bf16_f32 v56, v168, v169
	v_lshlrev_b32_e32 v168, 16, v57
	v_and_b32_e32 v169, 0xffff0000, v57
	v_lshlrev_b32_e32 v170, 16, v89
	v_and_b32_e32 v171, 0xffff0000, v89
	v_mul_f32_e32 v170, s101, v170
	v_mul_f32_e32 v171, s101, v171
	v_fma_f32 v168, v170, v4, v168
	v_fma_f32 v169, v171, v5, v169
	v_fma_f32 v187, v168, v168, v187
	v_fma_f32 v187, v169, v169, v187
	v_cvt_pk_bf16_f32 v57, v168, v169
	v_lshlrev_b32_e32 v168, 16, v58
	v_and_b32_e32 v169, 0xffff0000, v58
	v_lshlrev_b32_e32 v170, 16, v90
	v_and_b32_e32 v171, 0xffff0000, v90
	v_mul_f32_e32 v170, s101, v170
	v_mul_f32_e32 v171, s101, v171
	v_fma_f32 v168, v170, v6, v168
	v_fma_f32 v169, v171, v7, v169
	v_fma_f32 v187, v168, v168, v187
	v_fma_f32 v187, v169, v169, v187
	v_cvt_pk_bf16_f32 v58, v168, v169
	v_lshlrev_b32_e32 v168, 16, v59
	v_and_b32_e32 v169, 0xffff0000, v59
	v_lshlrev_b32_e32 v170, 16, v91
	v_and_b32_e32 v171, 0xffff0000, v91
	v_mul_f32_e32 v170, s101, v170
	v_mul_f32_e32 v171, s101, v171
	v_fma_f32 v168, v170, v8, v168
	v_fma_f32 v169, v171, v9, v169
	v_fma_f32 v187, v168, v168, v187
	v_fma_f32 v187, v169, v169, v187
	v_cvt_pk_bf16_f32 v59, v168, v169
	v_lshlrev_b32_e32 v168, 16, v60
	v_and_b32_e32 v169, 0xffff0000, v60
	v_lshlrev_b32_e32 v170, 16, v92
	v_and_b32_e32 v171, 0xffff0000, v92
	v_mul_f32_e32 v170, s101, v170
	v_mul_f32_e32 v171, s101, v171
	v_fma_f32 v168, v170, v10, v168
	v_fma_f32 v169, v171, v11, v169
	v_fma_f32 v187, v168, v168, v187
	v_fma_f32 v187, v169, v169, v187
	v_cvt_pk_bf16_f32 v60, v168, v169
	v_lshlrev_b32_e32 v168, 16, v61
	v_and_b32_e32 v169, 0xffff0000, v61
	v_lshlrev_b32_e32 v170, 16, v93
	v_and_b32_e32 v171, 0xffff0000, v93
	v_mul_f32_e32 v170, s101, v170
	v_mul_f32_e32 v171, s101, v171
	v_fma_f32 v168, v170, v12, v168
	v_fma_f32 v169, v171, v13, v169
	v_fma_f32 v187, v168, v168, v187
	v_fma_f32 v187, v169, v169, v187
	v_cvt_pk_bf16_f32 v61, v168, v169
	v_lshlrev_b32_e32 v168, 16, v62
	v_and_b32_e32 v169, 0xffff0000, v62
	v_lshlrev_b32_e32 v170, 16, v94
	v_and_b32_e32 v171, 0xffff0000, v94
	v_mul_f32_e32 v170, s101, v170
	v_mul_f32_e32 v171, s101, v171
	v_fma_f32 v168, v170, v14, v168
	v_fma_f32 v169, v171, v15, v169
	v_fma_f32 v187, v168, v168, v187
	v_fma_f32 v187, v169, v169, v187
	v_cvt_pk_bf16_f32 v62, v168, v169
	v_lshlrev_b32_e32 v168, 16, v63
	v_and_b32_e32 v169, 0xffff0000, v63
	v_lshlrev_b32_e32 v170, 16, v95
	v_and_b32_e32 v171, 0xffff0000, v95
	v_mul_f32_e32 v170, s101, v170
	v_mul_f32_e32 v171, s101, v171
	v_fma_f32 v168, v170, v16, v168
	v_fma_f32 v169, v171, v17, v169
	v_fma_f32 v187, v168, v168, v187
	v_fma_f32 v187, v169, v169, v187
	v_cvt_pk_bf16_f32 v63, v168, v169
	global_store_dwordx4 v19, v[56:59], s[0:1] offset:2048
	global_store_dwordx4 v19, v[60:63], s[0:1] offset:3072
	s_nop 1
	v_add_f32_dpp v184, v184, v184 quad_perm:[1,0,3,2] row_mask:0xf bank_mask:0xf
	v_add_f32_dpp v185, v185, v185 quad_perm:[1,0,3,2] row_mask:0xf bank_mask:0xf
	v_add_f32_dpp v186, v186, v186 quad_perm:[1,0,3,2] row_mask:0xf bank_mask:0xf
	v_add_f32_dpp v187, v187, v187 quad_perm:[1,0,3,2] row_mask:0xf bank_mask:0xf
	v_add_f32_dpp v184, v184, v184 quad_perm:[2,3,0,1] row_mask:0xf bank_mask:0xf
	v_add_f32_dpp v185, v185, v185 quad_perm:[2,3,0,1] row_mask:0xf bank_mask:0xf
	v_add_f32_dpp v186, v186, v186 quad_perm:[2,3,0,1] row_mask:0xf bank_mask:0xf
	v_add_f32_dpp v187, v187, v187 quad_perm:[2,3,0,1] row_mask:0xf bank_mask:0xf
; __device__ __forceinline__ float bf_lo(unsigned w) { return __uint_as_float(w << 16); }
; __device__ __forceinline__ float bf_hi(unsigned w) { return __uint_as_float(w & 0xffff0000u); }
; template <bool SRC_F32, int R> __device__ __forceinline__ void ew_load(EwSet<SRC_F32, R>& S, int rb, const float* hsrc32, const bf16* hsrcb, const bf16* f, const float* part, int lane) {
; #pragma unroll
;     for (int i = 0; i < R; ++i) S.p[i] = (lane < 16) ? part[(size_t)(rb + i) * 16 + lane] : 0.f;
; #pragma unroll
;     for (int i = 0; i < R; ++i)
; #pragma unroll
;         for (int j = 0; j < 4; ++j) {
;             S.fw[i][j] = ((const v2u*)(f + (size_t)(rb + i) * D) + lane)[64 * j];
;             if constexpr (SRC_F32) S.h32[i][j] = __builtin_nontemporal_load((const f32x4*)(hsrc32 + (size_t)(rb + i) * D) + lane + 64 * j);
;             else S.hb[i][j] = ((const v2u*)(hsrcb + (size_t)(rb + i) * D) + lane)[64 * j];
;         }
; }
; template <bool SRC_F32, bool FINAL, int R> __device__ __forceinline__ void ew_compute(const EwSet<SRC_F32, R>& S, int rb, const f32x4 (&g)[4], bf16* hb_out, float* out32, float scale, float* rs_out, int lane) {
; #pragma unroll
;     for (int i = 0; i < R; ++i) {
;         float q = S.p[i];
;         q += __shfl_xor(q, 1); q += __shfl_xor(q, 2); q += __shfl_xor(q, 4); q += __shfl_xor(q, 8);
;         const float ss = __shfl(q, 0);
;         const float rs = scale / sqrtf(ss * (1.f / D) + EPS);
;         float s2 = 0.f;
; #pragma unroll
;         for (int j = 0; j < 4; ++j) {
;             f32x4 h;
;             if constexpr (SRC_F32) h = S.h32[i][j];
;             else { const v2u hw = S.hb[i][j]; h.x = bf_lo(hw.x); h.y = bf_hi(hw.x); h.z = bf_lo(hw.y); h.w = bf_hi(hw.y); }
;             const v2u fw = S.fw[i][j];
;             f32x4 v; v.x = h.x + bf_lo(fw.x) * rs * g[j].x; v.y = h.y + bf_hi(fw.x) * rs * g[j].y; v.z = h.z + bf_lo(fw.y) * rs * g[j].z; v.w = h.w + bf_hi(fw.y) * rs * g[j].w;
;             if (FINAL) __builtin_nontemporal_store(v, (f32x4*)(out32 + (size_t)(rb + i) * D) + lane + 64 * j);
;             else { v2u o; o.x = pk2(v.x, v.y); o.y = pk2(v.z, v.w); ((v2u*)(hb_out + (size_t)(rb + i) * D) + lane)[64 * j] = o; s2 += (v.x * v.x + v.y * v.y) + (v.z * v.z + v.w * v.w); }
;         }
;         if (!FINAL) { const float tot = wave_sum(s2); if (lane == 0) rs_out[rb + i] = 1.0f / sqrtf(tot * (1.f / D) + EPS); }
;     }
	v_add_f32_dpp v184, v184, v184 row_half_mirror row_mask:0xf bank_mask:0xf
	v_add_f32_dpp v185, v185, v185 row_half_mirror row_mask:0xf bank_mask:0xf
	v_add_f32_dpp v186, v186, v186 row_half_mirror row_mask:0xf bank_mask:0xf
	v_add_f32_dpp v187, v187, v187 row_half_mirror row_mask:0xf bank_mask:0xf
	v_add_f32_dpp v184, v184, v184 row_mirror row_mask:0xf bank_mask:0xf
	v_add_f32_dpp v185, v185, v185 row_mirror row_mask:0xf bank_mask:0xf
	v_add_f32_dpp v186, v186, v186 row_mirror row_mask:0xf bank_mask:0xf
	v_add_f32_dpp v187, v187, v187 row_mirror row_mask:0xf bank_mask:0xf
	v_add_f32_dpp v184, v184, v184 row_bcast:15 row_mask:0xa bank_mask:0xf
	v_add_f32_dpp v185, v185, v185 row_bcast:15 row_mask:0xa bank_mask:0xf
	v_add_f32_dpp v186, v186, v186 row_bcast:15 row_mask:0xa bank_mask:0xf
	v_add_f32_dpp v187, v187, v187 row_bcast:15 row_mask:0xa bank_mask:0xf
	v_add_f32_dpp v184, v184, v184 row_bcast:31 row_mask:0xc bank_mask:0xf
	v_add_f32_dpp v185, v185, v185 row_bcast:31 row_mask:0xc bank_mask:0xf
	v_add_f32_dpp v186, v186, v186 row_bcast:31 row_mask:0xc bank_mask:0xf
	v_add_f32_dpp v187, v187, v187 row_bcast:31 row_mask:0xc bank_mask:0xf
	s_nop 1
	v_readlane_b32 s3, v184, 63
	v_readlane_b32 s24, v185, 63
	v_readlane_b32 s98, v186, 63
	v_readlane_b32 s101, v187, 63
	s_nop 3
	v_writelane_b32 v188, s3, 0
	v_writelane_b32 v188, s24, 1
	v_writelane_b32 v188, s98, 2
	v_writelane_b32 v188, s101, 3
	s_nop 1
	v_mul_f32_e32 v188, 0x3a800000, v188
	v_add_f32_e32 v188, 0x358637bd, v188
	v_rsq_f32_e32 v188, v188
	s_mov_b64 exec, 15
	global_store_dword v21, v188, s[14:15]
	s_mov_b64 exec, -1
	s_add_u32 s27, s26, 2048
	s_lshl_b32 s22, s27, 11
	v_lshl_add_u32 v18, v0, 4, s22
	v_add_u32_e32 v19, 0x1000, v18
	s_lshl_b32 s22, s27, 6
	v_lshl_add_u32 v20, v0, 2, s22
	s_lshl_b32 s22, s27, 2
	v_lshl_add_u32 v21, v0, 2, s22
	global_load_dwordx4 v[32:35], v18, s[0:1]
	global_load_dwordx4 v[36:39], v18, s[0:1] offset:1024
	global_load_dwordx4 v[64:67], v18, s[4:5]
	global_load_dwordx4 v[68:71], v18, s[4:5] offset:1024
	global_load_dwordx4 v[40:43], v18, s[0:1] offset:2048
	global_load_dwordx4 v[44:47], v18, s[0:1] offset:3072
	global_load_dwordx4 v[72:75], v18, s[4:5] offset:2048
	global_load_dwordx4 v[76:79], v18, s[4:5] offset:3072
	global_load_dwordx4 v[48:51], v19, s[0:1]
	global_load_dwordx4 v[52:55], v19, s[0:1] offset:1024
	global_load_dwordx4 v[80:83], v19, s[4:5]
	global_load_dwordx4 v[84:87], v19, s[4:5] offset:1024
	global_load_dwordx4 v[56:59], v19, s[0:1] offset:2048
	global_load_dwordx4 v[60:63], v19, s[0:1] offset:3072
	global_load_dwordx4 v[88:91], v19, s[4:5] offset:2048
	global_load_dwordx4 v[92:95], v19, s[4:5] offset:3072
	global_load_dword v96, v20, s[6:7]
	s_waitcnt vmcnt(26)
	v_add_f32_dpp v164, v164, v164 quad_perm:[1,0,3,2] row_mask:0xf bank_mask:0xf
	s_nop 1
	v_add_f32_dpp v164, v164, v164 quad_perm:[2,3,0,1] row_mask:0xf bank_mask:0xf
	s_nop 1
	v_add_f32_dpp v164, v164, v164 row_half_mirror row_mask:0xf bank_mask:0xf
	s_nop 1
	v_add_f32_dpp v164, v164, v164 row_mirror row_mask:0xf bank_mask:0xf
	s_nop 1
	v_mul_f32_e32 v164, 0x3a800000, v164
	v_add_f32_e32 v164, 0x358637bd, v164
	v_rsq_f32_e32 v164, v164
	s_nop 0
	v_mul_f32_e32 v164, 0x3f000000, v164
	s_nop 0
	v_readlane_b32 s3, v164, 0
	v_readlane_b32 s24, v164, 16
	v_readlane_b32 s98, v164, 32
	v_readlane_b32 s101, v164, 48
	s_nop 1
	v_mov_b32_e32 v184, 0
	v_mov_b32_e32 v185, 0
	v_mov_b32_e32 v186, 0
	v_mov_b32_e32 v187, 0
	v_lshlrev_b32_e32 v168, 16, v100
	v_and_b32_e32 v169, 0xffff0000, v100
	v_lshlrev_b32_e32 v170, 16, v132
	v_and_b32_e32 v171, 0xffff0000, v132
	v_mul_f32_e32 v170, s3, v170
	v_mul_f32_e32 v171, s3, v171
	v_fma_f32 v168, v170, v2, v168
	v_fma_f32 v169, v171, v3, v169
	v_fma_f32 v184, v168, v168, v184
	v_fma_f32 v184, v169, v169, v184
	v_cvt_pk_bf16_f32 v100, v168, v169
	v_lshlrev_b32_e32 v168, 16, v101
	v_and_b32_e32 v169, 0xffff0000, v101
	v_lshlrev_b32_e32 v170, 16, v133
	v_and_b32_e32 v171, 0xffff0000, v133
	v_mul_f32_e32 v170, s3, v170
	v_mul_f32_e32 v171, s3, v171
	v_fma_f32 v168, v170, v4, v168
	v_fma_f32 v169, v171, v5, v169
	v_fma_f32 v184, v168, v168, v184
	v_fma_f32 v184, v169, v169, v184
	v_cvt_pk_bf16_f32 v101, v168, v169
	v_lshlrev_b32_e32 v168, 16, v102
	v_and_b32_e32 v169, 0xffff0000, v102
	v_lshlrev_b32_e32 v170, 16, v134
	v_and_b32_e32 v171, 0xffff0000, v134
	v_mul_f32_e32 v170, s3, v170
	v_mul_f32_e32 v171, s3, v171
	v_fma_f32 v168, v170, v6, v168
	v_fma_f32 v169, v171, v7, v169
	v_fma_f32 v184, v168, v168, v184
	v_fma_f32 v184, v169, v169, v184
	v_cvt_pk_bf16_f32 v102, v168, v169
	v_lshlrev_b32_e32 v168, 16, v103
	v_and_b32_e32 v169, 0xffff0000, v103
	v_lshlrev_b32_e32 v170, 16, v135
	v_and_b32_e32 v171, 0xffff0000, v135
	v_mul_f32_e32 v170, s3, v170
	v_mul_f32_e32 v171, s3, v171
	v_fma_f32 v168, v170, v8, v168
	v_fma_f32 v169, v171, v9, v169
	v_fma_f32 v184, v168, v168, v184
	v_fma_f32 v184, v169, v169, v184
	v_cvt_pk_bf16_f32 v103, v168, v169
	v_lshlrev_b32_e32 v168, 16, v104
	v_and_b32_e32 v169, 0xffff0000, v104
	v_lshlrev_b32_e32 v170, 16, v136
	v_and_b32_e32 v171, 0xffff0000, v136
	v_mul_f32_e32 v170, s3, v170
	v_mul_f32_e32 v171, s3, v171
	v_fma_f32 v168, v170, v10, v168
	v_fma_f32 v169, v171, v11, v169
	v_fma_f32 v184, v168, v168, v184
	v_fma_f32 v184, v169, v169, v184
	v_cvt_pk_bf16_f32 v104, v168, v169
	v_lshlrev_b32_e32 v168, 16, v105
	v_and_b32_e32 v169, 0xffff0000, v105
	v_lshlrev_b32_e32 v170, 16, v137
	v_and_b32_e32 v171, 0xffff0000, v137
	v_mul_f32_e32 v170, s3, v170
	v_mul_f32_e32 v171, s3, v171
	v_fma_f32 v168, v170, v12, v168
	v_fma_f32 v169, v171, v13, v169
	v_fma_f32 v184, v168, v168, v184
	v_fma_f32 v184, v169, v169, v184
; __device__ __forceinline__ float bf_lo(unsigned w) { return __uint_as_float(w << 16); }
; __device__ __forceinline__ float bf_hi(unsigned w) { return __uint_as_float(w & 0xffff0000u); }
; __device__ __forceinline__ unsigned pk2(float lo, float hi) { bf16x2_t r = __builtin_convertvector((f32x2_t){lo, hi}, bf16x2_t); return __builtin_bit_cast(unsigned, r); }
; template <bool SRC_F32, bool FINAL, int R> __device__ __forceinline__ void ew_compute(const EwSet<SRC_F32, R>& S, int rb, const f32x4 (&g)[4], bf16* hb_out, float* out32, float scale, float* rs_out, int lane) {
; #pragma unroll
;     for (int i = 0; i < R; ++i) {
;         float q = S.p[i];
;         q += __shfl_xor(q, 1); q += __shfl_xor(q, 2); q += __shfl_xor(q, 4); q += __shfl_xor(q, 8);
;         const float ss = __shfl(q, 0);
;         const float rs = scale / sqrtf(ss * (1.f / D) + EPS);
;         float s2 = 0.f;
; #pragma unroll
;         for (int j = 0; j < 4; ++j) {
;             f32x4 h;
;             if constexpr (SRC_F32) h = S.h32[i][j];
;             else { const v2u hw = S.hb[i][j]; h.x = bf_lo(hw.x); h.y = bf_hi(hw.x); h.z = bf_lo(hw.y); h.w = bf_hi(hw.y); }
;             const v2u fw = S.fw[i][j];
;             f32x4 v; v.x = h.x + bf_lo(fw.x) * rs * g[j].x; v.y = h.y + bf_hi(fw.x) * rs * g[j].y; v.z = h.z + bf_lo(fw.y) * rs * g[j].z; v.w = h.w + bf_hi(fw.y) * rs * g[j].w;
;             if (FINAL) __builtin_nontemporal_store(v, (f32x4*)(out32 + (size_t)(rb + i) * D) + lane + 64 * j);
;             else { v2u o; o.x = pk2(v.x, v.y); o.y = pk2(v.z, v.w); ((v2u*)(hb_out + (size_t)(rb + i) * D) + lane)[64 * j] = o; s2 += (v.x * v.x + v.y * v.y) + (v.z * v.z + v.w * v.w); }
;         }
;         if (!FINAL) { const float tot = wave_sum(s2); if (lane == 0) rs_out[rb + i] = 1.0f / sqrtf(tot * (1.f / D) + EPS); }
;     }
	v_cvt_pk_bf16_f32 v105, v168, v169
	v_lshlrev_b32_e32 v168, 16, v106
	v_and_b32_e32 v169, 0xffff0000, v106
	v_lshlrev_b32_e32 v170, 16, v138
	v_and_b32_e32 v171, 0xffff0000, v138
	v_mul_f32_e32 v170, s3, v170
	v_mul_f32_e32 v171, s3, v171
	v_fma_f32 v168, v170, v14, v168
	v_fma_f32 v169, v171, v15, v169
	v_fma_f32 v184, v168, v168, v184
	v_fma_f32 v184, v169, v169, v184
	v_cvt_pk_bf16_f32 v106, v168, v169
	v_lshlrev_b32_e32 v168, 16, v107
	v_and_b32_e32 v169, 0xffff0000, v107
	v_lshlrev_b32_e32 v170, 16, v139
	v_and_b32_e32 v171, 0xffff0000, v139
	v_mul_f32_e32 v170, s3, v170
	v_mul_f32_e32 v171, s3, v171
	v_fma_f32 v168, v170, v16, v168
	v_fma_f32 v169, v171, v17, v169
	v_fma_f32 v184, v168, v168, v184
	v_fma_f32 v184, v169, v169, v184
	v_cvt_pk_bf16_f32 v107, v168, v169
	global_store_dwordx4 v23, v[100:103], s[0:1]
	global_store_dwordx4 v23, v[104:107], s[0:1] offset:1024
	v_lshlrev_b32_e32 v168, 16, v108
	v_and_b32_e32 v169, 0xffff0000, v108
	v_lshlrev_b32_e32 v170, 16, v140
	v_and_b32_e32 v171, 0xffff0000, v140
	v_mul_f32_e32 v170, s24, v170
	v_mul_f32_e32 v171, s24, v171
	v_fma_f32 v168, v170, v2, v168
	v_fma_f32 v169, v171, v3, v169
	v_fma_f32 v185, v168, v168, v185
	v_fma_f32 v185, v169, v169, v185
	v_cvt_pk_bf16_f32 v108, v168, v169
	v_lshlrev_b32_e32 v168, 16, v109
	v_and_b32_e32 v169, 0xffff0000, v109
	v_lshlrev_b32_e32 v170, 16, v141
	v_and_b32_e32 v171, 0xffff0000, v141
	v_mul_f32_e32 v170, s24, v170
	v_mul_f32_e32 v171, s24, v171
	v_fma_f32 v168, v170, v4, v168
	v_fma_f32 v169, v171, v5, v169
	v_fma_f32 v185, v168, v168, v185
	v_fma_f32 v185, v169, v169, v185
	v_cvt_pk_bf16_f32 v109, v168, v169
	v_lshlrev_b32_e32 v168, 16, v110
	v_and_b32_e32 v169, 0xffff0000, v110
	v_lshlrev_b32_e32 v170, 16, v142
	v_and_b32_e32 v171, 0xffff0000, v142
	v_mul_f32_e32 v170, s24, v170
	v_mul_f32_e32 v171, s24, v171
	v_fma_f32 v168, v170, v6, v168
	v_fma_f32 v169, v171, v7, v169
	v_fma_f32 v185, v168, v168, v185
	v_fma_f32 v185, v169, v169, v185
	v_cvt_pk_bf16_f32 v110, v168, v169
	v_lshlrev_b32_e32 v168, 16, v111
	v_and_b32_e32 v169, 0xffff0000, v111
	v_lshlrev_b32_e32 v170, 16, v143
	v_and_b32_e32 v171, 0xffff0000, v143
	v_mul_f32_e32 v170, s24, v170
	v_mul_f32_e32 v171, s24, v171
	v_fma_f32 v168, v170, v8, v168
	v_fma_f32 v169, v171, v9, v169
	v_fma_f32 v185, v168, v168, v185
	v_fma_f32 v185, v169, v169, v185
	v_cvt_pk_bf16_f32 v111, v168, v169
	v_lshlrev_b32_e32 v168, 16, v112
	v_and_b32_e32 v169, 0xffff0000, v112
	v_lshlrev_b32_e32 v170, 16, v144
	v_and_b32_e32 v171, 0xffff0000, v144
	v_mul_f32_e32 v170, s24, v170
	v_mul_f32_e32 v171, s24, v171
	v_fma_f32 v168, v170, v10, v168
	v_fma_f32 v169, v171, v11, v169
	v_fma_f32 v185, v168, v168, v185
	v_fma_f32 v185, v169, v169, v185
	v_cvt_pk_bf16_f32 v112, v168, v169
	v_lshlrev_b32_e32 v168, 16, v113
	v_and_b32_e32 v169, 0xffff0000, v113
	v_lshlrev_b32_e32 v170, 16, v145
	v_and_b32_e32 v171, 0xffff0000, v145
	v_mul_f32_e32 v170, s24, v170
	v_mul_f32_e32 v171, s24, v171
	v_fma_f32 v168, v170, v12, v168
	v_fma_f32 v169, v171, v13, v169
	v_fma_f32 v185, v168, v168, v185
	v_fma_f32 v185, v169, v169, v185
	v_cvt_pk_bf16_f32 v113, v168, v169
	v_lshlrev_b32_e32 v168, 16, v114
	v_and_b32_e32 v169, 0xffff0000, v114
	v_lshlrev_b32_e32 v170, 16, v146
	v_and_b32_e32 v171, 0xffff0000, v146
	v_mul_f32_e32 v170, s24, v170
	v_mul_f32_e32 v171, s24, v171
	v_fma_f32 v168, v170, v14, v168
	v_fma_f32 v169, v171, v15, v169
	v_fma_f32 v185, v168, v168, v185
	v_fma_f32 v185, v169, v169, v185
	v_cvt_pk_bf16_f32 v114, v168, v169
	v_lshlrev_b32_e32 v168, 16, v115
	v_and_b32_e32 v169, 0xffff0000, v115
	v_lshlrev_b32_e32 v170, 16, v147
	v_and_b32_e32 v171, 0xffff0000, v147
	v_mul_f32_e32 v170, s24, v170
	v_mul_f32_e32 v171, s24, v171
	v_fma_f32 v168, v170, v16, v168
	v_fma_f32 v169, v171, v17, v169
	v_fma_f32 v185, v168, v168, v185
	v_fma_f32 v185, v169, v169, v185
	v_cvt_pk_bf16_f32 v115, v168, v169
	global_store_dwordx4 v23, v[108:111], s[0:1] offset:2048
	global_store_dwordx4 v23, v[112:115], s[0:1] offset:3072
	v_lshlrev_b32_e32 v168, 16, v116
	v_and_b32_e32 v169, 0xffff0000, v116
	v_lshlrev_b32_e32 v170, 16, v148
	v_and_b32_e32 v171, 0xffff0000, v148
	v_mul_f32_e32 v170, s98, v170
	v_mul_f32_e32 v171, s98, v171
	v_fma_f32 v168, v170, v2, v168
	v_fma_f32 v169, v171, v3, v169
	v_fma_f32 v186, v168, v168, v186
	v_fma_f32 v186, v169, v169, v186
	v_cvt_pk_bf16_f32 v116, v168, v169
	v_lshlrev_b32_e32 v168, 16, v117
	v_and_b32_e32 v169, 0xffff0000, v117
	v_lshlrev_b32_e32 v170, 16, v149
	v_and_b32_e32 v171, 0xffff0000, v149
	v_mul_f32_e32 v170, s98, v170
	v_mul_f32_e32 v171, s98, v171
	v_fma_f32 v168, v170, v4, v168
	v_fma_f32 v169, v171, v5, v169
	v_fma_f32 v186, v168, v168, v186
	v_fma_f32 v186, v169, v169, v186
	v_cvt_pk_bf16_f32 v117, v168, v169
	v_lshlrev_b32_e32 v168, 16, v118
	v_and_b32_e32 v169, 0xffff0000, v118
	v_lshlrev_b32_e32 v170, 16, v150
	v_and_b32_e32 v171, 0xffff0000, v150
	v_mul_f32_e32 v170, s98, v170
	v_mul_f32_e32 v171, s98, v171
	v_fma_f32 v168, v170, v6, v168
	v_fma_f32 v169, v171, v7, v169
	v_fma_f32 v186, v168, v168, v186
	v_fma_f32 v186, v169, v169, v186
	v_cvt_pk_bf16_f32 v118, v168, v169
	v_lshlrev_b32_e32 v168, 16, v119
	v_and_b32_e32 v169, 0xffff0000, v119
	v_lshlrev_b32_e32 v170, 16, v151
	v_and_b32_e32 v171, 0xffff0000, v151
	v_mul_f32_e32 v170, s98, v170
	v_mul_f32_e32 v171, s98, v171
	v_fma_f32 v168, v170, v8, v168
	v_fma_f32 v169, v171, v9, v169
	v_fma_f32 v186, v168, v168, v186
	v_fma_f32 v186, v169, v169, v186
	v_cvt_pk_bf16_f32 v119, v168, v169
	v_lshlrev_b32_e32 v168, 16, v120
	v_and_b32_e32 v169, 0xffff0000, v120
	v_lshlrev_b32_e32 v170, 16, v152
	v_and_b32_e32 v171, 0xffff0000, v152
; __device__ __forceinline__ float bf_lo(unsigned w) { return __uint_as_float(w << 16); }
; __device__ __forceinline__ float bf_hi(unsigned w) { return __uint_as_float(w & 0xffff0000u); }
; __device__ __forceinline__ unsigned pk2(float lo, float hi) { bf16x2_t r = __builtin_convertvector((f32x2_t){lo, hi}, bf16x2_t); return __builtin_bit_cast(unsigned, r); }
; template <bool SRC_F32, bool FINAL, int R> __device__ __forceinline__ void ew_compute(const EwSet<SRC_F32, R>& S, int rb, const f32x4 (&g)[4], bf16* hb_out, float* out32, float scale, float* rs_out, int lane) {
; #pragma unroll
;     for (int i = 0; i < R; ++i) {
;         float q = S.p[i];
;         q += __shfl_xor(q, 1); q += __shfl_xor(q, 2); q += __shfl_xor(q, 4); q += __shfl_xor(q, 8);
;         const float ss = __shfl(q, 0);
;         const float rs = scale / sqrtf(ss * (1.f / D) + EPS);
;         float s2 = 0.f;
; #pragma unroll
;         for (int j = 0; j < 4; ++j) {
;             f32x4 h;
;             if constexpr (SRC_F32) h = S.h32[i][j];
;             else { const v2u hw = S.hb[i][j]; h.x = bf_lo(hw.x); h.y = bf_hi(hw.x); h.z = bf_lo(hw.y); h.w = bf_hi(hw.y); }
;             const v2u fw = S.fw[i][j];
;             f32x4 v; v.x = h.x + bf_lo(fw.x) * rs * g[j].x; v.y = h.y + bf_hi(fw.x) * rs * g[j].y; v.z = h.z + bf_lo(fw.y) * rs * g[j].z; v.w = h.w + bf_hi(fw.y) * rs * g[j].w;
;             if (FINAL) __builtin_nontemporal_store(v, (f32x4*)(out32 + (size_t)(rb + i) * D) + lane + 64 * j);
;             else { v2u o; o.x = pk2(v.x, v.y); o.y = pk2(v.z, v.w); ((v2u*)(hb_out + (size_t)(rb + i) * D) + lane)[64 * j] = o; s2 += (v.x * v.x + v.y * v.y) + (v.z * v.z + v.w * v.w); }
;         }
;         if (!FINAL) { const float tot = wave_sum(s2); if (lane == 0) rs_out[rb + i] = 1.0f / sqrtf(tot * (1.f / D) + EPS); }
;     }
	v_mul_f32_e32 v170, s98, v170
	v_mul_f32_e32 v171, s98, v171
	v_fma_f32 v168, v170, v10, v168
	v_fma_f32 v169, v171, v11, v169
	v_fma_f32 v186, v168, v168, v186
	v_fma_f32 v186, v169, v169, v186
	v_cvt_pk_bf16_f32 v120, v168, v169
	v_lshlrev_b32_e32 v168, 16, v121
	v_and_b32_e32 v169, 0xffff0000, v121
	v_lshlrev_b32_e32 v170, 16, v153
	v_and_b32_e32 v171, 0xffff0000, v153
	v_mul_f32_e32 v170, s98, v170
	v_mul_f32_e32 v171, s98, v171
	v_fma_f32 v168, v170, v12, v168
	v_fma_f32 v169, v171, v13, v169
	v_fma_f32 v186, v168, v168, v186
	v_fma_f32 v186, v169, v169, v186
	v_cvt_pk_bf16_f32 v121, v168, v169
	v_lshlrev_b32_e32 v168, 16, v122
	v_and_b32_e32 v169, 0xffff0000, v122
	v_lshlrev_b32_e32 v170, 16, v154
	v_and_b32_e32 v171, 0xffff0000, v154
	v_mul_f32_e32 v170, s98, v170
	v_mul_f32_e32 v171, s98, v171
	v_fma_f32 v168, v170, v14, v168
	v_fma_f32 v169, v171, v15, v169
	v_fma_f32 v186, v168, v168, v186
	v_fma_f32 v186, v169, v169, v186
	v_cvt_pk_bf16_f32 v122, v168, v169
	v_lshlrev_b32_e32 v168, 16, v123
	v_and_b32_e32 v169, 0xffff0000, v123
	v_lshlrev_b32_e32 v170, 16, v155
	v_and_b32_e32 v171, 0xffff0000, v155
	v_mul_f32_e32 v170, s98, v170
	v_mul_f32_e32 v171, s98, v171
	v_fma_f32 v168, v170, v16, v168
	v_fma_f32 v169, v171, v17, v169
	v_fma_f32 v186, v168, v168, v186
	v_fma_f32 v186, v169, v169, v186
	v_cvt_pk_bf16_f32 v123, v168, v169
	global_store_dwordx4 v24, v[116:119], s[0:1]
	global_store_dwordx4 v24, v[120:123], s[0:1] offset:1024
	v_lshlrev_b32_e32 v168, 16, v124
	v_and_b32_e32 v169, 0xffff0000, v124
	v_lshlrev_b32_e32 v170, 16, v156
	v_and_b32_e32 v171, 0xffff0000, v156
	v_mul_f32_e32 v170, s101, v170
	v_mul_f32_e32 v171, s101, v171
	v_fma_f32 v168, v170, v2, v168
	v_fma_f32 v169, v171, v3, v169
	v_fma_f32 v187, v168, v168, v187
	v_fma_f32 v187, v169, v169, v187
	v_cvt_pk_bf16_f32 v124, v168, v169
	v_lshlrev_b32_e32 v168, 16, v125
	v_and_b32_e32 v169, 0xffff0000, v125
	v_lshlrev_b32_e32 v170, 16, v157
	v_and_b32_e32 v171, 0xffff0000, v157
	v_mul_f32_e32 v170, s101, v170
	v_mul_f32_e32 v171, s101, v171
	v_fma_f32 v168, v170, v4, v168
	v_fma_f32 v169, v171, v5, v169
	v_fma_f32 v187, v168, v168, v187
	v_fma_f32 v187, v169, v169, v187
	v_cvt_pk_bf16_f32 v125, v168, v169
	v_lshlrev_b32_e32 v168, 16, v126
	v_and_b32_e32 v169, 0xffff0000, v126
	v_lshlrev_b32_e32 v170, 16, v158
	v_and_b32_e32 v171, 0xffff0000, v158
	v_mul_f32_e32 v170, s101, v170
	v_mul_f32_e32 v171, s101, v171
	v_fma_f32 v168, v170, v6, v168
	v_fma_f32 v169, v171, v7, v169
	v_fma_f32 v187, v168, v168, v187
	v_fma_f32 v187, v169, v169, v187
	v_cvt_pk_bf16_f32 v126, v168, v169
	v_lshlrev_b32_e32 v168, 16, v127
	v_and_b32_e32 v169, 0xffff0000, v127
	v_lshlrev_b32_e32 v170, 16, v159
	v_and_b32_e32 v171, 0xffff0000, v159
	v_mul_f32_e32 v170, s101, v170
	v_mul_f32_e32 v171, s101, v171
	v_fma_f32 v168, v170, v8, v168
	v_fma_f32 v169, v171, v9, v169
	v_fma_f32 v187, v168, v168, v187
	v_fma_f32 v187, v169, v169, v187
	v_cvt_pk_bf16_f32 v127, v168, v169
	v_lshlrev_b32_e32 v168, 16, v128
	v_and_b32_e32 v169, 0xffff0000, v128
	v_lshlrev_b32_e32 v170, 16, v160
	v_and_b32_e32 v171, 0xffff0000, v160
	v_mul_f32_e32 v170, s101, v170
	v_mul_f32_e32 v171, s101, v171
	v_fma_f32 v168, v170, v10, v168
	v_fma_f32 v169, v171, v11, v169
	v_fma_f32 v187, v168, v168, v187
	v_fma_f32 v187, v169, v169, v187
	v_cvt_pk_bf16_f32 v128, v168, v169
	v_lshlrev_b32_e32 v168, 16, v129
	v_and_b32_e32 v169, 0xffff0000, v129
	v_lshlrev_b32_e32 v170, 16, v161
	v_and_b32_e32 v171, 0xffff0000, v161
	v_mul_f32_e32 v170, s101, v170
	v_mul_f32_e32 v171, s101, v171
	v_fma_f32 v168, v170, v12, v168
	v_fma_f32 v169, v171, v13, v169
	v_fma_f32 v187, v168, v168, v187
	v_fma_f32 v187, v169, v169, v187
	v_cvt_pk_bf16_f32 v129, v168, v169
	v_lshlrev_b32_e32 v168, 16, v130
	v_and_b32_e32 v169, 0xffff0000, v130
	v_lshlrev_b32_e32 v170, 16, v162
	v_and_b32_e32 v171, 0xffff0000, v162
	v_mul_f32_e32 v170, s101, v170
	v_mul_f32_e32 v171, s101, v171
	v_fma_f32 v168, v170, v14, v168
	v_fma_f32 v169, v171, v15, v169
	v_fma_f32 v187, v168, v168, v187
	v_fma_f32 v187, v169, v169, v187
	v_cvt_pk_bf16_f32 v130, v168, v169
	v_lshlrev_b32_e32 v168, 16, v131
	v_and_b32_e32 v169, 0xffff0000, v131
	v_lshlrev_b32_e32 v170, 16, v163
	v_and_b32_e32 v171, 0xffff0000, v163
	v_mul_f32_e32 v170, s101, v170
	v_mul_f32_e32 v171, s101, v171
	v_fma_f32 v168, v170, v16, v168
	v_fma_f32 v169, v171, v17, v169
	v_fma_f32 v187, v168, v168, v187
	v_fma_f32 v187, v169, v169, v187
	v_cvt_pk_bf16_f32 v131, v168, v169
	global_store_dwordx4 v24, v[124:127], s[0:1] offset:2048
	global_store_dwordx4 v24, v[128:131], s[0:1] offset:3072
	s_nop 1
	v_add_f32_dpp v184, v184, v184 quad_perm:[1,0,3,2] row_mask:0xf bank_mask:0xf
	v_add_f32_dpp v185, v185, v185 quad_perm:[1,0,3,2] row_mask:0xf bank_mask:0xf
	v_add_f32_dpp v186, v186, v186 quad_perm:[1,0,3,2] row_mask:0xf bank_mask:0xf
	v_add_f32_dpp v187, v187, v187 quad_perm:[1,0,3,2] row_mask:0xf bank_mask:0xf
	v_add_f32_dpp v184, v184, v184 quad_perm:[2,3,0,1] row_mask:0xf bank_mask:0xf
	v_add_f32_dpp v185, v185, v185 quad_perm:[2,3,0,1] row_mask:0xf bank_mask:0xf
	v_add_f32_dpp v186, v186, v186 quad_perm:[2,3,0,1] row_mask:0xf bank_mask:0xf
	v_add_f32_dpp v187, v187, v187 quad_perm:[2,3,0,1] row_mask:0xf bank_mask:0xf
	v_add_f32_dpp v184, v184, v184 row_half_mirror row_mask:0xf bank_mask:0xf
	v_add_f32_dpp v185, v185, v185 row_half_mirror row_mask:0xf bank_mask:0xf
	v_add_f32_dpp v186, v186, v186 row_half_mirror row_mask:0xf bank_mask:0xf
	v_add_f32_dpp v187, v187, v187 row_half_mirror row_mask:0xf bank_mask:0xf
	v_add_f32_dpp v184, v184, v184 row_mirror row_mask:0xf bank_mask:0xf
; __device__ __forceinline__ float bf_lo(unsigned w) { return __uint_as_float(w << 16); }
; __device__ __forceinline__ float bf_hi(unsigned w) { return __uint_as_float(w & 0xffff0000u); }
; template <bool SRC_F32, int R> __device__ __forceinline__ void ew_load(EwSet<SRC_F32, R>& S, int rb, const float* hsrc32, const bf16* hsrcb, const bf16* f, const float* part, int lane) {
; #pragma unroll
;     for (int i = 0; i < R; ++i) S.p[i] = (lane < 16) ? part[(size_t)(rb + i) * 16 + lane] : 0.f;
; #pragma unroll
;     for (int i = 0; i < R; ++i)
; #pragma unroll
;         for (int j = 0; j < 4; ++j) {
;             S.fw[i][j] = ((const v2u*)(f + (size_t)(rb + i) * D) + lane)[64 * j];
;             if constexpr (SRC_F32) S.h32[i][j] = __builtin_nontemporal_load((const f32x4*)(hsrc32 + (size_t)(rb + i) * D) + lane + 64 * j);
;             else S.hb[i][j] = ((const v2u*)(hsrcb + (size_t)(rb + i) * D) + lane)[64 * j];
;         }
; }
; template <bool SRC_F32, bool FINAL, int R> __device__ __forceinline__ void ew_compute(const EwSet<SRC_F32, R>& S, int rb, const f32x4 (&g)[4], bf16* hb_out, float* out32, float scale, float* rs_out, int lane) {
; #pragma unroll
;     for (int i = 0; i < R; ++i) {
;         float q = S.p[i];
;         q += __shfl_xor(q, 1); q += __shfl_xor(q, 2); q += __shfl_xor(q, 4); q += __shfl_xor(q, 8);
;         const float ss = __shfl(q, 0);
;         const float rs = scale / sqrtf(ss * (1.f / D) + EPS);
;         float s2 = 0.f;
; #pragma unroll
;         for (int j = 0; j < 4; ++j) {
;             f32x4 h;
;             if constexpr (SRC_F32) h = S.h32[i][j];
;             else { const v2u hw = S.hb[i][j]; h.x = bf_lo(hw.x); h.y = bf_hi(hw.x); h.z = bf_lo(hw.y); h.w = bf_hi(hw.y); }
;             const v2u fw = S.fw[i][j];
;             f32x4 v; v.x = h.x + bf_lo(fw.x) * rs * g[j].x; v.y = h.y + bf_hi(fw.x) * rs * g[j].y; v.z = h.z + bf_lo(fw.y) * rs * g[j].z; v.w = h.w + bf_hi(fw.y) * rs * g[j].w;
;             if (FINAL) __builtin_nontemporal_store(v, (f32x4*)(out32 + (size_t)(rb + i) * D) + lane + 64 * j);
;             else { v2u o; o.x = pk2(v.x, v.y); o.y = pk2(v.z, v.w); ((v2u*)(hb_out + (size_t)(rb + i) * D) + lane)[64 * j] = o; s2 += (v.x * v.x + v.y * v.y) + (v.z * v.z + v.w * v.w); }
;         }
;         if (!FINAL) { const float tot = wave_sum(s2); if (lane == 0) rs_out[rb + i] = 1.0f / sqrtf(tot * (1.f / D) + EPS); }
;     }
	v_add_f32_dpp v185, v185, v185 row_mirror row_mask:0xf bank_mask:0xf
	v_add_f32_dpp v186, v186, v186 row_mirror row_mask:0xf bank_mask:0xf
	v_add_f32_dpp v187, v187, v187 row_mirror row_mask:0xf bank_mask:0xf
	v_add_f32_dpp v184, v184, v184 row_bcast:15 row_mask:0xa bank_mask:0xf
	v_add_f32_dpp v185, v185, v185 row_bcast:15 row_mask:0xa bank_mask:0xf
	v_add_f32_dpp v186, v186, v186 row_bcast:15 row_mask:0xa bank_mask:0xf
	v_add_f32_dpp v187, v187, v187 row_bcast:15 row_mask:0xa bank_mask:0xf
	v_add_f32_dpp v184, v184, v184 row_bcast:31 row_mask:0xc bank_mask:0xf
	v_add_f32_dpp v185, v185, v185 row_bcast:31 row_mask:0xc bank_mask:0xf
	v_add_f32_dpp v186, v186, v186 row_bcast:31 row_mask:0xc bank_mask:0xf
	v_add_f32_dpp v187, v187, v187 row_bcast:31 row_mask:0xc bank_mask:0xf
	s_nop 1
	v_readlane_b32 s3, v184, 63
	v_readlane_b32 s24, v185, 63
	v_readlane_b32 s98, v186, 63
	v_readlane_b32 s101, v187, 63
	s_nop 3
	v_writelane_b32 v188, s3, 0
	v_writelane_b32 v188, s24, 1
	v_writelane_b32 v188, s98, 2
	v_writelane_b32 v188, s101, 3
	s_nop 1
	v_mul_f32_e32 v188, 0x3a800000, v188
	v_add_f32_e32 v188, 0x358637bd, v188
	v_rsq_f32_e32 v188, v188
	s_mov_b64 exec, 15
	global_store_dword v26, v188, s[14:15]
	s_mov_b64 exec, -1
	s_add_u32 s27, s26, 2052
	s_lshl_b32 s22, s27, 11
	v_lshl_add_u32 v23, v0, 4, s22
	v_add_u32_e32 v24, 0x1000, v23
	s_lshl_b32 s22, s27, 6
	v_lshl_add_u32 v25, v0, 2, s22
	s_lshl_b32 s22, s27, 2
	v_lshl_add_u32 v26, v0, 2, s22
	global_load_dwordx4 v[100:103], v23, s[0:1]
	global_load_dwordx4 v[104:107], v23, s[0:1] offset:1024
	global_load_dwordx4 v[132:135], v23, s[4:5]
	global_load_dwordx4 v[136:139], v23, s[4:5] offset:1024
	global_load_dwordx4 v[108:111], v23, s[0:1] offset:2048
	global_load_dwordx4 v[112:115], v23, s[0:1] offset:3072
	global_load_dwordx4 v[140:143], v23, s[4:5] offset:2048
	global_load_dwordx4 v[144:147], v23, s[4:5] offset:3072
	global_load_dwordx4 v[116:119], v24, s[0:1]
	global_load_dwordx4 v[120:123], v24, s[0:1] offset:1024
	global_load_dwordx4 v[148:151], v24, s[4:5]
	global_load_dwordx4 v[152:155], v24, s[4:5] offset:1024
	global_load_dwordx4 v[124:127], v24, s[0:1] offset:2048
	global_load_dwordx4 v[128:131], v24, s[0:1] offset:3072
	global_load_dwordx4 v[156:159], v24, s[4:5] offset:2048
	global_load_dwordx4 v[160:163], v24, s[4:5] offset:3072
	global_load_dword v164, v25, s[6:7]
	s_waitcnt vmcnt(26)
	v_add_f32_dpp v96, v96, v96 quad_perm:[1,0,3,2] row_mask:0xf bank_mask:0xf
	s_nop 1
	v_add_f32_dpp v96, v96, v96 quad_perm:[2,3,0,1] row_mask:0xf bank_mask:0xf
	s_nop 1
	v_add_f32_dpp v96, v96, v96 row_half_mirror row_mask:0xf bank_mask:0xf
	s_nop 1
	v_add_f32_dpp v96, v96, v96 row_mirror row_mask:0xf bank_mask:0xf
	s_nop 1
	v_mul_f32_e32 v96, 0x3a800000, v96
	v_add_f32_e32 v96, 0x358637bd, v96
	v_rsq_f32_e32 v96, v96
	s_nop 0
	v_mul_f32_e32 v96, 0x3f000000, v96
	s_nop 0
	v_readlane_b32 s3, v96, 0
	v_readlane_b32 s24, v96, 16
	v_readlane_b32 s98, v96, 32
	v_readlane_b32 s101, v96, 48
	s_nop 1
	v_mov_b32_e32 v184, 0
	v_mov_b32_e32 v185, 0
	v_mov_b32_e32 v186, 0
	v_mov_b32_e32 v187, 0
	v_lshlrev_b32_e32 v168, 16, v32
	v_and_b32_e32 v169, 0xffff0000, v32
	v_lshlrev_b32_e32 v170, 16, v64
	v_and_b32_e32 v171, 0xffff0000, v64
	v_mul_f32_e32 v170, s3, v170
	v_mul_f32_e32 v171, s3, v171
	v_fma_f32 v168, v170, v2, v168
	v_fma_f32 v169, v171, v3, v169
	v_fma_f32 v184, v168, v168, v184
	v_fma_f32 v184, v169, v169, v184
	v_cvt_pk_bf16_f32 v32, v168, v169
	v_lshlrev_b32_e32 v168, 16, v33
	v_and_b32_e32 v169, 0xffff0000, v33
	v_lshlrev_b32_e32 v170, 16, v65
	v_and_b32_e32 v171, 0xffff0000, v65
	v_mul_f32_e32 v170, s3, v170
	v_mul_f32_e32 v171, s3, v171
	v_fma_f32 v168, v170, v4, v168
	v_fma_f32 v169, v171, v5, v169
	v_fma_f32 v184, v168, v168, v184
	v_fma_f32 v184, v169, v169, v184
	v_cvt_pk_bf16_f32 v33, v168, v169
	v_lshlrev_b32_e32 v168, 16, v34
	v_and_b32_e32 v169, 0xffff0000, v34
	v_lshlrev_b32_e32 v170, 16, v66
	v_and_b32_e32 v171, 0xffff0000, v66
	v_mul_f32_e32 v170, s3, v170
	v_mul_f32_e32 v171, s3, v171
	v_fma_f32 v168, v170, v6, v168
	v_fma_f32 v169, v171, v7, v169
	v_fma_f32 v184, v168, v168, v184
	v_fma_f32 v184, v169, v169, v184
	v_cvt_pk_bf16_f32 v34, v168, v169
	v_lshlrev_b32_e32 v168, 16, v35
	v_and_b32_e32 v169, 0xffff0000, v35
	v_lshlrev_b32_e32 v170, 16, v67
	v_and_b32_e32 v171, 0xffff0000, v67
	v_mul_f32_e32 v170, s3, v170
	v_mul_f32_e32 v171, s3, v171
	v_fma_f32 v168, v170, v8, v168
	v_fma_f32 v169, v171, v9, v169
	v_fma_f32 v184, v168, v168, v184
	v_fma_f32 v184, v169, v169, v184
	v_cvt_pk_bf16_f32 v35, v168, v169
	v_lshlrev_b32_e32 v168, 16, v36
	v_and_b32_e32 v169, 0xffff0000, v36
	v_lshlrev_b32_e32 v170, 16, v68
	v_and_b32_e32 v171, 0xffff0000, v68
	v_mul_f32_e32 v170, s3, v170
	v_mul_f32_e32 v171, s3, v171
	v_fma_f32 v168, v170, v10, v168
	v_fma_f32 v169, v171, v11, v169
	v_fma_f32 v184, v168, v168, v184
	v_fma_f32 v184, v169, v169, v184
	v_cvt_pk_bf16_f32 v36, v168, v169
	v_lshlrev_b32_e32 v168, 16, v37
	v_and_b32_e32 v169, 0xffff0000, v37
	v_lshlrev_b32_e32 v170, 16, v69
	v_and_b32_e32 v171, 0xffff0000, v69
	v_mul_f32_e32 v170, s3, v170
	v_mul_f32_e32 v171, s3, v171
	v_fma_f32 v168, v170, v12, v168
	v_fma_f32 v169, v171, v13, v169
	v_fma_f32 v184, v168, v168, v184
	v_fma_f32 v184, v169, v169, v184
	v_cvt_pk_bf16_f32 v37, v168, v169
	v_lshlrev_b32_e32 v168, 16, v38
	v_and_b32_e32 v169, 0xffff0000, v38
	v_lshlrev_b32_e32 v170, 16, v70
	v_and_b32_e32 v171, 0xffff0000, v70
	v_mul_f32_e32 v170, s3, v170
	v_mul_f32_e32 v171, s3, v171
	v_fma_f32 v168, v170, v14, v168
	v_fma_f32 v169, v171, v15, v169
	v_fma_f32 v184, v168, v168, v184
	v_fma_f32 v184, v169, v169, v184
	v_cvt_pk_bf16_f32 v38, v168, v169
; __device__ __forceinline__ float bf_lo(unsigned w) { return __uint_as_float(w << 16); }
; __device__ __forceinline__ float bf_hi(unsigned w) { return __uint_as_float(w & 0xffff0000u); }
; __device__ __forceinline__ unsigned pk2(float lo, float hi) { bf16x2_t r = __builtin_convertvector((f32x2_t){lo, hi}, bf16x2_t); return __builtin_bit_cast(unsigned, r); }
; template <bool SRC_F32, bool FINAL, int R> __device__ __forceinline__ void ew_compute(const EwSet<SRC_F32, R>& S, int rb, const f32x4 (&g)[4], bf16* hb_out, float* out32, float scale, float* rs_out, int lane) {
; #pragma unroll
;     for (int i = 0; i < R; ++i) {
;         float q = S.p[i];
;         q += __shfl_xor(q, 1); q += __shfl_xor(q, 2); q += __shfl_xor(q, 4); q += __shfl_xor(q, 8);
;         const float ss = __shfl(q, 0);
;         const float rs = scale / sqrtf(ss * (1.f / D) + EPS);
;         float s2 = 0.f;
; #pragma unroll
;         for (int j = 0; j < 4; ++j) {
;             f32x4 h;
;             if constexpr (SRC_F32) h = S.h32[i][j];
;             else { const v2u hw = S.hb[i][j]; h.x = bf_lo(hw.x); h.y = bf_hi(hw.x); h.z = bf_lo(hw.y); h.w = bf_hi(hw.y); }
;             const v2u fw = S.fw[i][j];
;             f32x4 v; v.x = h.x + bf_lo(fw.x) * rs * g[j].x; v.y = h.y + bf_hi(fw.x) * rs * g[j].y; v.z = h.z + bf_lo(fw.y) * rs * g[j].z; v.w = h.w + bf_hi(fw.y) * rs * g[j].w;
;             if (FINAL) __builtin_nontemporal_store(v, (f32x4*)(out32 + (size_t)(rb + i) * D) + lane + 64 * j);
;             else { v2u o; o.x = pk2(v.x, v.y); o.y = pk2(v.z, v.w); ((v2u*)(hb_out + (size_t)(rb + i) * D) + lane)[64 * j] = o; s2 += (v.x * v.x + v.y * v.y) + (v.z * v.z + v.w * v.w); }
;         }
;         if (!FINAL) { const float tot = wave_sum(s2); if (lane == 0) rs_out[rb + i] = 1.0f / sqrtf(tot * (1.f / D) + EPS); }
;     }
	v_lshlrev_b32_e32 v168, 16, v39
	v_and_b32_e32 v169, 0xffff0000, v39
	v_lshlrev_b32_e32 v170, 16, v71
	v_and_b32_e32 v171, 0xffff0000, v71
	v_mul_f32_e32 v170, s3, v170
	v_mul_f32_e32 v171, s3, v171
	v_fma_f32 v168, v170, v16, v168
	v_fma_f32 v169, v171, v17, v169
	v_fma_f32 v184, v168, v168, v184
	v_fma_f32 v184, v169, v169, v184
	v_cvt_pk_bf16_f32 v39, v168, v169
	global_store_dwordx4 v18, v[32:35], s[0:1]
	global_store_dwordx4 v18, v[36:39], s[0:1] offset:1024
	v_lshlrev_b32_e32 v168, 16, v40
	v_and_b32_e32 v169, 0xffff0000, v40
	v_lshlrev_b32_e32 v170, 16, v72
	v_and_b32_e32 v171, 0xffff0000, v72
	v_mul_f32_e32 v170, s24, v170
	v_mul_f32_e32 v171, s24, v171
	v_fma_f32 v168, v170, v2, v168
	v_fma_f32 v169, v171, v3, v169
	v_fma_f32 v185, v168, v168, v185
	v_fma_f32 v185, v169, v169, v185
	v_cvt_pk_bf16_f32 v40, v168, v169
	v_lshlrev_b32_e32 v168, 16, v41
	v_and_b32_e32 v169, 0xffff0000, v41
	v_lshlrev_b32_e32 v170, 16, v73
	v_and_b32_e32 v171, 0xffff0000, v73
	v_mul_f32_e32 v170, s24, v170
	v_mul_f32_e32 v171, s24, v171
	v_fma_f32 v168, v170, v4, v168
	v_fma_f32 v169, v171, v5, v169
	v_fma_f32 v185, v168, v168, v185
	v_fma_f32 v185, v169, v169, v185
	v_cvt_pk_bf16_f32 v41, v168, v169
	v_lshlrev_b32_e32 v168, 16, v42
	v_and_b32_e32 v169, 0xffff0000, v42
	v_lshlrev_b32_e32 v170, 16, v74
	v_and_b32_e32 v171, 0xffff0000, v74
	v_mul_f32_e32 v170, s24, v170
	v_mul_f32_e32 v171, s24, v171
	v_fma_f32 v168, v170, v6, v168
	v_fma_f32 v169, v171, v7, v169
	v_fma_f32 v185, v168, v168, v185
	v_fma_f32 v185, v169, v169, v185
	v_cvt_pk_bf16_f32 v42, v168, v169
	v_lshlrev_b32_e32 v168, 16, v43
	v_and_b32_e32 v169, 0xffff0000, v43
	v_lshlrev_b32_e32 v170, 16, v75
	v_and_b32_e32 v171, 0xffff0000, v75
	v_mul_f32_e32 v170, s24, v170
	v_mul_f32_e32 v171, s24, v171
	v_fma_f32 v168, v170, v8, v168
	v_fma_f32 v169, v171, v9, v169
	v_fma_f32 v185, v168, v168, v185
	v_fma_f32 v185, v169, v169, v185
	v_cvt_pk_bf16_f32 v43, v168, v169
	v_lshlrev_b32_e32 v168, 16, v44
	v_and_b32_e32 v169, 0xffff0000, v44
	v_lshlrev_b32_e32 v170, 16, v76
	v_and_b32_e32 v171, 0xffff0000, v76
	v_mul_f32_e32 v170, s24, v170
	v_mul_f32_e32 v171, s24, v171
	v_fma_f32 v168, v170, v10, v168
	v_fma_f32 v169, v171, v11, v169
	v_fma_f32 v185, v168, v168, v185
	v_fma_f32 v185, v169, v169, v185
	v_cvt_pk_bf16_f32 v44, v168, v169
	v_lshlrev_b32_e32 v168, 16, v45
	v_and_b32_e32 v169, 0xffff0000, v45
	v_lshlrev_b32_e32 v170, 16, v77
	v_and_b32_e32 v171, 0xffff0000, v77
	v_mul_f32_e32 v170, s24, v170
	v_mul_f32_e32 v171, s24, v171
	v_fma_f32 v168, v170, v12, v168
	v_fma_f32 v169, v171, v13, v169
	v_fma_f32 v185, v168, v168, v185
	v_fma_f32 v185, v169, v169, v185
	v_cvt_pk_bf16_f32 v45, v168, v169
	v_lshlrev_b32_e32 v168, 16, v46
	v_and_b32_e32 v169, 0xffff0000, v46
	v_lshlrev_b32_e32 v170, 16, v78
	v_and_b32_e32 v171, 0xffff0000, v78
	v_mul_f32_e32 v170, s24, v170
	v_mul_f32_e32 v171, s24, v171
	v_fma_f32 v168, v170, v14, v168
	v_fma_f32 v169, v171, v15, v169
	v_fma_f32 v185, v168, v168, v185
	v_fma_f32 v185, v169, v169, v185
	v_cvt_pk_bf16_f32 v46, v168, v169
	v_lshlrev_b32_e32 v168, 16, v47
	v_and_b32_e32 v169, 0xffff0000, v47
	v_lshlrev_b32_e32 v170, 16, v79
	v_and_b32_e32 v171, 0xffff0000, v79
	v_mul_f32_e32 v170, s24, v170
	v_mul_f32_e32 v171, s24, v171
	v_fma_f32 v168, v170, v16, v168
	v_fma_f32 v169, v171, v17, v169
	v_fma_f32 v185, v168, v168, v185
	v_fma_f32 v185, v169, v169, v185
	v_cvt_pk_bf16_f32 v47, v168, v169
	global_store_dwordx4 v18, v[40:43], s[0:1] offset:2048
	global_store_dwordx4 v18, v[44:47], s[0:1] offset:3072
	v_lshlrev_b32_e32 v168, 16, v48
	v_and_b32_e32 v169, 0xffff0000, v48
	v_lshlrev_b32_e32 v170, 16, v80
	v_and_b32_e32 v171, 0xffff0000, v80
	v_mul_f32_e32 v170, s98, v170
	v_mul_f32_e32 v171, s98, v171
	v_fma_f32 v168, v170, v2, v168
	v_fma_f32 v169, v171, v3, v169
	v_fma_f32 v186, v168, v168, v186
	v_fma_f32 v186, v169, v169, v186
	v_cvt_pk_bf16_f32 v48, v168, v169
	v_lshlrev_b32_e32 v168, 16, v49
	v_and_b32_e32 v169, 0xffff0000, v49
	v_lshlrev_b32_e32 v170, 16, v81
	v_and_b32_e32 v171, 0xffff0000, v81
	v_mul_f32_e32 v170, s98, v170
	v_mul_f32_e32 v171, s98, v171
	v_fma_f32 v168, v170, v4, v168
	v_fma_f32 v169, v171, v5, v169
	v_fma_f32 v186, v168, v168, v186
	v_fma_f32 v186, v169, v169, v186
	v_cvt_pk_bf16_f32 v49, v168, v169
	v_lshlrev_b32_e32 v168, 16, v50
	v_and_b32_e32 v169, 0xffff0000, v50
	v_lshlrev_b32_e32 v170, 16, v82
	v_and_b32_e32 v171, 0xffff0000, v82
	v_mul_f32_e32 v170, s98, v170
	v_mul_f32_e32 v171, s98, v171
	v_fma_f32 v168, v170, v6, v168
	v_fma_f32 v169, v171, v7, v169
	v_fma_f32 v186, v168, v168, v186
	v_fma_f32 v186, v169, v169, v186
	v_cvt_pk_bf16_f32 v50, v168, v169
	v_lshlrev_b32_e32 v168, 16, v51
	v_and_b32_e32 v169, 0xffff0000, v51
	v_lshlrev_b32_e32 v170, 16, v83
	v_and_b32_e32 v171, 0xffff0000, v83
	v_mul_f32_e32 v170, s98, v170
	v_mul_f32_e32 v171, s98, v171
	v_fma_f32 v168, v170, v8, v168
	v_fma_f32 v169, v171, v9, v169
	v_fma_f32 v186, v168, v168, v186
	v_fma_f32 v186, v169, v169, v186
	v_cvt_pk_bf16_f32 v51, v168, v169
	v_lshlrev_b32_e32 v168, 16, v52
	v_and_b32_e32 v169, 0xffff0000, v52
	v_lshlrev_b32_e32 v170, 16, v84
	v_and_b32_e32 v171, 0xffff0000, v84
	v_mul_f32_e32 v170, s98, v170
	v_mul_f32_e32 v171, s98, v171
	v_fma_f32 v168, v170, v10, v168
	v_fma_f32 v169, v171, v11, v169
	v_fma_f32 v186, v168, v168, v186
	v_fma_f32 v186, v169, v169, v186
	v_cvt_pk_bf16_f32 v52, v168, v169
	v_lshlrev_b32_e32 v168, 16, v53
	v_and_b32_e32 v169, 0xffff0000, v53
	v_lshlrev_b32_e32 v170, 16, v85
	v_and_b32_e32 v171, 0xffff0000, v85
	v_mul_f32_e32 v170, s98, v170
	v_mul_f32_e32 v171, s98, v171
	v_fma_f32 v168, v170, v12, v168
	v_fma_f32 v169, v171, v13, v169
; __device__ __forceinline__ float bf_lo(unsigned w) { return __uint_as_float(w << 16); }
; __device__ __forceinline__ float bf_hi(unsigned w) { return __uint_as_float(w & 0xffff0000u); }
; __device__ __forceinline__ unsigned pk2(float lo, float hi) { bf16x2_t r = __builtin_convertvector((f32x2_t){lo, hi}, bf16x2_t); return __builtin_bit_cast(unsigned, r); }
; template <bool SRC_F32, bool FINAL, int R> __device__ __forceinline__ void ew_compute(const EwSet<SRC_F32, R>& S, int rb, const f32x4 (&g)[4], bf16* hb_out, float* out32, float scale, float* rs_out, int lane) {
; #pragma unroll
;     for (int i = 0; i < R; ++i) {
;         float q = S.p[i];
;         q += __shfl_xor(q, 1); q += __shfl_xor(q, 2); q += __shfl_xor(q, 4); q += __shfl_xor(q, 8);
;         const float ss = __shfl(q, 0);
;         const float rs = scale / sqrtf(ss * (1.f / D) + EPS);
;         float s2 = 0.f;
; #pragma unroll
;         for (int j = 0; j < 4; ++j) {
;             f32x4 h;
;             if constexpr (SRC_F32) h = S.h32[i][j];
;             else { const v2u hw = S.hb[i][j]; h.x = bf_lo(hw.x); h.y = bf_hi(hw.x); h.z = bf_lo(hw.y); h.w = bf_hi(hw.y); }
;             const v2u fw = S.fw[i][j];
;             f32x4 v; v.x = h.x + bf_lo(fw.x) * rs * g[j].x; v.y = h.y + bf_hi(fw.x) * rs * g[j].y; v.z = h.z + bf_lo(fw.y) * rs * g[j].z; v.w = h.w + bf_hi(fw.y) * rs * g[j].w;
;             if (FINAL) __builtin_nontemporal_store(v, (f32x4*)(out32 + (size_t)(rb + i) * D) + lane + 64 * j);
;             else { v2u o; o.x = pk2(v.x, v.y); o.y = pk2(v.z, v.w); ((v2u*)(hb_out + (size_t)(rb + i) * D) + lane)[64 * j] = o; s2 += (v.x * v.x + v.y * v.y) + (v.z * v.z + v.w * v.w); }
;         }
;         if (!FINAL) { const float tot = wave_sum(s2); if (lane == 0) rs_out[rb + i] = 1.0f / sqrtf(tot * (1.f / D) + EPS); }
;     }
	v_fma_f32 v186, v168, v168, v186
	v_fma_f32 v186, v169, v169, v186
	v_cvt_pk_bf16_f32 v53, v168, v169
	v_lshlrev_b32_e32 v168, 16, v54
	v_and_b32_e32 v169, 0xffff0000, v54
	v_lshlrev_b32_e32 v170, 16, v86
	v_and_b32_e32 v171, 0xffff0000, v86
	v_mul_f32_e32 v170, s98, v170
	v_mul_f32_e32 v171, s98, v171
	v_fma_f32 v168, v170, v14, v168
	v_fma_f32 v169, v171, v15, v169
	v_fma_f32 v186, v168, v168, v186
	v_fma_f32 v186, v169, v169, v186
	v_cvt_pk_bf16_f32 v54, v168, v169
	v_lshlrev_b32_e32 v168, 16, v55
	v_and_b32_e32 v169, 0xffff0000, v55
	v_lshlrev_b32_e32 v170, 16, v87
	v_and_b32_e32 v171, 0xffff0000, v87
	v_mul_f32_e32 v170, s98, v170
	v_mul_f32_e32 v171, s98, v171
	v_fma_f32 v168, v170, v16, v168
	v_fma_f32 v169, v171, v17, v169
	v_fma_f32 v186, v168, v168, v186
	v_fma_f32 v186, v169, v169, v186
	v_cvt_pk_bf16_f32 v55, v168, v169
	global_store_dwordx4 v19, v[48:51], s[0:1]
	global_store_dwordx4 v19, v[52:55], s[0:1] offset:1024
	v_lshlrev_b32_e32 v168, 16, v56
	v_and_b32_e32 v169, 0xffff0000, v56
	v_lshlrev_b32_e32 v170, 16, v88
	v_and_b32_e32 v171, 0xffff0000, v88
	v_mul_f32_e32 v170, s101, v170
	v_mul_f32_e32 v171, s101, v171
	v_fma_f32 v168, v170, v2, v168
	v_fma_f32 v169, v171, v3, v169
	v_fma_f32 v187, v168, v168, v187
	v_fma_f32 v187, v169, v169, v187
	v_cvt_pk_bf16_f32 v56, v168, v169
	v_lshlrev_b32_e32 v168, 16, v57
	v_and_b32_e32 v169, 0xffff0000, v57
	v_lshlrev_b32_e32 v170, 16, v89
	v_and_b32_e32 v171, 0xffff0000, v89
	v_mul_f32_e32 v170, s101, v170
	v_mul_f32_e32 v171, s101, v171
	v_fma_f32 v168, v170, v4, v168
	v_fma_f32 v169, v171, v5, v169
	v_fma_f32 v187, v168, v168, v187
	v_fma_f32 v187, v169, v169, v187
	v_cvt_pk_bf16_f32 v57, v168, v169
	v_lshlrev_b32_e32 v168, 16, v58
	v_and_b32_e32 v169, 0xffff0000, v58
	v_lshlrev_b32_e32 v170, 16, v90
	v_and_b32_e32 v171, 0xffff0000, v90
	v_mul_f32_e32 v170, s101, v170
	v_mul_f32_e32 v171, s101, v171
	v_fma_f32 v168, v170, v6, v168
	v_fma_f32 v169, v171, v7, v169
	v_fma_f32 v187, v168, v168, v187
	v_fma_f32 v187, v169, v169, v187
	v_cvt_pk_bf16_f32 v58, v168, v169
	v_lshlrev_b32_e32 v168, 16, v59
	v_and_b32_e32 v169, 0xffff0000, v59
	v_lshlrev_b32_e32 v170, 16, v91
	v_and_b32_e32 v171, 0xffff0000, v91
	v_mul_f32_e32 v170, s101, v170
	v_mul_f32_e32 v171, s101, v171
	v_fma_f32 v168, v170, v8, v168
	v_fma_f32 v169, v171, v9, v169
	v_fma_f32 v187, v168, v168, v187
	v_fma_f32 v187, v169, v169, v187
	v_cvt_pk_bf16_f32 v59, v168, v169
	v_lshlrev_b32_e32 v168, 16, v60
	v_and_b32_e32 v169, 0xffff0000, v60
	v_lshlrev_b32_e32 v170, 16, v92
	v_and_b32_e32 v171, 0xffff0000, v92
	v_mul_f32_e32 v170, s101, v170
	v_mul_f32_e32 v171, s101, v171
	v_fma_f32 v168, v170, v10, v168
	v_fma_f32 v169, v171, v11, v169
	v_fma_f32 v187, v168, v168, v187
	v_fma_f32 v187, v169, v169, v187
	v_cvt_pk_bf16_f32 v60, v168, v169
	v_lshlrev_b32_e32 v168, 16, v61
	v_and_b32_e32 v169, 0xffff0000, v61
	v_lshlrev_b32_e32 v170, 16, v93
	v_and_b32_e32 v171, 0xffff0000, v93
	v_mul_f32_e32 v170, s101, v170
	v_mul_f32_e32 v171, s101, v171
	v_fma_f32 v168, v170, v12, v168
	v_fma_f32 v169, v171, v13, v169
	v_fma_f32 v187, v168, v168, v187
	v_fma_f32 v187, v169, v169, v187
	v_cvt_pk_bf16_f32 v61, v168, v169
	v_lshlrev_b32_e32 v168, 16, v62
	v_and_b32_e32 v169, 0xffff0000, v62
	v_lshlrev_b32_e32 v170, 16, v94
	v_and_b32_e32 v171, 0xffff0000, v94
	v_mul_f32_e32 v170, s101, v170
	v_mul_f32_e32 v171, s101, v171
	v_fma_f32 v168, v170, v14, v168
	v_fma_f32 v169, v171, v15, v169
	v_fma_f32 v187, v168, v168, v187
	v_fma_f32 v187, v169, v169, v187
	v_cvt_pk_bf16_f32 v62, v168, v169
	v_lshlrev_b32_e32 v168, 16, v63
	v_and_b32_e32 v169, 0xffff0000, v63
	v_lshlrev_b32_e32 v170, 16, v95
	v_and_b32_e32 v171, 0xffff0000, v95
	v_mul_f32_e32 v170, s101, v170
	v_mul_f32_e32 v171, s101, v171
	v_fma_f32 v168, v170, v16, v168
	v_fma_f32 v169, v171, v17, v169
	v_fma_f32 v187, v168, v168, v187
	v_fma_f32 v187, v169, v169, v187
	v_cvt_pk_bf16_f32 v63, v168, v169
	global_store_dwordx4 v19, v[56:59], s[0:1] offset:2048
	global_store_dwordx4 v19, v[60:63], s[0:1] offset:3072
	s_nop 1
	v_add_f32_dpp v184, v184, v184 quad_perm:[1,0,3,2] row_mask:0xf bank_mask:0xf
	v_add_f32_dpp v185, v185, v185 quad_perm:[1,0,3,2] row_mask:0xf bank_mask:0xf
	v_add_f32_dpp v186, v186, v186 quad_perm:[1,0,3,2] row_mask:0xf bank_mask:0xf
	v_add_f32_dpp v187, v187, v187 quad_perm:[1,0,3,2] row_mask:0xf bank_mask:0xf
	v_add_f32_dpp v184, v184, v184 quad_perm:[2,3,0,1] row_mask:0xf bank_mask:0xf
	v_add_f32_dpp v185, v185, v185 quad_perm:[2,3,0,1] row_mask:0xf bank_mask:0xf
	v_add_f32_dpp v186, v186, v186 quad_perm:[2,3,0,1] row_mask:0xf bank_mask:0xf
	v_add_f32_dpp v187, v187, v187 quad_perm:[2,3,0,1] row_mask:0xf bank_mask:0xf
	v_add_f32_dpp v184, v184, v184 row_half_mirror row_mask:0xf bank_mask:0xf
	v_add_f32_dpp v185, v185, v185 row_half_mirror row_mask:0xf bank_mask:0xf
	v_add_f32_dpp v186, v186, v186 row_half_mirror row_mask:0xf bank_mask:0xf
	v_add_f32_dpp v187, v187, v187 row_half_mirror row_mask:0xf bank_mask:0xf
	v_add_f32_dpp v184, v184, v184 row_mirror row_mask:0xf bank_mask:0xf
	v_add_f32_dpp v185, v185, v185 row_mirror row_mask:0xf bank_mask:0xf
	v_add_f32_dpp v186, v186, v186 row_mirror row_mask:0xf bank_mask:0xf
	v_add_f32_dpp v187, v187, v187 row_mirror row_mask:0xf bank_mask:0xf
	v_add_f32_dpp v184, v184, v184 row_bcast:15 row_mask:0xa bank_mask:0xf
	v_add_f32_dpp v185, v185, v185 row_bcast:15 row_mask:0xa bank_mask:0xf
	v_add_f32_dpp v186, v186, v186 row_bcast:15 row_mask:0xa bank_mask:0xf
	v_add_f32_dpp v187, v187, v187 row_bcast:15 row_mask:0xa bank_mask:0xf
	v_add_f32_dpp v184, v184, v184 row_bcast:31 row_mask:0xc bank_mask:0xf
	v_add_f32_dpp v185, v185, v185 row_bcast:31 row_mask:0xc bank_mask:0xf
	v_add_f32_dpp v186, v186, v186 row_bcast:31 row_mask:0xc bank_mask:0xf
	v_add_f32_dpp v187, v187, v187 row_bcast:31 row_mask:0xc bank_mask:0xf
	s_nop 1
	v_readlane_b32 s3, v184, 63
	v_readlane_b32 s24, v185, 63
	v_readlane_b32 s98, v186, 63
	v_readlane_b32 s101, v187, 63
	s_nop 3
	v_writelane_b32 v188, s3, 0
	v_writelane_b32 v188, s24, 1
	v_writelane_b32 v188, s98, 2
	v_writelane_b32 v188, s101, 3
	s_nop 1
	v_mul_f32_e32 v188, 0x3a800000, v188
	v_add_f32_e32 v188, 0x358637bd, v188
	v_rsq_f32_e32 v188, v188
	s_mov_b64 exec, 15
	global_store_dword v21, v188, s[14:15]
	s_mov_b64 exec, -1
	s_waitcnt vmcnt(9)
; __device__ __forceinline__ float bf_lo(unsigned w) { return __uint_as_float(w << 16); }
; __device__ __forceinline__ float bf_hi(unsigned w) { return __uint_as_float(w & 0xffff0000u); }
; __device__ __forceinline__ unsigned pk2(float lo, float hi) { bf16x2_t r = __builtin_convertvector((f32x2_t){lo, hi}, bf16x2_t); return __builtin_bit_cast(unsigned, r); }
; template <bool SRC_F32, bool FINAL, int R> __device__ __forceinline__ void ew_compute(const EwSet<SRC_F32, R>& S, int rb, const f32x4 (&g)[4], bf16* hb_out, float* out32, float scale, float* rs_out, int lane) {
;     ...
;         float q = S.p[i];
;         q += __shfl_xor(q, 1); q += __shfl_xor(q, 2); q += __shfl_xor(q, 4); q += __shfl_xor(q, 8);
;         const float ss = __shfl(q, 0);
;         const float rs = scale / sqrtf(ss * (1.f / D) + EPS);
;         float s2 = 0.f;
; #pragma unroll
;         for (int j = 0; j < 4; ++j) {
;             f32x4 h;
;             if constexpr (SRC_F32) h = S.h32[i][j];
;             else { const v2u hw = S.hb[i][j]; h.x = bf_lo(hw.x); h.y = bf_hi(hw.x); h.z = bf_lo(hw.y); h.w = bf_hi(hw.y); }
;             const v2u fw = S.fw[i][j];
;             f32x4 v; v.x = h.x + bf_lo(fw.x) * rs * g[j].x; v.y = h.y + bf_hi(fw.x) * rs * g[j].y; v.z = h.z + bf_lo(fw.y) * rs * g[j].z; v.w = h.w + bf_hi(fw.y) * rs * g[j].w;
;             if (FINAL) __builtin_nontemporal_store(v, (f32x4*)(out32 + (size_t)(rb + i) * D) + lane + 64 * j);
;             else { v2u o; o.x = pk2(v.x, v.y); o.y = pk2(v.z, v.w); ((v2u*)(hb_out + (size_t)(rb + i) * D) + lane)[64 * j] = o; s2 += (v.x * v.x + v.y * v.y) + (v.z * v.z + v.w * v.w); }
	v_add_f32_dpp v164, v164, v164 quad_perm:[1,0,3,2] row_mask:0xf bank_mask:0xf
	s_nop 1
	v_add_f32_dpp v164, v164, v164 quad_perm:[2,3,0,1] row_mask:0xf bank_mask:0xf
	s_nop 1
	v_add_f32_dpp v164, v164, v164 row_half_mirror row_mask:0xf bank_mask:0xf
	s_nop 1
	v_add_f32_dpp v164, v164, v164 row_mirror row_mask:0xf bank_mask:0xf
	s_nop 1
	v_mul_f32_e32 v164, 0x3a800000, v164
	v_add_f32_e32 v164, 0x358637bd, v164
	v_rsq_f32_e32 v164, v164
	s_nop 0
	v_mul_f32_e32 v164, 0x3f000000, v164
	s_nop 0
	v_readlane_b32 s3, v164, 0
	v_readlane_b32 s24, v164, 16
	v_readlane_b32 s98, v164, 32
	v_readlane_b32 s101, v164, 48
	s_nop 1
	v_mov_b32_e32 v184, 0
	v_mov_b32_e32 v185, 0
	v_mov_b32_e32 v186, 0
	v_mov_b32_e32 v187, 0
	v_lshlrev_b32_e32 v168, 16, v100
	v_and_b32_e32 v169, 0xffff0000, v100
	v_lshlrev_b32_e32 v170, 16, v132
	v_and_b32_e32 v171, 0xffff0000, v132
	v_mul_f32_e32 v170, s3, v170
	v_mul_f32_e32 v171, s3, v171
	v_fma_f32 v168, v170, v2, v168
	v_fma_f32 v169, v171, v3, v169
	v_fma_f32 v184, v168, v168, v184
	v_fma_f32 v184, v169, v169, v184
	v_cvt_pk_bf16_f32 v100, v168, v169
	v_lshlrev_b32_e32 v168, 16, v101
	v_and_b32_e32 v169, 0xffff0000, v101
	v_lshlrev_b32_e32 v170, 16, v133
	v_and_b32_e32 v171, 0xffff0000, v133
	v_mul_f32_e32 v170, s3, v170
	v_mul_f32_e32 v171, s3, v171
	v_fma_f32 v168, v170, v4, v168
	v_fma_f32 v169, v171, v5, v169
	v_fma_f32 v184, v168, v168, v184
	v_fma_f32 v184, v169, v169, v184
	v_cvt_pk_bf16_f32 v101, v168, v169
	v_lshlrev_b32_e32 v168, 16, v102
	v_and_b32_e32 v169, 0xffff0000, v102
	v_lshlrev_b32_e32 v170, 16, v134
	v_and_b32_e32 v171, 0xffff0000, v134
	v_mul_f32_e32 v170, s3, v170
	v_mul_f32_e32 v171, s3, v171
	v_fma_f32 v168, v170, v6, v168
	v_fma_f32 v169, v171, v7, v169
	v_fma_f32 v184, v168, v168, v184
	v_fma_f32 v184, v169, v169, v184
	v_cvt_pk_bf16_f32 v102, v168, v169
	v_lshlrev_b32_e32 v168, 16, v103
	v_and_b32_e32 v169, 0xffff0000, v103
	v_lshlrev_b32_e32 v170, 16, v135
	v_and_b32_e32 v171, 0xffff0000, v135
	v_mul_f32_e32 v170, s3, v170
	v_mul_f32_e32 v171, s3, v171
	v_fma_f32 v168, v170, v8, v168
	v_fma_f32 v169, v171, v9, v169
	v_fma_f32 v184, v168, v168, v184
	v_fma_f32 v184, v169, v169, v184
	v_cvt_pk_bf16_f32 v103, v168, v169
	v_lshlrev_b32_e32 v168, 16, v104
	v_and_b32_e32 v169, 0xffff0000, v104
	v_lshlrev_b32_e32 v170, 16, v136
	v_and_b32_e32 v171, 0xffff0000, v136
	v_mul_f32_e32 v170, s3, v170
	v_mul_f32_e32 v171, s3, v171
	v_fma_f32 v168, v170, v10, v168
	v_fma_f32 v169, v171, v11, v169
	v_fma_f32 v184, v168, v168, v184
	v_fma_f32 v184, v169, v169, v184
	v_cvt_pk_bf16_f32 v104, v168, v169
	v_lshlrev_b32_e32 v168, 16, v105
	v_and_b32_e32 v169, 0xffff0000, v105
	v_lshlrev_b32_e32 v170, 16, v137
	v_and_b32_e32 v171, 0xffff0000, v137
	v_mul_f32_e32 v170, s3, v170
	v_mul_f32_e32 v171, s3, v171
	v_fma_f32 v168, v170, v12, v168
	v_fma_f32 v169, v171, v13, v169
	v_fma_f32 v184, v168, v168, v184
	v_fma_f32 v184, v169, v169, v184
	v_cvt_pk_bf16_f32 v105, v168, v169
	v_lshlrev_b32_e32 v168, 16, v106
	v_and_b32_e32 v169, 0xffff0000, v106
	v_lshlrev_b32_e32 v170, 16, v138
	v_and_b32_e32 v171, 0xffff0000, v138
	v_mul_f32_e32 v170, s3, v170
	v_mul_f32_e32 v171, s3, v171
	v_fma_f32 v168, v170, v14, v168
	v_fma_f32 v169, v171, v15, v169
	v_fma_f32 v184, v168, v168, v184
	v_fma_f32 v184, v169, v169, v184
	v_cvt_pk_bf16_f32 v106, v168, v169
	v_lshlrev_b32_e32 v168, 16, v107
	v_and_b32_e32 v169, 0xffff0000, v107
	v_lshlrev_b32_e32 v170, 16, v139
	v_and_b32_e32 v171, 0xffff0000, v139
	v_mul_f32_e32 v170, s3, v170
	v_mul_f32_e32 v171, s3, v171
	v_fma_f32 v168, v170, v16, v168
	v_fma_f32 v169, v171, v17, v169
	v_fma_f32 v184, v168, v168, v184
	v_fma_f32 v184, v169, v169, v184
	v_cvt_pk_bf16_f32 v107, v168, v169
	global_store_dwordx4 v23, v[100:103], s[0:1]
	global_store_dwordx4 v23, v[104:107], s[0:1] offset:1024
	v_lshlrev_b32_e32 v168, 16, v108
	v_and_b32_e32 v169, 0xffff0000, v108
	v_lshlrev_b32_e32 v170, 16, v140
	v_and_b32_e32 v171, 0xffff0000, v140
	v_mul_f32_e32 v170, s24, v170
	v_mul_f32_e32 v171, s24, v171
	v_fma_f32 v168, v170, v2, v168
	v_fma_f32 v169, v171, v3, v169
	v_fma_f32 v185, v168, v168, v185
	v_fma_f32 v185, v169, v169, v185
	v_cvt_pk_bf16_f32 v108, v168, v169
	v_lshlrev_b32_e32 v168, 16, v109
	v_and_b32_e32 v169, 0xffff0000, v109
	v_lshlrev_b32_e32 v170, 16, v141
	v_and_b32_e32 v171, 0xffff0000, v141
	v_mul_f32_e32 v170, s24, v170
	v_mul_f32_e32 v171, s24, v171
	v_fma_f32 v168, v170, v4, v168
	v_fma_f32 v169, v171, v5, v169
	v_fma_f32 v185, v168, v168, v185
	v_fma_f32 v185, v169, v169, v185
	v_cvt_pk_bf16_f32 v109, v168, v169
	v_lshlrev_b32_e32 v168, 16, v110
	v_and_b32_e32 v169, 0xffff0000, v110
	v_lshlrev_b32_e32 v170, 16, v142
	v_and_b32_e32 v171, 0xffff0000, v142
	v_mul_f32_e32 v170, s24, v170
	v_mul_f32_e32 v171, s24, v171
	v_fma_f32 v168, v170, v6, v168
	v_fma_f32 v169, v171, v7, v169
	v_fma_f32 v185, v168, v168, v185
	v_fma_f32 v185, v169, v169, v185
	v_cvt_pk_bf16_f32 v110, v168, v169
	v_lshlrev_b32_e32 v168, 16, v111
	v_and_b32_e32 v169, 0xffff0000, v111
	v_lshlrev_b32_e32 v170, 16, v143
	v_and_b32_e32 v171, 0xffff0000, v143
	v_mul_f32_e32 v170, s24, v170
	v_mul_f32_e32 v171, s24, v171
	v_fma_f32 v168, v170, v8, v168
	v_fma_f32 v169, v171, v9, v169
	v_fma_f32 v185, v168, v168, v185
	v_fma_f32 v185, v169, v169, v185
	v_cvt_pk_bf16_f32 v111, v168, v169
	v_lshlrev_b32_e32 v168, 16, v112
	v_and_b32_e32 v169, 0xffff0000, v112
	v_lshlrev_b32_e32 v170, 16, v144
	v_and_b32_e32 v171, 0xffff0000, v144
	v_mul_f32_e32 v170, s24, v170
	v_mul_f32_e32 v171, s24, v171
	v_fma_f32 v168, v170, v10, v168
	v_fma_f32 v169, v171, v11, v169
	v_fma_f32 v185, v168, v168, v185
	v_fma_f32 v185, v169, v169, v185
; __device__ __forceinline__ float bf_lo(unsigned w) { return __uint_as_float(w << 16); }
; __device__ __forceinline__ float bf_hi(unsigned w) { return __uint_as_float(w & 0xffff0000u); }
; __device__ __forceinline__ unsigned pk2(float lo, float hi) { bf16x2_t r = __builtin_convertvector((f32x2_t){lo, hi}, bf16x2_t); return __builtin_bit_cast(unsigned, r); }
; template <bool SRC_F32, bool FINAL, int R> __device__ __forceinline__ void ew_compute(const EwSet<SRC_F32, R>& S, int rb, const f32x4 (&g)[4], bf16* hb_out, float* out32, float scale, float* rs_out, int lane) {
; #pragma unroll
;     for (int i = 0; i < R; ++i) {
;         float q = S.p[i];
;         q += __shfl_xor(q, 1); q += __shfl_xor(q, 2); q += __shfl_xor(q, 4); q += __shfl_xor(q, 8);
;         const float ss = __shfl(q, 0);
;         const float rs = scale / sqrtf(ss * (1.f / D) + EPS);
;         float s2 = 0.f;
; #pragma unroll
;         for (int j = 0; j < 4; ++j) {
;             f32x4 h;
;             if constexpr (SRC_F32) h = S.h32[i][j];
;             else { const v2u hw = S.hb[i][j]; h.x = bf_lo(hw.x); h.y = bf_hi(hw.x); h.z = bf_lo(hw.y); h.w = bf_hi(hw.y); }
;             const v2u fw = S.fw[i][j];
;             f32x4 v; v.x = h.x + bf_lo(fw.x) * rs * g[j].x; v.y = h.y + bf_hi(fw.x) * rs * g[j].y; v.z = h.z + bf_lo(fw.y) * rs * g[j].z; v.w = h.w + bf_hi(fw.y) * rs * g[j].w;
;             if (FINAL) __builtin_nontemporal_store(v, (f32x4*)(out32 + (size_t)(rb + i) * D) + lane + 64 * j);
;             else { v2u o; o.x = pk2(v.x, v.y); o.y = pk2(v.z, v.w); ((v2u*)(hb_out + (size_t)(rb + i) * D) + lane)[64 * j] = o; s2 += (v.x * v.x + v.y * v.y) + (v.z * v.z + v.w * v.w); }
;         }
;         if (!FINAL) { const float tot = wave_sum(s2); if (lane == 0) rs_out[rb + i] = 1.0f / sqrtf(tot * (1.f / D) + EPS); }
;     }
	v_cvt_pk_bf16_f32 v112, v168, v169
	v_lshlrev_b32_e32 v168, 16, v113
	v_and_b32_e32 v169, 0xffff0000, v113
	v_lshlrev_b32_e32 v170, 16, v145
	v_and_b32_e32 v171, 0xffff0000, v145
	v_mul_f32_e32 v170, s24, v170
	v_mul_f32_e32 v171, s24, v171
	v_fma_f32 v168, v170, v12, v168
	v_fma_f32 v169, v171, v13, v169
	v_fma_f32 v185, v168, v168, v185
	v_fma_f32 v185, v169, v169, v185
	v_cvt_pk_bf16_f32 v113, v168, v169
	v_lshlrev_b32_e32 v168, 16, v114
	v_and_b32_e32 v169, 0xffff0000, v114
	v_lshlrev_b32_e32 v170, 16, v146
	v_and_b32_e32 v171, 0xffff0000, v146
	v_mul_f32_e32 v170, s24, v170
	v_mul_f32_e32 v171, s24, v171
	v_fma_f32 v168, v170, v14, v168
	v_fma_f32 v169, v171, v15, v169
	v_fma_f32 v185, v168, v168, v185
	v_fma_f32 v185, v169, v169, v185
	v_cvt_pk_bf16_f32 v114, v168, v169
	v_lshlrev_b32_e32 v168, 16, v115
	v_and_b32_e32 v169, 0xffff0000, v115
	v_lshlrev_b32_e32 v170, 16, v147
	v_and_b32_e32 v171, 0xffff0000, v147
	v_mul_f32_e32 v170, s24, v170
	v_mul_f32_e32 v171, s24, v171
	v_fma_f32 v168, v170, v16, v168
	v_fma_f32 v169, v171, v17, v169
	v_fma_f32 v185, v168, v168, v185
	v_fma_f32 v185, v169, v169, v185
	v_cvt_pk_bf16_f32 v115, v168, v169
	global_store_dwordx4 v23, v[108:111], s[0:1] offset:2048
	global_store_dwordx4 v23, v[112:115], s[0:1] offset:3072
	v_lshlrev_b32_e32 v168, 16, v116
	v_and_b32_e32 v169, 0xffff0000, v116
	v_lshlrev_b32_e32 v170, 16, v148
	v_and_b32_e32 v171, 0xffff0000, v148
	v_mul_f32_e32 v170, s98, v170
	v_mul_f32_e32 v171, s98, v171
	v_fma_f32 v168, v170, v2, v168
	v_fma_f32 v169, v171, v3, v169
	v_fma_f32 v186, v168, v168, v186
	v_fma_f32 v186, v169, v169, v186
	v_cvt_pk_bf16_f32 v116, v168, v169
	v_lshlrev_b32_e32 v168, 16, v117
	v_and_b32_e32 v169, 0xffff0000, v117
	v_lshlrev_b32_e32 v170, 16, v149
	v_and_b32_e32 v171, 0xffff0000, v149
	v_mul_f32_e32 v170, s98, v170
	v_mul_f32_e32 v171, s98, v171
	v_fma_f32 v168, v170, v4, v168
	v_fma_f32 v169, v171, v5, v169
	v_fma_f32 v186, v168, v168, v186
	v_fma_f32 v186, v169, v169, v186
	v_cvt_pk_bf16_f32 v117, v168, v169
	v_lshlrev_b32_e32 v168, 16, v118
	v_and_b32_e32 v169, 0xffff0000, v118
	v_lshlrev_b32_e32 v170, 16, v150
	v_and_b32_e32 v171, 0xffff0000, v150
	v_mul_f32_e32 v170, s98, v170
	v_mul_f32_e32 v171, s98, v171
	v_fma_f32 v168, v170, v6, v168
	v_fma_f32 v169, v171, v7, v169
	v_fma_f32 v186, v168, v168, v186
	v_fma_f32 v186, v169, v169, v186
	v_cvt_pk_bf16_f32 v118, v168, v169
	v_lshlrev_b32_e32 v168, 16, v119
	v_and_b32_e32 v169, 0xffff0000, v119
	v_lshlrev_b32_e32 v170, 16, v151
	v_and_b32_e32 v171, 0xffff0000, v151
	v_mul_f32_e32 v170, s98, v170
	v_mul_f32_e32 v171, s98, v171
	v_fma_f32 v168, v170, v8, v168
	v_fma_f32 v169, v171, v9, v169
	v_fma_f32 v186, v168, v168, v186
	v_fma_f32 v186, v169, v169, v186
	v_cvt_pk_bf16_f32 v119, v168, v169
	v_lshlrev_b32_e32 v168, 16, v120
	v_and_b32_e32 v169, 0xffff0000, v120
	v_lshlrev_b32_e32 v170, 16, v152
	v_and_b32_e32 v171, 0xffff0000, v152
	v_mul_f32_e32 v170, s98, v170
	v_mul_f32_e32 v171, s98, v171
	v_fma_f32 v168, v170, v10, v168
	v_fma_f32 v169, v171, v11, v169
	v_fma_f32 v186, v168, v168, v186
	v_fma_f32 v186, v169, v169, v186
	v_cvt_pk_bf16_f32 v120, v168, v169
	v_lshlrev_b32_e32 v168, 16, v121
	v_and_b32_e32 v169, 0xffff0000, v121
	v_lshlrev_b32_e32 v170, 16, v153
	v_and_b32_e32 v171, 0xffff0000, v153
	v_mul_f32_e32 v170, s98, v170
	v_mul_f32_e32 v171, s98, v171
	v_fma_f32 v168, v170, v12, v168
	v_fma_f32 v169, v171, v13, v169
	v_fma_f32 v186, v168, v168, v186
	v_fma_f32 v186, v169, v169, v186
	v_cvt_pk_bf16_f32 v121, v168, v169
	v_lshlrev_b32_e32 v168, 16, v122
	v_and_b32_e32 v169, 0xffff0000, v122
	v_lshlrev_b32_e32 v170, 16, v154
	v_and_b32_e32 v171, 0xffff0000, v154
	v_mul_f32_e32 v170, s98, v170
	v_mul_f32_e32 v171, s98, v171
	v_fma_f32 v168, v170, v14, v168
	v_fma_f32 v169, v171, v15, v169
	v_fma_f32 v186, v168, v168, v186
	v_fma_f32 v186, v169, v169, v186
	v_cvt_pk_bf16_f32 v122, v168, v169
	v_lshlrev_b32_e32 v168, 16, v123
	v_and_b32_e32 v169, 0xffff0000, v123
	v_lshlrev_b32_e32 v170, 16, v155
	v_and_b32_e32 v171, 0xffff0000, v155
	v_mul_f32_e32 v170, s98, v170
	v_mul_f32_e32 v171, s98, v171
	v_fma_f32 v168, v170, v16, v168
	v_fma_f32 v169, v171, v17, v169
	v_fma_f32 v186, v168, v168, v186
	v_fma_f32 v186, v169, v169, v186
	v_cvt_pk_bf16_f32 v123, v168, v169
	global_store_dwordx4 v24, v[116:119], s[0:1]
	global_store_dwordx4 v24, v[120:123], s[0:1] offset:1024
	v_lshlrev_b32_e32 v168, 16, v124
	v_and_b32_e32 v169, 0xffff0000, v124
	v_lshlrev_b32_e32 v170, 16, v156
	v_and_b32_e32 v171, 0xffff0000, v156
	v_mul_f32_e32 v170, s101, v170
	v_mul_f32_e32 v171, s101, v171
	v_fma_f32 v168, v170, v2, v168
	v_fma_f32 v169, v171, v3, v169
	v_fma_f32 v187, v168, v168, v187
	v_fma_f32 v187, v169, v169, v187
	v_cvt_pk_bf16_f32 v124, v168, v169
	v_lshlrev_b32_e32 v168, 16, v125
	v_and_b32_e32 v169, 0xffff0000, v125
	v_lshlrev_b32_e32 v170, 16, v157
	v_and_b32_e32 v171, 0xffff0000, v157
	v_mul_f32_e32 v170, s101, v170
	v_mul_f32_e32 v171, s101, v171
	v_fma_f32 v168, v170, v4, v168
	v_fma_f32 v169, v171, v5, v169
	v_fma_f32 v187, v168, v168, v187
; __device__ __forceinline__ float bf_lo(unsigned w) { return __uint_as_float(w << 16); }
; __device__ __forceinline__ float bf_hi(unsigned w) { return __uint_as_float(w & 0xffff0000u); }
; __device__ __forceinline__ unsigned pk2(float lo, float hi) { bf16x2_t r = __builtin_convertvector((f32x2_t){lo, hi}, bf16x2_t); return __builtin_bit_cast(unsigned, r); }
; template <bool SRC_F32, bool FINAL, int R> __device__ __forceinline__ void ew_compute(const EwSet<SRC_F32, R>& S, int rb, const f32x4 (&g)[4], bf16* hb_out, float* out32, float scale, float* rs_out, int lane) {
; #pragma unroll
;     for (int i = 0; i < R; ++i) {
;         float q = S.p[i];
;         q += __shfl_xor(q, 1); q += __shfl_xor(q, 2); q += __shfl_xor(q, 4); q += __shfl_xor(q, 8);
;         const float ss = __shfl(q, 0);
;         const float rs = scale / sqrtf(ss * (1.f / D) + EPS);
;         float s2 = 0.f;
; #pragma unroll
;         for (int j = 0; j < 4; ++j) {
;             f32x4 h;
;             if constexpr (SRC_F32) h = S.h32[i][j];
;             else { const v2u hw = S.hb[i][j]; h.x = bf_lo(hw.x); h.y = bf_hi(hw.x); h.z = bf_lo(hw.y); h.w = bf_hi(hw.y); }
;             const v2u fw = S.fw[i][j];
;             f32x4 v; v.x = h.x + bf_lo(fw.x) * rs * g[j].x; v.y = h.y + bf_hi(fw.x) * rs * g[j].y; v.z = h.z + bf_lo(fw.y) * rs * g[j].z; v.w = h.w + bf_hi(fw.y) * rs * g[j].w;
;             if (FINAL) __builtin_nontemporal_store(v, (f32x4*)(out32 + (size_t)(rb + i) * D) + lane + 64 * j);
;             else { v2u o; o.x = pk2(v.x, v.y); o.y = pk2(v.z, v.w); ((v2u*)(hb_out + (size_t)(rb + i) * D) + lane)[64 * j] = o; s2 += (v.x * v.x + v.y * v.y) + (v.z * v.z + v.w * v.w); }
;         }
;         if (!FINAL) { const float tot = wave_sum(s2); if (lane == 0) rs_out[rb + i] = 1.0f / sqrtf(tot * (1.f / D) + EPS); }
;     }
; }
; __device__ __forceinline__ void xcd_barrier(const XcdBarrier& b) {
;     asm volatile("s_waitcnt vmcnt(0)" ::: "memory");
;     __syncthreads();
;     if (threadIdx.x == 0) {
;         unsigned* bar = b.bar;
;         __builtin_amdgcn_s_waitcnt(0);
;         unsigned nloc = b.st[0], nx = b.st[1];
;         if (nloc == 0u) { xcd_barrier_complete(bar, b.x, nloc, nx); b.st[0] = nloc; b.st[1] = nx; }
	v_fma_f32 v187, v169, v169, v187
	v_cvt_pk_bf16_f32 v125, v168, v169
	v_lshlrev_b32_e32 v168, 16, v126
	v_and_b32_e32 v169, 0xffff0000, v126
	v_lshlrev_b32_e32 v170, 16, v158
	v_and_b32_e32 v171, 0xffff0000, v158
	v_mul_f32_e32 v170, s101, v170
	v_mul_f32_e32 v171, s101, v171
	v_fma_f32 v168, v170, v6, v168
	v_fma_f32 v169, v171, v7, v169
	v_fma_f32 v187, v168, v168, v187
	v_fma_f32 v187, v169, v169, v187
	v_cvt_pk_bf16_f32 v126, v168, v169
	v_lshlrev_b32_e32 v168, 16, v127
	v_and_b32_e32 v169, 0xffff0000, v127
	v_lshlrev_b32_e32 v170, 16, v159
	v_and_b32_e32 v171, 0xffff0000, v159
	v_mul_f32_e32 v170, s101, v170
	v_mul_f32_e32 v171, s101, v171
	v_fma_f32 v168, v170, v8, v168
	v_fma_f32 v169, v171, v9, v169
	v_fma_f32 v187, v168, v168, v187
	v_fma_f32 v187, v169, v169, v187
	v_cvt_pk_bf16_f32 v127, v168, v169
	v_lshlrev_b32_e32 v168, 16, v128
	v_and_b32_e32 v169, 0xffff0000, v128
	v_lshlrev_b32_e32 v170, 16, v160
	v_and_b32_e32 v171, 0xffff0000, v160
	v_mul_f32_e32 v170, s101, v170
	v_mul_f32_e32 v171, s101, v171
	v_fma_f32 v168, v170, v10, v168
	v_fma_f32 v169, v171, v11, v169
	v_fma_f32 v187, v168, v168, v187
	v_fma_f32 v187, v169, v169, v187
	v_cvt_pk_bf16_f32 v128, v168, v169
	v_lshlrev_b32_e32 v168, 16, v129
	v_and_b32_e32 v169, 0xffff0000, v129
	v_lshlrev_b32_e32 v170, 16, v161
	v_and_b32_e32 v171, 0xffff0000, v161
	v_mul_f32_e32 v170, s101, v170
	v_mul_f32_e32 v171, s101, v171
	v_fma_f32 v168, v170, v12, v168
	v_fma_f32 v169, v171, v13, v169
	v_fma_f32 v187, v168, v168, v187
	v_fma_f32 v187, v169, v169, v187
	v_cvt_pk_bf16_f32 v129, v168, v169
	v_lshlrev_b32_e32 v168, 16, v130
	v_and_b32_e32 v169, 0xffff0000, v130
	v_lshlrev_b32_e32 v170, 16, v162
	v_and_b32_e32 v171, 0xffff0000, v162
	v_mul_f32_e32 v170, s101, v170
	v_mul_f32_e32 v171, s101, v171
	v_fma_f32 v168, v170, v14, v168
	v_fma_f32 v169, v171, v15, v169
	v_fma_f32 v187, v168, v168, v187
	v_fma_f32 v187, v169, v169, v187
	v_cvt_pk_bf16_f32 v130, v168, v169
	v_lshlrev_b32_e32 v168, 16, v131
	v_and_b32_e32 v169, 0xffff0000, v131
	v_lshlrev_b32_e32 v170, 16, v163
	v_and_b32_e32 v171, 0xffff0000, v163
	v_mul_f32_e32 v170, s101, v170
	v_mul_f32_e32 v171, s101, v171
	v_fma_f32 v168, v170, v16, v168
	v_fma_f32 v169, v171, v17, v169
	v_fma_f32 v187, v168, v168, v187
	v_fma_f32 v187, v169, v169, v187
	v_cvt_pk_bf16_f32 v131, v168, v169
	global_store_dwordx4 v24, v[124:127], s[0:1] offset:2048
	global_store_dwordx4 v24, v[128:131], s[0:1] offset:3072
	s_nop 1
	v_add_f32_dpp v184, v184, v184 quad_perm:[1,0,3,2] row_mask:0xf bank_mask:0xf
	v_add_f32_dpp v185, v185, v185 quad_perm:[1,0,3,2] row_mask:0xf bank_mask:0xf
	v_add_f32_dpp v186, v186, v186 quad_perm:[1,0,3,2] row_mask:0xf bank_mask:0xf
	v_add_f32_dpp v187, v187, v187 quad_perm:[1,0,3,2] row_mask:0xf bank_mask:0xf
	v_add_f32_dpp v184, v184, v184 quad_perm:[2,3,0,1] row_mask:0xf bank_mask:0xf
	v_add_f32_dpp v185, v185, v185 quad_perm:[2,3,0,1] row_mask:0xf bank_mask:0xf
	v_add_f32_dpp v186, v186, v186 quad_perm:[2,3,0,1] row_mask:0xf bank_mask:0xf
	v_add_f32_dpp v187, v187, v187 quad_perm:[2,3,0,1] row_mask:0xf bank_mask:0xf
	v_add_f32_dpp v184, v184, v184 row_half_mirror row_mask:0xf bank_mask:0xf
	v_add_f32_dpp v185, v185, v185 row_half_mirror row_mask:0xf bank_mask:0xf
	v_add_f32_dpp v186, v186, v186 row_half_mirror row_mask:0xf bank_mask:0xf
	v_add_f32_dpp v187, v187, v187 row_half_mirror row_mask:0xf bank_mask:0xf
	v_add_f32_dpp v184, v184, v184 row_mirror row_mask:0xf bank_mask:0xf
	v_add_f32_dpp v185, v185, v185 row_mirror row_mask:0xf bank_mask:0xf
	v_add_f32_dpp v186, v186, v186 row_mirror row_mask:0xf bank_mask:0xf
	v_add_f32_dpp v187, v187, v187 row_mirror row_mask:0xf bank_mask:0xf
	v_add_f32_dpp v184, v184, v184 row_bcast:15 row_mask:0xa bank_mask:0xf
	v_add_f32_dpp v185, v185, v185 row_bcast:15 row_mask:0xa bank_mask:0xf
	v_add_f32_dpp v186, v186, v186 row_bcast:15 row_mask:0xa bank_mask:0xf
	v_add_f32_dpp v187, v187, v187 row_bcast:15 row_mask:0xa bank_mask:0xf
	v_add_f32_dpp v184, v184, v184 row_bcast:31 row_mask:0xc bank_mask:0xf
	v_add_f32_dpp v185, v185, v185 row_bcast:31 row_mask:0xc bank_mask:0xf
	v_add_f32_dpp v186, v186, v186 row_bcast:31 row_mask:0xc bank_mask:0xf
	v_add_f32_dpp v187, v187, v187 row_bcast:31 row_mask:0xc bank_mask:0xf
	s_nop 1
	v_readlane_b32 s3, v184, 63
	v_readlane_b32 s24, v185, 63
	v_readlane_b32 s98, v186, 63
	v_readlane_b32 s101, v187, 63
	s_nop 3
	v_writelane_b32 v188, s3, 0
	v_writelane_b32 v188, s24, 1
	v_writelane_b32 v188, s98, 2
	v_writelane_b32 v188, s101, 3
	s_nop 1
	v_mul_f32_e32 v188, 0x3a800000, v188
	v_add_f32_e32 v188, 0x358637bd, v188
	v_rsq_f32_e32 v188, v188
	s_mov_b64 exec, 15
	global_store_dword v26, v188, s[14:15]
	s_mov_b64 exec, -1
.LBB0_1259:
	s_cmp_gt_i32 s31, 12
	s_cselect_b64 s[0:1], -1, 0
	s_and_b64 s[4:5], s[8:9], s[0:1]
	s_andn2_b64 vcc, exec, s[4:5]
	s_cbranch_vccnz .LBB0_1309
	s_waitcnt vmcnt(0)
	s_barrier
	v_cmp_eq_u32_e32 vcc, 0, v195
	s_and_saveexec_b64 s[4:5], vcc
	s_cbranch_execz .Ltb1309_done
	s_cmp_eq_u32 s99, 1
	s_cbranch_scc1 .Ltb1309_fast
	buffer_wbl2 sc1
	s_waitcnt vmcnt(0)

; __device__ __forceinline__ unsigned xb_ld(unsigned* p)              { return __hip_atomic_load(p, __ATOMIC_RELAXED, __HIP_MEMORY_SCOPE_AGENT); }
; __device__ __forceinline__ unsigned xb_add(unsigned* p, unsigned v) { return __hip_atomic_fetch_add(p, v, __ATOMIC_RELAXED, __HIP_MEMORY_SCOPE_AGENT); }
; #define XB_SPIN(cond, bar) do { unsigned _sp = 0; while (cond) { __builtin_amdgcn_s_sleep(1); \
;     if ((++_sp & 255u) == 0u) { if (xb_ld(&(bar)[XB_TMO])) break; if (_sp > XB_SPIN_CAP) { atomicAdd(&(bar)[XB_TMO], 1u); break; } } } } while (0)
; __device__ __forceinline__ void xcd_barrier(const XcdBarrier& b) {
;     ...
;         const unsigned old = xb_add(&bar[XB_XSUB(b.x)], 1u);
;         const unsigned gen = old / nloc;
;         if (old + 1u == (gen + 1u) * nloc) {
;             __builtin_amdgcn_fence(__ATOMIC_RELEASE, "agent");
;             asm volatile("s_waitcnt vmcnt(0)" ::: "memory");
;             const unsigned og = xb_add(&bar[XB_TOP], 1u);
;             const unsigned tg = og / nx;
;             if (og + 1u == (tg + 1u) * nx) xb_add(&bar[XB_TOPGEN], 1u);
;             else XB_SPIN(xb_ld(&bar[XB_TOPGEN]) == tg, bar);
;             __builtin_amdgcn_fence(__ATOMIC_ACQUIRE, "agent");
;             xb_add(&bar[XB_XGEN(b.x)], 1u);
;             asm volatile("s_waitcnt vmcnt(0)" ::: "memory");
;         } else {
;             XB_SPIN(xb_ld(&bar[XB_XGEN(b.x)]) == gen, bar);
;             __builtin_amdgcn_fence(__ATOMIC_ACQUIRE, "agent");
;             asm volatile("s_waitcnt vmcnt(0)" ::: "memory");
;         }
;     }
;     __syncthreads();
; }
; __global__ void __launch_bounds__(NWAVES * 64, 2) mk_fwd(Args a) {
;     ...
;     if (IN(12)) {
;         { pg8::Gemm g{XN, WPG, M, D, D}; pg8::StaticOrder S; S.init(M, D, G, bid); EpiN<1, false, false, false, true> E{S1, nullptr, nullptr, nullptr, RS, lds}; rs_table_fill(lds, S, RS);
;           pg8::gemm_phase<EpiN<1, false, false, false, true>, pg8::StaticOrder, true, true, NT_NARROW, ZZ, PEELK>(lds, g, S, E); }
.Ltb1309_done:
	s_or_b64 exec, exec, s[4:5]
	s_barrier
.LBB0_1309:
	s_cmp_lt_i32 s30, 13
	s_cselect_b64 s[4:5], -1, 0
	s_and_b64 s[0:1], s[4:5], s[0:1]
	s_andn2_b64 vcc, exec, s[0:1]
	s_cbranch_vccnz .LBB0_1366
	s_mov_b32 s6, -1
	s_ashr_i32 s3, s2, 31
	s_mov_b32 s7, s6
	s_ashr_i32 s48, s33, 31
	s_waitcnt vmcnt(0)
	v_mov_b64_e32 v[0:1], 0x200
	v_mov_b64_e32 v[2:3], 0x1ff
	s_mov_b64 s[10:11], s[2:3]
	s_mov_b32 s14, s6
	s_mov_b64 s[8:9], s[6:7]
	s_branch .LBB0_1313

; __device__ __forceinline__ void xcd_barrier(const XcdBarrier& b) {
;     asm volatile("s_waitcnt vmcnt(0)" ::: "memory");
;     __syncthreads();
;     if (threadIdx.x == 0) {
;         unsigned* bar = b.bar;
;         __builtin_amdgcn_s_waitcnt(0);
;         unsigned nloc = b.st[0], nx = b.st[1];
;         if (nloc == 0u) { xcd_barrier_complete(bar, b.x, nloc, nx); b.st[0] = nloc; b.st[1] = nx; }
.LBB0_1396:
	s_cmp_gt_i32 s31, 14
	s_cselect_b64 s[0:1], -1, 0
	s_and_b64 s[4:5], s[8:9], s[0:1]
	s_andn2_b64 vcc, exec, s[4:5]
	s_cbranch_vccnz .LBB0_1446
	s_waitcnt vmcnt(0)
	s_barrier
	v_cmp_eq_u32_e32 vcc, 0, v195
	s_and_saveexec_b64 s[4:5], vcc
	s_cbranch_execz .Ltb1446_done
	s_cmp_eq_u32 s99, 1
	s_cbranch_scc1 .Ltb1446_fast
	buffer_wbl2 sc1
	s_waitcnt vmcnt(0)

; __device__ __forceinline__ float bf_lo(unsigned w) { return __uint_as_float(w << 16); }
; __device__ __forceinline__ float bf_hi(unsigned w) { return __uint_as_float(w & 0xffff0000u); }
; template <bool SRC_F32, int R> __device__ __forceinline__ void ew_load(EwSet<SRC_F32, R>& S, int rb, const float* hsrc32, const bf16* hsrcb, const bf16* f, const float* part, int lane) {
; #pragma unroll
;     for (int i = 0; i < R; ++i) S.p[i] = (lane < 16) ? part[(size_t)(rb + i) * 16 + lane] : 0.f;
; #pragma unroll
;     for (int i = 0; i < R; ++i)
; #pragma unroll
;         for (int j = 0; j < 4; ++j) {
;             S.fw[i][j] = ((const v2u*)(f + (size_t)(rb + i) * D) + lane)[64 * j];
;             if constexpr (SRC_F32) S.h32[i][j] = __builtin_nontemporal_load((const f32x4*)(hsrc32 + (size_t)(rb + i) * D) + lane + 64 * j);
;             else S.hb[i][j] = ((const v2u*)(hsrcb + (size_t)(rb + i) * D) + lane)[64 * j];
;         }
; }
; template <bool SRC_F32, bool FINAL, int R> __device__ __forceinline__ void ew_compute(const EwSet<SRC_F32, R>& S, int rb, const f32x4 (&g)[4], bf16* hb_out, float* out32, float scale, float* rs_out, int lane) {
; #pragma unroll
;     for (int i = 0; i < R; ++i) {
;         float q = S.p[i];
;         q += __shfl_xor(q, 1); q += __shfl_xor(q, 2); q += __shfl_xor(q, 4); q += __shfl_xor(q, 8);
;         const float ss = __shfl(q, 0);
;         const float rs = scale / sqrtf(ss * (1.f / D) + EPS);
;         float s2 = 0.f;
; #pragma unroll
;         for (int j = 0; j < 4; ++j) {
;             f32x4 h;
;             if constexpr (SRC_F32) h = S.h32[i][j];
;             else { const v2u hw = S.hb[i][j]; h.x = bf_lo(hw.x); h.y = bf_hi(hw.x); h.z = bf_lo(hw.y); h.w = bf_hi(hw.y); }
;             const v2u fw = S.fw[i][j];
;             f32x4 v; v.x = h.x + bf_lo(fw.x) * rs * g[j].x; v.y = h.y + bf_hi(fw.x) * rs * g[j].y; v.z = h.z + bf_lo(fw.y) * rs * g[j].z; v.w = h.w + bf_hi(fw.y) * rs * g[j].w;
; __global__ void __launch_bounds__(NWAVES * 64, 2) mk_fwd(Args a) {
;     ...
;     if (IN(14)) ew_phase<false, true>(nullptr, HB, nullptr, a.out, FB, PART, a.in[I_PLEPOST], 1.0f, nullptr, gw, NGW, lane);
.LBB0_1446:
	s_cmp_lt_i32 s30, 15
	s_cselect_b64 s[4:5], -1, 0
	s_and_b64 s[0:1], s[4:5], s[0:1]
	s_andn2_b64 vcc, exec, s[0:1]
	s_cbranch_vccnz .LBB0_1474
	s_waitcnt vmcnt(0) lgkmcnt(0)
	s_add_u32 s22, s84, 0xffffff10
	s_addc_u32 s23, s85, -1
	s_load_dwordx2 s[26:27], s[22:23], 0xd0
	s_load_dwordx2 s[14:15], s[22:23], 0xd8
	s_add_u32 s0, s28, 0x5000000
	s_addc_u32 s1, s29, 0
	s_add_u32 s4, s28, 0x15000000
	s_addc_u32 s5, s29, 0
	s_add_u32 s6, s28, 0x3700000
	s_addc_u32 s7, s29, 0
	v_and_b32_e32 v0, 63, v195
	v_lshlrev_b32_e32 v1, 5, v0
	s_waitcnt lgkmcnt(0)
	global_load_dwordx4 v[2:5], v1, s[26:27]
	global_load_dwordx4 v[6:9], v1, s[26:27] offset:16
	global_load_dwordx4 v[10:13], v1, s[26:27] offset:2048
	global_load_dwordx4 v[14:17], v1, s[26:27] offset:2064
	s_and_b32 s26, s2, 7
	s_lshl_b32 s26, s26, 4
	s_bfe_u32 s27, s2, 0x30003
	s_add_u32 s26, s26, s27
	s_lshl_b32 s26, s26, 8
	s_lshr_b32 s27, s2, 6
	s_lshl_b32 s27, s27, 6
	s_add_u32 s26, s26, s27
	v_readfirstlane_b32 s27, v195
	s_lshr_b32 s27, s27, 6
	s_lshl_b32 s27, s27, 3
	s_add_u32 s26, s26, s27
	s_add_u32 s27, s26, 0
	s_lshl_b32 s22, s27, 11
	v_lshl_add_u32 v18, v0, 4, s22
	v_add_u32_e32 v19, 0x1000, v18
	s_lshl_b32 s22, s27, 6
	v_lshl_add_u32 v20, v0, 2, s22
	s_lshl_b32 s22, s27, 12
	v_lshl_add_u32 v22, v0, 5, s22
	global_load_dwordx4 v[32:35], v18, s[0:1]
	global_load_dwordx4 v[36:39], v18, s[0:1] offset:1024
	global_load_dwordx4 v[64:67], v18, s[4:5]
	global_load_dwordx4 v[68:71], v18, s[4:5] offset:1024
	global_load_dwordx4 v[40:43], v18, s[0:1] offset:2048
	global_load_dwordx4 v[44:47], v18, s[0:1] offset:3072
	global_load_dwordx4 v[72:75], v18, s[4:5] offset:2048
	global_load_dwordx4 v[76:79], v18, s[4:5] offset:3072
	global_load_dwordx4 v[48:51], v19, s[0:1]
	global_load_dwordx4 v[52:55], v19, s[0:1] offset:1024
	global_load_dwordx4 v[80:83], v19, s[4:5]
	global_load_dwordx4 v[84:87], v19, s[4:5] offset:1024
	global_load_dwordx4 v[56:59], v19, s[0:1] offset:2048
	global_load_dwordx4 v[60:63], v19, s[0:1] offset:3072
	global_load_dwordx4 v[88:91], v19, s[4:5] offset:2048
	global_load_dwordx4 v[92:95], v19, s[4:5] offset:3072
	global_load_dword v96, v20, s[6:7]
	s_add_u32 s27, s26, 4
	s_lshl_b32 s22, s27, 11
	v_lshl_add_u32 v23, v0, 4, s22
	v_add_u32_e32 v24, 0x1000, v23
	s_lshl_b32 s22, s27, 6
	v_lshl_add_u32 v25, v0, 2, s22
	s_lshl_b32 s22, s27, 12
	v_lshl_add_u32 v27, v0, 5, s22
	global_load_dwordx4 v[100:103], v23, s[0:1]
	global_load_dwordx4 v[104:107], v23, s[0:1] offset:1024
	global_load_dwordx4 v[132:135], v23, s[4:5]
	global_load_dwordx4 v[136:139], v23, s[4:5] offset:1024
	global_load_dwordx4 v[108:111], v23, s[0:1] offset:2048
	global_load_dwordx4 v[112:115], v23, s[0:1] offset:3072
	global_load_dwordx4 v[140:143], v23, s[4:5] offset:2048
	global_load_dwordx4 v[144:147], v23, s[4:5] offset:3072
	global_load_dwordx4 v[116:119], v24, s[0:1]
	global_load_dwordx4 v[120:123], v24, s[0:1] offset:1024
	global_load_dwordx4 v[148:151], v24, s[4:5]
	global_load_dwordx4 v[152:155], v24, s[4:5] offset:1024
	global_load_dwordx4 v[124:127], v24, s[0:1] offset:2048
	global_load_dwordx4 v[128:131], v24, s[0:1] offset:3072
	global_load_dwordx4 v[156:159], v24, s[4:5] offset:2048
	global_load_dwordx4 v[160:163], v24, s[4:5] offset:3072
	global_load_dword v164, v25, s[6:7]
	s_waitcnt vmcnt(17)
	v_add_f32_dpp v96, v96, v96 quad_perm:[1,0,3,2] row_mask:0xf bank_mask:0xf
	s_nop 1
	v_add_f32_dpp v96, v96, v96 quad_perm:[2,3,0,1] row_mask:0xf bank_mask:0xf
	s_nop 1
	v_add_f32_dpp v96, v96, v96 row_half_mirror row_mask:0xf bank_mask:0xf
	s_nop 1
	v_add_f32_dpp v96, v96, v96 row_mirror row_mask:0xf bank_mask:0xf
	s_nop 1
	v_mul_f32_e32 v96, 0x3a800000, v96
	v_add_f32_e32 v96, 0x358637bd, v96
	v_rsq_f32_e32 v96, v96
	s_nop 0
	v_readlane_b32 s3, v96, 0
	v_readlane_b32 s24, v96, 16
	v_readlane_b32 s98, v96, 32
	v_readlane_b32 s101, v96, 48
	s_nop 1
	v_lshlrev_b32_e32 v168, 16, v32
	v_and_b32_e32 v169, 0xffff0000, v32
	v_lshlrev_b32_e32 v184, 16, v64
	v_and_b32_e32 v185, 0xffff0000, v64
	v_mul_f32_e32 v184, s3, v184
	v_mul_f32_e32 v185, s3, v185
	v_fma_f32 v168, v184, v2, v168
	v_fma_f32 v169, v185, v3, v169
	v_lshlrev_b32_e32 v170, 16, v33
	v_and_b32_e32 v171, 0xffff0000, v33
	v_lshlrev_b32_e32 v184, 16, v65
	v_and_b32_e32 v185, 0xffff0000, v65
	v_mul_f32_e32 v184, s3, v184
	v_mul_f32_e32 v185, s3, v185
	v_fma_f32 v170, v184, v4, v170
	v_fma_f32 v171, v185, v5, v171
	v_lshlrev_b32_e32 v172, 16, v34
	v_and_b32_e32 v173, 0xffff0000, v34
	v_lshlrev_b32_e32 v184, 16, v66
	v_and_b32_e32 v185, 0xffff0000, v66
	v_mul_f32_e32 v184, s3, v184
	v_mul_f32_e32 v185, s3, v185
	v_fma_f32 v172, v184, v6, v172
	v_fma_f32 v173, v185, v7, v173
	v_lshlrev_b32_e32 v174, 16, v35
	v_and_b32_e32 v175, 0xffff0000, v35
	v_lshlrev_b32_e32 v184, 16, v67
	v_and_b32_e32 v185, 0xffff0000, v67
	v_mul_f32_e32 v184, s3, v184
	v_mul_f32_e32 v185, s3, v185
	v_fma_f32 v174, v184, v8, v174
	v_fma_f32 v175, v185, v9, v175
	v_lshlrev_b32_e32 v176, 16, v36
	v_and_b32_e32 v177, 0xffff0000, v36
	v_lshlrev_b32_e32 v184, 16, v68
	v_and_b32_e32 v185, 0xffff0000, v68
	v_mul_f32_e32 v184, s3, v184
	v_mul_f32_e32 v185, s3, v185
	v_fma_f32 v176, v184, v10, v176
	v_fma_f32 v177, v185, v11, v177
	v_lshlrev_b32_e32 v178, 16, v37
	v_and_b32_e32 v179, 0xffff0000, v37
	v_lshlrev_b32_e32 v184, 16, v69
	v_and_b32_e32 v185, 0xffff0000, v69
	v_mul_f32_e32 v184, s3, v184
	v_mul_f32_e32 v185, s3, v185
	v_fma_f32 v178, v184, v12, v178
	v_fma_f32 v179, v185, v13, v179
	v_lshlrev_b32_e32 v180, 16, v38
	v_and_b32_e32 v181, 0xffff0000, v38
	v_lshlrev_b32_e32 v184, 16, v70
	v_and_b32_e32 v185, 0xffff0000, v70
	v_mul_f32_e32 v184, s3, v184
	v_mul_f32_e32 v185, s3, v185
; __device__ __forceinline__ float bf_lo(unsigned w) { return __uint_as_float(w << 16); }
; __device__ __forceinline__ float bf_hi(unsigned w) { return __uint_as_float(w & 0xffff0000u); }
; __device__ __forceinline__ unsigned pk2(float lo, float hi) { bf16x2_t r = __builtin_convertvector((f32x2_t){lo, hi}, bf16x2_t); return __builtin_bit_cast(unsigned, r); }
; template <bool SRC_F32, bool FINAL, int R> __device__ __forceinline__ void ew_compute(const EwSet<SRC_F32, R>& S, int rb, const f32x4 (&g)[4], bf16* hb_out, float* out32, float scale, float* rs_out, int lane) {
;     ...
; #pragma unroll
;         for (int j = 0; j < 4; ++j) {
;             f32x4 h;
;             if constexpr (SRC_F32) h = S.h32[i][j];
;             else { const v2u hw = S.hb[i][j]; h.x = bf_lo(hw.x); h.y = bf_hi(hw.x); h.z = bf_lo(hw.y); h.w = bf_hi(hw.y); }
;             const v2u fw = S.fw[i][j];
;             f32x4 v; v.x = h.x + bf_lo(fw.x) * rs * g[j].x; v.y = h.y + bf_hi(fw.x) * rs * g[j].y; v.z = h.z + bf_lo(fw.y) * rs * g[j].z; v.w = h.w + bf_hi(fw.y) * rs * g[j].w;
;             if (FINAL) __builtin_nontemporal_store(v, (f32x4*)(out32 + (size_t)(rb + i) * D) + lane + 64 * j);
;             else { v2u o; o.x = pk2(v.x, v.y); o.y = pk2(v.z, v.w); ((v2u*)(hb_out + (size_t)(rb + i) * D) + lane)[64 * j] = o; s2 += (v.x * v.x + v.y * v.y) + (v.z * v.z + v.w * v.w); }
	v_fma_f32 v180, v184, v14, v180
	v_fma_f32 v181, v185, v15, v181
	v_lshlrev_b32_e32 v182, 16, v39
	v_and_b32_e32 v183, 0xffff0000, v39
	v_lshlrev_b32_e32 v184, 16, v71
	v_and_b32_e32 v185, 0xffff0000, v71
	v_mul_f32_e32 v184, s3, v184
	v_mul_f32_e32 v185, s3, v185
	v_fma_f32 v182, v184, v16, v182
	v_fma_f32 v183, v185, v17, v183
	global_store_dwordx4 v22, v[168:171], s[14:15] nt
	global_store_dwordx4 v22, v[172:175], s[14:15] offset:16 nt
	global_store_dwordx4 v22, v[176:179], s[14:15] offset:2048 nt
	global_store_dwordx4 v22, v[180:183], s[14:15] offset:2064 nt
	s_nop 1
	v_lshlrev_b32_e32 v168, 16, v40
	v_and_b32_e32 v169, 0xffff0000, v40
	v_lshlrev_b32_e32 v184, 16, v72
	v_and_b32_e32 v185, 0xffff0000, v72
	v_mul_f32_e32 v184, s24, v184
	v_mul_f32_e32 v185, s24, v185
	v_fma_f32 v168, v184, v2, v168
	v_fma_f32 v169, v185, v3, v169
	v_lshlrev_b32_e32 v170, 16, v41
	v_and_b32_e32 v171, 0xffff0000, v41
	v_lshlrev_b32_e32 v184, 16, v73
	v_and_b32_e32 v185, 0xffff0000, v73
	v_mul_f32_e32 v184, s24, v184
	v_mul_f32_e32 v185, s24, v185
	v_fma_f32 v170, v184, v4, v170
	v_fma_f32 v171, v185, v5, v171
	v_lshlrev_b32_e32 v172, 16, v42
	v_and_b32_e32 v173, 0xffff0000, v42
	v_lshlrev_b32_e32 v184, 16, v74
	v_and_b32_e32 v185, 0xffff0000, v74
	v_mul_f32_e32 v184, s24, v184
	v_mul_f32_e32 v185, s24, v185
	v_fma_f32 v172, v184, v6, v172
	v_fma_f32 v173, v185, v7, v173
	v_lshlrev_b32_e32 v174, 16, v43
	v_and_b32_e32 v175, 0xffff0000, v43
	v_lshlrev_b32_e32 v184, 16, v75
	v_and_b32_e32 v185, 0xffff0000, v75
	v_mul_f32_e32 v184, s24, v184
	v_mul_f32_e32 v185, s24, v185
	v_fma_f32 v174, v184, v8, v174
	v_fma_f32 v175, v185, v9, v175
	v_lshlrev_b32_e32 v176, 16, v44
	v_and_b32_e32 v177, 0xffff0000, v44
	v_lshlrev_b32_e32 v184, 16, v76
	v_and_b32_e32 v185, 0xffff0000, v76
	v_mul_f32_e32 v184, s24, v184
	v_mul_f32_e32 v185, s24, v185
	v_fma_f32 v176, v184, v10, v176
	v_fma_f32 v177, v185, v11, v177
	v_lshlrev_b32_e32 v178, 16, v45
	v_and_b32_e32 v179, 0xffff0000, v45
	v_lshlrev_b32_e32 v184, 16, v77
	v_and_b32_e32 v185, 0xffff0000, v77
	v_mul_f32_e32 v184, s24, v184
	v_mul_f32_e32 v185, s24, v185
	v_fma_f32 v178, v184, v12, v178
	v_fma_f32 v179, v185, v13, v179
	v_lshlrev_b32_e32 v180, 16, v46
	v_and_b32_e32 v181, 0xffff0000, v46
	v_lshlrev_b32_e32 v184, 16, v78
	v_and_b32_e32 v185, 0xffff0000, v78
	v_mul_f32_e32 v184, s24, v184
	v_mul_f32_e32 v185, s24, v185
	v_fma_f32 v180, v184, v14, v180
	v_fma_f32 v181, v185, v15, v181
	v_lshlrev_b32_e32 v182, 16, v47
	v_and_b32_e32 v183, 0xffff0000, v47
	v_lshlrev_b32_e32 v184, 16, v79
	v_and_b32_e32 v185, 0xffff0000, v79
	v_mul_f32_e32 v184, s24, v184
	v_mul_f32_e32 v185, s24, v185
	v_fma_f32 v182, v184, v16, v182
	v_fma_f32 v183, v185, v17, v183
	v_add_u32_e32 v1, 0x1000, v22
	global_store_dwordx4 v1, v[168:171], s[14:15] nt
	global_store_dwordx4 v1, v[172:175], s[14:15] offset:16 nt
	global_store_dwordx4 v1, v[176:179], s[14:15] offset:2048 nt
	global_store_dwordx4 v1, v[180:183], s[14:15] offset:2064 nt
	s_nop 1
	v_lshlrev_b32_e32 v168, 16, v48
	v_and_b32_e32 v169, 0xffff0000, v48
	v_lshlrev_b32_e32 v184, 16, v80
	v_and_b32_e32 v185, 0xffff0000, v80
	v_mul_f32_e32 v184, s98, v184
	v_mul_f32_e32 v185, s98, v185
	v_fma_f32 v168, v184, v2, v168
	v_fma_f32 v169, v185, v3, v169
	v_lshlrev_b32_e32 v170, 16, v49
	v_and_b32_e32 v171, 0xffff0000, v49
	v_lshlrev_b32_e32 v184, 16, v81
	v_and_b32_e32 v185, 0xffff0000, v81
	v_mul_f32_e32 v184, s98, v184
	v_mul_f32_e32 v185, s98, v185
	v_fma_f32 v170, v184, v4, v170
	v_fma_f32 v171, v185, v5, v171
	v_lshlrev_b32_e32 v172, 16, v50
	v_and_b32_e32 v173, 0xffff0000, v50
	v_lshlrev_b32_e32 v184, 16, v82
	v_and_b32_e32 v185, 0xffff0000, v82
	v_mul_f32_e32 v184, s98, v184
	v_mul_f32_e32 v185, s98, v185
	v_fma_f32 v172, v184, v6, v172
	v_fma_f32 v173, v185, v7, v173
	v_lshlrev_b32_e32 v174, 16, v51
	v_and_b32_e32 v175, 0xffff0000, v51
	v_lshlrev_b32_e32 v184, 16, v83
	v_and_b32_e32 v185, 0xffff0000, v83
	v_mul_f32_e32 v184, s98, v184
	v_mul_f32_e32 v185, s98, v185
	v_fma_f32 v174, v184, v8, v174
	v_fma_f32 v175, v185, v9, v175
	v_lshlrev_b32_e32 v176, 16, v52
	v_and_b32_e32 v177, 0xffff0000, v52
	v_lshlrev_b32_e32 v184, 16, v84
	v_and_b32_e32 v185, 0xffff0000, v84
	v_mul_f32_e32 v184, s98, v184
	v_mul_f32_e32 v185, s98, v185
	v_fma_f32 v176, v184, v10, v176
	v_fma_f32 v177, v185, v11, v177
	v_lshlrev_b32_e32 v178, 16, v53
	v_and_b32_e32 v179, 0xffff0000, v53
	v_lshlrev_b32_e32 v184, 16, v85
	v_and_b32_e32 v185, 0xffff0000, v85
	v_mul_f32_e32 v184, s98, v184
	v_mul_f32_e32 v185, s98, v185
	v_fma_f32 v178, v184, v12, v178
	v_fma_f32 v179, v185, v13, v179
	v_lshlrev_b32_e32 v180, 16, v54
	v_and_b32_e32 v181, 0xffff0000, v54
	v_lshlrev_b32_e32 v184, 16, v86
	v_and_b32_e32 v185, 0xffff0000, v86
	v_mul_f32_e32 v184, s98, v184
	v_mul_f32_e32 v185, s98, v185
	v_fma_f32 v180, v184, v14, v180
	v_fma_f32 v181, v185, v15, v181
	v_lshlrev_b32_e32 v182, 16, v55
	v_and_b32_e32 v183, 0xffff0000, v55
	v_lshlrev_b32_e32 v184, 16, v87
	v_and_b32_e32 v185, 0xffff0000, v87
	v_mul_f32_e32 v184, s98, v184
	v_mul_f32_e32 v185, s98, v185
	v_fma_f32 v182, v184, v16, v182
	v_fma_f32 v183, v185, v17, v183
	v_add_u32_e32 v1, 0x2000, v22
	global_store_dwordx4 v1, v[168:171], s[14:15] nt
	global_store_dwordx4 v1, v[172:175], s[14:15] offset:16 nt
	global_store_dwordx4 v1, v[176:179], s[14:15] offset:2048 nt
	global_store_dwordx4 v1, v[180:183], s[14:15] offset:2064 nt
	s_nop 1
	v_lshlrev_b32_e32 v168, 16, v56
	v_and_b32_e32 v169, 0xffff0000, v56
	v_lshlrev_b32_e32 v184, 16, v88
	v_and_b32_e32 v185, 0xffff0000, v88
	v_mul_f32_e32 v184, s101, v184
	v_mul_f32_e32 v185, s101, v185
	v_fma_f32 v168, v184, v2, v168
; __device__ __forceinline__ float bf_lo(unsigned w) { return __uint_as_float(w << 16); }
; __device__ __forceinline__ float bf_hi(unsigned w) { return __uint_as_float(w & 0xffff0000u); }
; __device__ __forceinline__ unsigned pk2(float lo, float hi) { bf16x2_t r = __builtin_convertvector((f32x2_t){lo, hi}, bf16x2_t); return __builtin_bit_cast(unsigned, r); }
; template <bool SRC_F32, int R> __device__ __forceinline__ void ew_load(EwSet<SRC_F32, R>& S, int rb, const float* hsrc32, const bf16* hsrcb, const bf16* f, const float* part, int lane) {
; #pragma unroll
;     for (int i = 0; i < R; ++i) S.p[i] = (lane < 16) ? part[(size_t)(rb + i) * 16 + lane] : 0.f;
; #pragma unroll
;     for (int i = 0; i < R; ++i)
; #pragma unroll
;         for (int j = 0; j < 4; ++j) {
;             S.fw[i][j] = ((const v2u*)(f + (size_t)(rb + i) * D) + lane)[64 * j];
;             if constexpr (SRC_F32) S.h32[i][j] = __builtin_nontemporal_load((const f32x4*)(hsrc32 + (size_t)(rb + i) * D) + lane + 64 * j);
;             else S.hb[i][j] = ((const v2u*)(hsrcb + (size_t)(rb + i) * D) + lane)[64 * j];
;         }
; }
; template <bool SRC_F32, bool FINAL, int R> __device__ __forceinline__ void ew_compute(const EwSet<SRC_F32, R>& S, int rb, const f32x4 (&g)[4], bf16* hb_out, float* out32, float scale, float* rs_out, int lane) {
;     ...
; #pragma unroll
;         for (int j = 0; j < 4; ++j) {
;             f32x4 h;
;             if constexpr (SRC_F32) h = S.h32[i][j];
;             else { const v2u hw = S.hb[i][j]; h.x = bf_lo(hw.x); h.y = bf_hi(hw.x); h.z = bf_lo(hw.y); h.w = bf_hi(hw.y); }
;             const v2u fw = S.fw[i][j];
;             f32x4 v; v.x = h.x + bf_lo(fw.x) * rs * g[j].x; v.y = h.y + bf_hi(fw.x) * rs * g[j].y; v.z = h.z + bf_lo(fw.y) * rs * g[j].z; v.w = h.w + bf_hi(fw.y) * rs * g[j].w;
;             if (FINAL) __builtin_nontemporal_store(v, (f32x4*)(out32 + (size_t)(rb + i) * D) + lane + 64 * j);
;             else { v2u o; o.x = pk2(v.x, v.y); o.y = pk2(v.z, v.w); ((v2u*)(hb_out + (size_t)(rb + i) * D) + lane)[64 * j] = o; s2 += (v.x * v.x + v.y * v.y) + (v.z * v.z + v.w * v.w); }
	v_fma_f32 v169, v185, v3, v169
	v_lshlrev_b32_e32 v170, 16, v57
	v_and_b32_e32 v171, 0xffff0000, v57
	v_lshlrev_b32_e32 v184, 16, v89
	v_and_b32_e32 v185, 0xffff0000, v89
	v_mul_f32_e32 v184, s101, v184
	v_mul_f32_e32 v185, s101, v185
	v_fma_f32 v170, v184, v4, v170
	v_fma_f32 v171, v185, v5, v171
	v_lshlrev_b32_e32 v172, 16, v58
	v_and_b32_e32 v173, 0xffff0000, v58
	v_lshlrev_b32_e32 v184, 16, v90
	v_and_b32_e32 v185, 0xffff0000, v90
	v_mul_f32_e32 v184, s101, v184
	v_mul_f32_e32 v185, s101, v185
	v_fma_f32 v172, v184, v6, v172
	v_fma_f32 v173, v185, v7, v173
	v_lshlrev_b32_e32 v174, 16, v59
	v_and_b32_e32 v175, 0xffff0000, v59
	v_lshlrev_b32_e32 v184, 16, v91
	v_and_b32_e32 v185, 0xffff0000, v91
	v_mul_f32_e32 v184, s101, v184
	v_mul_f32_e32 v185, s101, v185
	v_fma_f32 v174, v184, v8, v174
	v_fma_f32 v175, v185, v9, v175
	v_lshlrev_b32_e32 v176, 16, v60
	v_and_b32_e32 v177, 0xffff0000, v60
	v_lshlrev_b32_e32 v184, 16, v92
	v_and_b32_e32 v185, 0xffff0000, v92
	v_mul_f32_e32 v184, s101, v184
	v_mul_f32_e32 v185, s101, v185
	v_fma_f32 v176, v184, v10, v176
	v_fma_f32 v177, v185, v11, v177
	v_lshlrev_b32_e32 v178, 16, v61
	v_and_b32_e32 v179, 0xffff0000, v61
	v_lshlrev_b32_e32 v184, 16, v93
	v_and_b32_e32 v185, 0xffff0000, v93
	v_mul_f32_e32 v184, s101, v184
	v_mul_f32_e32 v185, s101, v185
	v_fma_f32 v178, v184, v12, v178
	v_fma_f32 v179, v185, v13, v179
	v_lshlrev_b32_e32 v180, 16, v62
	v_and_b32_e32 v181, 0xffff0000, v62
	v_lshlrev_b32_e32 v184, 16, v94
	v_and_b32_e32 v185, 0xffff0000, v94
	v_mul_f32_e32 v184, s101, v184
	v_mul_f32_e32 v185, s101, v185
	v_fma_f32 v180, v184, v14, v180
	v_fma_f32 v181, v185, v15, v181
	v_lshlrev_b32_e32 v182, 16, v63
	v_and_b32_e32 v183, 0xffff0000, v63
	v_lshlrev_b32_e32 v184, 16, v95
	v_and_b32_e32 v185, 0xffff0000, v95
	v_mul_f32_e32 v184, s101, v184
	v_mul_f32_e32 v185, s101, v185
	v_fma_f32 v182, v184, v16, v182
	v_fma_f32 v183, v185, v17, v183
	v_add_u32_e32 v1, 0x3000, v22
	global_store_dwordx4 v1, v[168:171], s[14:15] nt
	global_store_dwordx4 v1, v[172:175], s[14:15] offset:16 nt
	global_store_dwordx4 v1, v[176:179], s[14:15] offset:2048 nt
	global_store_dwordx4 v1, v[180:183], s[14:15] offset:2064 nt
	s_nop 1
	s_add_u32 s27, s26, 2048
	s_lshl_b32 s22, s27, 11
	v_lshl_add_u32 v18, v0, 4, s22
	v_add_u32_e32 v19, 0x1000, v18
	s_lshl_b32 s22, s27, 6
	v_lshl_add_u32 v20, v0, 2, s22
	s_lshl_b32 s22, s27, 12
	v_lshl_add_u32 v22, v0, 5, s22
	global_load_dwordx4 v[32:35], v18, s[0:1]
	global_load_dwordx4 v[36:39], v18, s[0:1] offset:1024
	global_load_dwordx4 v[64:67], v18, s[4:5]
	global_load_dwordx4 v[68:71], v18, s[4:5] offset:1024
	global_load_dwordx4 v[40:43], v18, s[0:1] offset:2048
	global_load_dwordx4 v[44:47], v18, s[0:1] offset:3072
	global_load_dwordx4 v[72:75], v18, s[4:5] offset:2048
	global_load_dwordx4 v[76:79], v18, s[4:5] offset:3072
	global_load_dwordx4 v[48:51], v19, s[0:1]
	global_load_dwordx4 v[52:55], v19, s[0:1] offset:1024
	global_load_dwordx4 v[80:83], v19, s[4:5]
	global_load_dwordx4 v[84:87], v19, s[4:5] offset:1024
	global_load_dwordx4 v[56:59], v19, s[0:1] offset:2048
	global_load_dwordx4 v[60:63], v19, s[0:1] offset:3072
	global_load_dwordx4 v[88:91], v19, s[4:5] offset:2048
	global_load_dwordx4 v[92:95], v19, s[4:5] offset:3072
	global_load_dword v96, v20, s[6:7]
	s_waitcnt vmcnt(33)
	v_add_f32_dpp v164, v164, v164 quad_perm:[1,0,3,2] row_mask:0xf bank_mask:0xf
	s_nop 1
	v_add_f32_dpp v164, v164, v164 quad_perm:[2,3,0,1] row_mask:0xf bank_mask:0xf
	s_nop 1
	v_add_f32_dpp v164, v164, v164 row_half_mirror row_mask:0xf bank_mask:0xf
	s_nop 1
	v_add_f32_dpp v164, v164, v164 row_mirror row_mask:0xf bank_mask:0xf
	s_nop 1
	v_mul_f32_e32 v164, 0x3a800000, v164
	v_add_f32_e32 v164, 0x358637bd, v164
	v_rsq_f32_e32 v164, v164
	s_nop 0
	v_readlane_b32 s3, v164, 0
	v_readlane_b32 s24, v164, 16
	v_readlane_b32 s98, v164, 32
	v_readlane_b32 s101, v164, 48
	s_nop 1
	v_lshlrev_b32_e32 v168, 16, v100
	v_and_b32_e32 v169, 0xffff0000, v100
	v_lshlrev_b32_e32 v184, 16, v132
	v_and_b32_e32 v185, 0xffff0000, v132
	v_mul_f32_e32 v184, s3, v184
	v_mul_f32_e32 v185, s3, v185
	v_fma_f32 v168, v184, v2, v168
	v_fma_f32 v169, v185, v3, v169
	v_lshlrev_b32_e32 v170, 16, v101
	v_and_b32_e32 v171, 0xffff0000, v101
	v_lshlrev_b32_e32 v184, 16, v133
	v_and_b32_e32 v185, 0xffff0000, v133
	v_mul_f32_e32 v184, s3, v184
	v_mul_f32_e32 v185, s3, v185
	v_fma_f32 v170, v184, v4, v170
	v_fma_f32 v171, v185, v5, v171
	v_lshlrev_b32_e32 v172, 16, v102
	v_and_b32_e32 v173, 0xffff0000, v102
	v_lshlrev_b32_e32 v184, 16, v134
	v_and_b32_e32 v185, 0xffff0000, v134
	v_mul_f32_e32 v184, s3, v184
	v_mul_f32_e32 v185, s3, v185
	v_fma_f32 v172, v184, v6, v172
	v_fma_f32 v173, v185, v7, v173
	v_lshlrev_b32_e32 v174, 16, v103
	v_and_b32_e32 v175, 0xffff0000, v103
	v_lshlrev_b32_e32 v184, 16, v135
	v_and_b32_e32 v185, 0xffff0000, v135
	v_mul_f32_e32 v184, s3, v184
	v_mul_f32_e32 v185, s3, v185
	v_fma_f32 v174, v184, v8, v174
	v_fma_f32 v175, v185, v9, v175
	v_lshlrev_b32_e32 v176, 16, v104
	v_and_b32_e32 v177, 0xffff0000, v104
	v_lshlrev_b32_e32 v184, 16, v136
	v_and_b32_e32 v185, 0xffff0000, v136
	v_mul_f32_e32 v184, s3, v184
	v_mul_f32_e32 v185, s3, v185
	v_fma_f32 v176, v184, v10, v176
	v_fma_f32 v177, v185, v11, v177
	v_lshlrev_b32_e32 v178, 16, v105
	v_and_b32_e32 v179, 0xffff0000, v105
	v_lshlrev_b32_e32 v184, 16, v137
	v_and_b32_e32 v185, 0xffff0000, v137
	v_mul_f32_e32 v184, s3, v184
	v_mul_f32_e32 v185, s3, v185
	v_fma_f32 v178, v184, v12, v178
	v_fma_f32 v179, v185, v13, v179
	v_lshlrev_b32_e32 v180, 16, v106
	v_and_b32_e32 v181, 0xffff0000, v106
	v_lshlrev_b32_e32 v184, 16, v138
	v_and_b32_e32 v185, 0xffff0000, v138
; __device__ __forceinline__ float bf_lo(unsigned w) { return __uint_as_float(w << 16); }
; __device__ __forceinline__ float bf_hi(unsigned w) { return __uint_as_float(w & 0xffff0000u); }
; __device__ __forceinline__ unsigned pk2(float lo, float hi) { bf16x2_t r = __builtin_convertvector((f32x2_t){lo, hi}, bf16x2_t); return __builtin_bit_cast(unsigned, r); }
; template <bool SRC_F32, bool FINAL, int R> __device__ __forceinline__ void ew_compute(const EwSet<SRC_F32, R>& S, int rb, const f32x4 (&g)[4], bf16* hb_out, float* out32, float scale, float* rs_out, int lane) {
;     ...
; #pragma unroll
;         for (int j = 0; j < 4; ++j) {
;             f32x4 h;
;             if constexpr (SRC_F32) h = S.h32[i][j];
;             else { const v2u hw = S.hb[i][j]; h.x = bf_lo(hw.x); h.y = bf_hi(hw.x); h.z = bf_lo(hw.y); h.w = bf_hi(hw.y); }
;             const v2u fw = S.fw[i][j];
;             f32x4 v; v.x = h.x + bf_lo(fw.x) * rs * g[j].x; v.y = h.y + bf_hi(fw.x) * rs * g[j].y; v.z = h.z + bf_lo(fw.y) * rs * g[j].z; v.w = h.w + bf_hi(fw.y) * rs * g[j].w;
;             if (FINAL) __builtin_nontemporal_store(v, (f32x4*)(out32 + (size_t)(rb + i) * D) + lane + 64 * j);
;             else { v2u o; o.x = pk2(v.x, v.y); o.y = pk2(v.z, v.w); ((v2u*)(hb_out + (size_t)(rb + i) * D) + lane)[64 * j] = o; s2 += (v.x * v.x + v.y * v.y) + (v.z * v.z + v.w * v.w); }
	v_mul_f32_e32 v184, s3, v184
	v_mul_f32_e32 v185, s3, v185
	v_fma_f32 v180, v184, v14, v180
	v_fma_f32 v181, v185, v15, v181
	v_lshlrev_b32_e32 v182, 16, v107
	v_and_b32_e32 v183, 0xffff0000, v107
	v_lshlrev_b32_e32 v184, 16, v139
	v_and_b32_e32 v185, 0xffff0000, v139
	v_mul_f32_e32 v184, s3, v184
	v_mul_f32_e32 v185, s3, v185
	v_fma_f32 v182, v184, v16, v182
	v_fma_f32 v183, v185, v17, v183
	global_store_dwordx4 v27, v[168:171], s[14:15] nt
	global_store_dwordx4 v27, v[172:175], s[14:15] offset:16 nt
	global_store_dwordx4 v27, v[176:179], s[14:15] offset:2048 nt
	global_store_dwordx4 v27, v[180:183], s[14:15] offset:2064 nt
	s_nop 1
	v_lshlrev_b32_e32 v168, 16, v108
	v_and_b32_e32 v169, 0xffff0000, v108
	v_lshlrev_b32_e32 v184, 16, v140
	v_and_b32_e32 v185, 0xffff0000, v140
	v_mul_f32_e32 v184, s24, v184
	v_mul_f32_e32 v185, s24, v185
	v_fma_f32 v168, v184, v2, v168
	v_fma_f32 v169, v185, v3, v169
	v_lshlrev_b32_e32 v170, 16, v109
	v_and_b32_e32 v171, 0xffff0000, v109
	v_lshlrev_b32_e32 v184, 16, v141
	v_and_b32_e32 v185, 0xffff0000, v141
	v_mul_f32_e32 v184, s24, v184
	v_mul_f32_e32 v185, s24, v185
	v_fma_f32 v170, v184, v4, v170
	v_fma_f32 v171, v185, v5, v171
	v_lshlrev_b32_e32 v172, 16, v110
	v_and_b32_e32 v173, 0xffff0000, v110
	v_lshlrev_b32_e32 v184, 16, v142
	v_and_b32_e32 v185, 0xffff0000, v142
	v_mul_f32_e32 v184, s24, v184
	v_mul_f32_e32 v185, s24, v185
	v_fma_f32 v172, v184, v6, v172
	v_fma_f32 v173, v185, v7, v173
	v_lshlrev_b32_e32 v174, 16, v111
	v_and_b32_e32 v175, 0xffff0000, v111
	v_lshlrev_b32_e32 v184, 16, v143
	v_and_b32_e32 v185, 0xffff0000, v143
	v_mul_f32_e32 v184, s24, v184
	v_mul_f32_e32 v185, s24, v185
	v_fma_f32 v174, v184, v8, v174
	v_fma_f32 v175, v185, v9, v175
	v_lshlrev_b32_e32 v176, 16, v112
	v_and_b32_e32 v177, 0xffff0000, v112
	v_lshlrev_b32_e32 v184, 16, v144
	v_and_b32_e32 v185, 0xffff0000, v144
	v_mul_f32_e32 v184, s24, v184
	v_mul_f32_e32 v185, s24, v185
	v_fma_f32 v176, v184, v10, v176
	v_fma_f32 v177, v185, v11, v177
	v_lshlrev_b32_e32 v178, 16, v113
	v_and_b32_e32 v179, 0xffff0000, v113
	v_lshlrev_b32_e32 v184, 16, v145
	v_and_b32_e32 v185, 0xffff0000, v145
	v_mul_f32_e32 v184, s24, v184
	v_mul_f32_e32 v185, s24, v185
	v_fma_f32 v178, v184, v12, v178
	v_fma_f32 v179, v185, v13, v179
	v_lshlrev_b32_e32 v180, 16, v114
	v_and_b32_e32 v181, 0xffff0000, v114
	v_lshlrev_b32_e32 v184, 16, v146
	v_and_b32_e32 v185, 0xffff0000, v146
	v_mul_f32_e32 v184, s24, v184
	v_mul_f32_e32 v185, s24, v185
	v_fma_f32 v180, v184, v14, v180
	v_fma_f32 v181, v185, v15, v181
	v_lshlrev_b32_e32 v182, 16, v115
	v_and_b32_e32 v183, 0xffff0000, v115
	v_lshlrev_b32_e32 v184, 16, v147
	v_and_b32_e32 v185, 0xffff0000, v147
	v_mul_f32_e32 v184, s24, v184
	v_mul_f32_e32 v185, s24, v185
	v_fma_f32 v182, v184, v16, v182
	v_fma_f32 v183, v185, v17, v183
	v_add_u32_e32 v1, 0x1000, v27
	global_store_dwordx4 v1, v[168:171], s[14:15] nt
	global_store_dwordx4 v1, v[172:175], s[14:15] offset:16 nt
	global_store_dwordx4 v1, v[176:179], s[14:15] offset:2048 nt
	global_store_dwordx4 v1, v[180:183], s[14:15] offset:2064 nt
	s_nop 1
	v_lshlrev_b32_e32 v168, 16, v116
	v_and_b32_e32 v169, 0xffff0000, v116
	v_lshlrev_b32_e32 v184, 16, v148
	v_and_b32_e32 v185, 0xffff0000, v148
	v_mul_f32_e32 v184, s98, v184
	v_mul_f32_e32 v185, s98, v185
	v_fma_f32 v168, v184, v2, v168
	v_fma_f32 v169, v185, v3, v169
	v_lshlrev_b32_e32 v170, 16, v117
	v_and_b32_e32 v171, 0xffff0000, v117
	v_lshlrev_b32_e32 v184, 16, v149
	v_and_b32_e32 v185, 0xffff0000, v149
	v_mul_f32_e32 v184, s98, v184
	v_mul_f32_e32 v185, s98, v185
	v_fma_f32 v170, v184, v4, v170
	v_fma_f32 v171, v185, v5, v171
	v_lshlrev_b32_e32 v172, 16, v118
	v_and_b32_e32 v173, 0xffff0000, v118
	v_lshlrev_b32_e32 v184, 16, v150
	v_and_b32_e32 v185, 0xffff0000, v150
	v_mul_f32_e32 v184, s98, v184
	v_mul_f32_e32 v185, s98, v185
	v_fma_f32 v172, v184, v6, v172
	v_fma_f32 v173, v185, v7, v173
	v_lshlrev_b32_e32 v174, 16, v119
	v_and_b32_e32 v175, 0xffff0000, v119
	v_lshlrev_b32_e32 v184, 16, v151
	v_and_b32_e32 v185, 0xffff0000, v151
	v_mul_f32_e32 v184, s98, v184
	v_mul_f32_e32 v185, s98, v185
	v_fma_f32 v174, v184, v8, v174
	v_fma_f32 v175, v185, v9, v175
	v_lshlrev_b32_e32 v176, 16, v120
	v_and_b32_e32 v177, 0xffff0000, v120
	v_lshlrev_b32_e32 v184, 16, v152
	v_and_b32_e32 v185, 0xffff0000, v152
	v_mul_f32_e32 v184, s98, v184
	v_mul_f32_e32 v185, s98, v185
	v_fma_f32 v176, v184, v10, v176
	v_fma_f32 v177, v185, v11, v177
	v_lshlrev_b32_e32 v178, 16, v121
	v_and_b32_e32 v179, 0xffff0000, v121
	v_lshlrev_b32_e32 v184, 16, v153
	v_and_b32_e32 v185, 0xffff0000, v153
	v_mul_f32_e32 v184, s98, v184
	v_mul_f32_e32 v185, s98, v185
	v_fma_f32 v178, v184, v12, v178
	v_fma_f32 v179, v185, v13, v179
	v_lshlrev_b32_e32 v180, 16, v122
	v_and_b32_e32 v181, 0xffff0000, v122
	v_lshlrev_b32_e32 v184, 16, v154
	v_and_b32_e32 v185, 0xffff0000, v154
	v_mul_f32_e32 v184, s98, v184
	v_mul_f32_e32 v185, s98, v185
	v_fma_f32 v180, v184, v14, v180
	v_fma_f32 v181, v185, v15, v181
	v_lshlrev_b32_e32 v182, 16, v123
	v_and_b32_e32 v183, 0xffff0000, v123
	v_lshlrev_b32_e32 v184, 16, v155
	v_and_b32_e32 v185, 0xffff0000, v155
	v_mul_f32_e32 v184, s98, v184
	v_mul_f32_e32 v185, s98, v185
	v_fma_f32 v182, v184, v16, v182
	v_fma_f32 v183, v185, v17, v183
	v_add_u32_e32 v1, 0x2000, v27
	global_store_dwordx4 v1, v[168:171], s[14:15] nt
	global_store_dwordx4 v1, v[172:175], s[14:15] offset:16 nt
	global_store_dwordx4 v1, v[176:179], s[14:15] offset:2048 nt
	global_store_dwordx4 v1, v[180:183], s[14:15] offset:2064 nt
	s_nop 1
	v_lshlrev_b32_e32 v168, 16, v124
	v_and_b32_e32 v169, 0xffff0000, v124
	v_lshlrev_b32_e32 v184, 16, v156
; __device__ __forceinline__ float bf_lo(unsigned w) { return __uint_as_float(w << 16); }
; __device__ __forceinline__ float bf_hi(unsigned w) { return __uint_as_float(w & 0xffff0000u); }
; __device__ __forceinline__ unsigned pk2(float lo, float hi) { bf16x2_t r = __builtin_convertvector((f32x2_t){lo, hi}, bf16x2_t); return __builtin_bit_cast(unsigned, r); }
; template <bool SRC_F32, int R> __device__ __forceinline__ void ew_load(EwSet<SRC_F32, R>& S, int rb, const float* hsrc32, const bf16* hsrcb, const bf16* f, const float* part, int lane) {
; #pragma unroll
;     for (int i = 0; i < R; ++i) S.p[i] = (lane < 16) ? part[(size_t)(rb + i) * 16 + lane] : 0.f;
; #pragma unroll
;     for (int i = 0; i < R; ++i)
; #pragma unroll
;         for (int j = 0; j < 4; ++j) {
;             S.fw[i][j] = ((const v2u*)(f + (size_t)(rb + i) * D) + lane)[64 * j];
;             if constexpr (SRC_F32) S.h32[i][j] = __builtin_nontemporal_load((const f32x4*)(hsrc32 + (size_t)(rb + i) * D) + lane + 64 * j);
;             else S.hb[i][j] = ((const v2u*)(hsrcb + (size_t)(rb + i) * D) + lane)[64 * j];
;         }
; }
; template <bool SRC_F32, bool FINAL, int R> __device__ __forceinline__ void ew_compute(const EwSet<SRC_F32, R>& S, int rb, const f32x4 (&g)[4], bf16* hb_out, float* out32, float scale, float* rs_out, int lane) {
;     ...
; #pragma unroll
;         for (int j = 0; j < 4; ++j) {
;             f32x4 h;
;             if constexpr (SRC_F32) h = S.h32[i][j];
;             else { const v2u hw = S.hb[i][j]; h.x = bf_lo(hw.x); h.y = bf_hi(hw.x); h.z = bf_lo(hw.y); h.w = bf_hi(hw.y); }
;             const v2u fw = S.fw[i][j];
;             f32x4 v; v.x = h.x + bf_lo(fw.x) * rs * g[j].x; v.y = h.y + bf_hi(fw.x) * rs * g[j].y; v.z = h.z + bf_lo(fw.y) * rs * g[j].z; v.w = h.w + bf_hi(fw.y) * rs * g[j].w;
;             if (FINAL) __builtin_nontemporal_store(v, (f32x4*)(out32 + (size_t)(rb + i) * D) + lane + 64 * j);
;             else { v2u o; o.x = pk2(v.x, v.y); o.y = pk2(v.z, v.w); ((v2u*)(hb_out + (size_t)(rb + i) * D) + lane)[64 * j] = o; s2 += (v.x * v.x + v.y * v.y) + (v.z * v.z + v.w * v.w); }
	v_and_b32_e32 v185, 0xffff0000, v156
	v_mul_f32_e32 v184, s101, v184
	v_mul_f32_e32 v185, s101, v185
	v_fma_f32 v168, v184, v2, v168
	v_fma_f32 v169, v185, v3, v169
	v_lshlrev_b32_e32 v170, 16, v125
	v_and_b32_e32 v171, 0xffff0000, v125
	v_lshlrev_b32_e32 v184, 16, v157
	v_and_b32_e32 v185, 0xffff0000, v157
	v_mul_f32_e32 v184, s101, v184
	v_mul_f32_e32 v185, s101, v185
	v_fma_f32 v170, v184, v4, v170
	v_fma_f32 v171, v185, v5, v171
	v_lshlrev_b32_e32 v172, 16, v126
	v_and_b32_e32 v173, 0xffff0000, v126
	v_lshlrev_b32_e32 v184, 16, v158
	v_and_b32_e32 v185, 0xffff0000, v158
	v_mul_f32_e32 v184, s101, v184
	v_mul_f32_e32 v185, s101, v185
	v_fma_f32 v172, v184, v6, v172
	v_fma_f32 v173, v185, v7, v173
	v_lshlrev_b32_e32 v174, 16, v127
	v_and_b32_e32 v175, 0xffff0000, v127
	v_lshlrev_b32_e32 v184, 16, v159
	v_and_b32_e32 v185, 0xffff0000, v159
	v_mul_f32_e32 v184, s101, v184
	v_mul_f32_e32 v185, s101, v185
	v_fma_f32 v174, v184, v8, v174
	v_fma_f32 v175, v185, v9, v175
	v_lshlrev_b32_e32 v176, 16, v128
	v_and_b32_e32 v177, 0xffff0000, v128
	v_lshlrev_b32_e32 v184, 16, v160
	v_and_b32_e32 v185, 0xffff0000, v160
	v_mul_f32_e32 v184, s101, v184
	v_mul_f32_e32 v185, s101, v185
	v_fma_f32 v176, v184, v10, v176
	v_fma_f32 v177, v185, v11, v177
	v_lshlrev_b32_e32 v178, 16, v129
	v_and_b32_e32 v179, 0xffff0000, v129
	v_lshlrev_b32_e32 v184, 16, v161
	v_and_b32_e32 v185, 0xffff0000, v161
	v_mul_f32_e32 v184, s101, v184
	v_mul_f32_e32 v185, s101, v185
	v_fma_f32 v178, v184, v12, v178
	v_fma_f32 v179, v185, v13, v179
	v_lshlrev_b32_e32 v180, 16, v130
	v_and_b32_e32 v181, 0xffff0000, v130
	v_lshlrev_b32_e32 v184, 16, v162
	v_and_b32_e32 v185, 0xffff0000, v162
	v_mul_f32_e32 v184, s101, v184
	v_mul_f32_e32 v185, s101, v185
	v_fma_f32 v180, v184, v14, v180
	v_fma_f32 v181, v185, v15, v181
	v_lshlrev_b32_e32 v182, 16, v131
	v_and_b32_e32 v183, 0xffff0000, v131
	v_lshlrev_b32_e32 v184, 16, v163
	v_and_b32_e32 v185, 0xffff0000, v163
	v_mul_f32_e32 v184, s101, v184
	v_mul_f32_e32 v185, s101, v185
	v_fma_f32 v182, v184, v16, v182
	v_fma_f32 v183, v185, v17, v183
	v_add_u32_e32 v1, 0x3000, v27
	global_store_dwordx4 v1, v[168:171], s[14:15] nt
	global_store_dwordx4 v1, v[172:175], s[14:15] offset:16 nt
	global_store_dwordx4 v1, v[176:179], s[14:15] offset:2048 nt
	global_store_dwordx4 v1, v[180:183], s[14:15] offset:2064 nt
	s_nop 1
	s_add_u32 s27, s26, 2052
	s_lshl_b32 s22, s27, 11
	v_lshl_add_u32 v23, v0, 4, s22
	v_add_u32_e32 v24, 0x1000, v23
	s_lshl_b32 s22, s27, 6
	v_lshl_add_u32 v25, v0, 2, s22
	s_lshl_b32 s22, s27, 12
	v_lshl_add_u32 v27, v0, 5, s22
	global_load_dwordx4 v[100:103], v23, s[0:1]
	global_load_dwordx4 v[104:107], v23, s[0:1] offset:1024
	global_load_dwordx4 v[132:135], v23, s[4:5]
	global_load_dwordx4 v[136:139], v23, s[4:5] offset:1024
	global_load_dwordx4 v[108:111], v23, s[0:1] offset:2048
	global_load_dwordx4 v[112:115], v23, s[0:1] offset:3072
	global_load_dwordx4 v[140:143], v23, s[4:5] offset:2048
	global_load_dwordx4 v[144:147], v23, s[4:5] offset:3072
	global_load_dwordx4 v[116:119], v24, s[0:1]
	global_load_dwordx4 v[120:123], v24, s[0:1] offset:1024
	global_load_dwordx4 v[148:151], v24, s[4:5]
	global_load_dwordx4 v[152:155], v24, s[4:5] offset:1024
	global_load_dwordx4 v[124:127], v24, s[0:1] offset:2048
	global_load_dwordx4 v[128:131], v24, s[0:1] offset:3072
	global_load_dwordx4 v[156:159], v24, s[4:5] offset:2048
	global_load_dwordx4 v[160:163], v24, s[4:5] offset:3072
	global_load_dword v164, v25, s[6:7]
	s_waitcnt vmcnt(33)
	v_add_f32_dpp v96, v96, v96 quad_perm:[1,0,3,2] row_mask:0xf bank_mask:0xf
	s_nop 1
	v_add_f32_dpp v96, v96, v96 quad_perm:[2,3,0,1] row_mask:0xf bank_mask:0xf
	s_nop 1
	v_add_f32_dpp v96, v96, v96 row_half_mirror row_mask:0xf bank_mask:0xf
	s_nop 1
	v_add_f32_dpp v96, v96, v96 row_mirror row_mask:0xf bank_mask:0xf
	s_nop 1
	v_mul_f32_e32 v96, 0x3a800000, v96
	v_add_f32_e32 v96, 0x358637bd, v96
	v_rsq_f32_e32 v96, v96
	s_nop 0
	v_readlane_b32 s3, v96, 0
	v_readlane_b32 s24, v96, 16
	v_readlane_b32 s98, v96, 32
	v_readlane_b32 s101, v96, 48
	s_nop 1
	v_lshlrev_b32_e32 v168, 16, v32
	v_and_b32_e32 v169, 0xffff0000, v32
	v_lshlrev_b32_e32 v184, 16, v64
	v_and_b32_e32 v185, 0xffff0000, v64
	v_mul_f32_e32 v184, s3, v184
	v_mul_f32_e32 v185, s3, v185
	v_fma_f32 v168, v184, v2, v168
	v_fma_f32 v169, v185, v3, v169
	v_lshlrev_b32_e32 v170, 16, v33
	v_and_b32_e32 v171, 0xffff0000, v33
	v_lshlrev_b32_e32 v184, 16, v65
	v_and_b32_e32 v185, 0xffff0000, v65
	v_mul_f32_e32 v184, s3, v184
	v_mul_f32_e32 v185, s3, v185
	v_fma_f32 v170, v184, v4, v170
	v_fma_f32 v171, v185, v5, v171
	v_lshlrev_b32_e32 v172, 16, v34
	v_and_b32_e32 v173, 0xffff0000, v34
	v_lshlrev_b32_e32 v184, 16, v66
	v_and_b32_e32 v185, 0xffff0000, v66
	v_mul_f32_e32 v184, s3, v184
	v_mul_f32_e32 v185, s3, v185
	v_fma_f32 v172, v184, v6, v172
	v_fma_f32 v173, v185, v7, v173
	v_lshlrev_b32_e32 v174, 16, v35
	v_and_b32_e32 v175, 0xffff0000, v35
	v_lshlrev_b32_e32 v184, 16, v67
	v_and_b32_e32 v185, 0xffff0000, v67
	v_mul_f32_e32 v184, s3, v184
	v_mul_f32_e32 v185, s3, v185
	v_fma_f32 v174, v184, v8, v174
	v_fma_f32 v175, v185, v9, v175
	v_lshlrev_b32_e32 v176, 16, v36
	v_and_b32_e32 v177, 0xffff0000, v36
	v_lshlrev_b32_e32 v184, 16, v68
	v_and_b32_e32 v185, 0xffff0000, v68
	v_mul_f32_e32 v184, s3, v184
	v_mul_f32_e32 v185, s3, v185
	v_fma_f32 v176, v184, v10, v176
	v_fma_f32 v177, v185, v11, v177
	v_lshlrev_b32_e32 v178, 16, v37
	v_and_b32_e32 v179, 0xffff0000, v37
	v_lshlrev_b32_e32 v184, 16, v69
	v_and_b32_e32 v185, 0xffff0000, v69
	v_mul_f32_e32 v184, s3, v184
	v_mul_f32_e32 v185, s3, v185
	v_fma_f32 v178, v184, v12, v178
	v_fma_f32 v179, v185, v13, v179
; __device__ __forceinline__ float bf_lo(unsigned w) { return __uint_as_float(w << 16); }
; __device__ __forceinline__ float bf_hi(unsigned w) { return __uint_as_float(w & 0xffff0000u); }
; __device__ __forceinline__ unsigned pk2(float lo, float hi) { bf16x2_t r = __builtin_convertvector((f32x2_t){lo, hi}, bf16x2_t); return __builtin_bit_cast(unsigned, r); }
; template <bool SRC_F32, bool FINAL, int R> __device__ __forceinline__ void ew_compute(const EwSet<SRC_F32, R>& S, int rb, const f32x4 (&g)[4], bf16* hb_out, float* out32, float scale, float* rs_out, int lane) {
;     ...
; #pragma unroll
;         for (int j = 0; j < 4; ++j) {
;             f32x4 h;
;             if constexpr (SRC_F32) h = S.h32[i][j];
;             else { const v2u hw = S.hb[i][j]; h.x = bf_lo(hw.x); h.y = bf_hi(hw.x); h.z = bf_lo(hw.y); h.w = bf_hi(hw.y); }
;             const v2u fw = S.fw[i][j];
;             f32x4 v; v.x = h.x + bf_lo(fw.x) * rs * g[j].x; v.y = h.y + bf_hi(fw.x) * rs * g[j].y; v.z = h.z + bf_lo(fw.y) * rs * g[j].z; v.w = h.w + bf_hi(fw.y) * rs * g[j].w;
;             if (FINAL) __builtin_nontemporal_store(v, (f32x4*)(out32 + (size_t)(rb + i) * D) + lane + 64 * j);
;             else { v2u o; o.x = pk2(v.x, v.y); o.y = pk2(v.z, v.w); ((v2u*)(hb_out + (size_t)(rb + i) * D) + lane)[64 * j] = o; s2 += (v.x * v.x + v.y * v.y) + (v.z * v.z + v.w * v.w); }
	v_lshlrev_b32_e32 v180, 16, v38
	v_and_b32_e32 v181, 0xffff0000, v38
	v_lshlrev_b32_e32 v184, 16, v70
	v_and_b32_e32 v185, 0xffff0000, v70
	v_mul_f32_e32 v184, s3, v184
	v_mul_f32_e32 v185, s3, v185
	v_fma_f32 v180, v184, v14, v180
	v_fma_f32 v181, v185, v15, v181
	v_lshlrev_b32_e32 v182, 16, v39
	v_and_b32_e32 v183, 0xffff0000, v39
	v_lshlrev_b32_e32 v184, 16, v71
	v_and_b32_e32 v185, 0xffff0000, v71
	v_mul_f32_e32 v184, s3, v184
	v_mul_f32_e32 v185, s3, v185
	v_fma_f32 v182, v184, v16, v182
	v_fma_f32 v183, v185, v17, v183
	global_store_dwordx4 v22, v[168:171], s[14:15] nt
	global_store_dwordx4 v22, v[172:175], s[14:15] offset:16 nt
	global_store_dwordx4 v22, v[176:179], s[14:15] offset:2048 nt
	global_store_dwordx4 v22, v[180:183], s[14:15] offset:2064 nt
	s_nop 1
	v_lshlrev_b32_e32 v168, 16, v40
	v_and_b32_e32 v169, 0xffff0000, v40
	v_lshlrev_b32_e32 v184, 16, v72
	v_and_b32_e32 v185, 0xffff0000, v72
	v_mul_f32_e32 v184, s24, v184
	v_mul_f32_e32 v185, s24, v185
	v_fma_f32 v168, v184, v2, v168
	v_fma_f32 v169, v185, v3, v169
	v_lshlrev_b32_e32 v170, 16, v41
	v_and_b32_e32 v171, 0xffff0000, v41
	v_lshlrev_b32_e32 v184, 16, v73
	v_and_b32_e32 v185, 0xffff0000, v73
	v_mul_f32_e32 v184, s24, v184
	v_mul_f32_e32 v185, s24, v185
	v_fma_f32 v170, v184, v4, v170
	v_fma_f32 v171, v185, v5, v171
	v_lshlrev_b32_e32 v172, 16, v42
	v_and_b32_e32 v173, 0xffff0000, v42
	v_lshlrev_b32_e32 v184, 16, v74
	v_and_b32_e32 v185, 0xffff0000, v74
	v_mul_f32_e32 v184, s24, v184
	v_mul_f32_e32 v185, s24, v185
	v_fma_f32 v172, v184, v6, v172
	v_fma_f32 v173, v185, v7, v173
	v_lshlrev_b32_e32 v174, 16, v43
	v_and_b32_e32 v175, 0xffff0000, v43
	v_lshlrev_b32_e32 v184, 16, v75
	v_and_b32_e32 v185, 0xffff0000, v75
	v_mul_f32_e32 v184, s24, v184
	v_mul_f32_e32 v185, s24, v185
	v_fma_f32 v174, v184, v8, v174
	v_fma_f32 v175, v185, v9, v175
	v_lshlrev_b32_e32 v176, 16, v44
	v_and_b32_e32 v177, 0xffff0000, v44
	v_lshlrev_b32_e32 v184, 16, v76
	v_and_b32_e32 v185, 0xffff0000, v76
	v_mul_f32_e32 v184, s24, v184
	v_mul_f32_e32 v185, s24, v185
	v_fma_f32 v176, v184, v10, v176
	v_fma_f32 v177, v185, v11, v177
	v_lshlrev_b32_e32 v178, 16, v45
	v_and_b32_e32 v179, 0xffff0000, v45
	v_lshlrev_b32_e32 v184, 16, v77
	v_and_b32_e32 v185, 0xffff0000, v77
	v_mul_f32_e32 v184, s24, v184
	v_mul_f32_e32 v185, s24, v185
	v_fma_f32 v178, v184, v12, v178
	v_fma_f32 v179, v185, v13, v179
	v_lshlrev_b32_e32 v180, 16, v46
	v_and_b32_e32 v181, 0xffff0000, v46
	v_lshlrev_b32_e32 v184, 16, v78
	v_and_b32_e32 v185, 0xffff0000, v78
	v_mul_f32_e32 v184, s24, v184
	v_mul_f32_e32 v185, s24, v185
	v_fma_f32 v180, v184, v14, v180
	v_fma_f32 v181, v185, v15, v181
	v_lshlrev_b32_e32 v182, 16, v47
	v_and_b32_e32 v183, 0xffff0000, v47
	v_lshlrev_b32_e32 v184, 16, v79
	v_and_b32_e32 v185, 0xffff0000, v79
	v_mul_f32_e32 v184, s24, v184
	v_mul_f32_e32 v185, s24, v185
	v_fma_f32 v182, v184, v16, v182
	v_fma_f32 v183, v185, v17, v183
	v_add_u32_e32 v1, 0x1000, v22
	global_store_dwordx4 v1, v[168:171], s[14:15] nt
	global_store_dwordx4 v1, v[172:175], s[14:15] offset:16 nt
	global_store_dwordx4 v1, v[176:179], s[14:15] offset:2048 nt
	global_store_dwordx4 v1, v[180:183], s[14:15] offset:2064 nt
	s_nop 1
	v_lshlrev_b32_e32 v168, 16, v48
	v_and_b32_e32 v169, 0xffff0000, v48
	v_lshlrev_b32_e32 v184, 16, v80
	v_and_b32_e32 v185, 0xffff0000, v80
	v_mul_f32_e32 v184, s98, v184
	v_mul_f32_e32 v185, s98, v185
	v_fma_f32 v168, v184, v2, v168
	v_fma_f32 v169, v185, v3, v169
	v_lshlrev_b32_e32 v170, 16, v49
	v_and_b32_e32 v171, 0xffff0000, v49
	v_lshlrev_b32_e32 v184, 16, v81
	v_and_b32_e32 v185, 0xffff0000, v81
	v_mul_f32_e32 v184, s98, v184
	v_mul_f32_e32 v185, s98, v185
	v_fma_f32 v170, v184, v4, v170
	v_fma_f32 v171, v185, v5, v171
	v_lshlrev_b32_e32 v172, 16, v50
	v_and_b32_e32 v173, 0xffff0000, v50
	v_lshlrev_b32_e32 v184, 16, v82
	v_and_b32_e32 v185, 0xffff0000, v82
	v_mul_f32_e32 v184, s98, v184
	v_mul_f32_e32 v185, s98, v185
	v_fma_f32 v172, v184, v6, v172
	v_fma_f32 v173, v185, v7, v173
	v_lshlrev_b32_e32 v174, 16, v51
	v_and_b32_e32 v175, 0xffff0000, v51
	v_lshlrev_b32_e32 v184, 16, v83
	v_and_b32_e32 v185, 0xffff0000, v83
	v_mul_f32_e32 v184, s98, v184
	v_mul_f32_e32 v185, s98, v185
	v_fma_f32 v174, v184, v8, v174
	v_fma_f32 v175, v185, v9, v175
	v_lshlrev_b32_e32 v176, 16, v52
	v_and_b32_e32 v177, 0xffff0000, v52
	v_lshlrev_b32_e32 v184, 16, v84
	v_and_b32_e32 v185, 0xffff0000, v84
	v_mul_f32_e32 v184, s98, v184
	v_mul_f32_e32 v185, s98, v185
	v_fma_f32 v176, v184, v10, v176
	v_fma_f32 v177, v185, v11, v177
	v_lshlrev_b32_e32 v178, 16, v53
	v_and_b32_e32 v179, 0xffff0000, v53
	v_lshlrev_b32_e32 v184, 16, v85
	v_and_b32_e32 v185, 0xffff0000, v85
	v_mul_f32_e32 v184, s98, v184
	v_mul_f32_e32 v185, s98, v185
	v_fma_f32 v178, v184, v12, v178
	v_fma_f32 v179, v185, v13, v179
	v_lshlrev_b32_e32 v180, 16, v54
	v_and_b32_e32 v181, 0xffff0000, v54
	v_lshlrev_b32_e32 v184, 16, v86
	v_and_b32_e32 v185, 0xffff0000, v86
	v_mul_f32_e32 v184, s98, v184
	v_mul_f32_e32 v185, s98, v185
	v_fma_f32 v180, v184, v14, v180
	v_fma_f32 v181, v185, v15, v181
	v_lshlrev_b32_e32 v182, 16, v55
	v_and_b32_e32 v183, 0xffff0000, v55
	v_lshlrev_b32_e32 v184, 16, v87
	v_and_b32_e32 v185, 0xffff0000, v87
	v_mul_f32_e32 v184, s98, v184
	v_mul_f32_e32 v185, s98, v185
	v_fma_f32 v182, v184, v16, v182
	v_fma_f32 v183, v185, v17, v183
	v_add_u32_e32 v1, 0x2000, v22
	global_store_dwordx4 v1, v[168:171], s[14:15] nt
	global_store_dwordx4 v1, v[172:175], s[14:15] offset:16 nt
	global_store_dwordx4 v1, v[176:179], s[14:15] offset:2048 nt
	global_store_dwordx4 v1, v[180:183], s[14:15] offset:2064 nt
	s_nop 1
	v_lshlrev_b32_e32 v168, 16, v56
; __device__ __forceinline__ float bf_lo(unsigned w) { return __uint_as_float(w << 16); }
; __device__ __forceinline__ float bf_hi(unsigned w) { return __uint_as_float(w & 0xffff0000u); }
; __device__ __forceinline__ unsigned pk2(float lo, float hi) { bf16x2_t r = __builtin_convertvector((f32x2_t){lo, hi}, bf16x2_t); return __builtin_bit_cast(unsigned, r); }
; template <bool SRC_F32, bool FINAL, int R> __device__ __forceinline__ void ew_compute(const EwSet<SRC_F32, R>& S, int rb, const f32x4 (&g)[4], bf16* hb_out, float* out32, float scale, float* rs_out, int lane) {
;     ...
;     for (int i = 0; i < R; ++i) {
;         float q = S.p[i];
;         q += __shfl_xor(q, 1); q += __shfl_xor(q, 2); q += __shfl_xor(q, 4); q += __shfl_xor(q, 8);
;         const float ss = __shfl(q, 0);
;         const float rs = scale / sqrtf(ss * (1.f / D) + EPS);
;         float s2 = 0.f;
; #pragma unroll
;         for (int j = 0; j < 4; ++j) {
;             f32x4 h;
;             if constexpr (SRC_F32) h = S.h32[i][j];
;             else { const v2u hw = S.hb[i][j]; h.x = bf_lo(hw.x); h.y = bf_hi(hw.x); h.z = bf_lo(hw.y); h.w = bf_hi(hw.y); }
;             const v2u fw = S.fw[i][j];
;             f32x4 v; v.x = h.x + bf_lo(fw.x) * rs * g[j].x; v.y = h.y + bf_hi(fw.x) * rs * g[j].y; v.z = h.z + bf_lo(fw.y) * rs * g[j].z; v.w = h.w + bf_hi(fw.y) * rs * g[j].w;
;             if (FINAL) __builtin_nontemporal_store(v, (f32x4*)(out32 + (size_t)(rb + i) * D) + lane + 64 * j);
;             else { v2u o; o.x = pk2(v.x, v.y); o.y = pk2(v.z, v.w); ((v2u*)(hb_out + (size_t)(rb + i) * D) + lane)[64 * j] = o; s2 += (v.x * v.x + v.y * v.y) + (v.z * v.z + v.w * v.w); }
	v_and_b32_e32 v169, 0xffff0000, v56
	v_lshlrev_b32_e32 v184, 16, v88
	v_and_b32_e32 v185, 0xffff0000, v88
	v_mul_f32_e32 v184, s101, v184
	v_mul_f32_e32 v185, s101, v185
	v_fma_f32 v168, v184, v2, v168
	v_fma_f32 v169, v185, v3, v169
	v_lshlrev_b32_e32 v170, 16, v57
	v_and_b32_e32 v171, 0xffff0000, v57
	v_lshlrev_b32_e32 v184, 16, v89
	v_and_b32_e32 v185, 0xffff0000, v89
	v_mul_f32_e32 v184, s101, v184
	v_mul_f32_e32 v185, s101, v185
	v_fma_f32 v170, v184, v4, v170
	v_fma_f32 v171, v185, v5, v171
	v_lshlrev_b32_e32 v172, 16, v58
	v_and_b32_e32 v173, 0xffff0000, v58
	v_lshlrev_b32_e32 v184, 16, v90
	v_and_b32_e32 v185, 0xffff0000, v90
	v_mul_f32_e32 v184, s101, v184
	v_mul_f32_e32 v185, s101, v185
	v_fma_f32 v172, v184, v6, v172
	v_fma_f32 v173, v185, v7, v173
	v_lshlrev_b32_e32 v174, 16, v59
	v_and_b32_e32 v175, 0xffff0000, v59
	v_lshlrev_b32_e32 v184, 16, v91
	v_and_b32_e32 v185, 0xffff0000, v91
	v_mul_f32_e32 v184, s101, v184
	v_mul_f32_e32 v185, s101, v185
	v_fma_f32 v174, v184, v8, v174
	v_fma_f32 v175, v185, v9, v175
	v_lshlrev_b32_e32 v176, 16, v60
	v_and_b32_e32 v177, 0xffff0000, v60
	v_lshlrev_b32_e32 v184, 16, v92
	v_and_b32_e32 v185, 0xffff0000, v92
	v_mul_f32_e32 v184, s101, v184
	v_mul_f32_e32 v185, s101, v185
	v_fma_f32 v176, v184, v10, v176
	v_fma_f32 v177, v185, v11, v177
	v_lshlrev_b32_e32 v178, 16, v61
	v_and_b32_e32 v179, 0xffff0000, v61
	v_lshlrev_b32_e32 v184, 16, v93
	v_and_b32_e32 v185, 0xffff0000, v93
	v_mul_f32_e32 v184, s101, v184
	v_mul_f32_e32 v185, s101, v185
	v_fma_f32 v178, v184, v12, v178
	v_fma_f32 v179, v185, v13, v179
	v_lshlrev_b32_e32 v180, 16, v62
	v_and_b32_e32 v181, 0xffff0000, v62
	v_lshlrev_b32_e32 v184, 16, v94
	v_and_b32_e32 v185, 0xffff0000, v94
	v_mul_f32_e32 v184, s101, v184
	v_mul_f32_e32 v185, s101, v185
	v_fma_f32 v180, v184, v14, v180
	v_fma_f32 v181, v185, v15, v181
	v_lshlrev_b32_e32 v182, 16, v63
	v_and_b32_e32 v183, 0xffff0000, v63
	v_lshlrev_b32_e32 v184, 16, v95
	v_and_b32_e32 v185, 0xffff0000, v95
	v_mul_f32_e32 v184, s101, v184
	v_mul_f32_e32 v185, s101, v185
	v_fma_f32 v182, v184, v16, v182
	v_fma_f32 v183, v185, v17, v183
	v_add_u32_e32 v1, 0x3000, v22
	global_store_dwordx4 v1, v[168:171], s[14:15] nt
	global_store_dwordx4 v1, v[172:175], s[14:15] offset:16 nt
	global_store_dwordx4 v1, v[176:179], s[14:15] offset:2048 nt
	global_store_dwordx4 v1, v[180:183], s[14:15] offset:2064 nt
	s_nop 1
	s_waitcnt vmcnt(16)
	v_add_f32_dpp v164, v164, v164 quad_perm:[1,0,3,2] row_mask:0xf bank_mask:0xf
	s_nop 1
	v_add_f32_dpp v164, v164, v164 quad_perm:[2,3,0,1] row_mask:0xf bank_mask:0xf
	s_nop 1
	v_add_f32_dpp v164, v164, v164 row_half_mirror row_mask:0xf bank_mask:0xf
	s_nop 1
	v_add_f32_dpp v164, v164, v164 row_mirror row_mask:0xf bank_mask:0xf
	s_nop 1
	v_mul_f32_e32 v164, 0x3a800000, v164
	v_add_f32_e32 v164, 0x358637bd, v164
	v_rsq_f32_e32 v164, v164
	s_nop 0
	v_readlane_b32 s3, v164, 0
	v_readlane_b32 s24, v164, 16
	v_readlane_b32 s98, v164, 32
	v_readlane_b32 s101, v164, 48
	s_nop 1
	v_lshlrev_b32_e32 v168, 16, v100
	v_and_b32_e32 v169, 0xffff0000, v100
	v_lshlrev_b32_e32 v184, 16, v132
	v_and_b32_e32 v185, 0xffff0000, v132
	v_mul_f32_e32 v184, s3, v184
	v_mul_f32_e32 v185, s3, v185
	v_fma_f32 v168, v184, v2, v168
	v_fma_f32 v169, v185, v3, v169
	v_lshlrev_b32_e32 v170, 16, v101
	v_and_b32_e32 v171, 0xffff0000, v101
	v_lshlrev_b32_e32 v184, 16, v133
	v_and_b32_e32 v185, 0xffff0000, v133
	v_mul_f32_e32 v184, s3, v184
	v_mul_f32_e32 v185, s3, v185
	v_fma_f32 v170, v184, v4, v170
	v_fma_f32 v171, v185, v5, v171
	v_lshlrev_b32_e32 v172, 16, v102
	v_and_b32_e32 v173, 0xffff0000, v102
	v_lshlrev_b32_e32 v184, 16, v134
	v_and_b32_e32 v185, 0xffff0000, v134
	v_mul_f32_e32 v184, s3, v184
	v_mul_f32_e32 v185, s3, v185
	v_fma_f32 v172, v184, v6, v172
	v_fma_f32 v173, v185, v7, v173
	v_lshlrev_b32_e32 v174, 16, v103
	v_and_b32_e32 v175, 0xffff0000, v103
	v_lshlrev_b32_e32 v184, 16, v135
	v_and_b32_e32 v185, 0xffff0000, v135
	v_mul_f32_e32 v184, s3, v184
	v_mul_f32_e32 v185, s3, v185
	v_fma_f32 v174, v184, v8, v174
	v_fma_f32 v175, v185, v9, v175
	v_lshlrev_b32_e32 v176, 16, v104
	v_and_b32_e32 v177, 0xffff0000, v104
	v_lshlrev_b32_e32 v184, 16, v136
	v_and_b32_e32 v185, 0xffff0000, v136
	v_mul_f32_e32 v184, s3, v184
	v_mul_f32_e32 v185, s3, v185
	v_fma_f32 v176, v184, v10, v176
	v_fma_f32 v177, v185, v11, v177
	v_lshlrev_b32_e32 v178, 16, v105
	v_and_b32_e32 v179, 0xffff0000, v105
	v_lshlrev_b32_e32 v184, 16, v137
	v_and_b32_e32 v185, 0xffff0000, v137
	v_mul_f32_e32 v184, s3, v184
	v_mul_f32_e32 v185, s3, v185
	v_fma_f32 v178, v184, v12, v178
	v_fma_f32 v179, v185, v13, v179
	v_lshlrev_b32_e32 v180, 16, v106
	v_and_b32_e32 v181, 0xffff0000, v106
	v_lshlrev_b32_e32 v184, 16, v138
	v_and_b32_e32 v185, 0xffff0000, v138
	v_mul_f32_e32 v184, s3, v184
	v_mul_f32_e32 v185, s3, v185
	v_fma_f32 v180, v184, v14, v180
	v_fma_f32 v181, v185, v15, v181
	v_lshlrev_b32_e32 v182, 16, v107
	v_and_b32_e32 v183, 0xffff0000, v107
	v_lshlrev_b32_e32 v184, 16, v139
	v_and_b32_e32 v185, 0xffff0000, v139
	v_mul_f32_e32 v184, s3, v184
	v_mul_f32_e32 v185, s3, v185
	v_fma_f32 v182, v184, v16, v182
	v_fma_f32 v183, v185, v17, v183
	global_store_dwordx4 v27, v[168:171], s[14:15] nt
	global_store_dwordx4 v27, v[172:175], s[14:15] offset:16 nt
	global_store_dwordx4 v27, v[176:179], s[14:15] offset:2048 nt
	global_store_dwordx4 v27, v[180:183], s[14:15] offset:2064 nt
	s_nop 1
	v_lshlrev_b32_e32 v168, 16, v108
	v_and_b32_e32 v169, 0xffff0000, v108
	v_lshlrev_b32_e32 v184, 16, v140
	v_and_b32_e32 v185, 0xffff0000, v140
	v_mul_f32_e32 v184, s24, v184
	v_mul_f32_e32 v185, s24, v185
	v_fma_f32 v168, v184, v2, v168
; __device__ __forceinline__ float bf_lo(unsigned w) { return __uint_as_float(w << 16); }
; __device__ __forceinline__ float bf_hi(unsigned w) { return __uint_as_float(w & 0xffff0000u); }
; __device__ __forceinline__ unsigned pk2(float lo, float hi) { bf16x2_t r = __builtin_convertvector((f32x2_t){lo, hi}, bf16x2_t); return __builtin_bit_cast(unsigned, r); }
; template <bool SRC_F32, bool FINAL, int R> __device__ __forceinline__ void ew_compute(const EwSet<SRC_F32, R>& S, int rb, const f32x4 (&g)[4], bf16* hb_out, float* out32, float scale, float* rs_out, int lane) {
;     ...
; #pragma unroll
;         for (int j = 0; j < 4; ++j) {
;             f32x4 h;
;             if constexpr (SRC_F32) h = S.h32[i][j];
;             else { const v2u hw = S.hb[i][j]; h.x = bf_lo(hw.x); h.y = bf_hi(hw.x); h.z = bf_lo(hw.y); h.w = bf_hi(hw.y); }
;             const v2u fw = S.fw[i][j];
;             f32x4 v; v.x = h.x + bf_lo(fw.x) * rs * g[j].x; v.y = h.y + bf_hi(fw.x) * rs * g[j].y; v.z = h.z + bf_lo(fw.y) * rs * g[j].z; v.w = h.w + bf_hi(fw.y) * rs * g[j].w;
;             if (FINAL) __builtin_nontemporal_store(v, (f32x4*)(out32 + (size_t)(rb + i) * D) + lane + 64 * j);
;             else { v2u o; o.x = pk2(v.x, v.y); o.y = pk2(v.z, v.w); ((v2u*)(hb_out + (size_t)(rb + i) * D) + lane)[64 * j] = o; s2 += (v.x * v.x + v.y * v.y) + (v.z * v.z + v.w * v.w); }
	v_fma_f32 v169, v185, v3, v169
	v_lshlrev_b32_e32 v170, 16, v109
	v_and_b32_e32 v171, 0xffff0000, v109
	v_lshlrev_b32_e32 v184, 16, v141
	v_and_b32_e32 v185, 0xffff0000, v141
	v_mul_f32_e32 v184, s24, v184
	v_mul_f32_e32 v185, s24, v185
	v_fma_f32 v170, v184, v4, v170
	v_fma_f32 v171, v185, v5, v171
	v_lshlrev_b32_e32 v172, 16, v110
	v_and_b32_e32 v173, 0xffff0000, v110
	v_lshlrev_b32_e32 v184, 16, v142
	v_and_b32_e32 v185, 0xffff0000, v142
	v_mul_f32_e32 v184, s24, v184
	v_mul_f32_e32 v185, s24, v185
	v_fma_f32 v172, v184, v6, v172
	v_fma_f32 v173, v185, v7, v173
	v_lshlrev_b32_e32 v174, 16, v111
	v_and_b32_e32 v175, 0xffff0000, v111
	v_lshlrev_b32_e32 v184, 16, v143
	v_and_b32_e32 v185, 0xffff0000, v143
	v_mul_f32_e32 v184, s24, v184
	v_mul_f32_e32 v185, s24, v185
	v_fma_f32 v174, v184, v8, v174
	v_fma_f32 v175, v185, v9, v175
	v_lshlrev_b32_e32 v176, 16, v112
	v_and_b32_e32 v177, 0xffff0000, v112
	v_lshlrev_b32_e32 v184, 16, v144
	v_and_b32_e32 v185, 0xffff0000, v144
	v_mul_f32_e32 v184, s24, v184
	v_mul_f32_e32 v185, s24, v185
	v_fma_f32 v176, v184, v10, v176
	v_fma_f32 v177, v185, v11, v177
	v_lshlrev_b32_e32 v178, 16, v113
	v_and_b32_e32 v179, 0xffff0000, v113
	v_lshlrev_b32_e32 v184, 16, v145
	v_and_b32_e32 v185, 0xffff0000, v145
	v_mul_f32_e32 v184, s24, v184
	v_mul_f32_e32 v185, s24, v185
	v_fma_f32 v178, v184, v12, v178
	v_fma_f32 v179, v185, v13, v179
	v_lshlrev_b32_e32 v180, 16, v114
	v_and_b32_e32 v181, 0xffff0000, v114
	v_lshlrev_b32_e32 v184, 16, v146
	v_and_b32_e32 v185, 0xffff0000, v146
	v_mul_f32_e32 v184, s24, v184
	v_mul_f32_e32 v185, s24, v185
	v_fma_f32 v180, v184, v14, v180
	v_fma_f32 v181, v185, v15, v181
	v_lshlrev_b32_e32 v182, 16, v115
	v_and_b32_e32 v183, 0xffff0000, v115
	v_lshlrev_b32_e32 v184, 16, v147
	v_and_b32_e32 v185, 0xffff0000, v147
	v_mul_f32_e32 v184, s24, v184
	v_mul_f32_e32 v185, s24, v185
	v_fma_f32 v182, v184, v16, v182
	v_fma_f32 v183, v185, v17, v183
	v_add_u32_e32 v1, 0x1000, v27
	global_store_dwordx4 v1, v[168:171], s[14:15] nt
	global_store_dwordx4 v1, v[172:175], s[14:15] offset:16 nt
	global_store_dwordx4 v1, v[176:179], s[14:15] offset:2048 nt
	global_store_dwordx4 v1, v[180:183], s[14:15] offset:2064 nt
	s_nop 1
	v_lshlrev_b32_e32 v168, 16, v116
	v_and_b32_e32 v169, 0xffff0000, v116
	v_lshlrev_b32_e32 v184, 16, v148
	v_and_b32_e32 v185, 0xffff0000, v148
	v_mul_f32_e32 v184, s98, v184
	v_mul_f32_e32 v185, s98, v185
	v_fma_f32 v168, v184, v2, v168
	v_fma_f32 v169, v185, v3, v169
	v_lshlrev_b32_e32 v170, 16, v117
	v_and_b32_e32 v171, 0xffff0000, v117
	v_lshlrev_b32_e32 v184, 16, v149
	v_and_b32_e32 v185, 0xffff0000, v149
	v_mul_f32_e32 v184, s98, v184
	v_mul_f32_e32 v185, s98, v185
	v_fma_f32 v170, v184, v4, v170
	v_fma_f32 v171, v185, v5, v171
	v_lshlrev_b32_e32 v172, 16, v118
	v_and_b32_e32 v173, 0xffff0000, v118
	v_lshlrev_b32_e32 v184, 16, v150
	v_and_b32_e32 v185, 0xffff0000, v150
	v_mul_f32_e32 v184, s98, v184
	v_mul_f32_e32 v185, s98, v185
	v_fma_f32 v172, v184, v6, v172
	v_fma_f32 v173, v185, v7, v173
	v_lshlrev_b32_e32 v174, 16, v119
	v_and_b32_e32 v175, 0xffff0000, v119
	v_lshlrev_b32_e32 v184, 16, v151
	v_and_b32_e32 v185, 0xffff0000, v151
	v_mul_f32_e32 v184, s98, v184
	v_mul_f32_e32 v185, s98, v185
	v_fma_f32 v174, v184, v8, v174
	v_fma_f32 v175, v185, v9, v175
	v_lshlrev_b32_e32 v176, 16, v120
	v_and_b32_e32 v177, 0xffff0000, v120
	v_lshlrev_b32_e32 v184, 16, v152
	v_and_b32_e32 v185, 0xffff0000, v152
	v_mul_f32_e32 v184, s98, v184
	v_mul_f32_e32 v185, s98, v185
	v_fma_f32 v176, v184, v10, v176
	v_fma_f32 v177, v185, v11, v177
; __device__ __forceinline__ float bf_lo(unsigned w) { return __uint_as_float(w << 16); }
; __device__ __forceinline__ float bf_hi(unsigned w) { return __uint_as_float(w & 0xffff0000u); }
; __device__ __forceinline__ unsigned pk2(float lo, float hi) { bf16x2_t r = __builtin_convertvector((f32x2_t){lo, hi}, bf16x2_t); return __builtin_bit_cast(unsigned, r); }
; template <bool SRC_F32, bool FINAL, int R> __device__ __forceinline__ void ew_compute(const EwSet<SRC_F32, R>& S, int rb, const f32x4 (&g)[4], bf16* hb_out, float* out32, float scale, float* rs_out, int lane) {
;     ...
; #pragma unroll
;         for (int j = 0; j < 4; ++j) {
;             f32x4 h;
;             if constexpr (SRC_F32) h = S.h32[i][j];
;             else { const v2u hw = S.hb[i][j]; h.x = bf_lo(hw.x); h.y = bf_hi(hw.x); h.z = bf_lo(hw.y); h.w = bf_hi(hw.y); }
;             const v2u fw = S.fw[i][j];
;             f32x4 v; v.x = h.x + bf_lo(fw.x) * rs * g[j].x; v.y = h.y + bf_hi(fw.x) * rs * g[j].y; v.z = h.z + bf_lo(fw.y) * rs * g[j].z; v.w = h.w + bf_hi(fw.y) * rs * g[j].w;
;             if (FINAL) __builtin_nontemporal_store(v, (f32x4*)(out32 + (size_t)(rb + i) * D) + lane + 64 * j);
;             else { v2u o; o.x = pk2(v.x, v.y); o.y = pk2(v.z, v.w); ((v2u*)(hb_out + (size_t)(rb + i) * D) + lane)[64 * j] = o; s2 += (v.x * v.x + v.y * v.y) + (v.z * v.z + v.w * v.w); }
	v_lshlrev_b32_e32 v178, 16, v121
	v_and_b32_e32 v179, 0xffff0000, v121
	v_lshlrev_b32_e32 v184, 16, v153
	v_and_b32_e32 v185, 0xffff0000, v153
	v_mul_f32_e32 v184, s98, v184
	v_mul_f32_e32 v185, s98, v185
	v_fma_f32 v178, v184, v12, v178
	v_fma_f32 v179, v185, v13, v179
	v_lshlrev_b32_e32 v180, 16, v122
	v_and_b32_e32 v181, 0xffff0000, v122
	v_lshlrev_b32_e32 v184, 16, v154
	v_and_b32_e32 v185, 0xffff0000, v154
	v_mul_f32_e32 v184, s98, v184
	v_mul_f32_e32 v185, s98, v185
	v_fma_f32 v180, v184, v14, v180
	v_fma_f32 v181, v185, v15, v181
	v_lshlrev_b32_e32 v182, 16, v123
	v_and_b32_e32 v183, 0xffff0000, v123
	v_lshlrev_b32_e32 v184, 16, v155
	v_and_b32_e32 v185, 0xffff0000, v155
	v_mul_f32_e32 v184, s98, v184
	v_mul_f32_e32 v185, s98, v185
	v_fma_f32 v182, v184, v16, v182
	v_fma_f32 v183, v185, v17, v183
	v_add_u32_e32 v1, 0x2000, v27
	global_store_dwordx4 v1, v[168:171], s[14:15] nt
	global_store_dwordx4 v1, v[172:175], s[14:15] offset:16 nt
	global_store_dwordx4 v1, v[176:179], s[14:15] offset:2048 nt
	global_store_dwordx4 v1, v[180:183], s[14:15] offset:2064 nt
	s_nop 1
	v_lshlrev_b32_e32 v168, 16, v124
	v_and_b32_e32 v169, 0xffff0000, v124
	v_lshlrev_b32_e32 v184, 16, v156
	v_and_b32_e32 v185, 0xffff0000, v156
	v_mul_f32_e32 v184, s101, v184
	v_mul_f32_e32 v185, s101, v185
	v_fma_f32 v168, v184, v2, v168
	v_fma_f32 v169, v185, v3, v169
	v_lshlrev_b32_e32 v170, 16, v125
	v_and_b32_e32 v171, 0xffff0000, v125
	v_lshlrev_b32_e32 v184, 16, v157
	v_and_b32_e32 v185, 0xffff0000, v157
	v_mul_f32_e32 v184, s101, v184
	v_mul_f32_e32 v185, s101, v185
	v_fma_f32 v170, v184, v4, v170
	v_fma_f32 v171, v185, v5, v171
	v_lshlrev_b32_e32 v172, 16, v126
	v_and_b32_e32 v173, 0xffff0000, v126
	v_lshlrev_b32_e32 v184, 16, v158
	v_and_b32_e32 v185, 0xffff0000, v158
	v_mul_f32_e32 v184, s101, v184
	v_mul_f32_e32 v185, s101, v185
	v_fma_f32 v172, v184, v6, v172
	v_fma_f32 v173, v185, v7, v173
	v_lshlrev_b32_e32 v174, 16, v127
	v_and_b32_e32 v175, 0xffff0000, v127
	v_lshlrev_b32_e32 v184, 16, v159
	v_and_b32_e32 v185, 0xffff0000, v159
	v_mul_f32_e32 v184, s101, v184
	v_mul_f32_e32 v185, s101, v185
	v_fma_f32 v174, v184, v8, v174
	v_fma_f32 v175, v185, v9, v175
	v_lshlrev_b32_e32 v176, 16, v128
	v_and_b32_e32 v177, 0xffff0000, v128
	v_lshlrev_b32_e32 v184, 16, v160
	v_and_b32_e32 v185, 0xffff0000, v160
	v_mul_f32_e32 v184, s101, v184
	v_mul_f32_e32 v185, s101, v185
	v_fma_f32 v176, v184, v10, v176
	v_fma_f32 v177, v185, v11, v177
	v_lshlrev_b32_e32 v178, 16, v129
	v_and_b32_e32 v179, 0xffff0000, v129
	v_lshlrev_b32_e32 v184, 16, v161
	v_and_b32_e32 v185, 0xffff0000, v161
	v_mul_f32_e32 v184, s101, v184
	v_mul_f32_e32 v185, s101, v185
	v_fma_f32 v178, v184, v12, v178
	v_fma_f32 v179, v185, v13, v179
	v_lshlrev_b32_e32 v180, 16, v130
	v_and_b32_e32 v181, 0xffff0000, v130
	v_lshlrev_b32_e32 v184, 16, v162
	v_and_b32_e32 v185, 0xffff0000, v162
	v_mul_f32_e32 v184, s101, v184
	v_mul_f32_e32 v185, s101, v185
	v_fma_f32 v180, v184, v14, v180
	v_fma_f32 v181, v185, v15, v181
	v_lshlrev_b32_e32 v182, 16, v131
	v_and_b32_e32 v183, 0xffff0000, v131
	v_lshlrev_b32_e32 v184, 16, v163
	v_and_b32_e32 v185, 0xffff0000, v163
	v_mul_f32_e32 v184, s101, v184
	v_mul_f32_e32 v185, s101, v185
	v_fma_f32 v182, v184, v16, v182
	v_fma_f32 v183, v185, v17, v183
	v_add_u32_e32 v1, 0x3000, v27
	global_store_dwordx4 v1, v[168:171], s[14:15] nt
	global_store_dwordx4 v1, v[172:175], s[14:15] offset:16 nt
	global_store_dwordx4 v1, v[176:179], s[14:15] offset:2048 nt
	global_store_dwordx4 v1, v[180:183], s[14:15] offset:2064 nt
	s_nop 1
